# v17: v16 + GEMM-phase output stores global_store_dwordx4 sc1 (write-through) so the grid barrier's buffer_wbl2 finds no freshly dirtied L2 lines
# baseline (speedup 1.0000x reference)
; __device__ __forceinline__ f32x4 silu4(f32x4 v) { return v * sigm4(v); }
; __device__ __forceinline__ u32x4 pack8(f32x4 v0, f32x4 v1) { u32x4 w; w.x = cvt_pk_bf16(v0[0], v0[1]); w.y = cvt_pk_bf16(v0[2], v0[3]); w.z = cvt_pk_bf16(v1[0], v1[1]); w.w = cvt_pk_bf16(v1[2], v1[3]); return w; }
; __device__ __forceinline__ void hg_gate4(f32x4& z, f32x4& key, const f32x4 l) {
;     const f32x4 zc = {__builtin_amdgcn_fmed3f(z[0], -80.f, 80.f), __builtin_amdgcn_fmed3f(z[1], -80.f, 80.f), __builtin_amdgcn_fmed3f(z[2], -80.f, 80.f), __builtin_amdgcn_fmed3f(z[3], -80.f, 80.f)};
;     const f32x4 t = zc * -1.4426950408889634f;
;     const f32x4 e = {__builtin_amdgcn_exp2f(t[0]), __builtin_amdgcn_exp2f(t[1]), __builtin_amdgcn_exp2f(t[2]), __builtin_amdgcn_exp2f(t[3])};
;     const f32x4 den = e + 1.0f;
;     const f32x4 sg = {__builtin_amdgcn_rcpf(den[0]), __builtin_amdgcn_rcpf(den[1]), __builtin_amdgcn_rcpf(den[2]), __builtin_amdgcn_rcpf(den[3])};
;     const f32x4 oml = 1.0f - l;
;     const f32x4 f = l + oml * sg;
;     z = (f32x4){__builtin_amdgcn_logf(f[0]), __builtin_amdgcn_logf(f[1]), __builtin_amdgcn_logf(f[2]), __builtin_amdgcn_logf(f[3])} * 0.6931471805599453f;
;     key = oml * (e * sg);
; }
;     __device__ __forceinline__ void operator()(const f32x4 (&acc)[2][2][4][2], const Unit& u, int wr, int wc, int fr_in, int fq_in) const {
;     ...
;         for (int ai = 0; ai < 2; ++ai)
; #pragma unroll
;             for (int m = 0; m < 4; ++m) {
;                 const int r = row0 + ai * HALF + m * 16;
;                 const size_t roff = (size_t)r * 2048 + cb;
; #pragma unroll
;                 for (int bj = 0; bj < 2; ++bj) {
;                     f32x4 v0 = acc[ai][bj][m][0], v1 = acc[ai][bj][m][1];
;                     if (type == 0) { v0 = silu4(v0); v1 = silu4(v1); }
;                     if (type == 4) { v0 = sigm4(v0); v1 = sigm4(v1); }
;                     if (type == 1 || type == 2) {
;                         f32x4 k0, k1;
;                         hg_gate4(v0, k0, lbv[bj][0]); hg_gate4(v1, k1, lbv[bj][1]);
;                         st16(base + tstride, roff + bj * HALF, pack8(k0, k1));
;                     }
;                     st16(base, roff + bj * HALF, pack8(v0, v1));
;                 }
.LBB0_317:
	s_andn2_b64 vcc, exec, s[12:13]
	s_waitcnt vmcnt(0)
	v_sub_f32_e32 v153, 1.0, v49
	v_sub_f32_e32 v152, 1.0, v48
	v_sub_f32_e32 v155, 1.0, v51
	v_sub_f32_e32 v154, 1.0, v50
	v_sub_f32_e32 v149, 1.0, v37
	v_sub_f32_e32 v148, 1.0, v36
	v_sub_f32_e32 v151, 1.0, v39
	v_sub_f32_e32 v150, 1.0, v38
	s_cbranch_vccnz .LBB0_319
	v_med3_f32 v2, v144, s95, v182
	v_med3_f32 v3, v145, s95, v182
	v_med3_f32 v144, v146, s95, v182
	v_med3_f32 v145, v147, s95, v182
	v_pk_mul_f32 v[144:145], v[144:145], s[96:97] op_sel_hi:[1,0]
	v_pk_mul_f32 v[2:3], v[2:3], s[96:97] op_sel_hi:[1,0]
	v_exp_f32_e32 v170, v144
	v_exp_f32_e32 v2, v2
	v_exp_f32_e32 v171, v145
	v_exp_f32_e32 v3, v3
	v_med3_f32 v140, v140, s95, v182
	v_med3_f32 v141, v141, s95, v182
	v_pk_add_f32 v[144:145], v[170:171], 1.0 op_sel_hi:[1,0]
	v_pk_add_f32 v[146:147], v[2:3], 1.0 op_sel_hi:[1,0]
	v_rcp_f32_e32 v174, v144
	v_rcp_f32_e32 v172, v146
	v_rcp_f32_e32 v175, v145
	v_rcp_f32_e32 v173, v147
	v_pk_mul_f32 v[140:141], v[140:141], s[96:97] op_sel_hi:[1,0]
	v_med3_f32 v142, v142, s95, v182
	v_pk_fma_f32 v[144:145], v[154:155], v[174:175], v[50:51]
	v_pk_fma_f32 v[146:147], v[152:153], v[172:173], v[48:49]
	v_exp_f32_e32 v178, v140
	v_exp_f32_e32 v179, v141
	v_log_f32_e32 v176, v146
	v_log_f32_e32 v177, v147
	v_log_f32_e32 v144, v144
	v_log_f32_e32 v145, v145
	v_med3_f32 v143, v143, s95, v182
	v_pk_mul_f32 v[142:143], v[142:143], s[96:97] op_sel_hi:[1,0]
	v_pk_mul_f32 v[2:3], v[2:3], v[172:173]
	v_exp_f32_e32 v180, v142
	v_exp_f32_e32 v181, v143
	v_pk_add_f32 v[142:143], v[178:179], 1.0 op_sel_hi:[1,0]
	v_pk_mul_f32 v[146:147], v[144:145], s[68:69] op_sel_hi:[1,0]
	v_pk_mul_f32 v[144:145], v[176:177], s[68:69] op_sel_hi:[1,0]
	v_rcp_f32_e32 v176, v142
	v_rcp_f32_e32 v177, v143
	v_pk_add_f32 v[140:141], v[180:181], 1.0 op_sel_hi:[1,0]
	v_pk_mul_f32 v[2:3], v[152:153], v[2:3]
	v_rcp_f32_e32 v184, v140
	v_rcp_f32_e32 v185, v141
	v_pk_mul_f32 v[140:141], v[170:171], v[174:175]
	v_pk_fma_f32 v[170:171], v[148:149], v[176:177], v[36:37]
	v_pk_mul_f32 v[172:173], v[154:155], v[140:141]
	v_log_f32_e32 v170, v170
	v_log_f32_e32 v171, v171
	v_pk_fma_f32 v[142:143], v[150:151], v[184:185], v[38:39]
	v_pk_mul_f32 v[174:175], v[180:181], v[184:185]
	v_log_f32_e32 v142, v142
	v_log_f32_e32 v143, v143
	v_pk_mul_f32 v[140:141], v[170:171], s[68:69] op_sel_hi:[1,0]
	v_pk_mul_f32 v[170:171], v[178:179], v[176:177]
	v_pk_mul_f32 v[174:175], v[150:151], v[174:175]
	v_pk_mul_f32 v[176:177], v[148:149], v[170:171]
	v_cvt_pk_bf16_f32 v170, v2, v3
	v_lshl_add_u64 v[2:3], s[30:31], 0, v[0:1]
	v_add_co_u32_e32 v2, vcc, 0x4400000, v2
	v_pk_mul_f32 v[142:143], v[142:143], s[68:69] op_sel_hi:[1,0]
	s_nop 0
	v_addc_co_u32_e32 v3, vcc, 0, v3, vcc
	v_cvt_pk_bf16_f32 v171, v172, v173
	v_cvt_pk_bf16_f32 v172, v176, v177
	v_cvt_pk_bf16_f32 v173, v174, v175
	global_store_dwordx4 v[2:3], v[170:173], off sc1
.LBB0_319:
	v_lshl_add_u64 v[2:3], s[30:31], 0, v[0:1]
	s_and_b64 vcc, exec, s[8:9]
	v_cvt_pk_bf16_f32 v144, v144, v145
	v_cvt_pk_bf16_f32 v145, v146, v147
	v_cvt_pk_bf16_f32 v146, v140, v141
	v_cvt_pk_bf16_f32 v147, v142, v143
	global_store_dwordx4 v[2:3], v[144:147], off sc1
	s_cbranch_vccnz .LBB0_331
	v_pk_mul_f32 v[2:3], v[138:139], s[96:97] op_sel_hi:[1,0]
	v_pk_mul_f32 v[140:141], v[136:137], s[96:97] op_sel_hi:[1,0]
	v_exp_f32_e32 v2, v2
	v_exp_f32_e32 v140, v140
	v_exp_f32_e32 v141, v141
	v_exp_f32_e32 v3, v3
	v_pk_add_f32 v[140:141], v[140:141], 1.0 op_sel_hi:[1,0]
	v_pk_add_f32 v[2:3], v[2:3], 1.0 op_sel_hi:[1,0]
	v_rcp_f32_e32 v140, v140
	v_rcp_f32_e32 v141, v141
	v_rcp_f32_e32 v2, v2
	v_rcp_f32_e32 v3, v3
	v_pk_mul_f32 v[136:137], v[136:137], v[140:141]
	v_pk_mul_f32 v[140:141], v[132:133], s[96:97] op_sel_hi:[1,0]
	v_pk_mul_f32 v[138:139], v[138:139], v[2:3]
	v_pk_mul_f32 v[2:3], v[134:135], s[96:97] op_sel_hi:[1,0]
	v_exp_f32_e32 v140, v140
	v_exp_f32_e32 v141, v141
	v_exp_f32_e32 v2, v2
	v_exp_f32_e32 v3, v3
	v_pk_add_f32 v[140:141], v[140:141], 1.0 op_sel_hi:[1,0]
	s_nop 0
	v_rcp_f32_e32 v140, v140
	v_pk_add_f32 v[2:3], v[2:3], 1.0 op_sel_hi:[1,0]
	v_rcp_f32_e32 v141, v141
	v_rcp_f32_e32 v2, v2
	v_rcp_f32_e32 v3, v3
	v_pk_mul_f32 v[132:133], v[132:133], v[140:141]
	v_pk_mul_f32 v[134:135], v[134:135], v[2:3]
	v_cndmask_b32_e64 v2, 0, 1, s[34:35]
	v_cmp_ne_u32_e64 s[12:13], 1, v2
	s_andn2_b64 vcc, exec, s[34:35]
	s_cbranch_vccz .LBB0_332

; __device__ __forceinline__ f32x4 silu4(f32x4 v) { return v * sigm4(v); }
; __device__ __forceinline__ u32x4 pack8(f32x4 v0, f32x4 v1) { u32x4 w; w.x = cvt_pk_bf16(v0[0], v0[1]); w.y = cvt_pk_bf16(v0[2], v0[3]); w.z = cvt_pk_bf16(v1[0], v1[1]); w.w = cvt_pk_bf16(v1[2], v1[3]); return w; }
; __device__ __forceinline__ void hg_gate4(f32x4& z, f32x4& key, const f32x4 l) {
;     const f32x4 zc = {__builtin_amdgcn_fmed3f(z[0], -80.f, 80.f), __builtin_amdgcn_fmed3f(z[1], -80.f, 80.f), __builtin_amdgcn_fmed3f(z[2], -80.f, 80.f), __builtin_amdgcn_fmed3f(z[3], -80.f, 80.f)};
;     const f32x4 t = zc * -1.4426950408889634f;
;     const f32x4 e = {__builtin_amdgcn_exp2f(t[0]), __builtin_amdgcn_exp2f(t[1]), __builtin_amdgcn_exp2f(t[2]), __builtin_amdgcn_exp2f(t[3])};
;     const f32x4 den = e + 1.0f;
;     const f32x4 sg = {__builtin_amdgcn_rcpf(den[0]), __builtin_amdgcn_rcpf(den[1]), __builtin_amdgcn_rcpf(den[2]), __builtin_amdgcn_rcpf(den[3])};
;     const f32x4 oml = 1.0f - l;
;     const f32x4 f = l + oml * sg;
;     z = (f32x4){__builtin_amdgcn_logf(f[0]), __builtin_amdgcn_logf(f[1]), __builtin_amdgcn_logf(f[2]), __builtin_amdgcn_logf(f[3])} * 0.6931471805599453f;
;     key = oml * (e * sg);
; }
;     __device__ __forceinline__ void operator()(const f32x4 (&acc)[2][2][4][2], const Unit& u, int wr, int wc, int fr_in, int fq_in) const {
;     ...
;         for (int ai = 0; ai < 2; ++ai)
; #pragma unroll
;             for (int m = 0; m < 4; ++m) {
;                 const int r = row0 + ai * HALF + m * 16;
;                 const size_t roff = (size_t)r * 2048 + cb;
; #pragma unroll
;                 for (int bj = 0; bj < 2; ++bj) {
;                     f32x4 v0 = acc[ai][bj][m][0], v1 = acc[ai][bj][m][1];
;                     if (type == 0) { v0 = silu4(v0); v1 = silu4(v1); }
;                     if (type == 4) { v0 = sigm4(v0); v1 = sigm4(v1); }
;                     if (type == 1 || type == 2) {
;                         f32x4 k0, k1;
;                         hg_gate4(v0, k0, lbv[bj][0]); hg_gate4(v1, k1, lbv[bj][1]);
;                         st16(base + tstride, roff + bj * HALF, pack8(k0, k1));
;                     }
;                     st16(base, roff + bj * HALF, pack8(v0, v1));
;                 }
.LBB0_323:
	s_andn2_b64 vcc, exec, s[34:35]
	v_sub_f32_e32 v143, 1.0, v25
	v_sub_f32_e32 v142, 1.0, v24
	v_sub_f32_e32 v145, 1.0, v27
	v_sub_f32_e32 v144, 1.0, v26
	v_sub_f32_e32 v3, 1.0, v21
	v_sub_f32_e32 v2, 1.0, v20
	v_sub_f32_e32 v141, 1.0, v23
	v_sub_f32_e32 v140, 1.0, v22
	s_cbranch_vccnz .LBB0_325
	v_med3_f32 v136, v136, s95, v182
	v_med3_f32 v137, v137, s95, v182
	v_med3_f32 v138, v138, s95, v182
	v_med3_f32 v139, v139, s95, v182
	v_pk_mul_f32 v[138:139], v[138:139], s[96:97] op_sel_hi:[1,0]
	v_pk_mul_f32 v[136:137], v[136:137], s[96:97] op_sel_hi:[1,0]
	v_exp_f32_e32 v170, v138
	v_exp_f32_e32 v146, v136
	v_exp_f32_e32 v171, v139
	v_exp_f32_e32 v147, v137
	v_med3_f32 v134, v134, s95, v182
	v_med3_f32 v135, v135, s95, v182
	v_pk_add_f32 v[136:137], v[170:171], 1.0 op_sel_hi:[1,0]
	v_pk_add_f32 v[138:139], v[146:147], 1.0 op_sel_hi:[1,0]
	v_rcp_f32_e32 v174, v136
	v_rcp_f32_e32 v172, v138
	v_rcp_f32_e32 v175, v137
	v_rcp_f32_e32 v173, v139
	v_med3_f32 v132, v132, s95, v182
	v_med3_f32 v133, v133, s95, v182
	v_pk_mul_f32 v[134:135], v[134:135], s[96:97] op_sel_hi:[1,0]
	v_pk_mul_f32 v[132:133], v[132:133], s[96:97] op_sel_hi:[1,0]
	v_exp_f32_e32 v180, v134
	v_exp_f32_e32 v181, v135
	v_pk_fma_f32 v[136:137], v[144:145], v[174:175], v[26:27]
	v_pk_fma_f32 v[138:139], v[142:143], v[172:173], v[24:25]
	v_exp_f32_e32 v178, v132
	v_exp_f32_e32 v179, v133
	v_log_f32_e32 v176, v138
	v_log_f32_e32 v177, v139
	v_log_f32_e32 v136, v136
	v_log_f32_e32 v137, v137
	v_pk_add_f32 v[132:133], v[180:181], 1.0 op_sel_hi:[1,0]
	v_pk_add_f32 v[134:135], v[178:179], 1.0 op_sel_hi:[1,0]
	v_rcp_f32_e32 v184, v132
	v_rcp_f32_e32 v185, v133
	v_pk_mul_f32 v[138:139], v[136:137], s[68:69] op_sel_hi:[1,0]
	v_pk_mul_f32 v[136:137], v[176:177], s[68:69] op_sel_hi:[1,0]
	v_rcp_f32_e32 v176, v134
	v_rcp_f32_e32 v177, v135
	v_pk_mul_f32 v[132:133], v[146:147], v[172:173]
	v_pk_fma_f32 v[146:147], v[140:141], v[184:185], v[22:23]
	v_pk_mul_f32 v[134:135], v[170:171], v[174:175]
	v_pk_fma_f32 v[170:171], v[2:3], v[176:177], v[20:21]
	v_log_f32_e32 v146, v146
	v_log_f32_e32 v147, v147
	v_log_f32_e32 v170, v170
	v_log_f32_e32 v171, v171
	v_pk_mul_f32 v[172:173], v[144:145], v[134:135]
	v_pk_mul_f32 v[134:135], v[146:147], s[68:69] op_sel_hi:[1,0]
	v_pk_mul_f32 v[146:147], v[178:179], v[176:177]
	v_pk_mul_f32 v[174:175], v[142:143], v[132:133]
	v_pk_mul_f32 v[132:133], v[170:171], s[68:69] op_sel_hi:[1,0]
	v_pk_mul_f32 v[170:171], v[180:181], v[184:185]
	v_pk_mul_f32 v[146:147], v[2:3], v[146:147]
	v_pk_mul_f32 v[176:177], v[140:141], v[170:171]
	v_cvt_pk_bf16_f32 v170, v174, v175
	v_cvt_pk_bf16_f32 v171, v172, v173
	v_cvt_pk_bf16_f32 v172, v146, v147
	v_lshl_add_u64 v[146:147], s[30:31], 0, v[0:1]
	v_add_co_u32_e32 v146, vcc, 0x4400000, v146
	v_cvt_pk_bf16_f32 v173, v176, v177
	s_nop 1
	v_addc_co_u32_e32 v147, vcc, 0, v147, vcc
	global_store_dwordx4 v[146:147], v[170:173], off sc1
.LBB0_325:
	v_cvt_pk_bf16_f32 v136, v136, v137
	v_cvt_pk_bf16_f32 v137, v138, v139
	v_cvt_pk_bf16_f32 v138, v132, v133
	v_lshl_add_u64 v[132:133], s[30:31], 0, v[0:1]
	s_and_b64 vcc, exec, s[8:9]
	v_cvt_pk_bf16_f32 v139, v134, v135
	global_store_dwordx4 v[132:133], v[136:139], off sc1
	s_cbranch_vccnz .LBB0_327
	v_pk_mul_f32 v[132:133], v[130:131], s[96:97] op_sel_hi:[1,0]
	v_pk_mul_f32 v[134:135], v[128:129], s[96:97] op_sel_hi:[1,0]
	v_exp_f32_e32 v132, v132
	v_exp_f32_e32 v134, v134
	v_exp_f32_e32 v135, v135
	v_exp_f32_e32 v133, v133
	v_pk_add_f32 v[134:135], v[134:135], 1.0 op_sel_hi:[1,0]
	v_pk_add_f32 v[132:133], v[132:133], 1.0 op_sel_hi:[1,0]
	v_rcp_f32_e32 v134, v134
	v_rcp_f32_e32 v135, v135
	v_rcp_f32_e32 v132, v132
	v_rcp_f32_e32 v133, v133
	v_pk_mul_f32 v[128:129], v[128:129], v[134:135]
	v_pk_mul_f32 v[134:135], v[124:125], s[96:97] op_sel_hi:[1,0]
	v_pk_mul_f32 v[130:131], v[130:131], v[132:133]
	v_pk_mul_f32 v[132:133], v[126:127], s[96:97] op_sel_hi:[1,0]
	v_exp_f32_e32 v134, v134
	v_exp_f32_e32 v135, v135
	v_exp_f32_e32 v132, v132
	v_exp_f32_e32 v133, v133
	v_pk_add_f32 v[134:135], v[134:135], 1.0 op_sel_hi:[1,0]
	s_nop 0
	v_rcp_f32_e32 v134, v134
	v_pk_add_f32 v[132:133], v[132:133], 1.0 op_sel_hi:[1,0]
	v_rcp_f32_e32 v135, v135
	v_rcp_f32_e32 v132, v132
	v_rcp_f32_e32 v133, v133
	v_pk_mul_f32 v[124:125], v[124:125], v[134:135]
	v_pk_mul_f32 v[126:127], v[126:127], v[132:133]

; __device__ __forceinline__ f32x4 silu4(f32x4 v) { return v * sigm4(v); }
; __device__ __forceinline__ u32x4 pack8(f32x4 v0, f32x4 v1) { u32x4 w; w.x = cvt_pk_bf16(v0[0], v0[1]); w.y = cvt_pk_bf16(v0[2], v0[3]); w.z = cvt_pk_bf16(v1[0], v1[1]); w.w = cvt_pk_bf16(v1[2], v1[3]); return w; }
; __device__ __forceinline__ void hg_gate4(f32x4& z, f32x4& key, const f32x4 l) {
;     const f32x4 zc = {__builtin_amdgcn_fmed3f(z[0], -80.f, 80.f), __builtin_amdgcn_fmed3f(z[1], -80.f, 80.f), __builtin_amdgcn_fmed3f(z[2], -80.f, 80.f), __builtin_amdgcn_fmed3f(z[3], -80.f, 80.f)};
;     const f32x4 t = zc * -1.4426950408889634f;
;     const f32x4 e = {__builtin_amdgcn_exp2f(t[0]), __builtin_amdgcn_exp2f(t[1]), __builtin_amdgcn_exp2f(t[2]), __builtin_amdgcn_exp2f(t[3])};
;     const f32x4 den = e + 1.0f;
;     const f32x4 sg = {__builtin_amdgcn_rcpf(den[0]), __builtin_amdgcn_rcpf(den[1]), __builtin_amdgcn_rcpf(den[2]), __builtin_amdgcn_rcpf(den[3])};
;     const f32x4 oml = 1.0f - l;
;     const f32x4 f = l + oml * sg;
;     z = (f32x4){__builtin_amdgcn_logf(f[0]), __builtin_amdgcn_logf(f[1]), __builtin_amdgcn_logf(f[2]), __builtin_amdgcn_logf(f[3])} * 0.6931471805599453f;
;     key = oml * (e * sg);
; }
;     __device__ __forceinline__ void operator()(const f32x4 (&acc)[2][2][4][2], const Unit& u, int wr, int wc, int fr_in, int fq_in) const {
;     ...
;         for (int ai = 0; ai < 2; ++ai)
; #pragma unroll
;             for (int m = 0; m < 4; ++m) {
;                 const int r = row0 + ai * HALF + m * 16;
;                 const size_t roff = (size_t)r * 2048 + cb;
; #pragma unroll
;                 for (int bj = 0; bj < 2; ++bj) {
;                     f32x4 v0 = acc[ai][bj][m][0], v1 = acc[ai][bj][m][1];
;                     if (type == 0) { v0 = silu4(v0); v1 = silu4(v1); }
;                     if (type == 4) { v0 = sigm4(v0); v1 = sigm4(v1); }
;                     if (type == 1 || type == 2) {
;                         f32x4 k0, k1;
;                         hg_gate4(v0, k0, lbv[bj][0]); hg_gate4(v1, k1, lbv[bj][1]);
;                         st16(base + tstride, roff + bj * HALF, pack8(k0, k1));
;                     }
;                     st16(base, roff + bj * HALF, pack8(v0, v1));
;                 }
.LBB0_333:
.LBB0_334:
	v_med3_f32 v128, v128, s95, v182
	v_med3_f32 v129, v129, s95, v182
	v_med3_f32 v130, v130, s95, v182
	v_med3_f32 v131, v131, s95, v182
	v_pk_mul_f32 v[130:131], v[130:131], s[96:97] op_sel_hi:[1,0]
	v_pk_mul_f32 v[128:129], v[128:129], s[96:97] op_sel_hi:[1,0]
	v_exp_f32_e32 v136, v130
	v_exp_f32_e32 v134, v128
	v_exp_f32_e32 v137, v131
	v_exp_f32_e32 v135, v129
	v_med3_f32 v124, v124, s95, v182
	v_med3_f32 v125, v125, s95, v182
	v_pk_add_f32 v[128:129], v[136:137], 1.0 op_sel_hi:[1,0]
	v_pk_add_f32 v[130:131], v[134:135], 1.0 op_sel_hi:[1,0]
	v_rcp_f32_e32 v146, v128
	v_rcp_f32_e32 v138, v130
	v_rcp_f32_e32 v147, v129
	v_rcp_f32_e32 v139, v131
	v_med3_f32 v126, v126, s95, v182
	v_med3_f32 v127, v127, s95, v182
	v_pk_mul_f32 v[126:127], v[126:127], s[96:97] op_sel_hi:[1,0]
	v_pk_mul_f32 v[124:125], v[124:125], s[96:97] op_sel_hi:[1,0]
	v_pk_fma_f32 v[128:129], v[154:155], v[146:147], v[50:51]
	v_pk_fma_f32 v[130:131], v[152:153], v[138:139], v[48:49]
	v_exp_f32_e32 v170, v124
	v_exp_f32_e32 v172, v126
	v_exp_f32_e32 v173, v127
	v_exp_f32_e32 v171, v125
	v_log_f32_e32 v156, v130
	v_log_f32_e32 v157, v131
	v_log_f32_e32 v128, v128
	v_log_f32_e32 v129, v129
	v_pk_add_f32 v[124:125], v[172:173], 1.0 op_sel_hi:[1,0]
	v_pk_add_f32 v[126:127], v[170:171], 1.0 op_sel_hi:[1,0]
	v_rcp_f32_e32 v174, v124
	v_pk_mul_f32 v[130:131], v[128:129], s[68:69] op_sel_hi:[1,0]
	v_pk_mul_f32 v[128:129], v[156:157], s[68:69] op_sel_hi:[1,0]
	v_rcp_f32_e32 v156, v126
	v_rcp_f32_e32 v175, v125
	v_rcp_f32_e32 v157, v127
	v_pk_mul_f32 v[124:125], v[134:135], v[138:139]
	v_pk_mul_f32 v[126:127], v[136:137], v[146:147]
	v_pk_fma_f32 v[134:135], v[150:151], v[174:175], v[38:39]
	v_pk_fma_f32 v[136:137], v[148:149], v[156:157], v[36:37]
	v_log_f32_e32 v134, v134
	v_log_f32_e32 v136, v136
	v_log_f32_e32 v135, v135
	v_log_f32_e32 v137, v137
	v_pk_mul_f32 v[138:139], v[154:155], v[126:127]
	v_pk_mul_f32 v[146:147], v[152:153], v[124:125]
	v_pk_mul_f32 v[126:127], v[134:135], s[68:69] op_sel_hi:[1,0]
	v_pk_mul_f32 v[124:125], v[136:137], s[68:69] op_sel_hi:[1,0]
	v_pk_mul_f32 v[134:135], v[170:171], v[156:157]
	v_pk_mul_f32 v[136:137], v[172:173], v[174:175]
	s_nop 0
	v_pk_mul_f32 v[156:157], v[150:151], v[136:137]
	v_pk_mul_f32 v[136:137], v[148:149], v[134:135]
	v_cvt_pk_bf16_f32 v134, v146, v147
	v_cvt_pk_bf16_f32 v135, v138, v139
	v_lshl_add_u64 v[138:139], s[30:31], 0, v[0:1]
	v_add_co_u32_e32 v138, vcc, 0x4400000, v138
	v_cvt_pk_bf16_f32 v136, v136, v137
	v_cvt_pk_bf16_f32 v137, v156, v157
	s_nop 1
	v_addc_co_u32_e32 v139, vcc, 0, v139, vcc
	global_store_dwordx4 v[138:139], v[134:137], off sc1
.LBB0_335:
	v_cvt_pk_bf16_f32 v128, v128, v129
	v_cvt_pk_bf16_f32 v129, v130, v131
	v_cvt_pk_bf16_f32 v130, v124, v125
	v_lshl_add_u64 v[124:125], s[30:31], 0, v[0:1]
	s_and_b64 vcc, exec, s[8:9]
	v_cvt_pk_bf16_f32 v131, v126, v127
	global_store_dwordx4 v[124:125], v[128:131], off sc1
	s_cbranch_vccnz .LBB0_339
	v_pk_mul_f32 v[124:125], v[122:123], s[96:97] op_sel_hi:[1,0]
	v_pk_mul_f32 v[126:127], v[120:121], s[96:97] op_sel_hi:[1,0]
	v_exp_f32_e32 v124, v124
	v_exp_f32_e32 v126, v126
	v_exp_f32_e32 v127, v127
	v_exp_f32_e32 v125, v125
	v_pk_add_f32 v[126:127], v[126:127], 1.0 op_sel_hi:[1,0]
	v_pk_add_f32 v[124:125], v[124:125], 1.0 op_sel_hi:[1,0]
	v_rcp_f32_e32 v126, v126
	v_rcp_f32_e32 v127, v127
	v_rcp_f32_e32 v124, v124
	v_rcp_f32_e32 v125, v125
	v_pk_mul_f32 v[120:121], v[120:121], v[126:127]
	v_pk_mul_f32 v[126:127], v[116:117], s[96:97] op_sel_hi:[1,0]
	v_pk_mul_f32 v[122:123], v[122:123], v[124:125]
	v_pk_mul_f32 v[124:125], v[118:119], s[96:97] op_sel_hi:[1,0]
	v_exp_f32_e32 v126, v126
	v_exp_f32_e32 v127, v127
	v_exp_f32_e32 v124, v124
	v_exp_f32_e32 v125, v125
	v_pk_add_f32 v[126:127], v[126:127], 1.0 op_sel_hi:[1,0]
	s_nop 0
	v_rcp_f32_e32 v126, v126
	v_pk_add_f32 v[124:125], v[124:125], 1.0 op_sel_hi:[1,0]
	v_rcp_f32_e32 v127, v127
	v_rcp_f32_e32 v124, v124
	v_rcp_f32_e32 v125, v125
	v_pk_mul_f32 v[116:117], v[116:117], v[126:127]
	v_pk_mul_f32 v[118:119], v[118:119], v[124:125]
	s_and_b64 vcc, exec, s[12:13]
	s_cbranch_vccz .LBB0_340

; __device__ __forceinline__ f32x4 silu4(f32x4 v) { return v * sigm4(v); }
; __device__ __forceinline__ u32x4 pack8(f32x4 v0, f32x4 v1) { u32x4 w; w.x = cvt_pk_bf16(v0[0], v0[1]); w.y = cvt_pk_bf16(v0[2], v0[3]); w.z = cvt_pk_bf16(v1[0], v1[1]); w.w = cvt_pk_bf16(v1[2], v1[3]); return w; }
; __device__ __forceinline__ void hg_gate4(f32x4& z, f32x4& key, const f32x4 l) {
;     const f32x4 zc = {__builtin_amdgcn_fmed3f(z[0], -80.f, 80.f), __builtin_amdgcn_fmed3f(z[1], -80.f, 80.f), __builtin_amdgcn_fmed3f(z[2], -80.f, 80.f), __builtin_amdgcn_fmed3f(z[3], -80.f, 80.f)};
;     const f32x4 t = zc * -1.4426950408889634f;
;     const f32x4 e = {__builtin_amdgcn_exp2f(t[0]), __builtin_amdgcn_exp2f(t[1]), __builtin_amdgcn_exp2f(t[2]), __builtin_amdgcn_exp2f(t[3])};
;     const f32x4 den = e + 1.0f;
;     const f32x4 sg = {__builtin_amdgcn_rcpf(den[0]), __builtin_amdgcn_rcpf(den[1]), __builtin_amdgcn_rcpf(den[2]), __builtin_amdgcn_rcpf(den[3])};
;     const f32x4 oml = 1.0f - l;
;     const f32x4 f = l + oml * sg;
;     z = (f32x4){__builtin_amdgcn_logf(f[0]), __builtin_amdgcn_logf(f[1]), __builtin_amdgcn_logf(f[2]), __builtin_amdgcn_logf(f[3])} * 0.6931471805599453f;
;     key = oml * (e * sg);
; }
;     __device__ __forceinline__ void operator()(const f32x4 (&acc)[2][2][4][2], const Unit& u, int wr, int wc, int fr_in, int fq_in) const {
;     ...
;         for (int ai = 0; ai < 2; ++ai)
; #pragma unroll
;             for (int m = 0; m < 4; ++m) {
;                 const int r = row0 + ai * HALF + m * 16;
;                 const size_t roff = (size_t)r * 2048 + cb;
; #pragma unroll
;                 for (int bj = 0; bj < 2; ++bj) {
;                     f32x4 v0 = acc[ai][bj][m][0], v1 = acc[ai][bj][m][1];
;                     if (type == 0) { v0 = silu4(v0); v1 = silu4(v1); }
;                     if (type == 4) { v0 = sigm4(v0); v1 = sigm4(v1); }
;                     if (type == 1 || type == 2) {
;                         f32x4 k0, k1;
;                         hg_gate4(v0, k0, lbv[bj][0]); hg_gate4(v1, k1, lbv[bj][1]);
;                         st16(base + tstride, roff + bj * HALF, pack8(k0, k1));
;                     }
;                     st16(base, roff + bj * HALF, pack8(v0, v1));
;                 }
.LBB0_342:
	v_med3_f32 v120, v120, s95, v182
	v_med3_f32 v121, v121, s95, v182
	v_med3_f32 v122, v122, s95, v182
	v_med3_f32 v123, v123, s95, v182
	v_pk_mul_f32 v[122:123], v[122:123], s[96:97] op_sel_hi:[1,0]
	v_pk_mul_f32 v[120:121], v[120:121], s[96:97] op_sel_hi:[1,0]
	v_exp_f32_e32 v126, v122
	v_exp_f32_e32 v124, v120
	v_exp_f32_e32 v127, v123
	v_exp_f32_e32 v125, v121
	v_med3_f32 v116, v116, s95, v182
	v_med3_f32 v117, v117, s95, v182
	v_pk_add_f32 v[120:121], v[126:127], 1.0 op_sel_hi:[1,0]
	v_pk_add_f32 v[122:123], v[124:125], 1.0 op_sel_hi:[1,0]
	v_rcp_f32_e32 v130, v120
	v_rcp_f32_e32 v128, v122
	v_rcp_f32_e32 v131, v121
	v_rcp_f32_e32 v129, v123
	v_med3_f32 v118, v118, s95, v182
	v_med3_f32 v119, v119, s95, v182
	v_pk_mul_f32 v[118:119], v[118:119], s[96:97] op_sel_hi:[1,0]
	v_pk_mul_f32 v[116:117], v[116:117], s[96:97] op_sel_hi:[1,0]
	v_pk_fma_f32 v[120:121], v[144:145], v[130:131], v[26:27]
	v_pk_fma_f32 v[122:123], v[142:143], v[128:129], v[24:25]
	v_exp_f32_e32 v136, v116
	v_exp_f32_e32 v138, v118
	v_exp_f32_e32 v139, v119
	v_exp_f32_e32 v137, v117
	v_log_f32_e32 v134, v122
	v_log_f32_e32 v135, v123
	v_log_f32_e32 v120, v120
	v_log_f32_e32 v121, v121
	v_pk_add_f32 v[116:117], v[138:139], 1.0 op_sel_hi:[1,0]
	v_pk_add_f32 v[118:119], v[136:137], 1.0 op_sel_hi:[1,0]
	v_rcp_f32_e32 v146, v116
	v_pk_mul_f32 v[122:123], v[120:121], s[68:69] op_sel_hi:[1,0]
	v_pk_mul_f32 v[120:121], v[134:135], s[68:69] op_sel_hi:[1,0]
	v_rcp_f32_e32 v134, v118
	v_rcp_f32_e32 v147, v117
	v_rcp_f32_e32 v135, v119
	v_pk_mul_f32 v[116:117], v[124:125], v[128:129]
	v_pk_mul_f32 v[118:119], v[126:127], v[130:131]
	v_pk_fma_f32 v[124:125], v[140:141], v[146:147], v[22:23]
	v_pk_fma_f32 v[126:127], v[2:3], v[134:135], v[20:21]
	v_log_f32_e32 v124, v124
	v_log_f32_e32 v126, v126
	v_log_f32_e32 v125, v125
	v_log_f32_e32 v127, v127
	v_pk_mul_f32 v[128:129], v[144:145], v[118:119]
	v_pk_mul_f32 v[130:131], v[142:143], v[116:117]
	v_pk_mul_f32 v[118:119], v[124:125], s[68:69] op_sel_hi:[1,0]
	v_pk_mul_f32 v[116:117], v[126:127], s[68:69] op_sel_hi:[1,0]
	v_pk_mul_f32 v[124:125], v[136:137], v[134:135]
	v_pk_mul_f32 v[126:127], v[138:139], v[146:147]
	s_nop 0
	v_pk_mul_f32 v[134:135], v[140:141], v[126:127]
	v_pk_mul_f32 v[126:127], v[2:3], v[124:125]
	v_cvt_pk_bf16_f32 v124, v130, v131
	v_cvt_pk_bf16_f32 v125, v128, v129
	v_lshl_add_u64 v[128:129], s[30:31], 0, v[0:1]
	v_add_co_u32_e32 v128, vcc, 0x4400000, v128
	v_cvt_pk_bf16_f32 v126, v126, v127
	v_cvt_pk_bf16_f32 v127, v134, v135
	s_nop 1
	v_addc_co_u32_e32 v129, vcc, 0, v129, vcc
	global_store_dwordx4 v[128:129], v[124:127], off sc1
.LBB0_343:
	v_cvt_pk_bf16_f32 v120, v120, v121
	v_cvt_pk_bf16_f32 v121, v122, v123
	v_cvt_pk_bf16_f32 v122, v116, v117
	v_lshl_add_u64 v[116:117], s[30:31], 0, v[0:1]
	s_and_b64 vcc, exec, s[8:9]
	v_cvt_pk_bf16_f32 v123, v118, v119
	global_store_dwordx4 v[116:117], v[120:123], off sc1
	s_cbranch_vccnz .LBB0_347
	v_pk_mul_f32 v[116:117], v[114:115], s[96:97] op_sel_hi:[1,0]
	v_pk_mul_f32 v[118:119], v[112:113], s[96:97] op_sel_hi:[1,0]
	v_exp_f32_e32 v116, v116
	v_exp_f32_e32 v118, v118
	v_exp_f32_e32 v119, v119
	v_exp_f32_e32 v117, v117
	v_pk_add_f32 v[118:119], v[118:119], 1.0 op_sel_hi:[1,0]
	v_pk_add_f32 v[116:117], v[116:117], 1.0 op_sel_hi:[1,0]
	v_rcp_f32_e32 v118, v118
	v_rcp_f32_e32 v119, v119
	v_rcp_f32_e32 v116, v116
	v_rcp_f32_e32 v117, v117
	v_pk_mul_f32 v[112:113], v[112:113], v[118:119]
	v_pk_mul_f32 v[118:119], v[108:109], s[96:97] op_sel_hi:[1,0]
	v_pk_mul_f32 v[114:115], v[114:115], v[116:117]
	v_pk_mul_f32 v[116:117], v[110:111], s[96:97] op_sel_hi:[1,0]
	v_exp_f32_e32 v118, v118
	v_exp_f32_e32 v119, v119
	v_exp_f32_e32 v116, v116
	v_exp_f32_e32 v117, v117
	v_pk_add_f32 v[118:119], v[118:119], 1.0 op_sel_hi:[1,0]
	s_nop 0
	v_rcp_f32_e32 v118, v118
	v_pk_add_f32 v[116:117], v[116:117], 1.0 op_sel_hi:[1,0]
	v_rcp_f32_e32 v119, v119
	v_rcp_f32_e32 v116, v116
	v_rcp_f32_e32 v117, v117
	v_pk_mul_f32 v[108:109], v[108:109], v[118:119]
	v_pk_mul_f32 v[110:111], v[110:111], v[116:117]
	s_and_b64 vcc, exec, s[12:13]
	s_cbranch_vccz .LBB0_348

; __device__ __forceinline__ f32x4 silu4(f32x4 v) { return v * sigm4(v); }
; __device__ __forceinline__ u32x4 pack8(f32x4 v0, f32x4 v1) { u32x4 w; w.x = cvt_pk_bf16(v0[0], v0[1]); w.y = cvt_pk_bf16(v0[2], v0[3]); w.z = cvt_pk_bf16(v1[0], v1[1]); w.w = cvt_pk_bf16(v1[2], v1[3]); return w; }
; __device__ __forceinline__ void hg_gate4(f32x4& z, f32x4& key, const f32x4 l) {
;     const f32x4 zc = {__builtin_amdgcn_fmed3f(z[0], -80.f, 80.f), __builtin_amdgcn_fmed3f(z[1], -80.f, 80.f), __builtin_amdgcn_fmed3f(z[2], -80.f, 80.f), __builtin_amdgcn_fmed3f(z[3], -80.f, 80.f)};
;     const f32x4 t = zc * -1.4426950408889634f;
;     const f32x4 e = {__builtin_amdgcn_exp2f(t[0]), __builtin_amdgcn_exp2f(t[1]), __builtin_amdgcn_exp2f(t[2]), __builtin_amdgcn_exp2f(t[3])};
;     const f32x4 den = e + 1.0f;
;     const f32x4 sg = {__builtin_amdgcn_rcpf(den[0]), __builtin_amdgcn_rcpf(den[1]), __builtin_amdgcn_rcpf(den[2]), __builtin_amdgcn_rcpf(den[3])};
;     const f32x4 oml = 1.0f - l;
;     const f32x4 f = l + oml * sg;
;     z = (f32x4){__builtin_amdgcn_logf(f[0]), __builtin_amdgcn_logf(f[1]), __builtin_amdgcn_logf(f[2]), __builtin_amdgcn_logf(f[3])} * 0.6931471805599453f;
;     key = oml * (e * sg);
; }
;     __device__ __forceinline__ void operator()(const f32x4 (&acc)[2][2][4][2], const Unit& u, int wr, int wc, int fr_in, int fq_in) const {
;     ...
;         for (int ai = 0; ai < 2; ++ai)
; #pragma unroll
;             for (int m = 0; m < 4; ++m) {
;                 const int r = row0 + ai * HALF + m * 16;
;                 const size_t roff = (size_t)r * 2048 + cb;
; #pragma unroll
;                 for (int bj = 0; bj < 2; ++bj) {
;                     f32x4 v0 = acc[ai][bj][m][0], v1 = acc[ai][bj][m][1];
;                     if (type == 0) { v0 = silu4(v0); v1 = silu4(v1); }
;                     if (type == 4) { v0 = sigm4(v0); v1 = sigm4(v1); }
;                     if (type == 1 || type == 2) {
;                         f32x4 k0, k1;
;                         hg_gate4(v0, k0, lbv[bj][0]); hg_gate4(v1, k1, lbv[bj][1]);
;                         st16(base + tstride, roff + bj * HALF, pack8(k0, k1));
;                     }
;                     st16(base, roff + bj * HALF, pack8(v0, v1));
;                 }
.LBB0_349:
.LBB0_350:
	v_med3_f32 v112, v112, s95, v182
	v_med3_f32 v113, v113, s95, v182
	v_med3_f32 v114, v114, s95, v182
	v_med3_f32 v115, v115, s95, v182
	v_pk_mul_f32 v[114:115], v[114:115], s[96:97] op_sel_hi:[1,0]
	v_pk_mul_f32 v[112:113], v[112:113], s[96:97] op_sel_hi:[1,0]
	v_exp_f32_e32 v118, v114
	v_exp_f32_e32 v116, v112
	v_exp_f32_e32 v119, v115
	v_exp_f32_e32 v117, v113
	v_med3_f32 v108, v108, s95, v182
	v_med3_f32 v109, v109, s95, v182
	v_pk_add_f32 v[112:113], v[118:119], 1.0 op_sel_hi:[1,0]
	v_pk_add_f32 v[114:115], v[116:117], 1.0 op_sel_hi:[1,0]
	v_rcp_f32_e32 v122, v112
	v_rcp_f32_e32 v120, v114
	v_rcp_f32_e32 v123, v113
	v_rcp_f32_e32 v121, v115
	v_med3_f32 v110, v110, s95, v182
	v_med3_f32 v111, v111, s95, v182
	v_pk_mul_f32 v[110:111], v[110:111], s[96:97] op_sel_hi:[1,0]
	v_pk_mul_f32 v[108:109], v[108:109], s[96:97] op_sel_hi:[1,0]
	v_pk_fma_f32 v[112:113], v[154:155], v[122:123], v[50:51]
	v_pk_fma_f32 v[114:115], v[152:153], v[120:121], v[48:49]
	v_exp_f32_e32 v126, v108
	v_exp_f32_e32 v128, v110
	v_exp_f32_e32 v129, v111
	v_exp_f32_e32 v127, v109
	v_log_f32_e32 v124, v114
	v_log_f32_e32 v125, v115
	v_log_f32_e32 v112, v112
	v_log_f32_e32 v113, v113
	v_pk_add_f32 v[108:109], v[128:129], 1.0 op_sel_hi:[1,0]
	v_pk_add_f32 v[110:111], v[126:127], 1.0 op_sel_hi:[1,0]
	v_rcp_f32_e32 v130, v108
	v_pk_mul_f32 v[114:115], v[112:113], s[68:69] op_sel_hi:[1,0]
	v_pk_mul_f32 v[112:113], v[124:125], s[68:69] op_sel_hi:[1,0]
	v_rcp_f32_e32 v124, v110
	v_rcp_f32_e32 v131, v109
	v_rcp_f32_e32 v125, v111
	v_pk_mul_f32 v[108:109], v[116:117], v[120:121]
	v_pk_mul_f32 v[110:111], v[118:119], v[122:123]
	v_pk_fma_f32 v[116:117], v[150:151], v[130:131], v[38:39]
	v_pk_fma_f32 v[118:119], v[148:149], v[124:125], v[36:37]
	v_log_f32_e32 v116, v116
	v_log_f32_e32 v118, v118
	v_log_f32_e32 v117, v117
	v_log_f32_e32 v119, v119
	v_pk_mul_f32 v[120:121], v[154:155], v[110:111]
	v_pk_mul_f32 v[122:123], v[152:153], v[108:109]
	v_pk_mul_f32 v[110:111], v[116:117], s[68:69] op_sel_hi:[1,0]
	v_pk_mul_f32 v[108:109], v[118:119], s[68:69] op_sel_hi:[1,0]
	v_pk_mul_f32 v[116:117], v[126:127], v[124:125]
	v_pk_mul_f32 v[118:119], v[128:129], v[130:131]
	s_nop 0
	v_pk_mul_f32 v[124:125], v[150:151], v[118:119]
	v_pk_mul_f32 v[118:119], v[148:149], v[116:117]
	v_cvt_pk_bf16_f32 v116, v122, v123
	v_cvt_pk_bf16_f32 v117, v120, v121
	v_lshl_add_u64 v[120:121], s[30:31], 0, v[0:1]
	v_add_co_u32_e32 v120, vcc, 0x4400000, v120
	v_cvt_pk_bf16_f32 v118, v118, v119
	v_cvt_pk_bf16_f32 v119, v124, v125
	s_nop 1
	v_addc_co_u32_e32 v121, vcc, 0, v121, vcc
	global_store_dwordx4 v[120:121], v[116:119], off sc1
.LBB0_351:
	v_cvt_pk_bf16_f32 v112, v112, v113
	v_cvt_pk_bf16_f32 v113, v114, v115
	v_cvt_pk_bf16_f32 v114, v108, v109
	v_lshl_add_u64 v[108:109], s[30:31], 0, v[0:1]
	s_and_b64 vcc, exec, s[8:9]
	v_cvt_pk_bf16_f32 v115, v110, v111
	global_store_dwordx4 v[108:109], v[112:115], off sc1
	s_cbranch_vccnz .LBB0_355
	v_pk_mul_f32 v[108:109], v[106:107], s[96:97] op_sel_hi:[1,0]
	v_pk_mul_f32 v[110:111], v[104:105], s[96:97] op_sel_hi:[1,0]
	v_exp_f32_e32 v108, v108
	v_exp_f32_e32 v110, v110
	v_exp_f32_e32 v111, v111
	v_exp_f32_e32 v109, v109
	v_pk_add_f32 v[110:111], v[110:111], 1.0 op_sel_hi:[1,0]
	v_pk_add_f32 v[108:109], v[108:109], 1.0 op_sel_hi:[1,0]
	v_rcp_f32_e32 v110, v110
	v_rcp_f32_e32 v111, v111
	v_rcp_f32_e32 v108, v108
	v_rcp_f32_e32 v109, v109
	v_pk_mul_f32 v[104:105], v[104:105], v[110:111]
	v_pk_mul_f32 v[110:111], v[100:101], s[96:97] op_sel_hi:[1,0]
	v_pk_mul_f32 v[106:107], v[106:107], v[108:109]
	v_pk_mul_f32 v[108:109], v[102:103], s[96:97] op_sel_hi:[1,0]
	v_exp_f32_e32 v110, v110
	v_exp_f32_e32 v111, v111
	v_exp_f32_e32 v108, v108
	v_exp_f32_e32 v109, v109
	v_pk_add_f32 v[110:111], v[110:111], 1.0 op_sel_hi:[1,0]
	s_nop 0
	v_rcp_f32_e32 v110, v110
	v_pk_add_f32 v[108:109], v[108:109], 1.0 op_sel_hi:[1,0]
	v_rcp_f32_e32 v111, v111
	v_rcp_f32_e32 v108, v108
	v_rcp_f32_e32 v109, v109
	v_pk_mul_f32 v[100:101], v[100:101], v[110:111]
	v_pk_mul_f32 v[102:103], v[102:103], v[108:109]
	s_and_b64 vcc, exec, s[12:13]
	s_cbranch_vccz .LBB0_356

; __device__ __forceinline__ f32x4 silu4(f32x4 v) { return v * sigm4(v); }
; __device__ __forceinline__ u32x4 pack8(f32x4 v0, f32x4 v1) { u32x4 w; w.x = cvt_pk_bf16(v0[0], v0[1]); w.y = cvt_pk_bf16(v0[2], v0[3]); w.z = cvt_pk_bf16(v1[0], v1[1]); w.w = cvt_pk_bf16(v1[2], v1[3]); return w; }
; __device__ __forceinline__ void hg_gate4(f32x4& z, f32x4& key, const f32x4 l) {
;     const f32x4 zc = {__builtin_amdgcn_fmed3f(z[0], -80.f, 80.f), __builtin_amdgcn_fmed3f(z[1], -80.f, 80.f), __builtin_amdgcn_fmed3f(z[2], -80.f, 80.f), __builtin_amdgcn_fmed3f(z[3], -80.f, 80.f)};
;     const f32x4 t = zc * -1.4426950408889634f;
;     const f32x4 e = {__builtin_amdgcn_exp2f(t[0]), __builtin_amdgcn_exp2f(t[1]), __builtin_amdgcn_exp2f(t[2]), __builtin_amdgcn_exp2f(t[3])};
;     const f32x4 den = e + 1.0f;
;     const f32x4 sg = {__builtin_amdgcn_rcpf(den[0]), __builtin_amdgcn_rcpf(den[1]), __builtin_amdgcn_rcpf(den[2]), __builtin_amdgcn_rcpf(den[3])};
;     const f32x4 oml = 1.0f - l;
;     const f32x4 f = l + oml * sg;
;     z = (f32x4){__builtin_amdgcn_logf(f[0]), __builtin_amdgcn_logf(f[1]), __builtin_amdgcn_logf(f[2]), __builtin_amdgcn_logf(f[3])} * 0.6931471805599453f;
;     key = oml * (e * sg);
; }
;     __device__ __forceinline__ void operator()(const f32x4 (&acc)[2][2][4][2], const Unit& u, int wr, int wc, int fr_in, int fq_in) const {
;     ...
;         for (int ai = 0; ai < 2; ++ai)
; #pragma unroll
;             for (int m = 0; m < 4; ++m) {
;                 const int r = row0 + ai * HALF + m * 16;
;                 const size_t roff = (size_t)r * 2048 + cb;
; #pragma unroll
;                 for (int bj = 0; bj < 2; ++bj) {
;                     f32x4 v0 = acc[ai][bj][m][0], v1 = acc[ai][bj][m][1];
;                     if (type == 0) { v0 = silu4(v0); v1 = silu4(v1); }
;                     if (type == 4) { v0 = sigm4(v0); v1 = sigm4(v1); }
;                     if (type == 1 || type == 2) {
;                         f32x4 k0, k1;
;                         hg_gate4(v0, k0, lbv[bj][0]); hg_gate4(v1, k1, lbv[bj][1]);
;                         st16(base + tstride, roff + bj * HALF, pack8(k0, k1));
;                     }
;                     st16(base, roff + bj * HALF, pack8(v0, v1));
;                 }
.LBB0_358:
	v_med3_f32 v104, v104, s95, v182
	v_med3_f32 v105, v105, s95, v182
	v_med3_f32 v106, v106, s95, v182
	v_med3_f32 v107, v107, s95, v182
	v_pk_mul_f32 v[106:107], v[106:107], s[96:97] op_sel_hi:[1,0]
	v_pk_mul_f32 v[104:105], v[104:105], s[96:97] op_sel_hi:[1,0]
	v_exp_f32_e32 v110, v106
	v_exp_f32_e32 v108, v104
	v_exp_f32_e32 v111, v107
	v_exp_f32_e32 v109, v105
	v_med3_f32 v100, v100, s95, v182
	v_med3_f32 v101, v101, s95, v182
	v_pk_add_f32 v[104:105], v[110:111], 1.0 op_sel_hi:[1,0]
	v_pk_add_f32 v[106:107], v[108:109], 1.0 op_sel_hi:[1,0]
	v_rcp_f32_e32 v114, v104
	v_rcp_f32_e32 v112, v106
	v_rcp_f32_e32 v115, v105
	v_rcp_f32_e32 v113, v107
	v_med3_f32 v102, v102, s95, v182
	v_med3_f32 v103, v103, s95, v182
	v_pk_mul_f32 v[102:103], v[102:103], s[96:97] op_sel_hi:[1,0]
	v_pk_mul_f32 v[100:101], v[100:101], s[96:97] op_sel_hi:[1,0]
	v_pk_fma_f32 v[104:105], v[144:145], v[114:115], v[26:27]
	v_pk_fma_f32 v[106:107], v[142:143], v[112:113], v[24:25]
	v_exp_f32_e32 v118, v100
	v_exp_f32_e32 v120, v102
	v_exp_f32_e32 v121, v103
	v_exp_f32_e32 v119, v101
	v_log_f32_e32 v116, v106
	v_log_f32_e32 v117, v107
	v_log_f32_e32 v104, v104
	v_log_f32_e32 v105, v105
	v_pk_add_f32 v[100:101], v[120:121], 1.0 op_sel_hi:[1,0]
	v_pk_add_f32 v[102:103], v[118:119], 1.0 op_sel_hi:[1,0]
	v_rcp_f32_e32 v122, v100
	v_pk_mul_f32 v[106:107], v[104:105], s[68:69] op_sel_hi:[1,0]
	v_pk_mul_f32 v[104:105], v[116:117], s[68:69] op_sel_hi:[1,0]
	v_rcp_f32_e32 v116, v102
	v_rcp_f32_e32 v123, v101
	v_rcp_f32_e32 v117, v103
	v_pk_mul_f32 v[100:101], v[108:109], v[112:113]
	v_pk_mul_f32 v[102:103], v[110:111], v[114:115]
	v_pk_fma_f32 v[108:109], v[140:141], v[122:123], v[22:23]
	v_pk_fma_f32 v[110:111], v[2:3], v[116:117], v[20:21]
	v_log_f32_e32 v108, v108
	v_log_f32_e32 v110, v110
	v_log_f32_e32 v109, v109
	v_log_f32_e32 v111, v111
	v_pk_mul_f32 v[112:113], v[144:145], v[102:103]
	v_pk_mul_f32 v[114:115], v[142:143], v[100:101]
	v_pk_mul_f32 v[102:103], v[108:109], s[68:69] op_sel_hi:[1,0]
	v_pk_mul_f32 v[100:101], v[110:111], s[68:69] op_sel_hi:[1,0]
	v_pk_mul_f32 v[108:109], v[118:119], v[116:117]
	v_pk_mul_f32 v[110:111], v[120:121], v[122:123]
	s_nop 0
	v_pk_mul_f32 v[116:117], v[140:141], v[110:111]
	v_pk_mul_f32 v[110:111], v[2:3], v[108:109]
	v_cvt_pk_bf16_f32 v108, v114, v115
	v_cvt_pk_bf16_f32 v109, v112, v113
	v_lshl_add_u64 v[112:113], s[30:31], 0, v[0:1]
	v_add_co_u32_e32 v112, vcc, 0x4400000, v112
	v_cvt_pk_bf16_f32 v110, v110, v111
	v_cvt_pk_bf16_f32 v111, v116, v117
	s_nop 1
	v_addc_co_u32_e32 v113, vcc, 0, v113, vcc
	global_store_dwordx4 v[112:113], v[108:111], off sc1
.LBB0_359:
	v_cvt_pk_bf16_f32 v104, v104, v105
	v_cvt_pk_bf16_f32 v105, v106, v107
	v_cvt_pk_bf16_f32 v106, v100, v101
	v_lshl_add_u64 v[100:101], s[30:31], 0, v[0:1]
	s_and_b64 vcc, exec, s[8:9]
	v_cvt_pk_bf16_f32 v107, v102, v103
	global_store_dwordx4 v[100:101], v[104:107], off sc1
	s_cbranch_vccnz .LBB0_363
	v_pk_mul_f32 v[100:101], v[98:99], s[96:97] op_sel_hi:[1,0]
	v_pk_mul_f32 v[102:103], v[96:97], s[96:97] op_sel_hi:[1,0]
	v_exp_f32_e32 v100, v100
	v_exp_f32_e32 v102, v102
	v_exp_f32_e32 v103, v103
	v_exp_f32_e32 v101, v101
	v_pk_add_f32 v[102:103], v[102:103], 1.0 op_sel_hi:[1,0]
	v_pk_add_f32 v[100:101], v[100:101], 1.0 op_sel_hi:[1,0]
	v_rcp_f32_e32 v102, v102
	v_rcp_f32_e32 v103, v103
	v_rcp_f32_e32 v100, v100
	v_rcp_f32_e32 v101, v101
	v_pk_mul_f32 v[96:97], v[96:97], v[102:103]
	v_pk_mul_f32 v[102:103], v[92:93], s[96:97] op_sel_hi:[1,0]
	v_pk_mul_f32 v[98:99], v[98:99], v[100:101]
	v_pk_mul_f32 v[100:101], v[94:95], s[96:97] op_sel_hi:[1,0]
	v_exp_f32_e32 v102, v102
	v_exp_f32_e32 v103, v103
	v_exp_f32_e32 v100, v100
	v_exp_f32_e32 v101, v101
	v_pk_add_f32 v[102:103], v[102:103], 1.0 op_sel_hi:[1,0]
	s_nop 0
	v_rcp_f32_e32 v102, v102
	v_pk_add_f32 v[100:101], v[100:101], 1.0 op_sel_hi:[1,0]
	v_rcp_f32_e32 v103, v103
	v_rcp_f32_e32 v100, v100
	v_rcp_f32_e32 v101, v101
	v_pk_mul_f32 v[92:93], v[92:93], v[102:103]
	v_pk_mul_f32 v[94:95], v[94:95], v[100:101]
	s_and_b64 vcc, exec, s[12:13]
	s_cbranch_vccz .LBB0_364

; __device__ __forceinline__ f32x4 silu4(f32x4 v) { return v * sigm4(v); }
; __device__ __forceinline__ u32x4 pack8(f32x4 v0, f32x4 v1) { u32x4 w; w.x = cvt_pk_bf16(v0[0], v0[1]); w.y = cvt_pk_bf16(v0[2], v0[3]); w.z = cvt_pk_bf16(v1[0], v1[1]); w.w = cvt_pk_bf16(v1[2], v1[3]); return w; }
; __device__ __forceinline__ void hg_gate4(f32x4& z, f32x4& key, const f32x4 l) {
;     const f32x4 zc = {__builtin_amdgcn_fmed3f(z[0], -80.f, 80.f), __builtin_amdgcn_fmed3f(z[1], -80.f, 80.f), __builtin_amdgcn_fmed3f(z[2], -80.f, 80.f), __builtin_amdgcn_fmed3f(z[3], -80.f, 80.f)};
;     const f32x4 t = zc * -1.4426950408889634f;
;     const f32x4 e = {__builtin_amdgcn_exp2f(t[0]), __builtin_amdgcn_exp2f(t[1]), __builtin_amdgcn_exp2f(t[2]), __builtin_amdgcn_exp2f(t[3])};
;     const f32x4 den = e + 1.0f;
;     const f32x4 sg = {__builtin_amdgcn_rcpf(den[0]), __builtin_amdgcn_rcpf(den[1]), __builtin_amdgcn_rcpf(den[2]), __builtin_amdgcn_rcpf(den[3])};
;     const f32x4 oml = 1.0f - l;
;     const f32x4 f = l + oml * sg;
;     z = (f32x4){__builtin_amdgcn_logf(f[0]), __builtin_amdgcn_logf(f[1]), __builtin_amdgcn_logf(f[2]), __builtin_amdgcn_logf(f[3])} * 0.6931471805599453f;
;     key = oml * (e * sg);
; }
;     __device__ __forceinline__ void operator()(const f32x4 (&acc)[2][2][4][2], const Unit& u, int wr, int wc, int fr_in, int fq_in) const {
;     ...
;         for (int ai = 0; ai < 2; ++ai)
; #pragma unroll
;             for (int m = 0; m < 4; ++m) {
;                 const int r = row0 + ai * HALF + m * 16;
;                 const size_t roff = (size_t)r * 2048 + cb;
; #pragma unroll
;                 for (int bj = 0; bj < 2; ++bj) {
;                     f32x4 v0 = acc[ai][bj][m][0], v1 = acc[ai][bj][m][1];
;                     if (type == 0) { v0 = silu4(v0); v1 = silu4(v1); }
;                     if (type == 4) { v0 = sigm4(v0); v1 = sigm4(v1); }
;                     if (type == 1 || type == 2) {
;                         f32x4 k0, k1;
;                         hg_gate4(v0, k0, lbv[bj][0]); hg_gate4(v1, k1, lbv[bj][1]);
;                         st16(base + tstride, roff + bj * HALF, pack8(k0, k1));
;                     }
;                     st16(base, roff + bj * HALF, pack8(v0, v1));
;                 }
.LBB0_365:
.LBB0_366:
	v_med3_f32 v96, v96, s95, v182
	v_med3_f32 v97, v97, s95, v182
	v_med3_f32 v98, v98, s95, v182
	v_med3_f32 v99, v99, s95, v182
	v_pk_mul_f32 v[98:99], v[98:99], s[96:97] op_sel_hi:[1,0]
	v_pk_mul_f32 v[96:97], v[96:97], s[96:97] op_sel_hi:[1,0]
	v_exp_f32_e32 v102, v98
	v_exp_f32_e32 v100, v96
	v_exp_f32_e32 v103, v99
	v_exp_f32_e32 v101, v97
	v_med3_f32 v92, v92, s95, v182
	v_med3_f32 v93, v93, s95, v182
	v_pk_add_f32 v[96:97], v[102:103], 1.0 op_sel_hi:[1,0]
	v_pk_add_f32 v[98:99], v[100:101], 1.0 op_sel_hi:[1,0]
	v_rcp_f32_e32 v106, v96
	v_rcp_f32_e32 v104, v98
	v_rcp_f32_e32 v107, v97
	v_rcp_f32_e32 v105, v99
	v_med3_f32 v94, v94, s95, v182
	v_med3_f32 v95, v95, s95, v182
	v_pk_mul_f32 v[94:95], v[94:95], s[96:97] op_sel_hi:[1,0]
	v_pk_mul_f32 v[92:93], v[92:93], s[96:97] op_sel_hi:[1,0]
	v_pk_fma_f32 v[96:97], v[154:155], v[106:107], v[50:51]
	v_pk_fma_f32 v[98:99], v[152:153], v[104:105], v[48:49]
	v_exp_f32_e32 v110, v92
	v_exp_f32_e32 v112, v94
	v_exp_f32_e32 v113, v95
	v_exp_f32_e32 v111, v93
	v_log_f32_e32 v108, v98
	v_log_f32_e32 v109, v99
	v_log_f32_e32 v96, v96
	v_log_f32_e32 v97, v97
	v_pk_add_f32 v[92:93], v[112:113], 1.0 op_sel_hi:[1,0]
	v_pk_add_f32 v[94:95], v[110:111], 1.0 op_sel_hi:[1,0]
	v_rcp_f32_e32 v114, v92
	v_pk_mul_f32 v[98:99], v[96:97], s[68:69] op_sel_hi:[1,0]
	v_pk_mul_f32 v[96:97], v[108:109], s[68:69] op_sel_hi:[1,0]
	v_rcp_f32_e32 v108, v94
	v_rcp_f32_e32 v115, v93
	v_rcp_f32_e32 v109, v95
	v_pk_mul_f32 v[92:93], v[100:101], v[104:105]
	v_pk_mul_f32 v[94:95], v[102:103], v[106:107]
	v_pk_fma_f32 v[100:101], v[150:151], v[114:115], v[38:39]
	v_pk_fma_f32 v[102:103], v[148:149], v[108:109], v[36:37]
	v_log_f32_e32 v100, v100
	v_log_f32_e32 v102, v102
	v_log_f32_e32 v101, v101
	v_log_f32_e32 v103, v103
	v_pk_mul_f32 v[104:105], v[154:155], v[94:95]
	v_pk_mul_f32 v[106:107], v[152:153], v[92:93]
	v_pk_mul_f32 v[94:95], v[100:101], s[68:69] op_sel_hi:[1,0]
	v_pk_mul_f32 v[92:93], v[102:103], s[68:69] op_sel_hi:[1,0]
	v_pk_mul_f32 v[100:101], v[110:111], v[108:109]
	v_pk_mul_f32 v[102:103], v[112:113], v[114:115]
	s_nop 0
	v_pk_mul_f32 v[108:109], v[150:151], v[102:103]
	v_pk_mul_f32 v[102:103], v[148:149], v[100:101]
	v_cvt_pk_bf16_f32 v100, v106, v107
	v_cvt_pk_bf16_f32 v101, v104, v105
	v_lshl_add_u64 v[104:105], s[30:31], 0, v[0:1]
	v_add_co_u32_e32 v104, vcc, 0x4400000, v104
	v_cvt_pk_bf16_f32 v102, v102, v103
	v_cvt_pk_bf16_f32 v103, v108, v109
	s_nop 1
	v_addc_co_u32_e32 v105, vcc, 0, v105, vcc
	global_store_dwordx4 v[104:105], v[100:103], off sc1
.LBB0_367:
	v_cvt_pk_bf16_f32 v96, v96, v97
	v_cvt_pk_bf16_f32 v97, v98, v99
	v_cvt_pk_bf16_f32 v98, v92, v93
	v_lshl_add_u64 v[92:93], s[30:31], 0, v[0:1]
	s_and_b64 vcc, exec, s[8:9]
	v_cvt_pk_bf16_f32 v99, v94, v95
	global_store_dwordx4 v[92:93], v[96:99], off sc1
	s_cbranch_vccnz .LBB0_371
	v_pk_mul_f32 v[92:93], v[90:91], s[96:97] op_sel_hi:[1,0]
	v_pk_mul_f32 v[94:95], v[88:89], s[96:97] op_sel_hi:[1,0]
	v_exp_f32_e32 v92, v92
	v_exp_f32_e32 v94, v94
	v_exp_f32_e32 v95, v95
	v_exp_f32_e32 v93, v93
	v_pk_add_f32 v[94:95], v[94:95], 1.0 op_sel_hi:[1,0]
	v_pk_add_f32 v[92:93], v[92:93], 1.0 op_sel_hi:[1,0]
	v_rcp_f32_e32 v94, v94
	v_rcp_f32_e32 v95, v95
	v_rcp_f32_e32 v92, v92
	v_rcp_f32_e32 v93, v93
	v_pk_mul_f32 v[88:89], v[88:89], v[94:95]
	v_pk_mul_f32 v[94:95], v[84:85], s[96:97] op_sel_hi:[1,0]
	v_pk_mul_f32 v[90:91], v[90:91], v[92:93]
	v_pk_mul_f32 v[92:93], v[86:87], s[96:97] op_sel_hi:[1,0]
	v_exp_f32_e32 v94, v94
	v_exp_f32_e32 v95, v95
	v_exp_f32_e32 v92, v92
	v_exp_f32_e32 v93, v93
	v_pk_add_f32 v[94:95], v[94:95], 1.0 op_sel_hi:[1,0]
	s_nop 0
	v_rcp_f32_e32 v94, v94
	v_pk_add_f32 v[92:93], v[92:93], 1.0 op_sel_hi:[1,0]
	v_rcp_f32_e32 v95, v95
	v_rcp_f32_e32 v92, v92
	v_rcp_f32_e32 v93, v93
	v_pk_mul_f32 v[84:85], v[84:85], v[94:95]
	v_pk_mul_f32 v[86:87], v[86:87], v[92:93]
	s_and_b64 vcc, exec, s[12:13]
	s_cbranch_vccz .LBB0_372

; __device__ __forceinline__ f32x4 silu4(f32x4 v) { return v * sigm4(v); }
; __device__ __forceinline__ u32x4 pack8(f32x4 v0, f32x4 v1) { u32x4 w; w.x = cvt_pk_bf16(v0[0], v0[1]); w.y = cvt_pk_bf16(v0[2], v0[3]); w.z = cvt_pk_bf16(v1[0], v1[1]); w.w = cvt_pk_bf16(v1[2], v1[3]); return w; }
; __device__ __forceinline__ void hg_gate4(f32x4& z, f32x4& key, const f32x4 l) {
;     const f32x4 zc = {__builtin_amdgcn_fmed3f(z[0], -80.f, 80.f), __builtin_amdgcn_fmed3f(z[1], -80.f, 80.f), __builtin_amdgcn_fmed3f(z[2], -80.f, 80.f), __builtin_amdgcn_fmed3f(z[3], -80.f, 80.f)};
;     const f32x4 t = zc * -1.4426950408889634f;
;     const f32x4 e = {__builtin_amdgcn_exp2f(t[0]), __builtin_amdgcn_exp2f(t[1]), __builtin_amdgcn_exp2f(t[2]), __builtin_amdgcn_exp2f(t[3])};
;     const f32x4 den = e + 1.0f;
;     const f32x4 sg = {__builtin_amdgcn_rcpf(den[0]), __builtin_amdgcn_rcpf(den[1]), __builtin_amdgcn_rcpf(den[2]), __builtin_amdgcn_rcpf(den[3])};
;     const f32x4 oml = 1.0f - l;
;     const f32x4 f = l + oml * sg;
;     z = (f32x4){__builtin_amdgcn_logf(f[0]), __builtin_amdgcn_logf(f[1]), __builtin_amdgcn_logf(f[2]), __builtin_amdgcn_logf(f[3])} * 0.6931471805599453f;
;     key = oml * (e * sg);
; }
;     __device__ __forceinline__ void operator()(const f32x4 (&acc)[2][2][4][2], const Unit& u, int wr, int wc, int fr_in, int fq_in) const {
;     ...
;         for (int ai = 0; ai < 2; ++ai)
; #pragma unroll
;             for (int m = 0; m < 4; ++m) {
;                 const int r = row0 + ai * HALF + m * 16;
;                 const size_t roff = (size_t)r * 2048 + cb;
; #pragma unroll
;                 for (int bj = 0; bj < 2; ++bj) {
;                     f32x4 v0 = acc[ai][bj][m][0], v1 = acc[ai][bj][m][1];
;                     if (type == 0) { v0 = silu4(v0); v1 = silu4(v1); }
;                     if (type == 4) { v0 = sigm4(v0); v1 = sigm4(v1); }
;                     if (type == 1 || type == 2) {
;                         f32x4 k0, k1;
;                         hg_gate4(v0, k0, lbv[bj][0]); hg_gate4(v1, k1, lbv[bj][1]);
;                         st16(base + tstride, roff + bj * HALF, pack8(k0, k1));
;                     }
;                     st16(base, roff + bj * HALF, pack8(v0, v1));
;                 }
.LBB0_374:
	v_med3_f32 v88, v88, s95, v182
	v_med3_f32 v89, v89, s95, v182
	v_med3_f32 v90, v90, s95, v182
	v_med3_f32 v91, v91, s95, v182
	v_pk_mul_f32 v[90:91], v[90:91], s[96:97] op_sel_hi:[1,0]
	v_pk_mul_f32 v[88:89], v[88:89], s[96:97] op_sel_hi:[1,0]
	v_exp_f32_e32 v94, v90
	v_exp_f32_e32 v92, v88
	v_exp_f32_e32 v95, v91
	v_exp_f32_e32 v93, v89
	v_med3_f32 v84, v84, s95, v182
	v_med3_f32 v85, v85, s95, v182
	v_pk_add_f32 v[88:89], v[94:95], 1.0 op_sel_hi:[1,0]
	v_pk_add_f32 v[90:91], v[92:93], 1.0 op_sel_hi:[1,0]
	v_rcp_f32_e32 v98, v88
	v_rcp_f32_e32 v96, v90
	v_rcp_f32_e32 v99, v89
	v_rcp_f32_e32 v97, v91
	v_med3_f32 v86, v86, s95, v182
	v_med3_f32 v87, v87, s95, v182
	v_pk_mul_f32 v[86:87], v[86:87], s[96:97] op_sel_hi:[1,0]
	v_pk_mul_f32 v[84:85], v[84:85], s[96:97] op_sel_hi:[1,0]
	v_pk_fma_f32 v[88:89], v[144:145], v[98:99], v[26:27]
	v_pk_fma_f32 v[90:91], v[142:143], v[96:97], v[24:25]
	v_exp_f32_e32 v102, v84
	v_exp_f32_e32 v104, v86
	v_exp_f32_e32 v105, v87
	v_exp_f32_e32 v103, v85
	v_log_f32_e32 v100, v90
	v_log_f32_e32 v101, v91
	v_log_f32_e32 v88, v88
	v_log_f32_e32 v89, v89
	v_pk_add_f32 v[84:85], v[104:105], 1.0 op_sel_hi:[1,0]
	v_pk_add_f32 v[86:87], v[102:103], 1.0 op_sel_hi:[1,0]
	v_rcp_f32_e32 v106, v84
	v_pk_mul_f32 v[90:91], v[88:89], s[68:69] op_sel_hi:[1,0]
	v_pk_mul_f32 v[88:89], v[100:101], s[68:69] op_sel_hi:[1,0]
	v_rcp_f32_e32 v100, v86
	v_rcp_f32_e32 v107, v85
	v_rcp_f32_e32 v101, v87
	v_pk_mul_f32 v[84:85], v[92:93], v[96:97]
	v_pk_mul_f32 v[86:87], v[94:95], v[98:99]
	v_pk_fma_f32 v[92:93], v[140:141], v[106:107], v[22:23]
	v_pk_fma_f32 v[94:95], v[2:3], v[100:101], v[20:21]
	v_log_f32_e32 v92, v92
	v_log_f32_e32 v94, v94
	v_log_f32_e32 v93, v93
	v_log_f32_e32 v95, v95
	v_pk_mul_f32 v[96:97], v[144:145], v[86:87]
	v_pk_mul_f32 v[98:99], v[142:143], v[84:85]
	v_pk_mul_f32 v[86:87], v[92:93], s[68:69] op_sel_hi:[1,0]
	v_pk_mul_f32 v[84:85], v[94:95], s[68:69] op_sel_hi:[1,0]
	v_pk_mul_f32 v[92:93], v[102:103], v[100:101]
	v_pk_mul_f32 v[94:95], v[104:105], v[106:107]
	s_nop 0
	v_pk_mul_f32 v[100:101], v[140:141], v[94:95]
	v_pk_mul_f32 v[94:95], v[2:3], v[92:93]
	v_cvt_pk_bf16_f32 v92, v98, v99
	v_cvt_pk_bf16_f32 v93, v96, v97
	v_lshl_add_u64 v[96:97], s[30:31], 0, v[0:1]
	v_add_co_u32_e32 v96, vcc, 0x4400000, v96
	v_cvt_pk_bf16_f32 v94, v94, v95
	v_cvt_pk_bf16_f32 v95, v100, v101
	s_nop 1
	v_addc_co_u32_e32 v97, vcc, 0, v97, vcc
	global_store_dwordx4 v[96:97], v[92:95], off sc1
.LBB0_375:
	v_cvt_pk_bf16_f32 v88, v88, v89
	v_cvt_pk_bf16_f32 v89, v90, v91
	v_cvt_pk_bf16_f32 v90, v84, v85
	v_lshl_add_u64 v[84:85], s[30:31], 0, v[0:1]
	s_and_b64 vcc, exec, s[8:9]
	v_cvt_pk_bf16_f32 v91, v86, v87
	global_store_dwordx4 v[84:85], v[88:91], off sc1
	s_cbranch_vccnz .LBB0_379
	v_pk_mul_f32 v[84:85], v[82:83], s[96:97] op_sel_hi:[1,0]
	v_pk_mul_f32 v[86:87], v[80:81], s[96:97] op_sel_hi:[1,0]
	v_exp_f32_e32 v84, v84
	v_exp_f32_e32 v86, v86
	v_exp_f32_e32 v87, v87
	v_exp_f32_e32 v85, v85
	v_pk_add_f32 v[86:87], v[86:87], 1.0 op_sel_hi:[1,0]
	v_pk_add_f32 v[84:85], v[84:85], 1.0 op_sel_hi:[1,0]
	v_rcp_f32_e32 v86, v86
	v_rcp_f32_e32 v87, v87
	v_rcp_f32_e32 v84, v84
	v_rcp_f32_e32 v85, v85
	v_pk_mul_f32 v[80:81], v[80:81], v[86:87]
	v_pk_mul_f32 v[86:87], v[76:77], s[96:97] op_sel_hi:[1,0]
	v_pk_mul_f32 v[82:83], v[82:83], v[84:85]
	v_pk_mul_f32 v[84:85], v[78:79], s[96:97] op_sel_hi:[1,0]
	v_exp_f32_e32 v86, v86
	v_exp_f32_e32 v87, v87
	v_exp_f32_e32 v84, v84
	v_exp_f32_e32 v85, v85
	v_pk_add_f32 v[86:87], v[86:87], 1.0 op_sel_hi:[1,0]
	s_nop 0
	v_rcp_f32_e32 v86, v86
	v_pk_add_f32 v[84:85], v[84:85], 1.0 op_sel_hi:[1,0]
	v_rcp_f32_e32 v87, v87
	v_rcp_f32_e32 v84, v84
	v_rcp_f32_e32 v85, v85
	v_pk_mul_f32 v[76:77], v[76:77], v[86:87]
	v_pk_mul_f32 v[78:79], v[78:79], v[84:85]
	s_and_b64 vcc, exec, s[12:13]
	s_cbranch_vccz .LBB0_380

; __device__ __forceinline__ f32x4 silu4(f32x4 v) { return v * sigm4(v); }
; __device__ __forceinline__ u32x4 pack8(f32x4 v0, f32x4 v1) { u32x4 w; w.x = cvt_pk_bf16(v0[0], v0[1]); w.y = cvt_pk_bf16(v0[2], v0[3]); w.z = cvt_pk_bf16(v1[0], v1[1]); w.w = cvt_pk_bf16(v1[2], v1[3]); return w; }
; __device__ __forceinline__ void hg_gate4(f32x4& z, f32x4& key, const f32x4 l) {
;     const f32x4 zc = {__builtin_amdgcn_fmed3f(z[0], -80.f, 80.f), __builtin_amdgcn_fmed3f(z[1], -80.f, 80.f), __builtin_amdgcn_fmed3f(z[2], -80.f, 80.f), __builtin_amdgcn_fmed3f(z[3], -80.f, 80.f)};
;     const f32x4 t = zc * -1.4426950408889634f;
;     const f32x4 e = {__builtin_amdgcn_exp2f(t[0]), __builtin_amdgcn_exp2f(t[1]), __builtin_amdgcn_exp2f(t[2]), __builtin_amdgcn_exp2f(t[3])};
;     const f32x4 den = e + 1.0f;
;     const f32x4 sg = {__builtin_amdgcn_rcpf(den[0]), __builtin_amdgcn_rcpf(den[1]), __builtin_amdgcn_rcpf(den[2]), __builtin_amdgcn_rcpf(den[3])};
;     const f32x4 oml = 1.0f - l;
;     const f32x4 f = l + oml * sg;
;     z = (f32x4){__builtin_amdgcn_logf(f[0]), __builtin_amdgcn_logf(f[1]), __builtin_amdgcn_logf(f[2]), __builtin_amdgcn_logf(f[3])} * 0.6931471805599453f;
;     key = oml * (e * sg);
; }
;     __device__ __forceinline__ void operator()(const f32x4 (&acc)[2][2][4][2], const Unit& u, int wr, int wc, int fr_in, int fq_in) const {
;     ...
;         for (int ai = 0; ai < 2; ++ai)
; #pragma unroll
;             for (int m = 0; m < 4; ++m) {
;                 const int r = row0 + ai * HALF + m * 16;
;                 const size_t roff = (size_t)r * 2048 + cb;
; #pragma unroll
;                 for (int bj = 0; bj < 2; ++bj) {
;                     f32x4 v0 = acc[ai][bj][m][0], v1 = acc[ai][bj][m][1];
;                     if (type == 0) { v0 = silu4(v0); v1 = silu4(v1); }
;                     if (type == 4) { v0 = sigm4(v0); v1 = sigm4(v1); }
;                     if (type == 1 || type == 2) {
;                         f32x4 k0, k1;
;                         hg_gate4(v0, k0, lbv[bj][0]); hg_gate4(v1, k1, lbv[bj][1]);
;                         st16(base + tstride, roff + bj * HALF, pack8(k0, k1));
;                     }
;                     st16(base, roff + bj * HALF, pack8(v0, v1));
;                 }
.LBB0_381:
.LBB0_382:
	v_med3_f32 v80, v80, s95, v182
	v_med3_f32 v81, v81, s95, v182
	v_med3_f32 v82, v82, s95, v182
	v_med3_f32 v83, v83, s95, v182
	v_pk_mul_f32 v[82:83], v[82:83], s[96:97] op_sel_hi:[1,0]
	v_pk_mul_f32 v[80:81], v[80:81], s[96:97] op_sel_hi:[1,0]
	v_exp_f32_e32 v86, v82
	v_exp_f32_e32 v84, v80
	v_exp_f32_e32 v87, v83
	v_exp_f32_e32 v85, v81
	v_med3_f32 v76, v76, s95, v182
	v_med3_f32 v77, v77, s95, v182
	v_pk_add_f32 v[80:81], v[86:87], 1.0 op_sel_hi:[1,0]
	v_pk_add_f32 v[82:83], v[84:85], 1.0 op_sel_hi:[1,0]
	v_rcp_f32_e32 v90, v80
	v_rcp_f32_e32 v88, v82
	v_rcp_f32_e32 v91, v81
	v_rcp_f32_e32 v89, v83
	v_med3_f32 v78, v78, s95, v182
	v_med3_f32 v79, v79, s95, v182
	v_pk_mul_f32 v[78:79], v[78:79], s[96:97] op_sel_hi:[1,0]
	v_pk_mul_f32 v[76:77], v[76:77], s[96:97] op_sel_hi:[1,0]
	v_pk_fma_f32 v[80:81], v[154:155], v[90:91], v[50:51]
	v_pk_fma_f32 v[82:83], v[152:153], v[88:89], v[48:49]
	v_exp_f32_e32 v94, v76
	v_exp_f32_e32 v96, v78
	v_exp_f32_e32 v97, v79
	v_exp_f32_e32 v95, v77
	v_log_f32_e32 v92, v82
	v_log_f32_e32 v93, v83
	v_log_f32_e32 v80, v80
	v_log_f32_e32 v81, v81
	v_pk_add_f32 v[76:77], v[96:97], 1.0 op_sel_hi:[1,0]
	v_pk_add_f32 v[78:79], v[94:95], 1.0 op_sel_hi:[1,0]
	v_rcp_f32_e32 v98, v76
	v_pk_mul_f32 v[82:83], v[80:81], s[68:69] op_sel_hi:[1,0]
	v_pk_mul_f32 v[80:81], v[92:93], s[68:69] op_sel_hi:[1,0]
	v_rcp_f32_e32 v92, v78
	v_rcp_f32_e32 v99, v77
	v_rcp_f32_e32 v93, v79
	v_pk_mul_f32 v[76:77], v[84:85], v[88:89]
	v_pk_mul_f32 v[78:79], v[86:87], v[90:91]
	v_pk_fma_f32 v[84:85], v[150:151], v[98:99], v[38:39]
	v_pk_fma_f32 v[86:87], v[148:149], v[92:93], v[36:37]
	v_log_f32_e32 v84, v84
	v_log_f32_e32 v86, v86
	v_log_f32_e32 v85, v85
	v_log_f32_e32 v87, v87
	v_pk_mul_f32 v[88:89], v[154:155], v[78:79]
	v_pk_mul_f32 v[90:91], v[152:153], v[76:77]
	v_pk_mul_f32 v[78:79], v[84:85], s[68:69] op_sel_hi:[1,0]
	v_pk_mul_f32 v[76:77], v[86:87], s[68:69] op_sel_hi:[1,0]
	v_pk_mul_f32 v[84:85], v[94:95], v[92:93]
	v_pk_mul_f32 v[86:87], v[96:97], v[98:99]
	s_nop 0
	v_pk_mul_f32 v[92:93], v[150:151], v[86:87]
	v_pk_mul_f32 v[86:87], v[148:149], v[84:85]
	v_cvt_pk_bf16_f32 v84, v90, v91
	v_cvt_pk_bf16_f32 v85, v88, v89
	v_lshl_add_u64 v[88:89], s[30:31], 0, v[0:1]
	v_add_co_u32_e32 v88, vcc, 0x4400000, v88
	v_cvt_pk_bf16_f32 v86, v86, v87
	v_cvt_pk_bf16_f32 v87, v92, v93
	s_nop 1
	v_addc_co_u32_e32 v89, vcc, 0, v89, vcc
	global_store_dwordx4 v[88:89], v[84:87], off sc1
.LBB0_383:
	v_cvt_pk_bf16_f32 v80, v80, v81
	v_cvt_pk_bf16_f32 v81, v82, v83
	v_cvt_pk_bf16_f32 v82, v76, v77
	v_lshl_add_u64 v[76:77], s[30:31], 0, v[0:1]
	s_and_b64 vcc, exec, s[8:9]
	v_cvt_pk_bf16_f32 v83, v78, v79
	global_store_dwordx4 v[76:77], v[80:83], off sc1
	s_cbranch_vccnz .LBB0_387
	v_pk_mul_f32 v[76:77], v[74:75], s[96:97] op_sel_hi:[1,0]
	v_pk_mul_f32 v[78:79], v[72:73], s[96:97] op_sel_hi:[1,0]
	v_exp_f32_e32 v76, v76
	v_exp_f32_e32 v78, v78
	v_exp_f32_e32 v79, v79
	v_exp_f32_e32 v77, v77
	v_pk_add_f32 v[78:79], v[78:79], 1.0 op_sel_hi:[1,0]
	v_pk_add_f32 v[76:77], v[76:77], 1.0 op_sel_hi:[1,0]
	v_rcp_f32_e32 v78, v78
	v_rcp_f32_e32 v79, v79
	v_rcp_f32_e32 v76, v76
	v_rcp_f32_e32 v77, v77
	v_pk_mul_f32 v[72:73], v[72:73], v[78:79]
	v_pk_mul_f32 v[78:79], v[68:69], s[96:97] op_sel_hi:[1,0]
	v_pk_mul_f32 v[74:75], v[74:75], v[76:77]
	v_pk_mul_f32 v[76:77], v[70:71], s[96:97] op_sel_hi:[1,0]
	v_exp_f32_e32 v78, v78
	v_exp_f32_e32 v79, v79
	v_exp_f32_e32 v76, v76
	v_exp_f32_e32 v77, v77
	v_pk_add_f32 v[78:79], v[78:79], 1.0 op_sel_hi:[1,0]
	s_nop 0
	v_rcp_f32_e32 v78, v78
	v_pk_add_f32 v[76:77], v[76:77], 1.0 op_sel_hi:[1,0]
	v_rcp_f32_e32 v79, v79
	v_rcp_f32_e32 v76, v76
	v_rcp_f32_e32 v77, v77
	v_pk_mul_f32 v[68:69], v[68:69], v[78:79]
	v_pk_mul_f32 v[70:71], v[70:71], v[76:77]
	s_and_b64 vcc, exec, s[12:13]
	s_cbranch_vccz .LBB0_388

; __device__ __forceinline__ f32x4 silu4(f32x4 v) { return v * sigm4(v); }
; __device__ __forceinline__ u32x4 pack8(f32x4 v0, f32x4 v1) { u32x4 w; w.x = cvt_pk_bf16(v0[0], v0[1]); w.y = cvt_pk_bf16(v0[2], v0[3]); w.z = cvt_pk_bf16(v1[0], v1[1]); w.w = cvt_pk_bf16(v1[2], v1[3]); return w; }
; __device__ __forceinline__ void hg_gate4(f32x4& z, f32x4& key, const f32x4 l) {
;     const f32x4 zc = {__builtin_amdgcn_fmed3f(z[0], -80.f, 80.f), __builtin_amdgcn_fmed3f(z[1], -80.f, 80.f), __builtin_amdgcn_fmed3f(z[2], -80.f, 80.f), __builtin_amdgcn_fmed3f(z[3], -80.f, 80.f)};
;     const f32x4 t = zc * -1.4426950408889634f;
;     const f32x4 e = {__builtin_amdgcn_exp2f(t[0]), __builtin_amdgcn_exp2f(t[1]), __builtin_amdgcn_exp2f(t[2]), __builtin_amdgcn_exp2f(t[3])};
;     const f32x4 den = e + 1.0f;
;     const f32x4 sg = {__builtin_amdgcn_rcpf(den[0]), __builtin_amdgcn_rcpf(den[1]), __builtin_amdgcn_rcpf(den[2]), __builtin_amdgcn_rcpf(den[3])};
;     const f32x4 oml = 1.0f - l;
;     const f32x4 f = l + oml * sg;
;     z = (f32x4){__builtin_amdgcn_logf(f[0]), __builtin_amdgcn_logf(f[1]), __builtin_amdgcn_logf(f[2]), __builtin_amdgcn_logf(f[3])} * 0.6931471805599453f;
;     key = oml * (e * sg);
; }
;     __device__ __forceinline__ void operator()(const f32x4 (&acc)[2][2][4][2], const Unit& u, int wr, int wc, int fr_in, int fq_in) const {
;     ...
;         for (int ai = 0; ai < 2; ++ai)
; #pragma unroll
;             for (int m = 0; m < 4; ++m) {
;                 const int r = row0 + ai * HALF + m * 16;
;                 const size_t roff = (size_t)r * 2048 + cb;
; #pragma unroll
;                 for (int bj = 0; bj < 2; ++bj) {
;                     f32x4 v0 = acc[ai][bj][m][0], v1 = acc[ai][bj][m][1];
;                     if (type == 0) { v0 = silu4(v0); v1 = silu4(v1); }
;                     if (type == 4) { v0 = sigm4(v0); v1 = sigm4(v1); }
;                     if (type == 1 || type == 2) {
;                         f32x4 k0, k1;
;                         hg_gate4(v0, k0, lbv[bj][0]); hg_gate4(v1, k1, lbv[bj][1]);
;                         st16(base + tstride, roff + bj * HALF, pack8(k0, k1));
;                     }
;                     st16(base, roff + bj * HALF, pack8(v0, v1));
;                 }
.LBB0_390:
	v_med3_f32 v72, v72, s95, v182
	v_med3_f32 v73, v73, s95, v182
	v_med3_f32 v74, v74, s95, v182
	v_med3_f32 v75, v75, s95, v182
	v_pk_mul_f32 v[74:75], v[74:75], s[96:97] op_sel_hi:[1,0]
	v_pk_mul_f32 v[72:73], v[72:73], s[96:97] op_sel_hi:[1,0]
	v_exp_f32_e32 v78, v74
	v_exp_f32_e32 v76, v72
	v_exp_f32_e32 v79, v75
	v_exp_f32_e32 v77, v73
	v_med3_f32 v68, v68, s95, v182
	v_med3_f32 v69, v69, s95, v182
	v_pk_add_f32 v[72:73], v[78:79], 1.0 op_sel_hi:[1,0]
	v_pk_add_f32 v[74:75], v[76:77], 1.0 op_sel_hi:[1,0]
	v_rcp_f32_e32 v82, v72
	v_rcp_f32_e32 v80, v74
	v_rcp_f32_e32 v83, v73
	v_rcp_f32_e32 v81, v75
	v_med3_f32 v70, v70, s95, v182
	v_med3_f32 v71, v71, s95, v182
	v_pk_mul_f32 v[70:71], v[70:71], s[96:97] op_sel_hi:[1,0]
	v_pk_mul_f32 v[68:69], v[68:69], s[96:97] op_sel_hi:[1,0]
	v_pk_fma_f32 v[72:73], v[144:145], v[82:83], v[26:27]
	v_pk_fma_f32 v[74:75], v[142:143], v[80:81], v[24:25]
	v_exp_f32_e32 v86, v68
	v_exp_f32_e32 v88, v70
	v_exp_f32_e32 v89, v71
	v_exp_f32_e32 v87, v69
	v_log_f32_e32 v84, v74
	v_log_f32_e32 v85, v75
	v_log_f32_e32 v72, v72
	v_log_f32_e32 v73, v73
	v_pk_add_f32 v[68:69], v[88:89], 1.0 op_sel_hi:[1,0]
	v_pk_add_f32 v[70:71], v[86:87], 1.0 op_sel_hi:[1,0]
	v_rcp_f32_e32 v90, v68
	v_pk_mul_f32 v[74:75], v[72:73], s[68:69] op_sel_hi:[1,0]
	v_pk_mul_f32 v[72:73], v[84:85], s[68:69] op_sel_hi:[1,0]
	v_rcp_f32_e32 v84, v70
	v_rcp_f32_e32 v91, v69
	v_rcp_f32_e32 v85, v71
	v_pk_mul_f32 v[68:69], v[76:77], v[80:81]
	v_pk_mul_f32 v[70:71], v[78:79], v[82:83]
	v_pk_fma_f32 v[76:77], v[140:141], v[90:91], v[22:23]
	v_pk_fma_f32 v[78:79], v[2:3], v[84:85], v[20:21]
	v_log_f32_e32 v76, v76
	v_log_f32_e32 v78, v78
	v_log_f32_e32 v77, v77
	v_log_f32_e32 v79, v79
	v_pk_mul_f32 v[80:81], v[144:145], v[70:71]
	v_pk_mul_f32 v[82:83], v[142:143], v[68:69]
	v_pk_mul_f32 v[70:71], v[76:77], s[68:69] op_sel_hi:[1,0]
	v_pk_mul_f32 v[68:69], v[78:79], s[68:69] op_sel_hi:[1,0]
	v_pk_mul_f32 v[76:77], v[86:87], v[84:85]
	v_pk_mul_f32 v[78:79], v[88:89], v[90:91]
	s_nop 0
	v_pk_mul_f32 v[84:85], v[140:141], v[78:79]
	v_pk_mul_f32 v[78:79], v[2:3], v[76:77]
	v_cvt_pk_bf16_f32 v76, v82, v83
	v_cvt_pk_bf16_f32 v77, v80, v81
	v_lshl_add_u64 v[80:81], s[30:31], 0, v[0:1]
	v_add_co_u32_e32 v80, vcc, 0x4400000, v80
	v_cvt_pk_bf16_f32 v78, v78, v79
	v_cvt_pk_bf16_f32 v79, v84, v85
	s_nop 1
	v_addc_co_u32_e32 v81, vcc, 0, v81, vcc
	global_store_dwordx4 v[80:81], v[76:79], off sc1
.LBB0_391:
	v_cvt_pk_bf16_f32 v72, v72, v73
	v_cvt_pk_bf16_f32 v73, v74, v75
	v_cvt_pk_bf16_f32 v74, v68, v69
	v_lshl_add_u64 v[68:69], s[30:31], 0, v[0:1]
	s_and_b64 vcc, exec, s[8:9]
	v_cvt_pk_bf16_f32 v75, v70, v71
	global_store_dwordx4 v[68:69], v[72:75], off sc1
	s_cbranch_vccnz .LBB0_395
	v_pk_mul_f32 v[68:69], v[66:67], s[96:97] op_sel_hi:[1,0]
	v_pk_mul_f32 v[70:71], v[64:65], s[96:97] op_sel_hi:[1,0]
	v_exp_f32_e32 v68, v68
	v_exp_f32_e32 v70, v70
	v_exp_f32_e32 v71, v71
	v_exp_f32_e32 v69, v69
	v_pk_add_f32 v[70:71], v[70:71], 1.0 op_sel_hi:[1,0]
	v_pk_add_f32 v[68:69], v[68:69], 1.0 op_sel_hi:[1,0]
	v_rcp_f32_e32 v70, v70
	v_rcp_f32_e32 v71, v71
	v_rcp_f32_e32 v68, v68
	v_rcp_f32_e32 v69, v69
	v_pk_mul_f32 v[64:65], v[64:65], v[70:71]
	v_pk_mul_f32 v[70:71], v[60:61], s[96:97] op_sel_hi:[1,0]
	v_pk_mul_f32 v[66:67], v[66:67], v[68:69]
	v_pk_mul_f32 v[68:69], v[62:63], s[96:97] op_sel_hi:[1,0]
	v_exp_f32_e32 v70, v70
	v_exp_f32_e32 v71, v71
	v_exp_f32_e32 v68, v68
	v_exp_f32_e32 v69, v69
	v_pk_add_f32 v[70:71], v[70:71], 1.0 op_sel_hi:[1,0]
	s_nop 0
	v_rcp_f32_e32 v70, v70
	v_pk_add_f32 v[68:69], v[68:69], 1.0 op_sel_hi:[1,0]
	v_rcp_f32_e32 v71, v71
	v_rcp_f32_e32 v68, v68
	v_rcp_f32_e32 v69, v69
	v_pk_mul_f32 v[60:61], v[60:61], v[70:71]
	v_pk_mul_f32 v[62:63], v[62:63], v[68:69]
	s_and_b64 vcc, exec, s[12:13]
	s_cbranch_vccz .LBB0_396

; __device__ __forceinline__ f32x4 silu4(f32x4 v) { return v * sigm4(v); }
; __device__ __forceinline__ u32x4 pack8(f32x4 v0, f32x4 v1) { u32x4 w; w.x = cvt_pk_bf16(v0[0], v0[1]); w.y = cvt_pk_bf16(v0[2], v0[3]); w.z = cvt_pk_bf16(v1[0], v1[1]); w.w = cvt_pk_bf16(v1[2], v1[3]); return w; }
; __device__ __forceinline__ void hg_gate4(f32x4& z, f32x4& key, const f32x4 l) {
;     const f32x4 zc = {__builtin_amdgcn_fmed3f(z[0], -80.f, 80.f), __builtin_amdgcn_fmed3f(z[1], -80.f, 80.f), __builtin_amdgcn_fmed3f(z[2], -80.f, 80.f), __builtin_amdgcn_fmed3f(z[3], -80.f, 80.f)};
;     const f32x4 t = zc * -1.4426950408889634f;
;     const f32x4 e = {__builtin_amdgcn_exp2f(t[0]), __builtin_amdgcn_exp2f(t[1]), __builtin_amdgcn_exp2f(t[2]), __builtin_amdgcn_exp2f(t[3])};
;     const f32x4 den = e + 1.0f;
;     const f32x4 sg = {__builtin_amdgcn_rcpf(den[0]), __builtin_amdgcn_rcpf(den[1]), __builtin_amdgcn_rcpf(den[2]), __builtin_amdgcn_rcpf(den[3])};
;     const f32x4 oml = 1.0f - l;
;     const f32x4 f = l + oml * sg;
;     z = (f32x4){__builtin_amdgcn_logf(f[0]), __builtin_amdgcn_logf(f[1]), __builtin_amdgcn_logf(f[2]), __builtin_amdgcn_logf(f[3])} * 0.6931471805599453f;
;     key = oml * (e * sg);
; }
;     __device__ __forceinline__ void operator()(const f32x4 (&acc)[2][2][4][2], const Unit& u, int wr, int wc, int fr_in, int fq_in) const {
;     ...
;         for (int ai = 0; ai < 2; ++ai)
; #pragma unroll
;             for (int m = 0; m < 4; ++m) {
;                 const int r = row0 + ai * HALF + m * 16;
;                 const size_t roff = (size_t)r * 2048 + cb;
; #pragma unroll
;                 for (int bj = 0; bj < 2; ++bj) {
;                     f32x4 v0 = acc[ai][bj][m][0], v1 = acc[ai][bj][m][1];
;                     if (type == 0) { v0 = silu4(v0); v1 = silu4(v1); }
;                     if (type == 4) { v0 = sigm4(v0); v1 = sigm4(v1); }
;                     if (type == 1 || type == 2) {
;                         f32x4 k0, k1;
;                         hg_gate4(v0, k0, lbv[bj][0]); hg_gate4(v1, k1, lbv[bj][1]);
;                         st16(base + tstride, roff + bj * HALF, pack8(k0, k1));
;                     }
;                     st16(base, roff + bj * HALF, pack8(v0, v1));
;                 }
.LBB0_397:
.LBB0_398:
	v_med3_f32 v64, v64, s95, v182
	v_med3_f32 v65, v65, s95, v182
	v_med3_f32 v66, v66, s95, v182
	v_med3_f32 v67, v67, s95, v182
	v_pk_mul_f32 v[66:67], v[66:67], s[96:97] op_sel_hi:[1,0]
	v_pk_mul_f32 v[64:65], v[64:65], s[96:97] op_sel_hi:[1,0]
	v_exp_f32_e32 v70, v66
	v_exp_f32_e32 v68, v64
	v_exp_f32_e32 v71, v67
	v_exp_f32_e32 v69, v65
	v_med3_f32 v60, v60, s95, v182
	v_med3_f32 v61, v61, s95, v182
	v_pk_add_f32 v[64:65], v[70:71], 1.0 op_sel_hi:[1,0]
	v_pk_add_f32 v[66:67], v[68:69], 1.0 op_sel_hi:[1,0]
	v_rcp_f32_e32 v74, v64
	v_rcp_f32_e32 v72, v66
	v_rcp_f32_e32 v75, v65
	v_rcp_f32_e32 v73, v67
	v_med3_f32 v62, v62, s95, v182
	v_med3_f32 v63, v63, s95, v182
	v_pk_mul_f32 v[62:63], v[62:63], s[96:97] op_sel_hi:[1,0]
	v_pk_mul_f32 v[60:61], v[60:61], s[96:97] op_sel_hi:[1,0]
	v_pk_fma_f32 v[64:65], v[154:155], v[74:75], v[50:51]
	v_pk_fma_f32 v[66:67], v[152:153], v[72:73], v[48:49]
	v_exp_f32_e32 v78, v60
	v_exp_f32_e32 v80, v62
	v_exp_f32_e32 v81, v63
	v_exp_f32_e32 v79, v61
	v_log_f32_e32 v76, v66
	v_log_f32_e32 v77, v67
	v_log_f32_e32 v64, v64
	v_log_f32_e32 v65, v65
	v_pk_add_f32 v[60:61], v[80:81], 1.0 op_sel_hi:[1,0]
	v_pk_add_f32 v[62:63], v[78:79], 1.0 op_sel_hi:[1,0]
	v_rcp_f32_e32 v82, v60
	v_pk_mul_f32 v[66:67], v[64:65], s[68:69] op_sel_hi:[1,0]
	v_pk_mul_f32 v[64:65], v[76:77], s[68:69] op_sel_hi:[1,0]
	v_rcp_f32_e32 v76, v62
	v_rcp_f32_e32 v83, v61
	v_rcp_f32_e32 v77, v63
	v_pk_mul_f32 v[60:61], v[68:69], v[72:73]
	v_pk_mul_f32 v[62:63], v[70:71], v[74:75]
	v_pk_fma_f32 v[68:69], v[150:151], v[82:83], v[38:39]
	v_pk_fma_f32 v[70:71], v[148:149], v[76:77], v[36:37]
	v_log_f32_e32 v68, v68
	v_log_f32_e32 v70, v70
	v_log_f32_e32 v69, v69
	v_log_f32_e32 v71, v71
	v_pk_mul_f32 v[72:73], v[154:155], v[62:63]
	v_pk_mul_f32 v[74:75], v[152:153], v[60:61]
	v_pk_mul_f32 v[62:63], v[68:69], s[68:69] op_sel_hi:[1,0]
	v_pk_mul_f32 v[60:61], v[70:71], s[68:69] op_sel_hi:[1,0]
	v_pk_mul_f32 v[68:69], v[78:79], v[76:77]
	v_pk_mul_f32 v[70:71], v[80:81], v[82:83]
	s_nop 0
	v_pk_mul_f32 v[76:77], v[150:151], v[70:71]
	v_pk_mul_f32 v[70:71], v[148:149], v[68:69]
	v_cvt_pk_bf16_f32 v68, v74, v75
	v_cvt_pk_bf16_f32 v69, v72, v73
	v_lshl_add_u64 v[72:73], s[30:31], 0, v[0:1]
	v_add_co_u32_e32 v72, vcc, 0x4400000, v72
	v_cvt_pk_bf16_f32 v70, v70, v71
	v_cvt_pk_bf16_f32 v71, v76, v77
	s_nop 1
	v_addc_co_u32_e32 v73, vcc, 0, v73, vcc
	global_store_dwordx4 v[72:73], v[68:71], off sc1
.LBB0_399:
	v_cvt_pk_bf16_f32 v64, v64, v65
	v_cvt_pk_bf16_f32 v65, v66, v67
	v_cvt_pk_bf16_f32 v66, v60, v61
	v_lshl_add_u64 v[60:61], s[30:31], 0, v[0:1]
	s_and_b64 vcc, exec, s[8:9]
	v_cvt_pk_bf16_f32 v67, v62, v63
	global_store_dwordx4 v[60:61], v[64:67], off sc1
	s_cbranch_vccnz .LBB0_403
	v_pk_mul_f32 v[60:61], v[58:59], s[96:97] op_sel_hi:[1,0]
	v_pk_mul_f32 v[62:63], v[56:57], s[96:97] op_sel_hi:[1,0]
	v_exp_f32_e32 v60, v60
	v_exp_f32_e32 v62, v62
	v_exp_f32_e32 v63, v63
	v_exp_f32_e32 v61, v61
	v_pk_add_f32 v[62:63], v[62:63], 1.0 op_sel_hi:[1,0]
	v_pk_add_f32 v[60:61], v[60:61], 1.0 op_sel_hi:[1,0]
	v_rcp_f32_e32 v62, v62
	v_rcp_f32_e32 v63, v63
	v_rcp_f32_e32 v60, v60
	v_rcp_f32_e32 v61, v61
	v_pk_mul_f32 v[56:57], v[56:57], v[62:63]
	v_pk_mul_f32 v[62:63], v[52:53], s[96:97] op_sel_hi:[1,0]
	v_pk_mul_f32 v[58:59], v[58:59], v[60:61]
	v_pk_mul_f32 v[60:61], v[54:55], s[96:97] op_sel_hi:[1,0]
	v_exp_f32_e32 v62, v62
	v_exp_f32_e32 v63, v63
	v_exp_f32_e32 v60, v60
	v_exp_f32_e32 v61, v61
	v_pk_add_f32 v[62:63], v[62:63], 1.0 op_sel_hi:[1,0]
	s_nop 0
	v_rcp_f32_e32 v62, v62
	v_pk_add_f32 v[60:61], v[60:61], 1.0 op_sel_hi:[1,0]
	v_rcp_f32_e32 v63, v63
	v_rcp_f32_e32 v60, v60
	v_rcp_f32_e32 v61, v61
	v_pk_mul_f32 v[52:53], v[52:53], v[62:63]
	v_pk_mul_f32 v[54:55], v[54:55], v[60:61]
	s_and_b64 vcc, exec, s[12:13]
	s_cbranch_vccz .LBB0_404

; __device__ __forceinline__ f32x4 silu4(f32x4 v) { return v * sigm4(v); }
; __device__ __forceinline__ u32x4 pack8(f32x4 v0, f32x4 v1) { u32x4 w; w.x = cvt_pk_bf16(v0[0], v0[1]); w.y = cvt_pk_bf16(v0[2], v0[3]); w.z = cvt_pk_bf16(v1[0], v1[1]); w.w = cvt_pk_bf16(v1[2], v1[3]); return w; }
; __device__ __forceinline__ void hg_gate4(f32x4& z, f32x4& key, const f32x4 l) {
;     const f32x4 zc = {__builtin_amdgcn_fmed3f(z[0], -80.f, 80.f), __builtin_amdgcn_fmed3f(z[1], -80.f, 80.f), __builtin_amdgcn_fmed3f(z[2], -80.f, 80.f), __builtin_amdgcn_fmed3f(z[3], -80.f, 80.f)};
;     const f32x4 t = zc * -1.4426950408889634f;
;     const f32x4 e = {__builtin_amdgcn_exp2f(t[0]), __builtin_amdgcn_exp2f(t[1]), __builtin_amdgcn_exp2f(t[2]), __builtin_amdgcn_exp2f(t[3])};
;     const f32x4 den = e + 1.0f;
;     const f32x4 sg = {__builtin_amdgcn_rcpf(den[0]), __builtin_amdgcn_rcpf(den[1]), __builtin_amdgcn_rcpf(den[2]), __builtin_amdgcn_rcpf(den[3])};
;     const f32x4 oml = 1.0f - l;
;     const f32x4 f = l + oml * sg;
;     z = (f32x4){__builtin_amdgcn_logf(f[0]), __builtin_amdgcn_logf(f[1]), __builtin_amdgcn_logf(f[2]), __builtin_amdgcn_logf(f[3])} * 0.6931471805599453f;
;     key = oml * (e * sg);
; }
;     __device__ __forceinline__ void operator()(const f32x4 (&acc)[2][2][4][2], const Unit& u, int wr, int wc, int fr_in, int fq_in) const {
;     ...
;         for (int ai = 0; ai < 2; ++ai)
; #pragma unroll
;             for (int m = 0; m < 4; ++m) {
;                 const int r = row0 + ai * HALF + m * 16;
;                 const size_t roff = (size_t)r * 2048 + cb;
; #pragma unroll
;                 for (int bj = 0; bj < 2; ++bj) {
;                     f32x4 v0 = acc[ai][bj][m][0], v1 = acc[ai][bj][m][1];
;                     if (type == 0) { v0 = silu4(v0); v1 = silu4(v1); }
;                     if (type == 4) { v0 = sigm4(v0); v1 = sigm4(v1); }
;                     if (type == 1 || type == 2) {
;                         f32x4 k0, k1;
;                         hg_gate4(v0, k0, lbv[bj][0]); hg_gate4(v1, k1, lbv[bj][1]);
;                         st16(base + tstride, roff + bj * HALF, pack8(k0, k1));
;                     }
;                     st16(base, roff + bj * HALF, pack8(v0, v1));
;                 }
.LBB0_406:
	v_med3_f32 v56, v56, s95, v182
	v_med3_f32 v57, v57, s95, v182
	v_med3_f32 v58, v58, s95, v182
	v_med3_f32 v59, v59, s95, v182
	v_pk_mul_f32 v[58:59], v[58:59], s[96:97] op_sel_hi:[1,0]
	v_pk_mul_f32 v[56:57], v[56:57], s[96:97] op_sel_hi:[1,0]
	v_exp_f32_e32 v62, v58
	v_exp_f32_e32 v60, v56
	v_exp_f32_e32 v63, v59
	v_exp_f32_e32 v61, v57
	v_med3_f32 v52, v52, s95, v182
	v_med3_f32 v53, v53, s95, v182
	v_pk_add_f32 v[56:57], v[62:63], 1.0 op_sel_hi:[1,0]
	v_pk_add_f32 v[58:59], v[60:61], 1.0 op_sel_hi:[1,0]
	v_rcp_f32_e32 v66, v56
	v_rcp_f32_e32 v64, v58
	v_rcp_f32_e32 v67, v57
	v_rcp_f32_e32 v65, v59
	v_med3_f32 v54, v54, s95, v182
	v_med3_f32 v55, v55, s95, v182
	v_pk_mul_f32 v[54:55], v[54:55], s[96:97] op_sel_hi:[1,0]
	v_pk_mul_f32 v[52:53], v[52:53], s[96:97] op_sel_hi:[1,0]
	v_pk_fma_f32 v[56:57], v[144:145], v[66:67], v[26:27]
	v_pk_fma_f32 v[58:59], v[142:143], v[64:65], v[24:25]
	v_exp_f32_e32 v70, v52
	v_exp_f32_e32 v72, v54
	v_exp_f32_e32 v73, v55
	v_exp_f32_e32 v71, v53
	v_log_f32_e32 v68, v58
	v_log_f32_e32 v69, v59
	v_log_f32_e32 v56, v56
	v_log_f32_e32 v57, v57
	v_pk_add_f32 v[52:53], v[72:73], 1.0 op_sel_hi:[1,0]
	v_pk_add_f32 v[54:55], v[70:71], 1.0 op_sel_hi:[1,0]
	v_rcp_f32_e32 v74, v52
	v_pk_mul_f32 v[58:59], v[56:57], s[68:69] op_sel_hi:[1,0]
	v_pk_mul_f32 v[56:57], v[68:69], s[68:69] op_sel_hi:[1,0]
	v_rcp_f32_e32 v68, v54
	v_rcp_f32_e32 v75, v53
	v_rcp_f32_e32 v69, v55
	v_pk_mul_f32 v[52:53], v[60:61], v[64:65]
	v_pk_mul_f32 v[54:55], v[62:63], v[66:67]
	v_pk_fma_f32 v[60:61], v[140:141], v[74:75], v[22:23]
	v_pk_fma_f32 v[62:63], v[2:3], v[68:69], v[20:21]
	v_log_f32_e32 v60, v60
	v_log_f32_e32 v62, v62
	v_log_f32_e32 v61, v61
	v_log_f32_e32 v63, v63
	v_pk_mul_f32 v[64:65], v[144:145], v[54:55]
	v_pk_mul_f32 v[66:67], v[142:143], v[52:53]
	v_pk_mul_f32 v[54:55], v[60:61], s[68:69] op_sel_hi:[1,0]
	v_pk_mul_f32 v[52:53], v[62:63], s[68:69] op_sel_hi:[1,0]
	v_pk_mul_f32 v[60:61], v[70:71], v[68:69]
	v_pk_mul_f32 v[62:63], v[72:73], v[74:75]
	s_nop 0
	v_pk_mul_f32 v[68:69], v[140:141], v[62:63]
	v_pk_mul_f32 v[62:63], v[2:3], v[60:61]
	v_cvt_pk_bf16_f32 v60, v66, v67
	v_cvt_pk_bf16_f32 v61, v64, v65
	v_lshl_add_u64 v[64:65], s[30:31], 0, v[0:1]
	v_add_co_u32_e32 v64, vcc, 0x4400000, v64
	v_cvt_pk_bf16_f32 v62, v62, v63
	v_cvt_pk_bf16_f32 v63, v68, v69
	s_nop 1
	v_addc_co_u32_e32 v65, vcc, 0, v65, vcc
	global_store_dwordx4 v[64:65], v[60:63], off sc1
.LBB0_407:
	v_cvt_pk_bf16_f32 v56, v56, v57
	v_cvt_pk_bf16_f32 v57, v58, v59
	v_cvt_pk_bf16_f32 v58, v52, v53
	v_lshl_add_u64 v[52:53], s[30:31], 0, v[0:1]
	s_and_b64 vcc, exec, s[8:9]
	v_cvt_pk_bf16_f32 v59, v54, v55
	global_store_dwordx4 v[52:53], v[56:59], off sc1
	s_cbranch_vccnz .LBB0_411
	v_pk_mul_f32 v[52:53], v[46:47], s[96:97] op_sel_hi:[1,0]
	v_pk_mul_f32 v[54:55], v[44:45], s[96:97] op_sel_hi:[1,0]
	v_exp_f32_e32 v52, v52
	v_exp_f32_e32 v54, v54
	v_exp_f32_e32 v55, v55
	v_exp_f32_e32 v53, v53
	v_pk_add_f32 v[54:55], v[54:55], 1.0 op_sel_hi:[1,0]
	v_pk_add_f32 v[52:53], v[52:53], 1.0 op_sel_hi:[1,0]
	v_rcp_f32_e32 v54, v54
	v_rcp_f32_e32 v55, v55
	v_rcp_f32_e32 v52, v52
	v_rcp_f32_e32 v53, v53
	v_pk_mul_f32 v[44:45], v[44:45], v[54:55]
	v_pk_mul_f32 v[54:55], v[40:41], s[96:97] op_sel_hi:[1,0]
	v_pk_mul_f32 v[46:47], v[46:47], v[52:53]
	v_pk_mul_f32 v[52:53], v[42:43], s[96:97] op_sel_hi:[1,0]
	v_exp_f32_e32 v54, v54
	v_exp_f32_e32 v55, v55
	v_exp_f32_e32 v52, v52
	v_exp_f32_e32 v53, v53
	v_pk_add_f32 v[54:55], v[54:55], 1.0 op_sel_hi:[1,0]
	s_nop 0
	v_rcp_f32_e32 v54, v54
	v_pk_add_f32 v[52:53], v[52:53], 1.0 op_sel_hi:[1,0]
	v_rcp_f32_e32 v55, v55
	v_rcp_f32_e32 v52, v52
	v_rcp_f32_e32 v53, v53
	v_pk_mul_f32 v[40:41], v[40:41], v[54:55]
	v_pk_mul_f32 v[42:43], v[42:43], v[52:53]
	s_and_b64 vcc, exec, s[12:13]
	s_cbranch_vccz .LBB0_412

; __device__ __forceinline__ f32x4 silu4(f32x4 v) { return v * sigm4(v); }
; __device__ __forceinline__ u32x4 pack8(f32x4 v0, f32x4 v1) { u32x4 w; w.x = cvt_pk_bf16(v0[0], v0[1]); w.y = cvt_pk_bf16(v0[2], v0[3]); w.z = cvt_pk_bf16(v1[0], v1[1]); w.w = cvt_pk_bf16(v1[2], v1[3]); return w; }
; __device__ __forceinline__ void hg_gate4(f32x4& z, f32x4& key, const f32x4 l) {
;     const f32x4 zc = {__builtin_amdgcn_fmed3f(z[0], -80.f, 80.f), __builtin_amdgcn_fmed3f(z[1], -80.f, 80.f), __builtin_amdgcn_fmed3f(z[2], -80.f, 80.f), __builtin_amdgcn_fmed3f(z[3], -80.f, 80.f)};
;     const f32x4 t = zc * -1.4426950408889634f;
;     const f32x4 e = {__builtin_amdgcn_exp2f(t[0]), __builtin_amdgcn_exp2f(t[1]), __builtin_amdgcn_exp2f(t[2]), __builtin_amdgcn_exp2f(t[3])};
;     const f32x4 den = e + 1.0f;
;     const f32x4 sg = {__builtin_amdgcn_rcpf(den[0]), __builtin_amdgcn_rcpf(den[1]), __builtin_amdgcn_rcpf(den[2]), __builtin_amdgcn_rcpf(den[3])};
;     const f32x4 oml = 1.0f - l;
;     const f32x4 f = l + oml * sg;
;     z = (f32x4){__builtin_amdgcn_logf(f[0]), __builtin_amdgcn_logf(f[1]), __builtin_amdgcn_logf(f[2]), __builtin_amdgcn_logf(f[3])} * 0.6931471805599453f;
;     key = oml * (e * sg);
; }
;     __device__ __forceinline__ void operator()(const f32x4 (&acc)[2][2][4][2], const Unit& u, int wr, int wc, int fr_in, int fq_in) const {
;     ...
;         for (int ai = 0; ai < 2; ++ai)
; #pragma unroll
;             for (int m = 0; m < 4; ++m) {
;                 const int r = row0 + ai * HALF + m * 16;
;                 const size_t roff = (size_t)r * 2048 + cb;
; #pragma unroll
;                 for (int bj = 0; bj < 2; ++bj) {
;                     f32x4 v0 = acc[ai][bj][m][0], v1 = acc[ai][bj][m][1];
;                     if (type == 0) { v0 = silu4(v0); v1 = silu4(v1); }
;                     if (type == 4) { v0 = sigm4(v0); v1 = sigm4(v1); }
;                     if (type == 1 || type == 2) {
;                         f32x4 k0, k1;
;                         hg_gate4(v0, k0, lbv[bj][0]); hg_gate4(v1, k1, lbv[bj][1]);
;                         st16(base + tstride, roff + bj * HALF, pack8(k0, k1));
;                     }
;                     st16(base, roff + bj * HALF, pack8(v0, v1));
;                 }
.LBB0_413:
.LBB0_414:
	v_med3_f32 v44, v44, s95, v182
	v_med3_f32 v45, v45, s95, v182
	v_med3_f32 v46, v46, s95, v182
	v_med3_f32 v47, v47, s95, v182
	v_pk_mul_f32 v[46:47], v[46:47], s[96:97] op_sel_hi:[1,0]
	v_pk_mul_f32 v[44:45], v[44:45], s[96:97] op_sel_hi:[1,0]
	v_exp_f32_e32 v54, v46
	v_exp_f32_e32 v52, v44
	v_exp_f32_e32 v55, v47
	v_exp_f32_e32 v53, v45
	v_med3_f32 v40, v40, s95, v182
	v_med3_f32 v41, v41, s95, v182
	v_pk_add_f32 v[44:45], v[54:55], 1.0 op_sel_hi:[1,0]
	v_pk_add_f32 v[46:47], v[52:53], 1.0 op_sel_hi:[1,0]
	v_rcp_f32_e32 v58, v44
	v_rcp_f32_e32 v56, v46
	v_rcp_f32_e32 v59, v45
	v_rcp_f32_e32 v57, v47
	v_med3_f32 v42, v42, s95, v182
	v_med3_f32 v43, v43, s95, v182
	v_pk_mul_f32 v[42:43], v[42:43], s[96:97] op_sel_hi:[1,0]
	v_pk_mul_f32 v[40:41], v[40:41], s[96:97] op_sel_hi:[1,0]
	v_pk_fma_f32 v[44:45], v[154:155], v[58:59], v[50:51]
	v_pk_fma_f32 v[46:47], v[152:153], v[56:57], v[48:49]
	v_exp_f32_e32 v62, v40
	v_exp_f32_e32 v64, v42
	v_exp_f32_e32 v65, v43
	v_exp_f32_e32 v63, v41
	v_log_f32_e32 v60, v46
	v_log_f32_e32 v61, v47
	v_log_f32_e32 v44, v44
	v_log_f32_e32 v45, v45
	v_pk_add_f32 v[40:41], v[64:65], 1.0 op_sel_hi:[1,0]
	v_pk_add_f32 v[42:43], v[62:63], 1.0 op_sel_hi:[1,0]
	v_rcp_f32_e32 v66, v40
	v_pk_mul_f32 v[46:47], v[44:45], s[68:69] op_sel_hi:[1,0]
	v_pk_mul_f32 v[44:45], v[60:61], s[68:69] op_sel_hi:[1,0]
	v_rcp_f32_e32 v60, v42
	v_rcp_f32_e32 v67, v41
	v_rcp_f32_e32 v61, v43
	v_pk_mul_f32 v[40:41], v[52:53], v[56:57]
	v_pk_mul_f32 v[42:43], v[54:55], v[58:59]
	v_pk_fma_f32 v[52:53], v[150:151], v[66:67], v[38:39]
	v_pk_fma_f32 v[54:55], v[148:149], v[60:61], v[36:37]
	v_log_f32_e32 v52, v52
	v_log_f32_e32 v54, v54
	v_log_f32_e32 v53, v53
	v_log_f32_e32 v55, v55
	v_pk_mul_f32 v[56:57], v[154:155], v[42:43]
	v_pk_mul_f32 v[58:59], v[152:153], v[40:41]
	v_pk_mul_f32 v[42:43], v[52:53], s[68:69] op_sel_hi:[1,0]
	v_pk_mul_f32 v[40:41], v[54:55], s[68:69] op_sel_hi:[1,0]
	v_pk_mul_f32 v[52:53], v[62:63], v[60:61]
	v_pk_mul_f32 v[54:55], v[64:65], v[66:67]
	s_nop 0
	v_pk_mul_f32 v[60:61], v[150:151], v[54:55]
	v_pk_mul_f32 v[54:55], v[148:149], v[52:53]
	v_cvt_pk_bf16_f32 v52, v58, v59
	v_cvt_pk_bf16_f32 v53, v56, v57
	v_lshl_add_u64 v[56:57], s[30:31], 0, v[0:1]
	v_add_co_u32_e32 v56, vcc, 0x4400000, v56
	v_cvt_pk_bf16_f32 v54, v54, v55
	v_cvt_pk_bf16_f32 v55, v60, v61
	s_nop 1
	v_addc_co_u32_e32 v57, vcc, 0, v57, vcc
	global_store_dwordx4 v[56:57], v[52:55], off sc1
.LBB0_415:
	v_cvt_pk_bf16_f32 v44, v44, v45
	v_cvt_pk_bf16_f32 v45, v46, v47
	v_cvt_pk_bf16_f32 v46, v40, v41
	v_lshl_add_u64 v[40:41], s[30:31], 0, v[0:1]
	s_and_b64 vcc, exec, s[8:9]
	v_cvt_pk_bf16_f32 v47, v42, v43
	global_store_dwordx4 v[40:41], v[44:47], off sc1
	s_cbranch_vccnz .LBB0_419
	v_pk_mul_f32 v[40:41], v[34:35], s[96:97] op_sel_hi:[1,0]
	v_pk_mul_f32 v[42:43], v[32:33], s[96:97] op_sel_hi:[1,0]
	v_exp_f32_e32 v40, v40
	v_exp_f32_e32 v42, v42
	v_exp_f32_e32 v43, v43
	v_exp_f32_e32 v41, v41
	v_pk_add_f32 v[42:43], v[42:43], 1.0 op_sel_hi:[1,0]
	v_pk_add_f32 v[40:41], v[40:41], 1.0 op_sel_hi:[1,0]
	v_rcp_f32_e32 v42, v42
	v_rcp_f32_e32 v43, v43
	v_rcp_f32_e32 v40, v40
	v_rcp_f32_e32 v41, v41
	v_pk_mul_f32 v[32:33], v[32:33], v[42:43]
	v_pk_mul_f32 v[42:43], v[28:29], s[96:97] op_sel_hi:[1,0]
	v_pk_mul_f32 v[34:35], v[34:35], v[40:41]
	v_pk_mul_f32 v[40:41], v[30:31], s[96:97] op_sel_hi:[1,0]
	v_exp_f32_e32 v42, v42
	v_exp_f32_e32 v43, v43
	v_exp_f32_e32 v40, v40
	v_exp_f32_e32 v41, v41
	v_pk_add_f32 v[42:43], v[42:43], 1.0 op_sel_hi:[1,0]
	s_nop 0
	v_rcp_f32_e32 v42, v42
	v_pk_add_f32 v[40:41], v[40:41], 1.0 op_sel_hi:[1,0]
	v_rcp_f32_e32 v43, v43
	v_rcp_f32_e32 v40, v40
	v_rcp_f32_e32 v41, v41
	v_pk_mul_f32 v[28:29], v[28:29], v[42:43]
	v_pk_mul_f32 v[30:31], v[30:31], v[40:41]
	s_and_b64 vcc, exec, s[12:13]
	s_cbranch_vccz .LBB0_420

; __device__ __forceinline__ f32x4 silu4(f32x4 v) { return v * sigm4(v); }
; __device__ __forceinline__ u32x4 pack8(f32x4 v0, f32x4 v1) { u32x4 w; w.x = cvt_pk_bf16(v0[0], v0[1]); w.y = cvt_pk_bf16(v0[2], v0[3]); w.z = cvt_pk_bf16(v1[0], v1[1]); w.w = cvt_pk_bf16(v1[2], v1[3]); return w; }
; __device__ __forceinline__ void hg_gate4(f32x4& z, f32x4& key, const f32x4 l) {
;     const f32x4 zc = {__builtin_amdgcn_fmed3f(z[0], -80.f, 80.f), __builtin_amdgcn_fmed3f(z[1], -80.f, 80.f), __builtin_amdgcn_fmed3f(z[2], -80.f, 80.f), __builtin_amdgcn_fmed3f(z[3], -80.f, 80.f)};
;     const f32x4 t = zc * -1.4426950408889634f;
;     const f32x4 e = {__builtin_amdgcn_exp2f(t[0]), __builtin_amdgcn_exp2f(t[1]), __builtin_amdgcn_exp2f(t[2]), __builtin_amdgcn_exp2f(t[3])};
;     const f32x4 den = e + 1.0f;
;     const f32x4 sg = {__builtin_amdgcn_rcpf(den[0]), __builtin_amdgcn_rcpf(den[1]), __builtin_amdgcn_rcpf(den[2]), __builtin_amdgcn_rcpf(den[3])};
;     const f32x4 oml = 1.0f - l;
;     const f32x4 f = l + oml * sg;
;     z = (f32x4){__builtin_amdgcn_logf(f[0]), __builtin_amdgcn_logf(f[1]), __builtin_amdgcn_logf(f[2]), __builtin_amdgcn_logf(f[3])} * 0.6931471805599453f;
;     key = oml * (e * sg);
; }
;     __device__ __forceinline__ void operator()(const f32x4 (&acc)[2][2][4][2], const Unit& u, int wr, int wc, int fr_in, int fq_in) const {
;     ...
;         for (int ai = 0; ai < 2; ++ai)
; #pragma unroll
;             for (int m = 0; m < 4; ++m) {
;                 const int r = row0 + ai * HALF + m * 16;
;                 const size_t roff = (size_t)r * 2048 + cb;
; #pragma unroll
;                 for (int bj = 0; bj < 2; ++bj) {
;                     f32x4 v0 = acc[ai][bj][m][0], v1 = acc[ai][bj][m][1];
;                     if (type == 0) { v0 = silu4(v0); v1 = silu4(v1); }
;                     if (type == 4) { v0 = sigm4(v0); v1 = sigm4(v1); }
;                     if (type == 1 || type == 2) {
;                         f32x4 k0, k1;
;                         hg_gate4(v0, k0, lbv[bj][0]); hg_gate4(v1, k1, lbv[bj][1]);
;                         st16(base + tstride, roff + bj * HALF, pack8(k0, k1));
;                     }
;                     st16(base, roff + bj * HALF, pack8(v0, v1));
;                 }
.LBB0_422:
	v_med3_f32 v32, v32, s95, v182
	v_med3_f32 v33, v33, s95, v182
	v_med3_f32 v34, v34, s95, v182
	v_med3_f32 v35, v35, s95, v182
	v_pk_mul_f32 v[34:35], v[34:35], s[96:97] op_sel_hi:[1,0]
	v_pk_mul_f32 v[32:33], v[32:33], s[96:97] op_sel_hi:[1,0]
	v_exp_f32_e32 v42, v34
	v_exp_f32_e32 v40, v32
	v_exp_f32_e32 v43, v35
	v_exp_f32_e32 v41, v33
	v_med3_f32 v28, v28, s95, v182
	v_med3_f32 v29, v29, s95, v182
	v_pk_add_f32 v[32:33], v[42:43], 1.0 op_sel_hi:[1,0]
	v_pk_add_f32 v[34:35], v[40:41], 1.0 op_sel_hi:[1,0]
	v_rcp_f32_e32 v46, v32
	v_rcp_f32_e32 v44, v34
	v_rcp_f32_e32 v47, v33
	v_rcp_f32_e32 v45, v35
	v_med3_f32 v30, v30, s95, v182
	v_med3_f32 v31, v31, s95, v182
	v_pk_mul_f32 v[30:31], v[30:31], s[96:97] op_sel_hi:[1,0]
	v_pk_mul_f32 v[28:29], v[28:29], s[96:97] op_sel_hi:[1,0]
	v_pk_fma_f32 v[32:33], v[144:145], v[46:47], v[26:27]
	v_pk_fma_f32 v[34:35], v[142:143], v[44:45], v[24:25]
	v_exp_f32_e32 v54, v28
	v_exp_f32_e32 v56, v30
	v_exp_f32_e32 v57, v31
	v_exp_f32_e32 v55, v29
	v_log_f32_e32 v52, v34
	v_log_f32_e32 v53, v35
	v_log_f32_e32 v32, v32
	v_log_f32_e32 v33, v33
	v_pk_add_f32 v[28:29], v[56:57], 1.0 op_sel_hi:[1,0]
	v_pk_add_f32 v[30:31], v[54:55], 1.0 op_sel_hi:[1,0]
	v_rcp_f32_e32 v58, v28
	v_pk_mul_f32 v[34:35], v[32:33], s[68:69] op_sel_hi:[1,0]
	v_pk_mul_f32 v[32:33], v[52:53], s[68:69] op_sel_hi:[1,0]
	v_rcp_f32_e32 v52, v30
	v_rcp_f32_e32 v59, v29
	v_rcp_f32_e32 v53, v31
	v_pk_mul_f32 v[28:29], v[40:41], v[44:45]
	v_pk_mul_f32 v[30:31], v[42:43], v[46:47]
	v_pk_fma_f32 v[40:41], v[140:141], v[58:59], v[22:23]
	v_pk_fma_f32 v[42:43], v[2:3], v[52:53], v[20:21]
	v_log_f32_e32 v40, v40
	v_log_f32_e32 v42, v42
	v_log_f32_e32 v41, v41
	v_log_f32_e32 v43, v43
	v_pk_mul_f32 v[44:45], v[144:145], v[30:31]
	v_pk_mul_f32 v[46:47], v[142:143], v[28:29]
	v_pk_mul_f32 v[30:31], v[40:41], s[68:69] op_sel_hi:[1,0]
	v_pk_mul_f32 v[28:29], v[42:43], s[68:69] op_sel_hi:[1,0]
	v_pk_mul_f32 v[40:41], v[54:55], v[52:53]
	v_pk_mul_f32 v[42:43], v[56:57], v[58:59]
	s_nop 0
	v_pk_mul_f32 v[52:53], v[140:141], v[42:43]
	v_pk_mul_f32 v[42:43], v[2:3], v[40:41]
	v_cvt_pk_bf16_f32 v40, v46, v47
	v_cvt_pk_bf16_f32 v41, v44, v45
	v_lshl_add_u64 v[44:45], s[30:31], 0, v[0:1]
	v_add_co_u32_e32 v44, vcc, 0x4400000, v44
	v_cvt_pk_bf16_f32 v42, v42, v43
	v_cvt_pk_bf16_f32 v43, v52, v53
	s_nop 1
	v_addc_co_u32_e32 v45, vcc, 0, v45, vcc
	global_store_dwordx4 v[44:45], v[40:43], off sc1
.LBB0_423:
	v_cvt_pk_bf16_f32 v32, v32, v33
	v_cvt_pk_bf16_f32 v33, v34, v35
	v_cvt_pk_bf16_f32 v34, v28, v29
	v_lshl_add_u64 v[28:29], s[30:31], 0, v[0:1]
	s_and_b64 vcc, exec, s[8:9]
	v_cvt_pk_bf16_f32 v35, v30, v31
	global_store_dwordx4 v[28:29], v[32:35], off sc1
	s_cbranch_vccnz .LBB0_427
	v_pk_mul_f32 v[28:29], v[14:15], s[96:97] op_sel_hi:[1,0]
	v_pk_mul_f32 v[30:31], v[12:13], s[96:97] op_sel_hi:[1,0]
	v_exp_f32_e32 v28, v28
	v_exp_f32_e32 v30, v30
	v_exp_f32_e32 v31, v31
	v_exp_f32_e32 v29, v29
	v_pk_add_f32 v[30:31], v[30:31], 1.0 op_sel_hi:[1,0]
	v_pk_add_f32 v[28:29], v[28:29], 1.0 op_sel_hi:[1,0]
	v_rcp_f32_e32 v30, v30
	v_rcp_f32_e32 v31, v31
	v_rcp_f32_e32 v28, v28
	v_rcp_f32_e32 v29, v29
	v_pk_mul_f32 v[12:13], v[12:13], v[30:31]
	v_pk_mul_f32 v[30:31], v[16:17], s[96:97] op_sel_hi:[1,0]
	v_pk_mul_f32 v[14:15], v[14:15], v[28:29]
	v_pk_mul_f32 v[28:29], v[18:19], s[96:97] op_sel_hi:[1,0]
	v_exp_f32_e32 v30, v30
	v_exp_f32_e32 v31, v31
	v_exp_f32_e32 v28, v28
	v_exp_f32_e32 v29, v29
	v_pk_add_f32 v[30:31], v[30:31], 1.0 op_sel_hi:[1,0]
	s_nop 0
	v_rcp_f32_e32 v30, v30
	v_pk_add_f32 v[28:29], v[28:29], 1.0 op_sel_hi:[1,0]
	v_rcp_f32_e32 v31, v31
	v_rcp_f32_e32 v28, v28
	v_rcp_f32_e32 v29, v29
	v_pk_mul_f32 v[16:17], v[16:17], v[30:31]
	v_pk_mul_f32 v[18:19], v[18:19], v[28:29]
	s_and_b64 vcc, exec, s[12:13]
	s_cbranch_vccz .LBB0_428

; __device__ __forceinline__ f32x4 silu4(f32x4 v) { return v * sigm4(v); }
; __device__ __forceinline__ u32x4 pack8(f32x4 v0, f32x4 v1) { u32x4 w; w.x = cvt_pk_bf16(v0[0], v0[1]); w.y = cvt_pk_bf16(v0[2], v0[3]); w.z = cvt_pk_bf16(v1[0], v1[1]); w.w = cvt_pk_bf16(v1[2], v1[3]); return w; }
; __device__ __forceinline__ void hg_gate4(f32x4& z, f32x4& key, const f32x4 l) {
;     const f32x4 zc = {__builtin_amdgcn_fmed3f(z[0], -80.f, 80.f), __builtin_amdgcn_fmed3f(z[1], -80.f, 80.f), __builtin_amdgcn_fmed3f(z[2], -80.f, 80.f), __builtin_amdgcn_fmed3f(z[3], -80.f, 80.f)};
;     const f32x4 t = zc * -1.4426950408889634f;
;     const f32x4 e = {__builtin_amdgcn_exp2f(t[0]), __builtin_amdgcn_exp2f(t[1]), __builtin_amdgcn_exp2f(t[2]), __builtin_amdgcn_exp2f(t[3])};
;     const f32x4 den = e + 1.0f;
;     const f32x4 sg = {__builtin_amdgcn_rcpf(den[0]), __builtin_amdgcn_rcpf(den[1]), __builtin_amdgcn_rcpf(den[2]), __builtin_amdgcn_rcpf(den[3])};
;     const f32x4 oml = 1.0f - l;
;     const f32x4 f = l + oml * sg;
;     z = (f32x4){__builtin_amdgcn_logf(f[0]), __builtin_amdgcn_logf(f[1]), __builtin_amdgcn_logf(f[2]), __builtin_amdgcn_logf(f[3])} * 0.6931471805599453f;
;     key = oml * (e * sg);
; }
;     __device__ __forceinline__ void operator()(const f32x4 (&acc)[2][2][4][2], const Unit& u, int wr, int wc, int fr_in, int fq_in) const {
;     ...
;         for (int ai = 0; ai < 2; ++ai)
; #pragma unroll
;             for (int m = 0; m < 4; ++m) {
;                 const int r = row0 + ai * HALF + m * 16;
;                 const size_t roff = (size_t)r * 2048 + cb;
; #pragma unroll
;                 for (int bj = 0; bj < 2; ++bj) {
;                     f32x4 v0 = acc[ai][bj][m][0], v1 = acc[ai][bj][m][1];
;                     if (type == 0) { v0 = silu4(v0); v1 = silu4(v1); }
;                     if (type == 4) { v0 = sigm4(v0); v1 = sigm4(v1); }
;                     if (type == 1 || type == 2) {
;                         f32x4 k0, k1;
;                         hg_gate4(v0, k0, lbv[bj][0]); hg_gate4(v1, k1, lbv[bj][1]);
;                         st16(base + tstride, roff + bj * HALF, pack8(k0, k1));
;                     }
;                     st16(base, roff + bj * HALF, pack8(v0, v1));
;                 }
.LBB0_429:
.LBB0_430:
	v_med3_f32 v12, v12, s95, v182
	v_med3_f32 v13, v13, s95, v182
	v_med3_f32 v14, v14, s95, v182
	v_med3_f32 v15, v15, s95, v182
	v_pk_mul_f32 v[14:15], v[14:15], s[96:97] op_sel_hi:[1,0]
	v_pk_mul_f32 v[12:13], v[12:13], s[96:97] op_sel_hi:[1,0]
	v_exp_f32_e32 v30, v14
	v_exp_f32_e32 v28, v12
	v_exp_f32_e32 v29, v13
	v_exp_f32_e32 v31, v15
	v_med3_f32 v16, v16, s95, v182
	v_med3_f32 v17, v17, s95, v182
	v_pk_add_f32 v[14:15], v[28:29], 1.0 op_sel_hi:[1,0]
	v_pk_add_f32 v[12:13], v[30:31], 1.0 op_sel_hi:[1,0]
	v_rcp_f32_e32 v32, v14
	v_rcp_f32_e32 v33, v15
	v_rcp_f32_e32 v34, v12
	v_rcp_f32_e32 v35, v13
	v_med3_f32 v18, v18, s95, v182
	v_med3_f32 v19, v19, s95, v182
	v_pk_mul_f32 v[18:19], v[18:19], s[96:97] op_sel_hi:[1,0]
	v_pk_mul_f32 v[16:17], v[16:17], s[96:97] op_sel_hi:[1,0]
	v_pk_fma_f32 v[12:13], v[154:155], v[34:35], v[50:51]
	v_pk_fma_f32 v[14:15], v[152:153], v[32:33], v[48:49]
	v_pk_mul_f32 v[28:29], v[28:29], v[32:33]
	v_pk_mul_f32 v[30:31], v[30:31], v[34:35]
	v_exp_f32_e32 v32, v16
	v_exp_f32_e32 v33, v17
	v_exp_f32_e32 v34, v18
	v_exp_f32_e32 v35, v19
	v_log_f32_e32 v40, v14
	v_log_f32_e32 v41, v15
	v_log_f32_e32 v12, v12
	v_log_f32_e32 v13, v13
	v_pk_add_f32 v[16:17], v[34:35], 1.0 op_sel_hi:[1,0]
	v_pk_add_f32 v[18:19], v[32:33], 1.0 op_sel_hi:[1,0]
	v_rcp_f32_e32 v42, v16
	v_pk_mul_f32 v[14:15], v[12:13], s[68:69] op_sel_hi:[1,0]
	v_pk_mul_f32 v[12:13], v[40:41], s[68:69] op_sel_hi:[1,0]
	v_rcp_f32_e32 v40, v18
	v_rcp_f32_e32 v41, v19
	v_rcp_f32_e32 v43, v17
	v_pk_mul_f32 v[30:31], v[154:155], v[30:31]
	v_pk_mul_f32 v[28:29], v[152:153], v[28:29]
	v_pk_fma_f32 v[18:19], v[148:149], v[40:41], v[36:37]
	v_pk_fma_f32 v[16:17], v[150:151], v[42:43], v[38:39]
	v_log_f32_e32 v36, v18
	v_log_f32_e32 v37, v19
	v_log_f32_e32 v16, v16
	v_log_f32_e32 v17, v17
	v_pk_mul_f32 v[32:33], v[32:33], v[40:41]
	v_cvt_pk_bf16_f32 v28, v28, v29
	v_cvt_pk_bf16_f32 v29, v30, v31
	v_pk_mul_f32 v[18:19], v[16:17], s[68:69] op_sel_hi:[1,0]
	v_pk_mul_f32 v[32:33], v[148:149], v[32:33]
	v_pk_mul_f32 v[16:17], v[36:37], s[68:69] op_sel_hi:[1,0]
	v_cvt_pk_bf16_f32 v30, v32, v33
	v_lshl_add_u64 v[32:33], s[30:31], 0, v[0:1]
	v_add_co_u32_e32 v32, vcc, 0x4400000, v32
	v_pk_mul_f32 v[34:35], v[34:35], v[42:43]
	s_nop 0
	v_addc_co_u32_e32 v33, vcc, 0, v33, vcc
	v_pk_mul_f32 v[34:35], v[150:151], v[34:35]
	s_nop 0
	v_cvt_pk_bf16_f32 v31, v34, v35
	global_store_dwordx4 v[32:33], v[28:31], off sc1
.LBB0_431:
	v_cvt_pk_bf16_f32 v12, v12, v13
	v_cvt_pk_bf16_f32 v13, v14, v15
	v_cvt_pk_bf16_f32 v14, v16, v17
	v_lshl_add_u64 v[16:17], s[30:31], 0, v[0:1]
	s_and_b64 vcc, exec, s[8:9]
	v_cvt_pk_bf16_f32 v15, v18, v19
	global_store_dwordx4 v[16:17], v[12:15], off sc1
	s_cbranch_vccnz .LBB0_435
	s_nop 0
	v_pk_mul_f32 v[12:13], v[6:7], s[96:97] op_sel_hi:[1,0]
	v_pk_mul_f32 v[14:15], v[4:5], s[96:97] op_sel_hi:[1,0]
	v_exp_f32_e32 v12, v12
	v_exp_f32_e32 v14, v14
	v_exp_f32_e32 v15, v15
	v_exp_f32_e32 v13, v13
	v_pk_add_f32 v[14:15], v[14:15], 1.0 op_sel_hi:[1,0]
	v_pk_add_f32 v[12:13], v[12:13], 1.0 op_sel_hi:[1,0]
	v_rcp_f32_e32 v14, v14
	v_rcp_f32_e32 v15, v15
	v_rcp_f32_e32 v12, v12
	v_rcp_f32_e32 v13, v13
	v_pk_mul_f32 v[4:5], v[4:5], v[14:15]
	v_pk_mul_f32 v[14:15], v[8:9], s[96:97] op_sel_hi:[1,0]
	v_pk_mul_f32 v[6:7], v[6:7], v[12:13]
	v_pk_mul_f32 v[12:13], v[10:11], s[96:97] op_sel_hi:[1,0]
	v_exp_f32_e32 v14, v14
	v_exp_f32_e32 v15, v15
	v_exp_f32_e32 v12, v12
	v_exp_f32_e32 v13, v13
	v_pk_add_f32 v[14:15], v[14:15], 1.0 op_sel_hi:[1,0]
	s_nop 0
	v_rcp_f32_e32 v14, v14
	v_pk_add_f32 v[12:13], v[12:13], 1.0 op_sel_hi:[1,0]
	v_rcp_f32_e32 v15, v15
	v_rcp_f32_e32 v12, v12
	v_rcp_f32_e32 v13, v13
	v_pk_mul_f32 v[8:9], v[8:9], v[14:15]
	v_pk_mul_f32 v[10:11], v[10:11], v[12:13]
	s_and_b64 vcc, exec, s[12:13]
	s_cbranch_vccz .LBB0_436

; __device__ __forceinline__ void hg_gate4(f32x4& z, f32x4& key, const f32x4 l) {
;     const f32x4 zc = {__builtin_amdgcn_fmed3f(z[0], -80.f, 80.f), __builtin_amdgcn_fmed3f(z[1], -80.f, 80.f), __builtin_amdgcn_fmed3f(z[2], -80.f, 80.f), __builtin_amdgcn_fmed3f(z[3], -80.f, 80.f)};
;     const f32x4 t = zc * -1.4426950408889634f;
;     const f32x4 e = {__builtin_amdgcn_exp2f(t[0]), __builtin_amdgcn_exp2f(t[1]), __builtin_amdgcn_exp2f(t[2]), __builtin_amdgcn_exp2f(t[3])};
;     const f32x4 den = e + 1.0f;
;     const f32x4 sg = {__builtin_amdgcn_rcpf(den[0]), __builtin_amdgcn_rcpf(den[1]), __builtin_amdgcn_rcpf(den[2]), __builtin_amdgcn_rcpf(den[3])};
;     const f32x4 oml = 1.0f - l;
;     const f32x4 f = l + oml * sg;
;     z = (f32x4){__builtin_amdgcn_logf(f[0]), __builtin_amdgcn_logf(f[1]), __builtin_amdgcn_logf(f[2]), __builtin_amdgcn_logf(f[3])} * 0.6931471805599453f;
;     key = oml * (e * sg);
; }
;     __device__ __forceinline__ void operator()(const f32x4 (&acc)[2][2][4][2], const Unit& u, int wr, int wc, int fr_in, int fq_in) const {
;     ...
;         for (int ai = 0; ai < 2; ++ai)
; #pragma unroll
;             for (int m = 0; m < 4; ++m) {
;                 const int r = row0 + ai * HALF + m * 16;
;                 const size_t roff = (size_t)r * 2048 + cb;
; #pragma unroll
;                 for (int bj = 0; bj < 2; ++bj) {
;                     f32x4 v0 = acc[ai][bj][m][0], v1 = acc[ai][bj][m][1];
;                     if (type == 0) { v0 = silu4(v0); v1 = silu4(v1); }
;                     if (type == 4) { v0 = sigm4(v0); v1 = sigm4(v1); }
;                     if (type == 1 || type == 2) {
;                         f32x4 k0, k1;
;                         hg_gate4(v0, k0, lbv[bj][0]); hg_gate4(v1, k1, lbv[bj][1]);
;                         st16(base + tstride, roff + bj * HALF, pack8(k0, k1));
;                     }
;                     st16(base, roff + bj * HALF, pack8(v0, v1));
;                 }
; template <class Epi, class Sched, bool ALIGN_EPI = false, bool SP2 = false>
; __device__ __forceinline__ void gemm_phase(PG8_LAS unsigned char* lds, const Gemm g, const Sched& S, const Epi& E) {
;     ...
;         if (!kp_first) if constexpr (!Epi::AFTER_DRAIN) { E(acc, cur, wr, wc, fr, fq); if constexpr (REP_EPI > 1 && Epi::REP2) { asm volatile("" ::: "memory"); E(acc, cur, wr, wc, fr, fq); } S.done(cur); }
;         asm volatile("" ::: "memory");
.LBB0_438:
	v_med3_f32 v4, v4, s95, v182
	v_med3_f32 v5, v5, s95, v182
	v_med3_f32 v6, v6, s95, v182
	v_med3_f32 v7, v7, s95, v182
	v_pk_mul_f32 v[6:7], v[6:7], s[96:97] op_sel_hi:[1,0]
	v_pk_mul_f32 v[4:5], v[4:5], s[96:97] op_sel_hi:[1,0]
	v_exp_f32_e32 v14, v6
	v_exp_f32_e32 v12, v4
	v_exp_f32_e32 v13, v5
	v_exp_f32_e32 v15, v7
	v_med3_f32 v8, v8, s95, v182
	v_med3_f32 v9, v9, s95, v182
	v_pk_add_f32 v[6:7], v[12:13], 1.0 op_sel_hi:[1,0]
	v_pk_add_f32 v[4:5], v[14:15], 1.0 op_sel_hi:[1,0]
	v_rcp_f32_e32 v16, v6
	v_rcp_f32_e32 v17, v7
	v_rcp_f32_e32 v18, v4
	v_rcp_f32_e32 v19, v5
	v_med3_f32 v10, v10, s95, v182
	v_med3_f32 v11, v11, s95, v182
	v_pk_mul_f32 v[10:11], v[10:11], s[96:97] op_sel_hi:[1,0]
	v_pk_mul_f32 v[8:9], v[8:9], s[96:97] op_sel_hi:[1,0]
	v_pk_fma_f32 v[4:5], v[144:145], v[18:19], v[26:27]
	v_pk_fma_f32 v[6:7], v[142:143], v[16:17], v[24:25]
	v_pk_mul_f32 v[12:13], v[12:13], v[16:17]
	v_pk_mul_f32 v[14:15], v[14:15], v[18:19]
	v_exp_f32_e32 v16, v8
	v_exp_f32_e32 v17, v9
	v_exp_f32_e32 v18, v10
	v_exp_f32_e32 v19, v11
	v_log_f32_e32 v24, v6
	v_log_f32_e32 v25, v7
	v_log_f32_e32 v4, v4
	v_log_f32_e32 v5, v5
	v_pk_add_f32 v[8:9], v[18:19], 1.0 op_sel_hi:[1,0]
	v_pk_add_f32 v[10:11], v[16:17], 1.0 op_sel_hi:[1,0]
	v_rcp_f32_e32 v26, v8
	v_pk_mul_f32 v[6:7], v[4:5], s[68:69] op_sel_hi:[1,0]
	v_pk_mul_f32 v[4:5], v[24:25], s[68:69] op_sel_hi:[1,0]
	v_rcp_f32_e32 v24, v10
	v_rcp_f32_e32 v25, v11
	v_rcp_f32_e32 v27, v9
	v_pk_mul_f32 v[14:15], v[144:145], v[14:15]
	v_pk_mul_f32 v[12:13], v[142:143], v[12:13]
	v_pk_fma_f32 v[10:11], v[2:3], v[24:25], v[20:21]
	v_pk_fma_f32 v[8:9], v[140:141], v[26:27], v[22:23]
	v_log_f32_e32 v20, v10
	v_log_f32_e32 v21, v11
	v_log_f32_e32 v8, v8
	v_log_f32_e32 v9, v9
	v_pk_mul_f32 v[16:17], v[16:17], v[24:25]
	v_cvt_pk_bf16_f32 v12, v12, v13
	v_cvt_pk_bf16_f32 v13, v14, v15
	v_pk_mul_f32 v[10:11], v[8:9], s[68:69] op_sel_hi:[1,0]
	v_pk_mul_f32 v[2:3], v[2:3], v[16:17]
	v_pk_mul_f32 v[8:9], v[20:21], s[68:69] op_sel_hi:[1,0]
	v_cvt_pk_bf16_f32 v14, v2, v3
	v_lshl_add_u64 v[2:3], s[30:31], 0, v[0:1]
	v_add_co_u32_e32 v2, vcc, 0x4400000, v2
	v_pk_mul_f32 v[18:19], v[18:19], v[26:27]
	s_nop 0
	v_addc_co_u32_e32 v3, vcc, 0, v3, vcc
	v_pk_mul_f32 v[18:19], v[140:141], v[18:19]
	s_nop 0
	v_cvt_pk_bf16_f32 v15, v18, v19
	global_store_dwordx4 v[2:3], v[12:15], off sc1
.LBB0_439:
	v_cvt_pk_bf16_f32 v2, v4, v5
	v_cvt_pk_bf16_f32 v3, v6, v7
	v_lshl_add_u64 v[6:7], s[30:31], 0, v[0:1]
	v_cvt_pk_bf16_f32 v4, v8, v9
	v_cvt_pk_bf16_f32 v5, v10, v11
	global_store_dwordx4 v[6:7], v[2:5], off sc1
	s_andn2_b64 vcc, exec, s[28:29]
	s_mov_b64 s[8:9], -1
	s_cbranch_vccnz .LBB0_281
	s_andn2_b64 vcc, exec, s[14:15]
	s_cbranch_vccnz .LBB0_280
	s_barrier
	s_branch .LBB0_280

; __device__ __forceinline__ f32x4 silu4(f32x4 v) { return v * sigm4(v); }
; __device__ __forceinline__ u32x4 pack8(f32x4 v0, f32x4 v1) { u32x4 w; w.x = cvt_pk_bf16(v0[0], v0[1]); w.y = cvt_pk_bf16(v0[2], v0[3]); w.z = cvt_pk_bf16(v1[0], v1[1]); w.w = cvt_pk_bf16(v1[2], v1[3]); return w; }
;     __device__ __forceinline__ void store_rows(const f32x4& a0, const f32x4& a1, const f32x4& b0, const f32x4& b1, int type, bf16_t* base, size_t off) const {
;         f32x4 x0 = a0, x1 = a1, y0 = b0, y1 = b1;
;         if (type == 1) { x0 = x0 * 0.0625f; x1 = x1 * 0.0625f; y0 = y0 * 0.0625f; y1 = y1 * 0.0625f; }
;         if (type == 3) { x0 = silu4(x0); x1 = silu4(x1); y0 = silu4(y0); y1 = silu4(y1); }
;         st16(base, off, pack8(x0, x1));
;         st16(base, off + HALF, pack8(y0, y1));
;     __device__ __forceinline__ void operator()(const f32x4 (&acc)[2][2][4][2], const Unit& u, int wr, int wc, int fr_in, int fq_in) const {
;     ...
;         if (!rope) {
; #pragma unroll
;             for (int ai = 0; ai < 2; ++ai)
; #pragma unroll
;                 for (int m = 0; m < 4; ++m) store_rows(acc[ai][0][m][0], acc[ai][0][m][1], acc[ai][1][m][0], acc[ai][1][m][1], type, base, (size_t)(row0 + ai * HALF + m * 16) * 2048 + coff);
.LBB0_657:
	v_lshlrev_b64 v[150:151], 1, v[148:149]
	v_lshl_add_u32 v0, v2, 12, v150
	v_cvt_pk_bf16_f32 v136, v136, v137
	v_cvt_pk_bf16_f32 v137, v138, v139
	v_cvt_pk_bf16_f32 v138, v144, v145
	v_lshl_add_u64 v[144:145], s[30:31], 0, v[0:1]
	v_cvt_pk_bf16_f32 v139, v146, v147
	global_store_dwordx4 v[144:145], v[136:139], off sc1
	v_cvt_pk_bf16_f32 v132, v132, v133
	v_cvt_pk_bf16_f32 v133, v134, v135
	v_cvt_pk_bf16_f32 v134, v140, v141
	v_cvt_pk_bf16_f32 v135, v142, v143
	v_add_u32_e32 v3, 0x100, v0
	global_store_dwordx4 v3, v[132:135], s[30:31] sc1
	v_cndmask_b32_e64 v3, 0, 1, s[8:9]
	v_mov_b64_e32 v[138:139], v[106:107]
	v_mov_b64_e32 v[146:147], v[102:103]
	v_mov_b64_e32 v[134:135], v[114:115]
	v_mov_b64_e32 v[142:143], v[110:111]
	v_cmp_ne_u32_e64 s[6:7], 1, v3
	s_andn2_b64 vcc, exec, s[8:9]
	v_mov_b64_e32 v[136:137], v[104:105]
	v_mov_b64_e32 v[144:145], v[100:101]
	v_mov_b64_e32 v[132:133], v[112:113]
	v_mov_b64_e32 v[140:141], v[108:109]
	s_cbranch_vccnz .LBB0_659
	v_pk_mul_f32 v[138:139], v[106:107], s[54:55] op_sel_hi:[1,0]
	v_pk_mul_f32 v[136:137], v[104:105], s[54:55] op_sel_hi:[1,0]
	v_pk_mul_f32 v[146:147], v[102:103], s[54:55] op_sel_hi:[1,0]
	v_pk_mul_f32 v[144:145], v[100:101], s[54:55] op_sel_hi:[1,0]
	v_pk_mul_f32 v[134:135], v[114:115], s[54:55] op_sel_hi:[1,0]
	v_pk_mul_f32 v[132:133], v[112:113], s[54:55] op_sel_hi:[1,0]
	v_pk_mul_f32 v[142:143], v[110:111], s[54:55] op_sel_hi:[1,0]
	v_pk_mul_f32 v[140:141], v[108:109], s[54:55] op_sel_hi:[1,0]

; __device__ __forceinline__ f32x4 silu4(f32x4 v) { return v * sigm4(v); }
; __device__ __forceinline__ u32x4 pack8(f32x4 v0, f32x4 v1) { u32x4 w; w.x = cvt_pk_bf16(v0[0], v0[1]); w.y = cvt_pk_bf16(v0[2], v0[3]); w.z = cvt_pk_bf16(v1[0], v1[1]); w.w = cvt_pk_bf16(v1[2], v1[3]); return w; }
;     __device__ __forceinline__ void store_rows(const f32x4& a0, const f32x4& a1, const f32x4& b0, const f32x4& b1, int type, bf16_t* base, size_t off) const {
;         f32x4 x0 = a0, x1 = a1, y0 = b0, y1 = b1;
;         if (type == 1) { x0 = x0 * 0.0625f; x1 = x1 * 0.0625f; y0 = y0 * 0.0625f; y1 = y1 * 0.0625f; }
;         if (type == 3) { x0 = silu4(x0); x1 = silu4(x1); y0 = silu4(y0); y1 = silu4(y1); }
;         st16(base, off, pack8(x0, x1));
;         st16(base, off + HALF, pack8(y0, y1));
;     __device__ __forceinline__ void operator()(const f32x4 (&acc)[2][2][4][2], const Unit& u, int wr, int wc, int fr_in, int fq_in) const {
;     ...
;         if (!rope) {
; #pragma unroll
;             for (int ai = 0; ai < 2; ++ai)
; #pragma unroll
;                 for (int m = 0; m < 4; ++m) store_rows(acc[ai][0][m][0], acc[ai][0][m][1], acc[ai][1][m][0], acc[ai][1][m][1], type, base, (size_t)(row0 + ai * HALF + m * 16) * 2048 + coff);
.LBB0_661:
	v_add_u32_e32 v3, 0x10000, v0
	v_cvt_pk_bf16_f32 v136, v136, v137
	v_cvt_pk_bf16_f32 v137, v138, v139
	v_cvt_pk_bf16_f32 v138, v144, v145
	v_and_b32_e32 v144, -2, v3
	v_mov_b32_e32 v145, v1
	v_lshl_add_u64 v[144:145], s[30:31], 0, v[144:145]
	v_add_u32_e32 v3, 0x10100, v0
	v_cvt_pk_bf16_f32 v139, v146, v147
	global_store_dwordx4 v[144:145], v[136:139], off sc1
	v_cvt_pk_bf16_f32 v132, v132, v133
	v_cvt_pk_bf16_f32 v133, v134, v135
	v_cvt_pk_bf16_f32 v134, v140, v141
	v_cvt_pk_bf16_f32 v135, v142, v143
	v_and_b32_e32 v3, -2, v3
	global_store_dwordx4 v3, v[132:135], s[30:31] sc1
	v_mov_b64_e32 v[138:139], v[90:91]
	v_mov_b64_e32 v[146:147], v[86:87]
	v_mov_b64_e32 v[134:135], v[98:99]
	v_mov_b64_e32 v[142:143], v[94:95]
	s_and_b64 vcc, exec, s[6:7]
	v_mov_b64_e32 v[136:137], v[88:89]
	v_mov_b64_e32 v[144:145], v[84:85]
	v_mov_b64_e32 v[132:133], v[96:97]
	v_mov_b64_e32 v[140:141], v[92:93]
	s_cbranch_vccnz .LBB0_663
	v_pk_mul_f32 v[138:139], v[90:91], s[54:55] op_sel_hi:[1,0]
	v_pk_mul_f32 v[136:137], v[88:89], s[54:55] op_sel_hi:[1,0]
	v_pk_mul_f32 v[146:147], v[86:87], s[54:55] op_sel_hi:[1,0]
	v_pk_mul_f32 v[144:145], v[84:85], s[54:55] op_sel_hi:[1,0]
	v_pk_mul_f32 v[134:135], v[98:99], s[54:55] op_sel_hi:[1,0]
	v_pk_mul_f32 v[132:133], v[96:97], s[54:55] op_sel_hi:[1,0]
	v_pk_mul_f32 v[142:143], v[94:95], s[54:55] op_sel_hi:[1,0]
	v_pk_mul_f32 v[140:141], v[92:93], s[54:55] op_sel_hi:[1,0]

; __device__ __forceinline__ f32x4 silu4(f32x4 v) { return v * sigm4(v); }
; __device__ __forceinline__ u32x4 pack8(f32x4 v0, f32x4 v1) { u32x4 w; w.x = cvt_pk_bf16(v0[0], v0[1]); w.y = cvt_pk_bf16(v0[2], v0[3]); w.z = cvt_pk_bf16(v1[0], v1[1]); w.w = cvt_pk_bf16(v1[2], v1[3]); return w; }
;     __device__ __forceinline__ void store_rows(const f32x4& a0, const f32x4& a1, const f32x4& b0, const f32x4& b1, int type, bf16_t* base, size_t off) const {
;         f32x4 x0 = a0, x1 = a1, y0 = b0, y1 = b1;
;         if (type == 1) { x0 = x0 * 0.0625f; x1 = x1 * 0.0625f; y0 = y0 * 0.0625f; y1 = y1 * 0.0625f; }
;         if (type == 3) { x0 = silu4(x0); x1 = silu4(x1); y0 = silu4(y0); y1 = silu4(y1); }
;         st16(base, off, pack8(x0, x1));
;         st16(base, off + HALF, pack8(y0, y1));
;     __device__ __forceinline__ void operator()(const f32x4 (&acc)[2][2][4][2], const Unit& u, int wr, int wc, int fr_in, int fq_in) const {
;     ...
;         if (!rope) {
; #pragma unroll
;             for (int ai = 0; ai < 2; ++ai)
; #pragma unroll
;                 for (int m = 0; m < 4; ++m) store_rows(acc[ai][0][m][0], acc[ai][0][m][1], acc[ai][1][m][0], acc[ai][1][m][1], type, base, (size_t)(row0 + ai * HALF + m * 16) * 2048 + coff);
.LBB0_665:
	v_add_u32_e32 v3, 0x20000, v0
	v_cvt_pk_bf16_f32 v136, v136, v137
	v_cvt_pk_bf16_f32 v137, v138, v139
	v_cvt_pk_bf16_f32 v138, v144, v145
	v_and_b32_e32 v144, -2, v3
	v_mov_b32_e32 v145, v1
	v_lshl_add_u64 v[144:145], s[30:31], 0, v[144:145]
	v_add_u32_e32 v3, 0x20100, v0
	v_cvt_pk_bf16_f32 v139, v146, v147
	global_store_dwordx4 v[144:145], v[136:139], off sc1
	v_cvt_pk_bf16_f32 v132, v132, v133
	v_cvt_pk_bf16_f32 v133, v134, v135
	v_cvt_pk_bf16_f32 v134, v140, v141
	v_cvt_pk_bf16_f32 v135, v142, v143
	v_and_b32_e32 v3, -2, v3
	global_store_dwordx4 v3, v[132:135], s[30:31] sc1
	v_mov_b64_e32 v[138:139], v[74:75]
	v_mov_b64_e32 v[146:147], v[70:71]
	v_mov_b64_e32 v[134:135], v[82:83]
	v_mov_b64_e32 v[142:143], v[78:79]
	s_and_b64 vcc, exec, s[6:7]
	v_mov_b64_e32 v[136:137], v[72:73]
	v_mov_b64_e32 v[144:145], v[68:69]
	v_mov_b64_e32 v[132:133], v[80:81]
	v_mov_b64_e32 v[140:141], v[76:77]
	s_cbranch_vccnz .LBB0_667
	v_pk_mul_f32 v[138:139], v[74:75], s[54:55] op_sel_hi:[1,0]
	v_pk_mul_f32 v[136:137], v[72:73], s[54:55] op_sel_hi:[1,0]
	v_pk_mul_f32 v[146:147], v[70:71], s[54:55] op_sel_hi:[1,0]
	v_pk_mul_f32 v[144:145], v[68:69], s[54:55] op_sel_hi:[1,0]
	v_pk_mul_f32 v[134:135], v[82:83], s[54:55] op_sel_hi:[1,0]
	v_pk_mul_f32 v[132:133], v[80:81], s[54:55] op_sel_hi:[1,0]
	v_pk_mul_f32 v[142:143], v[78:79], s[54:55] op_sel_hi:[1,0]
	v_pk_mul_f32 v[140:141], v[76:77], s[54:55] op_sel_hi:[1,0]

; __device__ __forceinline__ f32x4 silu4(f32x4 v) { return v * sigm4(v); }
; __device__ __forceinline__ u32x4 pack8(f32x4 v0, f32x4 v1) { u32x4 w; w.x = cvt_pk_bf16(v0[0], v0[1]); w.y = cvt_pk_bf16(v0[2], v0[3]); w.z = cvt_pk_bf16(v1[0], v1[1]); w.w = cvt_pk_bf16(v1[2], v1[3]); return w; }
;     __device__ __forceinline__ void store_rows(const f32x4& a0, const f32x4& a1, const f32x4& b0, const f32x4& b1, int type, bf16_t* base, size_t off) const {
;         f32x4 x0 = a0, x1 = a1, y0 = b0, y1 = b1;
;         if (type == 1) { x0 = x0 * 0.0625f; x1 = x1 * 0.0625f; y0 = y0 * 0.0625f; y1 = y1 * 0.0625f; }
;         if (type == 3) { x0 = silu4(x0); x1 = silu4(x1); y0 = silu4(y0); y1 = silu4(y1); }
;         st16(base, off, pack8(x0, x1));
;         st16(base, off + HALF, pack8(y0, y1));
;     __device__ __forceinline__ void operator()(const f32x4 (&acc)[2][2][4][2], const Unit& u, int wr, int wc, int fr_in, int fq_in) const {
;     ...
;         if (!rope) {
; #pragma unroll
;             for (int ai = 0; ai < 2; ++ai)
; #pragma unroll
;                 for (int m = 0; m < 4; ++m) store_rows(acc[ai][0][m][0], acc[ai][0][m][1], acc[ai][1][m][0], acc[ai][1][m][1], type, base, (size_t)(row0 + ai * HALF + m * 16) * 2048 + coff);
.LBB0_669:
	v_add_u32_e32 v3, 0x30000, v0
	v_cvt_pk_bf16_f32 v136, v136, v137
	v_cvt_pk_bf16_f32 v137, v138, v139
	v_cvt_pk_bf16_f32 v138, v144, v145
	v_and_b32_e32 v144, -2, v3
	v_mov_b32_e32 v145, v1
	v_lshl_add_u64 v[144:145], s[30:31], 0, v[144:145]
	v_add_u32_e32 v3, 0x30100, v0
	v_cvt_pk_bf16_f32 v139, v146, v147
	global_store_dwordx4 v[144:145], v[136:139], off sc1
	v_cvt_pk_bf16_f32 v132, v132, v133
	v_cvt_pk_bf16_f32 v133, v134, v135
	v_cvt_pk_bf16_f32 v134, v140, v141
	v_cvt_pk_bf16_f32 v135, v142, v143
	v_and_b32_e32 v3, -2, v3
	global_store_dwordx4 v3, v[132:135], s[30:31] sc1
	v_mov_b64_e32 v[138:139], v[58:59]
	v_mov_b64_e32 v[146:147], v[54:55]
	v_mov_b64_e32 v[134:135], v[66:67]
	v_mov_b64_e32 v[142:143], v[62:63]
	s_and_b64 vcc, exec, s[6:7]
	v_mov_b64_e32 v[136:137], v[56:57]
	v_mov_b64_e32 v[144:145], v[52:53]
	v_mov_b64_e32 v[132:133], v[64:65]
	v_mov_b64_e32 v[140:141], v[60:61]
	s_cbranch_vccnz .LBB0_671
	v_pk_mul_f32 v[138:139], v[58:59], s[54:55] op_sel_hi:[1,0]
	v_pk_mul_f32 v[136:137], v[56:57], s[54:55] op_sel_hi:[1,0]
	v_pk_mul_f32 v[146:147], v[54:55], s[54:55] op_sel_hi:[1,0]
	v_pk_mul_f32 v[144:145], v[52:53], s[54:55] op_sel_hi:[1,0]
	v_pk_mul_f32 v[134:135], v[66:67], s[54:55] op_sel_hi:[1,0]
	v_pk_mul_f32 v[132:133], v[64:65], s[54:55] op_sel_hi:[1,0]
	v_pk_mul_f32 v[142:143], v[62:63], s[54:55] op_sel_hi:[1,0]
	v_pk_mul_f32 v[140:141], v[60:61], s[54:55] op_sel_hi:[1,0]

; __device__ __forceinline__ f32x4 silu4(f32x4 v) { return v * sigm4(v); }
; __device__ __forceinline__ u32x4 pack8(f32x4 v0, f32x4 v1) { u32x4 w; w.x = cvt_pk_bf16(v0[0], v0[1]); w.y = cvt_pk_bf16(v0[2], v0[3]); w.z = cvt_pk_bf16(v1[0], v1[1]); w.w = cvt_pk_bf16(v1[2], v1[3]); return w; }
;     __device__ __forceinline__ void store_rows(const f32x4& a0, const f32x4& a1, const f32x4& b0, const f32x4& b1, int type, bf16_t* base, size_t off) const {
;         f32x4 x0 = a0, x1 = a1, y0 = b0, y1 = b1;
;         if (type == 1) { x0 = x0 * 0.0625f; x1 = x1 * 0.0625f; y0 = y0 * 0.0625f; y1 = y1 * 0.0625f; }
;         if (type == 3) { x0 = silu4(x0); x1 = silu4(x1); y0 = silu4(y0); y1 = silu4(y1); }
;         st16(base, off, pack8(x0, x1));
;         st16(base, off + HALF, pack8(y0, y1));
;     __device__ __forceinline__ void operator()(const f32x4 (&acc)[2][2][4][2], const Unit& u, int wr, int wc, int fr_in, int fq_in) const {
;     ...
;         if (!rope) {
; #pragma unroll
;             for (int ai = 0; ai < 2; ++ai)
; #pragma unroll
;                 for (int m = 0; m < 4; ++m) store_rows(acc[ai][0][m][0], acc[ai][0][m][1], acc[ai][1][m][0], acc[ai][1][m][1], type, base, (size_t)(row0 + ai * HALF + m * 16) * 2048 + coff);
.LBB0_673:
	v_add_u32_e32 v3, 0x80000, v0
	v_cvt_pk_bf16_f32 v136, v136, v137
	v_cvt_pk_bf16_f32 v137, v138, v139
	v_cvt_pk_bf16_f32 v138, v144, v145
	v_and_b32_e32 v144, -2, v3
	v_mov_b32_e32 v145, v1
	v_lshl_add_u64 v[144:145], s[30:31], 0, v[144:145]
	v_add_u32_e32 v3, 0x80100, v0
	v_cvt_pk_bf16_f32 v139, v146, v147
	global_store_dwordx4 v[144:145], v[136:139], off sc1
	v_cvt_pk_bf16_f32 v132, v132, v133
	v_cvt_pk_bf16_f32 v133, v134, v135
	v_cvt_pk_bf16_f32 v134, v140, v141
	v_cvt_pk_bf16_f32 v135, v142, v143
	v_and_b32_e32 v3, -2, v3
	global_store_dwordx4 v3, v[132:135], s[30:31] sc1
	v_mov_b64_e32 v[138:139], v[42:43]
	v_mov_b64_e32 v[146:147], v[38:39]
	v_mov_b64_e32 v[134:135], v[50:51]
	v_mov_b64_e32 v[142:143], v[46:47]
	s_and_b64 vcc, exec, s[6:7]
	v_mov_b64_e32 v[136:137], v[40:41]
	v_mov_b64_e32 v[144:145], v[36:37]
	v_mov_b64_e32 v[132:133], v[48:49]
	v_mov_b64_e32 v[140:141], v[44:45]
	s_cbranch_vccnz .LBB0_675
	v_pk_mul_f32 v[138:139], v[42:43], s[54:55] op_sel_hi:[1,0]
	v_pk_mul_f32 v[136:137], v[40:41], s[54:55] op_sel_hi:[1,0]
	v_pk_mul_f32 v[146:147], v[38:39], s[54:55] op_sel_hi:[1,0]
	v_pk_mul_f32 v[144:145], v[36:37], s[54:55] op_sel_hi:[1,0]
	v_pk_mul_f32 v[134:135], v[50:51], s[54:55] op_sel_hi:[1,0]
	v_pk_mul_f32 v[132:133], v[48:49], s[54:55] op_sel_hi:[1,0]
	v_pk_mul_f32 v[142:143], v[46:47], s[54:55] op_sel_hi:[1,0]
	v_pk_mul_f32 v[140:141], v[44:45], s[54:55] op_sel_hi:[1,0]

; __device__ __forceinline__ f32x4 silu4(f32x4 v) { return v * sigm4(v); }
; __device__ __forceinline__ u32x4 pack8(f32x4 v0, f32x4 v1) { u32x4 w; w.x = cvt_pk_bf16(v0[0], v0[1]); w.y = cvt_pk_bf16(v0[2], v0[3]); w.z = cvt_pk_bf16(v1[0], v1[1]); w.w = cvt_pk_bf16(v1[2], v1[3]); return w; }
;     __device__ __forceinline__ void store_rows(const f32x4& a0, const f32x4& a1, const f32x4& b0, const f32x4& b1, int type, bf16_t* base, size_t off) const {
;         f32x4 x0 = a0, x1 = a1, y0 = b0, y1 = b1;
;         if (type == 1) { x0 = x0 * 0.0625f; x1 = x1 * 0.0625f; y0 = y0 * 0.0625f; y1 = y1 * 0.0625f; }
;         if (type == 3) { x0 = silu4(x0); x1 = silu4(x1); y0 = silu4(y0); y1 = silu4(y1); }
;         st16(base, off, pack8(x0, x1));
;         st16(base, off + HALF, pack8(y0, y1));
;     __device__ __forceinline__ void operator()(const f32x4 (&acc)[2][2][4][2], const Unit& u, int wr, int wc, int fr_in, int fq_in) const {
;     ...
;         if (!rope) {
; #pragma unroll
;             for (int ai = 0; ai < 2; ++ai)
; #pragma unroll
;                 for (int m = 0; m < 4; ++m) store_rows(acc[ai][0][m][0], acc[ai][0][m][1], acc[ai][1][m][0], acc[ai][1][m][1], type, base, (size_t)(row0 + ai * HALF + m * 16) * 2048 + coff);
.LBB0_677:
	v_add_u32_e32 v3, 0x90000, v0
	v_cvt_pk_bf16_f32 v136, v136, v137
	v_cvt_pk_bf16_f32 v137, v138, v139
	v_cvt_pk_bf16_f32 v138, v144, v145
	v_and_b32_e32 v144, -2, v3
	v_mov_b32_e32 v145, v1
	v_lshl_add_u64 v[144:145], s[30:31], 0, v[144:145]
	v_add_u32_e32 v3, 0x90100, v0
	v_cvt_pk_bf16_f32 v139, v146, v147
	global_store_dwordx4 v[144:145], v[136:139], off sc1
	v_cvt_pk_bf16_f32 v132, v132, v133
	v_cvt_pk_bf16_f32 v133, v134, v135
	v_cvt_pk_bf16_f32 v134, v140, v141
	v_cvt_pk_bf16_f32 v135, v142, v143
	v_and_b32_e32 v3, -2, v3
	global_store_dwordx4 v3, v[132:135], s[30:31] sc1
	v_mov_b64_e32 v[138:139], v[26:27]
	v_mov_b64_e32 v[146:147], v[22:23]
	v_mov_b64_e32 v[134:135], v[34:35]
	v_mov_b64_e32 v[142:143], v[30:31]
	s_and_b64 vcc, exec, s[6:7]
	v_mov_b64_e32 v[136:137], v[24:25]
	v_mov_b64_e32 v[144:145], v[20:21]
	v_mov_b64_e32 v[132:133], v[32:33]
	v_mov_b64_e32 v[140:141], v[28:29]
	s_cbranch_vccnz .LBB0_679
	v_pk_mul_f32 v[138:139], v[26:27], s[54:55] op_sel_hi:[1,0]
	v_pk_mul_f32 v[136:137], v[24:25], s[54:55] op_sel_hi:[1,0]
	v_pk_mul_f32 v[146:147], v[22:23], s[54:55] op_sel_hi:[1,0]
	v_pk_mul_f32 v[144:145], v[20:21], s[54:55] op_sel_hi:[1,0]
	v_pk_mul_f32 v[134:135], v[34:35], s[54:55] op_sel_hi:[1,0]
	v_pk_mul_f32 v[132:133], v[32:33], s[54:55] op_sel_hi:[1,0]
	v_pk_mul_f32 v[142:143], v[30:31], s[54:55] op_sel_hi:[1,0]
	v_pk_mul_f32 v[140:141], v[28:29], s[54:55] op_sel_hi:[1,0]

; __device__ __forceinline__ f32x4 silu4(f32x4 v) { return v * sigm4(v); }
; __device__ __forceinline__ u32x4 pack8(f32x4 v0, f32x4 v1) { u32x4 w; w.x = cvt_pk_bf16(v0[0], v0[1]); w.y = cvt_pk_bf16(v0[2], v0[3]); w.z = cvt_pk_bf16(v1[0], v1[1]); w.w = cvt_pk_bf16(v1[2], v1[3]); return w; }
;     __device__ __forceinline__ void store_rows(const f32x4& a0, const f32x4& a1, const f32x4& b0, const f32x4& b1, int type, bf16_t* base, size_t off) const {
;         f32x4 x0 = a0, x1 = a1, y0 = b0, y1 = b1;
;         if (type == 1) { x0 = x0 * 0.0625f; x1 = x1 * 0.0625f; y0 = y0 * 0.0625f; y1 = y1 * 0.0625f; }
;         if (type == 3) { x0 = silu4(x0); x1 = silu4(x1); y0 = silu4(y0); y1 = silu4(y1); }
;         st16(base, off, pack8(x0, x1));
;         st16(base, off + HALF, pack8(y0, y1));
;     __device__ __forceinline__ void operator()(const f32x4 (&acc)[2][2][4][2], const Unit& u, int wr, int wc, int fr_in, int fq_in) const {
;     ...
;         if (!rope) {
; #pragma unroll
;             for (int ai = 0; ai < 2; ++ai)
; #pragma unroll
;                 for (int m = 0; m < 4; ++m) store_rows(acc[ai][0][m][0], acc[ai][0][m][1], acc[ai][1][m][0], acc[ai][1][m][1], type, base, (size_t)(row0 + ai * HALF + m * 16) * 2048 + coff);
.LBB0_681:
	v_add_u32_e32 v3, 0xa0000, v0
	v_cvt_pk_bf16_f32 v136, v136, v137
	v_cvt_pk_bf16_f32 v137, v138, v139
	v_cvt_pk_bf16_f32 v138, v144, v145
	v_and_b32_e32 v144, -2, v3
	v_mov_b32_e32 v145, v1
	v_lshl_add_u64 v[144:145], s[30:31], 0, v[144:145]
	v_add_u32_e32 v0, 0xa0100, v0
	v_cvt_pk_bf16_f32 v139, v146, v147
	global_store_dwordx4 v[144:145], v[136:139], off sc1
	v_cvt_pk_bf16_f32 v132, v132, v133
	v_cvt_pk_bf16_f32 v133, v134, v135
	v_cvt_pk_bf16_f32 v134, v140, v141
	v_cvt_pk_bf16_f32 v135, v142, v143
	v_and_b32_e32 v0, -2, v0
	global_store_dwordx4 v0, v[132:135], s[30:31] sc1
	v_mov_b64_e32 v[138:139], v[10:11]
	v_mov_b64_e32 v[146:147], v[6:7]
	v_mov_b64_e32 v[134:135], v[18:19]
	v_mov_b64_e32 v[142:143], v[14:15]
	s_and_b64 vcc, exec, s[6:7]
	v_mov_b64_e32 v[136:137], v[8:9]
	v_mov_b64_e32 v[144:145], v[4:5]
	v_mov_b64_e32 v[132:133], v[16:17]
	v_mov_b64_e32 v[140:141], v[12:13]
	s_cbranch_vccnz .LBB0_683
	v_pk_mul_f32 v[138:139], v[10:11], s[54:55] op_sel_hi:[1,0]
	v_pk_mul_f32 v[136:137], v[8:9], s[54:55] op_sel_hi:[1,0]
	v_pk_mul_f32 v[146:147], v[6:7], s[54:55] op_sel_hi:[1,0]
	v_pk_mul_f32 v[144:145], v[4:5], s[54:55] op_sel_hi:[1,0]
	v_pk_mul_f32 v[134:135], v[18:19], s[54:55] op_sel_hi:[1,0]
	v_pk_mul_f32 v[132:133], v[16:17], s[54:55] op_sel_hi:[1,0]
	v_pk_mul_f32 v[142:143], v[14:15], s[54:55] op_sel_hi:[1,0]
	v_pk_mul_f32 v[140:141], v[12:13], s[54:55] op_sel_hi:[1,0]

; __device__ __forceinline__ f32x4 silu4(f32x4 v) { return v * sigm4(v); }
; __device__ __forceinline__ u32x4 pack8(f32x4 v0, f32x4 v1) { u32x4 w; w.x = cvt_pk_bf16(v0[0], v0[1]); w.y = cvt_pk_bf16(v0[2], v0[3]); w.z = cvt_pk_bf16(v1[0], v1[1]); w.w = cvt_pk_bf16(v1[2], v1[3]); return w; }
;     __device__ __forceinline__ void store_rows(const f32x4& a0, const f32x4& a1, const f32x4& b0, const f32x4& b1, int type, bf16_t* base, size_t off) const {
;         f32x4 x0 = a0, x1 = a1, y0 = b0, y1 = b1;
;         if (type == 1) { x0 = x0 * 0.0625f; x1 = x1 * 0.0625f; y0 = y0 * 0.0625f; y1 = y1 * 0.0625f; }
;         if (type == 3) { x0 = silu4(x0); x1 = silu4(x1); y0 = silu4(y0); y1 = silu4(y1); }
;         st16(base, off, pack8(x0, x1));
;         st16(base, off + HALF, pack8(y0, y1));
;     __device__ __forceinline__ void operator()(const f32x4 (&acc)[2][2][4][2], const Unit& u, int wr, int wc, int fr_in, int fq_in) const {
;     ...
;         if (!rope) {
; #pragma unroll
;             for (int ai = 0; ai < 2; ++ai)
; #pragma unroll
;                 for (int m = 0; m < 4; ++m) store_rows(acc[ai][0][m][0], acc[ai][0][m][1], acc[ai][1][m][0], acc[ai][1][m][1], type, base, (size_t)(row0 + ai * HALF + m * 16) * 2048 + coff);
.LBB0_685:
	v_ashrrev_i32_e32 v3, 31, v2
	v_lshlrev_b64 v[154:155], 12, v[2:3]
	v_lshl_add_u64 v[150:151], v[154:155], 0, v[150:151]
	s_mov_b64 s[6:7], 0xb0000
	v_cvt_pk_bf16_f32 v154, v136, v137
	v_lshl_add_u64 v[136:137], v[150:151], 0, s[6:7]
	v_and_b32_e32 v0, -2, v136
	v_cvt_pk_bf16_f32 v155, v138, v139
	v_lshl_add_u64 v[138:139], s[30:31], 0, v[0:1]
	s_mov_b64 s[6:7], 0
	v_cvt_pk_bf16_f32 v156, v144, v145
	v_cvt_pk_bf16_f32 v157, v146, v147
	global_store_dwordx4 v[138:139], v[154:157], off sc1
	v_cvt_pk_bf16_f32 v132, v132, v133
	v_cvt_pk_bf16_f32 v133, v134, v135
	v_cvt_pk_bf16_f32 v134, v140, v141
	v_cvt_pk_bf16_f32 v135, v142, v143

; #define PG8_GAS __attribute__((address_space(1)))
; __device__ __forceinline__ f32x4 silu4(f32x4 v) { return v * sigm4(v); }
; __device__ __forceinline__ u32x4 pack8(f32x4 v0, f32x4 v1) { u32x4 w; w.x = cvt_pk_bf16(v0[0], v0[1]); w.y = cvt_pk_bf16(v0[2], v0[3]); w.z = cvt_pk_bf16(v1[0], v1[1]); w.w = cvt_pk_bf16(v1[2], v1[3]); return w; }
;     __device__ __forceinline__ void store_rows(const f32x4& a0, const f32x4& a1, const f32x4& b0, const f32x4& b1, int type, bf16_t* base, size_t off) const {
;         f32x4 x0 = a0, x1 = a1, y0 = b0, y1 = b1;
;         if (type == 1) { x0 = x0 * 0.0625f; x1 = x1 * 0.0625f; y0 = y0 * 0.0625f; y1 = y1 * 0.0625f; }
;         if (type == 3) { x0 = silu4(x0); x1 = silu4(x1); y0 = silu4(y0); y1 = silu4(y1); }
;         st16(base, off, pack8(x0, x1));
;         st16(base, off + HALF, pack8(y0, y1));
;     __device__ __forceinline__ void operator()(const f32x4 (&acc)[2][2][4][2], const Unit& u, int wr, int wc, int fr_in, int fq_in) const {
;     ...
;         } else {
; #pragma unroll
;             for (int m = 0; m < 4; ++m) {
;                 const int pos = 16 * m + fr;
;                 const f32x4 c0 = *(const PG8_GAS f32x4*)(cosT + pos * 64 + fidx), c1 = *(const PG8_GAS f32x4*)(cosT + pos * 64 + fidx + 4), s0 = *(const PG8_GAS f32x4*)(sinT + pos * 64 + fidx), s1 = *(const PG8_GAS f32x4*)(sinT + pos * 64 + fidx + 4);
; #pragma unroll
;                 for (int ai = 0; ai < 2; ++ai) { const f32x4 a0 = acc[ai][0][m][0], a1 = acc[ai][0][m][1], b0 = acc[ai][1][m][0], b1 = acc[ai][1][m][1];
;                     store_rows(a0 * c0 - b0 * s0, a1 * c1 - b1 * s1, a0 * s0 + b0 * c0, a1 * s1 + b1 * c1, type, base, (size_t)(row0 + ai * HALF + m * 16) * 2048 + coff); }
;             }
.LBB0_690:
	v_lshl_add_u32 v3, v2, 12, v148
	v_and_b32_e32 v0, -2, v3
	v_cvt_pk_bf16_f32 v188, v168, v169
	v_cvt_pk_bf16_f32 v189, v166, v167
	v_cvt_pk_bf16_f32 v190, v164, v165
	v_cvt_pk_bf16_f32 v191, v162, v163
	v_lshl_add_u64 v[162:163], s[30:31], 0, v[0:1]
	v_add_u32_e32 v0, 0x100, v3
	global_store_dwordx4 v[162:163], v[188:191], off sc1
	v_cvt_pk_bf16_f32 v160, v160, v161
	v_cvt_pk_bf16_f32 v161, v158, v159
	v_cvt_pk_bf16_f32 v162, v156, v157
	v_cvt_pk_bf16_f32 v163, v154, v155
	v_and_b32_e32 v0, -2, v0
	global_store_dwordx4 v0, v[160:163], s[30:31] sc1
	v_pk_mul_f32 v[154:155], v[66:67], v[142:143]
	v_pk_mul_f32 v[156:157], v[64:65], v[140:141]
	v_pk_mul_f32 v[158:159], v[62:63], v[138:139]
	v_pk_mul_f32 v[160:161], v[60:61], v[136:137]
	v_pk_mul_f32 v[142:143], v[58:59], v[142:143]
	v_pk_mul_f32 v[162:163], v[56:57], v[140:141]
	v_pk_mul_f32 v[138:139], v[54:55], v[138:139]
	v_pk_mul_f32 v[136:137], v[52:53], v[136:137]
	v_cndmask_b32_e64 v0, 0, 1, s[8:9]
	v_pk_fma_f32 v[154:155], v[58:59], v[146:147], v[154:155] neg_lo:[0,0,1] neg_hi:[0,0,1]
	v_pk_fma_f32 v[156:157], v[56:57], v[144:145], v[156:157] neg_lo:[0,0,1] neg_hi:[0,0,1]
	v_pk_fma_f32 v[158:159], v[54:55], v[134:135], v[158:159] neg_lo:[0,0,1] neg_hi:[0,0,1]
	v_pk_fma_f32 v[160:161], v[52:53], v[132:133], v[160:161] neg_lo:[0,0,1] neg_hi:[0,0,1]
	v_pk_fma_f32 v[140:141], v[66:67], v[146:147], v[142:143]
	v_pk_fma_f32 v[142:143], v[64:65], v[144:145], v[162:163]
	v_pk_fma_f32 v[134:135], v[62:63], v[134:135], v[138:139]
	v_cmp_ne_u32_e64 s[6:7], 1, v0
	s_andn2_b64 vcc, exec, s[8:9]
	v_pk_fma_f32 v[132:133], v[60:61], v[132:133], v[136:137]
	s_cbranch_vccnz .LBB0_692
	v_pk_mul_f32 v[154:155], v[154:155], s[54:55] op_sel_hi:[1,0]
	v_pk_mul_f32 v[156:157], v[156:157], s[54:55] op_sel_hi:[1,0]
	v_pk_mul_f32 v[158:159], v[158:159], s[54:55] op_sel_hi:[1,0]
	v_pk_mul_f32 v[160:161], v[160:161], s[54:55] op_sel_hi:[1,0]
	v_pk_mul_f32 v[140:141], v[140:141], s[54:55] op_sel_hi:[1,0]
	v_pk_mul_f32 v[142:143], v[142:143], s[54:55] op_sel_hi:[1,0]
	v_pk_mul_f32 v[134:135], v[134:135], s[54:55] op_sel_hi:[1,0]
	v_pk_mul_f32 v[132:133], v[132:133], s[54:55] op_sel_hi:[1,0]
.LBB0_692:
	v_add_u32_e32 v0, 0x80000, v3
	v_and_b32_e32 v0, -2, v0
	v_cvt_pk_bf16_f32 v136, v156, v157
	v_cvt_pk_bf16_f32 v137, v154, v155
	v_cvt_pk_bf16_f32 v138, v160, v161
	v_lshl_add_u64 v[144:145], s[30:31], 0, v[0:1]
	v_cvt_pk_bf16_f32 v139, v158, v159
	global_store_dwordx4 v[144:145], v[136:139], off sc1
	v_add_u32_e32 v0, 0x80100, v3
	v_and_b32_e32 v0, -2, v0
	v_cvt_pk_bf16_f32 v136, v142, v143
	v_cvt_pk_bf16_f32 v137, v140, v141
	v_cvt_pk_bf16_f32 v138, v132, v133
	v_cvt_pk_bf16_f32 v139, v134, v135
	global_store_dwordx4 v0, v[136:139], s[30:31] sc1
	s_and_b64 vcc, exec, s[6:7]
	s_waitcnt vmcnt(15)
	v_pk_mul_f32 v[154:155], v[114:115], v[202:203]
	v_pk_mul_f32 v[156:157], v[112:113], v[200:201]
	s_waitcnt vmcnt(14)
	v_pk_mul_f32 v[158:159], v[110:111], v[198:199]
	v_pk_mul_f32 v[160:161], v[108:109], v[196:197]
	v_pk_mul_f32 v[178:179], v[106:107], v[202:203]
	v_pk_mul_f32 v[180:181], v[104:105], v[200:201]
	v_pk_mul_f32 v[188:189], v[102:103], v[198:199]
	v_pk_mul_f32 v[190:191], v[100:101], v[196:197]
	s_waitcnt vmcnt(13)
	v_pk_fma_f32 v[166:167], v[106:107], v[206:207], v[154:155] neg_lo:[0,0,1] neg_hi:[0,0,1]
	v_pk_fma_f32 v[168:169], v[104:105], v[204:205], v[156:157] neg_lo:[0,0,1] neg_hi:[0,0,1]
	s_waitcnt vmcnt(12)
	v_pk_fma_f32 v[162:163], v[102:103], v[194:195], v[158:159] neg_lo:[0,0,1] neg_hi:[0,0,1]
	v_pk_fma_f32 v[164:165], v[100:101], v[192:193], v[160:161] neg_lo:[0,0,1] neg_hi:[0,0,1]
	v_pk_fma_f32 v[158:159], v[114:115], v[206:207], v[178:179]
	v_pk_fma_f32 v[160:161], v[112:113], v[204:205], v[180:181]
	v_pk_fma_f32 v[154:155], v[110:111], v[194:195], v[188:189]
	v_pk_fma_f32 v[156:157], v[108:109], v[192:193], v[190:191]
	s_cbranch_vccnz .LBB0_694
	v_pk_mul_f32 v[166:167], v[166:167], s[54:55] op_sel_hi:[1,0]
	v_pk_mul_f32 v[168:169], v[168:169], s[54:55] op_sel_hi:[1,0]
	v_pk_mul_f32 v[162:163], v[162:163], s[54:55] op_sel_hi:[1,0]
	v_pk_mul_f32 v[164:165], v[164:165], s[54:55] op_sel_hi:[1,0]
	v_pk_mul_f32 v[158:159], v[158:159], s[54:55] op_sel_hi:[1,0]
	v_pk_mul_f32 v[160:161], v[160:161], s[54:55] op_sel_hi:[1,0]
	v_pk_mul_f32 v[154:155], v[154:155], s[54:55] op_sel_hi:[1,0]
	v_pk_mul_f32 v[156:157], v[156:157], s[54:55] op_sel_hi:[1,0]
.LBB0_694:
	v_add_u32_e32 v0, 0x10000, v3
	v_and_b32_e32 v0, -2, v0
	v_cvt_pk_bf16_f32 v188, v168, v169
	v_cvt_pk_bf16_f32 v189, v166, v167
	v_cvt_pk_bf16_f32 v190, v164, v165
	v_cvt_pk_bf16_f32 v191, v162, v163
	v_lshl_add_u64 v[162:163], s[30:31], 0, v[0:1]
	v_add_u32_e32 v0, 0x10100, v3
	global_store_dwordx4 v[162:163], v[188:191], off sc1
	v_cvt_pk_bf16_f32 v160, v160, v161
	v_cvt_pk_bf16_f32 v161, v158, v159
	v_cvt_pk_bf16_f32 v162, v156, v157
	v_cvt_pk_bf16_f32 v163, v154, v155
	v_and_b32_e32 v0, -2, v0
	global_store_dwordx4 v0, v[160:163], s[30:31] sc1
	v_pk_mul_f32 v[154:155], v[50:51], v[202:203]
	v_pk_mul_f32 v[156:157], v[48:49], v[200:201]
	v_pk_mul_f32 v[158:159], v[46:47], v[198:199]
	v_pk_mul_f32 v[160:161], v[44:45], v[196:197]
	v_pk_mul_f32 v[142:143], v[42:43], v[202:203]
	v_pk_mul_f32 v[162:163], v[40:41], v[200:201]
	v_pk_mul_f32 v[138:139], v[38:39], v[198:199]
	v_pk_mul_f32 v[136:137], v[36:37], v[196:197]
	v_pk_fma_f32 v[154:155], v[42:43], v[206:207], v[154:155] neg_lo:[0,0,1] neg_hi:[0,0,1]
	v_pk_fma_f32 v[156:157], v[40:41], v[204:205], v[156:157] neg_lo:[0,0,1] neg_hi:[0,0,1]
	v_pk_fma_f32 v[158:159], v[38:39], v[194:195], v[158:159] neg_lo:[0,0,1] neg_hi:[0,0,1]
	v_pk_fma_f32 v[160:161], v[36:37], v[192:193], v[160:161] neg_lo:[0,0,1] neg_hi:[0,0,1]
	v_pk_fma_f32 v[140:141], v[50:51], v[206:207], v[142:143]
	v_pk_fma_f32 v[142:143], v[48:49], v[204:205], v[162:163]
	v_pk_fma_f32 v[134:135], v[46:47], v[194:195], v[138:139]
	s_and_b64 vcc, exec, s[6:7]
	v_pk_fma_f32 v[132:133], v[44:45], v[192:193], v[136:137]
	s_cbranch_vccnz .LBB0_696
	v_pk_mul_f32 v[154:155], v[154:155], s[54:55] op_sel_hi:[1,0]
	v_pk_mul_f32 v[156:157], v[156:157], s[54:55] op_sel_hi:[1,0]
	v_pk_mul_f32 v[158:159], v[158:159], s[54:55] op_sel_hi:[1,0]
	v_pk_mul_f32 v[160:161], v[160:161], s[54:55] op_sel_hi:[1,0]
	v_pk_mul_f32 v[140:141], v[140:141], s[54:55] op_sel_hi:[1,0]
	v_pk_mul_f32 v[142:143], v[142:143], s[54:55] op_sel_hi:[1,0]
	v_pk_mul_f32 v[134:135], v[134:135], s[54:55] op_sel_hi:[1,0]
	v_pk_mul_f32 v[132:133], v[132:133], s[54:55] op_sel_hi:[1,0]
; #define PG8_GAS __attribute__((address_space(1)))
; __device__ __forceinline__ f32x4 silu4(f32x4 v) { return v * sigm4(v); }
; __device__ __forceinline__ u32x4 pack8(f32x4 v0, f32x4 v1) { u32x4 w; w.x = cvt_pk_bf16(v0[0], v0[1]); w.y = cvt_pk_bf16(v0[2], v0[3]); w.z = cvt_pk_bf16(v1[0], v1[1]); w.w = cvt_pk_bf16(v1[2], v1[3]); return w; }
;     __device__ __forceinline__ void store_rows(const f32x4& a0, const f32x4& a1, const f32x4& b0, const f32x4& b1, int type, bf16_t* base, size_t off) const {
;         f32x4 x0 = a0, x1 = a1, y0 = b0, y1 = b1;
;         if (type == 1) { x0 = x0 * 0.0625f; x1 = x1 * 0.0625f; y0 = y0 * 0.0625f; y1 = y1 * 0.0625f; }
;         if (type == 3) { x0 = silu4(x0); x1 = silu4(x1); y0 = silu4(y0); y1 = silu4(y1); }
;         st16(base, off, pack8(x0, x1));
;         st16(base, off + HALF, pack8(y0, y1));
;     __device__ __forceinline__ void operator()(const f32x4 (&acc)[2][2][4][2], const Unit& u, int wr, int wc, int fr_in, int fq_in) const {
;     ...
;         } else {
; #pragma unroll
;             for (int m = 0; m < 4; ++m) {
;                 const int pos = 16 * m + fr;
;                 const f32x4 c0 = *(const PG8_GAS f32x4*)(cosT + pos * 64 + fidx), c1 = *(const PG8_GAS f32x4*)(cosT + pos * 64 + fidx + 4), s0 = *(const PG8_GAS f32x4*)(sinT + pos * 64 + fidx), s1 = *(const PG8_GAS f32x4*)(sinT + pos * 64 + fidx + 4);
; #pragma unroll
;                 for (int ai = 0; ai < 2; ++ai) { const f32x4 a0 = acc[ai][0][m][0], a1 = acc[ai][0][m][1], b0 = acc[ai][1][m][0], b1 = acc[ai][1][m][1];
;                     store_rows(a0 * c0 - b0 * s0, a1 * c1 - b1 * s1, a0 * s0 + b0 * c0, a1 * s1 + b1 * c1, type, base, (size_t)(row0 + ai * HALF + m * 16) * 2048 + coff); }
;             }
.LBB0_696:
	v_add_u32_e32 v0, 0x90000, v3
	v_and_b32_e32 v0, -2, v0
	v_cvt_pk_bf16_f32 v136, v156, v157
	v_cvt_pk_bf16_f32 v137, v154, v155
	v_cvt_pk_bf16_f32 v138, v160, v161
	v_lshl_add_u64 v[144:145], s[30:31], 0, v[0:1]
	v_cvt_pk_bf16_f32 v139, v158, v159
	global_store_dwordx4 v[144:145], v[136:139], off sc1
	v_add_u32_e32 v0, 0x90100, v3
	v_and_b32_e32 v0, -2, v0
	v_cvt_pk_bf16_f32 v136, v142, v143
	v_cvt_pk_bf16_f32 v137, v140, v141
	v_cvt_pk_bf16_f32 v138, v132, v133
	v_cvt_pk_bf16_f32 v139, v134, v135
	global_store_dwordx4 v0, v[136:139], s[30:31] sc1
	s_and_b64 vcc, exec, s[6:7]
	s_waitcnt vmcnt(15)
	v_pk_mul_f32 v[154:155], v[98:99], v[218:219]
	v_pk_mul_f32 v[156:157], v[96:97], v[216:217]
	s_waitcnt vmcnt(14)
	v_pk_mul_f32 v[158:159], v[94:95], v[214:215]
	v_pk_mul_f32 v[160:161], v[92:93], v[212:213]
	v_pk_mul_f32 v[178:179], v[90:91], v[218:219]
	v_pk_mul_f32 v[180:181], v[88:89], v[216:217]
	v_pk_mul_f32 v[188:189], v[86:87], v[214:215]
	v_pk_mul_f32 v[190:191], v[84:85], v[212:213]
	s_waitcnt vmcnt(13)
	v_pk_fma_f32 v[166:167], v[90:91], v[222:223], v[154:155] neg_lo:[0,0,1] neg_hi:[0,0,1]
	v_pk_fma_f32 v[168:169], v[88:89], v[220:221], v[156:157] neg_lo:[0,0,1] neg_hi:[0,0,1]
	s_waitcnt vmcnt(12)
	v_pk_fma_f32 v[162:163], v[86:87], v[210:211], v[158:159] neg_lo:[0,0,1] neg_hi:[0,0,1]
	v_pk_fma_f32 v[164:165], v[84:85], v[208:209], v[160:161] neg_lo:[0,0,1] neg_hi:[0,0,1]
	v_pk_fma_f32 v[158:159], v[98:99], v[222:223], v[178:179]
	v_pk_fma_f32 v[160:161], v[96:97], v[220:221], v[180:181]
	v_pk_fma_f32 v[154:155], v[94:95], v[210:211], v[188:189]
	v_pk_fma_f32 v[156:157], v[92:93], v[208:209], v[190:191]
	s_cbranch_vccnz .LBB0_698
	v_pk_mul_f32 v[166:167], v[166:167], s[54:55] op_sel_hi:[1,0]
	v_pk_mul_f32 v[168:169], v[168:169], s[54:55] op_sel_hi:[1,0]
	v_pk_mul_f32 v[162:163], v[162:163], s[54:55] op_sel_hi:[1,0]
	v_pk_mul_f32 v[164:165], v[164:165], s[54:55] op_sel_hi:[1,0]
	v_pk_mul_f32 v[158:159], v[158:159], s[54:55] op_sel_hi:[1,0]
	v_pk_mul_f32 v[160:161], v[160:161], s[54:55] op_sel_hi:[1,0]
	v_pk_mul_f32 v[154:155], v[154:155], s[54:55] op_sel_hi:[1,0]
	v_pk_mul_f32 v[156:157], v[156:157], s[54:55] op_sel_hi:[1,0]
.LBB0_698:
	v_add_u32_e32 v0, 0x20000, v3
	v_and_b32_e32 v0, -2, v0
	v_cvt_pk_bf16_f32 v188, v168, v169
	v_cvt_pk_bf16_f32 v189, v166, v167
	v_cvt_pk_bf16_f32 v190, v164, v165
	v_cvt_pk_bf16_f32 v191, v162, v163
	v_lshl_add_u64 v[162:163], s[30:31], 0, v[0:1]
	v_add_u32_e32 v0, 0x20100, v3
	global_store_dwordx4 v[162:163], v[188:191], off sc1
	v_cvt_pk_bf16_f32 v160, v160, v161
	v_cvt_pk_bf16_f32 v161, v158, v159
	v_cvt_pk_bf16_f32 v162, v156, v157
	v_cvt_pk_bf16_f32 v163, v154, v155
	v_and_b32_e32 v0, -2, v0
	global_store_dwordx4 v0, v[160:163], s[30:31] sc1
	v_pk_mul_f32 v[154:155], v[34:35], v[218:219]
	v_pk_mul_f32 v[156:157], v[32:33], v[216:217]
	v_pk_mul_f32 v[158:159], v[30:31], v[214:215]
	v_pk_mul_f32 v[160:161], v[28:29], v[212:213]
	v_pk_mul_f32 v[142:143], v[26:27], v[218:219]
	v_pk_mul_f32 v[162:163], v[24:25], v[216:217]
	v_pk_mul_f32 v[138:139], v[22:23], v[214:215]
	v_pk_mul_f32 v[136:137], v[20:21], v[212:213]
	v_pk_fma_f32 v[154:155], v[26:27], v[222:223], v[154:155] neg_lo:[0,0,1] neg_hi:[0,0,1]
	v_pk_fma_f32 v[156:157], v[24:25], v[220:221], v[156:157] neg_lo:[0,0,1] neg_hi:[0,0,1]
	v_pk_fma_f32 v[158:159], v[22:23], v[210:211], v[158:159] neg_lo:[0,0,1] neg_hi:[0,0,1]
	v_pk_fma_f32 v[160:161], v[20:21], v[208:209], v[160:161] neg_lo:[0,0,1] neg_hi:[0,0,1]
	v_pk_fma_f32 v[140:141], v[34:35], v[222:223], v[142:143]
	v_pk_fma_f32 v[142:143], v[32:33], v[220:221], v[162:163]
	v_pk_fma_f32 v[134:135], v[30:31], v[210:211], v[138:139]
	s_and_b64 vcc, exec, s[6:7]
	v_pk_fma_f32 v[132:133], v[28:29], v[208:209], v[136:137]
	s_cbranch_vccnz .LBB0_700
	v_pk_mul_f32 v[154:155], v[154:155], s[54:55] op_sel_hi:[1,0]
	v_pk_mul_f32 v[156:157], v[156:157], s[54:55] op_sel_hi:[1,0]
	v_pk_mul_f32 v[158:159], v[158:159], s[54:55] op_sel_hi:[1,0]
	v_pk_mul_f32 v[160:161], v[160:161], s[54:55] op_sel_hi:[1,0]
	v_pk_mul_f32 v[140:141], v[140:141], s[54:55] op_sel_hi:[1,0]
	v_pk_mul_f32 v[142:143], v[142:143], s[54:55] op_sel_hi:[1,0]
	v_pk_mul_f32 v[134:135], v[134:135], s[54:55] op_sel_hi:[1,0]
	v_pk_mul_f32 v[132:133], v[132:133], s[54:55] op_sel_hi:[1,0]
; #define PG8_GAS __attribute__((address_space(1)))
; __device__ __forceinline__ f32x4 silu4(f32x4 v) { return v * sigm4(v); }
; __device__ __forceinline__ u32x4 pack8(f32x4 v0, f32x4 v1) { u32x4 w; w.x = cvt_pk_bf16(v0[0], v0[1]); w.y = cvt_pk_bf16(v0[2], v0[3]); w.z = cvt_pk_bf16(v1[0], v1[1]); w.w = cvt_pk_bf16(v1[2], v1[3]); return w; }
;     __device__ __forceinline__ void store_rows(const f32x4& a0, const f32x4& a1, const f32x4& b0, const f32x4& b1, int type, bf16_t* base, size_t off) const {
;         f32x4 x0 = a0, x1 = a1, y0 = b0, y1 = b1;
;         if (type == 1) { x0 = x0 * 0.0625f; x1 = x1 * 0.0625f; y0 = y0 * 0.0625f; y1 = y1 * 0.0625f; }
;         if (type == 3) { x0 = silu4(x0); x1 = silu4(x1); y0 = silu4(y0); y1 = silu4(y1); }
;         st16(base, off, pack8(x0, x1));
;         st16(base, off + HALF, pack8(y0, y1));
;     __device__ __forceinline__ void operator()(const f32x4 (&acc)[2][2][4][2], const Unit& u, int wr, int wc, int fr_in, int fq_in) const {
;     ...
;         } else {
; #pragma unroll
;             for (int m = 0; m < 4; ++m) {
;                 const int pos = 16 * m + fr;
;                 const f32x4 c0 = *(const PG8_GAS f32x4*)(cosT + pos * 64 + fidx), c1 = *(const PG8_GAS f32x4*)(cosT + pos * 64 + fidx + 4), s0 = *(const PG8_GAS f32x4*)(sinT + pos * 64 + fidx), s1 = *(const PG8_GAS f32x4*)(sinT + pos * 64 + fidx + 4);
; #pragma unroll
;                 for (int ai = 0; ai < 2; ++ai) { const f32x4 a0 = acc[ai][0][m][0], a1 = acc[ai][0][m][1], b0 = acc[ai][1][m][0], b1 = acc[ai][1][m][1];
;                     store_rows(a0 * c0 - b0 * s0, a1 * c1 - b1 * s1, a0 * s0 + b0 * c0, a1 * s1 + b1 * c1, type, base, (size_t)(row0 + ai * HALF + m * 16) * 2048 + coff); }
;             }
.LBB0_700:
	v_add_u32_e32 v0, 0xa0000, v3
	v_and_b32_e32 v0, -2, v0
	v_cvt_pk_bf16_f32 v136, v156, v157
	v_cvt_pk_bf16_f32 v137, v154, v155
	v_cvt_pk_bf16_f32 v138, v160, v161
	v_lshl_add_u64 v[144:145], s[30:31], 0, v[0:1]
	v_cvt_pk_bf16_f32 v139, v158, v159
	global_store_dwordx4 v[144:145], v[136:139], off sc1
	v_add_u32_e32 v0, 0xa0100, v3
	v_and_b32_e32 v0, -2, v0
	v_cvt_pk_bf16_f32 v136, v142, v143
	v_cvt_pk_bf16_f32 v137, v140, v141
	v_cvt_pk_bf16_f32 v138, v132, v133
	v_cvt_pk_bf16_f32 v139, v134, v135
	global_store_dwordx4 v0, v[136:139], s[30:31] sc1
	s_and_b64 vcc, exec, s[6:7]
	s_waitcnt vmcnt(15)
	v_pk_mul_f32 v[152:153], v[82:83], v[234:235]
	v_pk_mul_f32 v[154:155], v[80:81], v[232:233]
	s_waitcnt vmcnt(14)
	v_pk_mul_f32 v[156:157], v[78:79], v[230:231]
	v_pk_mul_f32 v[158:159], v[76:77], v[228:229]
	v_pk_mul_f32 v[168:169], v[74:75], v[234:235]
	v_pk_mul_f32 v[178:179], v[72:73], v[232:233]
	v_pk_mul_f32 v[180:181], v[70:71], v[230:231]
	v_pk_mul_f32 v[188:189], v[68:69], v[228:229]
	s_waitcnt vmcnt(13)
	v_pk_fma_f32 v[164:165], v[74:75], v[238:239], v[152:153] neg_lo:[0,0,1] neg_hi:[0,0,1]
	v_pk_fma_f32 v[166:167], v[72:73], v[236:237], v[154:155] neg_lo:[0,0,1] neg_hi:[0,0,1]
	s_waitcnt vmcnt(12)
	v_pk_fma_f32 v[160:161], v[70:71], v[226:227], v[156:157] neg_lo:[0,0,1] neg_hi:[0,0,1]
	v_pk_fma_f32 v[162:163], v[68:69], v[224:225], v[158:159] neg_lo:[0,0,1] neg_hi:[0,0,1]
	v_pk_fma_f32 v[156:157], v[82:83], v[238:239], v[168:169]
	v_pk_fma_f32 v[158:159], v[80:81], v[236:237], v[178:179]
	v_pk_fma_f32 v[152:153], v[78:79], v[226:227], v[180:181]
	v_pk_fma_f32 v[154:155], v[76:77], v[224:225], v[188:189]
	s_cbranch_vccnz .LBB0_702
	v_pk_mul_f32 v[164:165], v[164:165], s[54:55] op_sel_hi:[1,0]
	v_pk_mul_f32 v[166:167], v[166:167], s[54:55] op_sel_hi:[1,0]
	v_pk_mul_f32 v[160:161], v[160:161], s[54:55] op_sel_hi:[1,0]
	v_pk_mul_f32 v[162:163], v[162:163], s[54:55] op_sel_hi:[1,0]
	v_pk_mul_f32 v[156:157], v[156:157], s[54:55] op_sel_hi:[1,0]
	v_pk_mul_f32 v[158:159], v[158:159], s[54:55] op_sel_hi:[1,0]
	v_pk_mul_f32 v[152:153], v[152:153], s[54:55] op_sel_hi:[1,0]
	v_pk_mul_f32 v[154:155], v[154:155], s[54:55] op_sel_hi:[1,0]
.LBB0_702:
	v_add_u32_e32 v0, 0x30000, v3
	v_and_b32_e32 v0, -2, v0
	v_cvt_pk_bf16_f32 v166, v166, v167
	v_cvt_pk_bf16_f32 v167, v164, v165
	v_cvt_pk_bf16_f32 v168, v162, v163
	v_cvt_pk_bf16_f32 v169, v160, v161
	v_lshl_add_u64 v[160:161], s[30:31], 0, v[0:1]
	v_add_u32_e32 v0, 0x30100, v3
	global_store_dwordx4 v[160:161], v[166:169], off sc1
	v_cvt_pk_bf16_f32 v158, v158, v159
	v_cvt_pk_bf16_f32 v159, v156, v157
	v_cvt_pk_bf16_f32 v160, v154, v155
	v_cvt_pk_bf16_f32 v161, v152, v153
	v_and_b32_e32 v0, -2, v0
	global_store_dwordx4 v0, v[158:161], s[30:31] sc1
	v_pk_mul_f32 v[152:153], v[18:19], v[234:235]
	v_pk_mul_f32 v[154:155], v[16:17], v[232:233]
	v_pk_mul_f32 v[156:157], v[14:15], v[230:231]
	v_pk_mul_f32 v[158:159], v[12:13], v[228:229]
	v_pk_mul_f32 v[142:143], v[10:11], v[234:235]
	v_pk_mul_f32 v[160:161], v[8:9], v[232:233]
	v_pk_mul_f32 v[138:139], v[6:7], v[230:231]
	v_pk_mul_f32 v[136:137], v[4:5], v[228:229]
	v_pk_fma_f32 v[152:153], v[10:11], v[238:239], v[152:153] neg_lo:[0,0,1] neg_hi:[0,0,1]
	v_pk_fma_f32 v[154:155], v[8:9], v[236:237], v[154:155] neg_lo:[0,0,1] neg_hi:[0,0,1]
	v_pk_fma_f32 v[156:157], v[6:7], v[226:227], v[156:157] neg_lo:[0,0,1] neg_hi:[0,0,1]
	v_pk_fma_f32 v[158:159], v[4:5], v[224:225], v[158:159] neg_lo:[0,0,1] neg_hi:[0,0,1]
	v_pk_fma_f32 v[140:141], v[18:19], v[238:239], v[142:143]
	v_pk_fma_f32 v[142:143], v[16:17], v[236:237], v[160:161]
	v_pk_fma_f32 v[138:139], v[14:15], v[226:227], v[138:139]
	s_and_b64 vcc, exec, s[6:7]
	v_pk_fma_f32 v[134:135], v[12:13], v[224:225], v[136:137]
	s_cbranch_vccnz .LBB0_704
	v_pk_mul_f32 v[152:153], v[152:153], s[54:55] op_sel_hi:[1,0]
	v_pk_mul_f32 v[154:155], v[154:155], s[54:55] op_sel_hi:[1,0]
	v_pk_mul_f32 v[156:157], v[156:157], s[54:55] op_sel_hi:[1,0]
	v_pk_mul_f32 v[158:159], v[158:159], s[54:55] op_sel_hi:[1,0]
	v_pk_mul_f32 v[140:141], v[140:141], s[54:55] op_sel_hi:[1,0]
	v_pk_mul_f32 v[142:143], v[142:143], s[54:55] op_sel_hi:[1,0]
	v_pk_mul_f32 v[138:139], v[138:139], s[54:55] op_sel_hi:[1,0]
	v_pk_mul_f32 v[134:135], v[134:135], s[54:55] op_sel_hi:[1,0]
.LBB0_704:
	v_add_u32_e32 v132, 0xb0, v2
	v_ashrrev_i32_e32 v133, 31, v132
	v_lshlrev_b64 v[132:133], 12, v[132:133]
	v_lshl_add_u64 v[136:137], v[132:133], 0, v[148:149]
	v_and_b32_e32 v0, -2, v136
	v_lshl_add_u64 v[132:133], s[30:31], 0, v[0:1]
	s_mov_b64 s[6:7], 0
	v_cvt_pk_bf16_f32 v144, v154, v155
	v_cvt_pk_bf16_f32 v145, v152, v153
	v_cvt_pk_bf16_f32 v146, v158, v159
	v_cvt_pk_bf16_f32 v147, v156, v157
	global_store_dwordx4 v[132:133], v[144:147], off sc1
	v_cvt_pk_bf16_f32 v132, v142, v143
	v_cvt_pk_bf16_f32 v133, v140, v141
	v_cvt_pk_bf16_f32 v134, v134, v135
	v_cvt_pk_bf16_f32 v135, v138, v139

; #define PG8_GAS __attribute__((address_space(1)))
; __device__ __forceinline__ f32x4 silu4(f32x4 v) { return v * sigm4(v); }
; __device__ __forceinline__ u32x4 pack8(f32x4 v0, f32x4 v1) { u32x4 w; w.x = cvt_pk_bf16(v0[0], v0[1]); w.y = cvt_pk_bf16(v0[2], v0[3]); w.z = cvt_pk_bf16(v1[0], v1[1]); w.w = cvt_pk_bf16(v1[2], v1[3]); return w; }
;     __device__ __forceinline__ void store_rows(const f32x4& a0, const f32x4& a1, const f32x4& b0, const f32x4& b1, int type, bf16_t* base, size_t off) const {
;         f32x4 x0 = a0, x1 = a1, y0 = b0, y1 = b1;
;         if (type == 1) { x0 = x0 * 0.0625f; x1 = x1 * 0.0625f; y0 = y0 * 0.0625f; y1 = y1 * 0.0625f; }
;         if (type == 3) { x0 = silu4(x0); x1 = silu4(x1); y0 = silu4(y0); y1 = silu4(y1); }
;         st16(base, off, pack8(x0, x1));
;         st16(base, off + HALF, pack8(y0, y1));
;     __device__ __forceinline__ void operator()(const f32x4 (&acc)[2][2][4][2], const Unit& u, int wr, int wc, int fr_in, int fq_in) const {
;     ...
;         } else if (wc < 2) {
; #pragma unroll
;             for (int ai = 0; ai < 2; ++ai) {
;                 const int pos = (4 * u.pm + 2 * ai + wr) & 63;
;                 const f32x4 c0 = *(const PG8_GAS f32x4*)(cosT + pos * 64 + fidx), c1 = *(const PG8_GAS f32x4*)(cosT + pos * 64 + fidx + 4), s0 = *(const PG8_GAS f32x4*)(sinT + pos * 64 + fidx), s1 = *(const PG8_GAS f32x4*)(sinT + pos * 64 + fidx + 4);
; #pragma unroll
;                 for (int m = 0; m < 4; ++m) { const f32x4 a0 = acc[ai][0][m][0], a1 = acc[ai][0][m][1], b0 = acc[ai][1][m][0], b1 = acc[ai][1][m][1];
;                     store_rows(a0 * c0 - b0 * s0, a1 * c1 - b1 * s1, a0 * s0 + b0 * c0, a1 * s1 + b1 * c1, type, base, (size_t)(row0 + ai * HALF + m * 16) * 2048 + coff); }
;             }
.LBB0_708:
	v_lshl_add_u32 v3, v2, 12, v148
	v_and_b32_e32 v0, -2, v3
	v_cvt_pk_bf16_f32 v124, v158, v159
	v_cvt_pk_bf16_f32 v125, v154, v155
	v_lshl_add_u64 v[128:129], s[30:31], 0, v[0:1]
	v_add_u32_e32 v0, 0x100, v3
	v_cvt_pk_bf16_f32 v126, v156, v157
	v_cvt_pk_bf16_f32 v127, v152, v153
	global_store_dwordx4 v[128:129], v[124:127], off sc1
	v_cvt_pk_bf16_f32 v122, v122, v123
	v_cvt_pk_bf16_f32 v123, v120, v121
	v_and_b32_e32 v0, -2, v0
	v_pk_mul_f32 v[120:121], v[110:111], v[142:143]
	v_cvt_pk_bf16_f32 v124, v118, v119
	v_cvt_pk_bf16_f32 v125, v116, v117
	v_pk_mul_f32 v[116:117], v[114:115], v[146:147]
	global_store_dwordx4 v0, v[122:125], s[30:31] sc1
	v_pk_mul_f32 v[118:119], v[112:113], v[144:145]
	v_pk_fma_f32 v[116:117], v[106:107], v[138:139], v[116:117] neg_lo:[0,0,1] neg_hi:[0,0,1]
	v_pk_mul_f32 v[106:107], v[106:107], v[146:147]
	v_pk_mul_f32 v[124:125], v[104:105], v[144:145]
	v_pk_fma_f32 v[118:119], v[104:105], v[136:137], v[118:119] neg_lo:[0,0,1] neg_hi:[0,0,1]
	v_pk_mul_f32 v[122:123], v[108:109], v[140:141]
	v_pk_fma_f32 v[120:121], v[102:103], v[134:135], v[120:121] neg_lo:[0,0,1] neg_hi:[0,0,1]
	v_pk_fma_f32 v[104:105], v[114:115], v[138:139], v[106:107]
	v_pk_fma_f32 v[106:107], v[112:113], v[136:137], v[124:125]
	v_pk_mul_f32 v[102:103], v[102:103], v[142:143]
	v_pk_mul_f32 v[112:113], v[100:101], v[140:141]
	v_pk_fma_f32 v[122:123], v[100:101], v[132:133], v[122:123] neg_lo:[0,0,1] neg_hi:[0,0,1]
	v_pk_fma_f32 v[100:101], v[110:111], v[134:135], v[102:103]
	s_and_b64 vcc, exec, s[6:7]
	v_pk_fma_f32 v[102:103], v[108:109], v[132:133], v[112:113]
	s_cbranch_vccnz .LBB0_710
	v_pk_mul_f32 v[116:117], v[116:117], s[54:55] op_sel_hi:[1,0]
	v_pk_mul_f32 v[118:119], v[118:119], s[54:55] op_sel_hi:[1,0]
	v_pk_mul_f32 v[120:121], v[120:121], s[54:55] op_sel_hi:[1,0]
	v_pk_mul_f32 v[122:123], v[122:123], s[54:55] op_sel_hi:[1,0]
	v_pk_mul_f32 v[104:105], v[104:105], s[54:55] op_sel_hi:[1,0]
	v_pk_mul_f32 v[106:107], v[106:107], s[54:55] op_sel_hi:[1,0]
	v_pk_mul_f32 v[100:101], v[100:101], s[54:55] op_sel_hi:[1,0]
	v_pk_mul_f32 v[102:103], v[102:103], s[54:55] op_sel_hi:[1,0]
.LBB0_710:
	v_add_u32_e32 v0, 0x10000, v3
	v_and_b32_e32 v0, -2, v0
	v_cvt_pk_bf16_f32 v108, v118, v119
	v_cvt_pk_bf16_f32 v109, v116, v117
	v_lshl_add_u64 v[112:113], s[30:31], 0, v[0:1]
	v_add_u32_e32 v0, 0x10100, v3
	v_cvt_pk_bf16_f32 v110, v122, v123
	v_cvt_pk_bf16_f32 v111, v120, v121
	global_store_dwordx4 v[112:113], v[108:111], off sc1
	v_cvt_pk_bf16_f32 v106, v106, v107
	v_cvt_pk_bf16_f32 v107, v104, v105
	v_and_b32_e32 v0, -2, v0
	v_pk_mul_f32 v[104:105], v[94:95], v[142:143]
	v_cvt_pk_bf16_f32 v108, v102, v103
	v_cvt_pk_bf16_f32 v109, v100, v101
	v_pk_mul_f32 v[100:101], v[98:99], v[146:147]
	global_store_dwordx4 v0, v[106:109], s[30:31] sc1
	v_pk_mul_f32 v[102:103], v[96:97], v[144:145]
	v_pk_fma_f32 v[100:101], v[90:91], v[138:139], v[100:101] neg_lo:[0,0,1] neg_hi:[0,0,1]
	v_pk_mul_f32 v[90:91], v[90:91], v[146:147]
	v_pk_mul_f32 v[108:109], v[88:89], v[144:145]
	v_pk_fma_f32 v[102:103], v[88:89], v[136:137], v[102:103] neg_lo:[0,0,1] neg_hi:[0,0,1]
	v_pk_mul_f32 v[106:107], v[92:93], v[140:141]
	v_pk_fma_f32 v[104:105], v[86:87], v[134:135], v[104:105] neg_lo:[0,0,1] neg_hi:[0,0,1]
	v_pk_fma_f32 v[88:89], v[98:99], v[138:139], v[90:91]
	v_pk_fma_f32 v[90:91], v[96:97], v[136:137], v[108:109]
	v_pk_mul_f32 v[86:87], v[86:87], v[142:143]
	v_pk_mul_f32 v[96:97], v[84:85], v[140:141]
	v_pk_fma_f32 v[106:107], v[84:85], v[132:133], v[106:107] neg_lo:[0,0,1] neg_hi:[0,0,1]
	v_pk_fma_f32 v[84:85], v[94:95], v[134:135], v[86:87]
	s_and_b64 vcc, exec, s[6:7]
	v_pk_fma_f32 v[86:87], v[92:93], v[132:133], v[96:97]
	s_cbranch_vccnz .LBB0_712
	v_pk_mul_f32 v[100:101], v[100:101], s[54:55] op_sel_hi:[1,0]
	v_pk_mul_f32 v[102:103], v[102:103], s[54:55] op_sel_hi:[1,0]
	v_pk_mul_f32 v[104:105], v[104:105], s[54:55] op_sel_hi:[1,0]
	v_pk_mul_f32 v[106:107], v[106:107], s[54:55] op_sel_hi:[1,0]
	v_pk_mul_f32 v[88:89], v[88:89], s[54:55] op_sel_hi:[1,0]
	v_pk_mul_f32 v[90:91], v[90:91], s[54:55] op_sel_hi:[1,0]
	v_pk_mul_f32 v[84:85], v[84:85], s[54:55] op_sel_hi:[1,0]
	v_pk_mul_f32 v[86:87], v[86:87], s[54:55] op_sel_hi:[1,0]
.LBB0_712:
	v_add_u32_e32 v0, 0x20000, v3
	v_and_b32_e32 v0, -2, v0
	v_cvt_pk_bf16_f32 v92, v102, v103
	v_cvt_pk_bf16_f32 v93, v100, v101
	v_lshl_add_u64 v[96:97], s[30:31], 0, v[0:1]
	v_add_u32_e32 v0, 0x20100, v3
	v_cvt_pk_bf16_f32 v94, v106, v107
	v_cvt_pk_bf16_f32 v95, v104, v105
	global_store_dwordx4 v[96:97], v[92:95], off sc1
	v_cvt_pk_bf16_f32 v90, v90, v91
	v_cvt_pk_bf16_f32 v91, v88, v89
	v_and_b32_e32 v0, -2, v0
	v_pk_mul_f32 v[88:89], v[78:79], v[142:143]
	v_cvt_pk_bf16_f32 v92, v86, v87
	v_cvt_pk_bf16_f32 v93, v84, v85
	v_pk_mul_f32 v[84:85], v[82:83], v[146:147]
	global_store_dwordx4 v0, v[90:93], s[30:31] sc1
	v_pk_mul_f32 v[86:87], v[80:81], v[144:145]
	v_pk_fma_f32 v[84:85], v[74:75], v[138:139], v[84:85] neg_lo:[0,0,1] neg_hi:[0,0,1]
	v_pk_mul_f32 v[74:75], v[74:75], v[146:147]
	v_pk_mul_f32 v[92:93], v[72:73], v[144:145]
	v_pk_fma_f32 v[86:87], v[72:73], v[136:137], v[86:87] neg_lo:[0,0,1] neg_hi:[0,0,1]
	v_pk_mul_f32 v[90:91], v[76:77], v[140:141]
	v_pk_fma_f32 v[88:89], v[70:71], v[134:135], v[88:89] neg_lo:[0,0,1] neg_hi:[0,0,1]
	v_pk_fma_f32 v[72:73], v[82:83], v[138:139], v[74:75]
	v_pk_fma_f32 v[74:75], v[80:81], v[136:137], v[92:93]
	v_pk_mul_f32 v[70:71], v[70:71], v[142:143]
	v_pk_mul_f32 v[80:81], v[68:69], v[140:141]
	v_pk_fma_f32 v[90:91], v[68:69], v[132:133], v[90:91] neg_lo:[0,0,1] neg_hi:[0,0,1]
	v_pk_fma_f32 v[68:69], v[78:79], v[134:135], v[70:71]
	s_and_b64 vcc, exec, s[6:7]
	v_pk_fma_f32 v[70:71], v[76:77], v[132:133], v[80:81]
	s_cbranch_vccnz .LBB0_714
	v_pk_mul_f32 v[84:85], v[84:85], s[54:55] op_sel_hi:[1,0]
	v_pk_mul_f32 v[86:87], v[86:87], s[54:55] op_sel_hi:[1,0]
	v_pk_mul_f32 v[88:89], v[88:89], s[54:55] op_sel_hi:[1,0]
	v_pk_mul_f32 v[90:91], v[90:91], s[54:55] op_sel_hi:[1,0]
	v_pk_mul_f32 v[72:73], v[72:73], s[54:55] op_sel_hi:[1,0]
	v_pk_mul_f32 v[74:75], v[74:75], s[54:55] op_sel_hi:[1,0]
	v_pk_mul_f32 v[68:69], v[68:69], s[54:55] op_sel_hi:[1,0]
	v_pk_mul_f32 v[70:71], v[70:71], s[54:55] op_sel_hi:[1,0]
; #define PG8_GAS __attribute__((address_space(1)))
;     __device__ __forceinline__ void operator()(const f32x4 (&acc)[2][2][4][2], const Unit& u, int wr, int wc, int fr_in, int fq_in) const {
;     ...
;         } else if (wc < 2) {
; #pragma unroll
;             for (int ai = 0; ai < 2; ++ai) {
;                 const int pos = (4 * u.pm + 2 * ai + wr) & 63;
;                 const f32x4 c0 = *(const PG8_GAS f32x4*)(cosT + pos * 64 + fidx), c1 = *(const PG8_GAS f32x4*)(cosT + pos * 64 + fidx + 4), s0 = *(const PG8_GAS f32x4*)(sinT + pos * 64 + fidx), s1 = *(const PG8_GAS f32x4*)(sinT + pos * 64 + fidx + 4);
; #pragma unroll
;                 for (int m = 0; m < 4; ++m) { const f32x4 a0 = acc[ai][0][m][0], a1 = acc[ai][0][m][1], b0 = acc[ai][1][m][0], b1 = acc[ai][1][m][1];
;                     store_rows(a0 * c0 - b0 * s0, a1 * c1 - b1 * s1, a0 * s0 + b0 * c0, a1 * s1 + b1 * c1, type, base, (size_t)(row0 + ai * HALF + m * 16) * 2048 + coff); }
;             }
.LBB0_714:
	s_addk_i32 s21, 0x80
	s_and_b32 s8, s21, 0xfc0
	v_add_u32_e32 v0, 0x30000, v3
	s_lshl_b32 s21, s8, 2
	v_and_b32_e32 v0, -2, v0
	s_add_u32 s8, s14, s21
	v_lshl_add_u64 v[80:81], s[30:31], 0, v[0:1]
	s_addc_u32 s9, s15, 0
	v_cvt_pk_bf16_f32 v76, v86, v87
	v_cvt_pk_bf16_f32 v77, v84, v85
	v_cvt_pk_bf16_f32 v78, v90, v91
	v_cvt_pk_bf16_f32 v79, v88, v89
	global_store_dwordx4 v[80:81], v[76:79], off sc1
	v_cvt_pk_bf16_f32 v74, v74, v75
	v_cvt_pk_bf16_f32 v75, v72, v73
	v_add_u32_e32 v0, 0x30100, v3
	s_add_u32 s8, s12, s21
	v_and_b32_e32 v0, -2, v0
	s_addc_u32 s9, s13, 0
	v_cvt_pk_bf16_f32 v76, v70, v71
	v_cvt_pk_bf16_f32 v77, v68, v69
	global_store_dwordx4 v0, v[74:77], s[30:31] sc1
	s_and_b64 vcc, exec, s[6:7]
	s_waitcnt vmcnt(8)
	v_pk_mul_f32 v[84:85], v[66:67], v[206:207]
	v_pk_mul_f32 v[88:89], v[64:65], v[204:205]
	v_pk_fma_f32 v[86:87], v[58:59], v[198:199], v[84:85] neg_lo:[0,0,1] neg_hi:[0,0,1]
	v_pk_mul_f32 v[84:85], v[62:63], v[202:203]
	v_pk_mul_f32 v[58:59], v[58:59], v[206:207]
	v_pk_mul_f32 v[92:93], v[56:57], v[204:205]
	v_pk_fma_f32 v[90:91], v[56:57], v[196:197], v[88:89] neg_lo:[0,0,1] neg_hi:[0,0,1]
	v_pk_mul_f32 v[88:89], v[60:61], v[200:201]
	v_pk_fma_f32 v[84:85], v[54:55], v[194:195], v[84:85] neg_lo:[0,0,1] neg_hi:[0,0,1]
	v_pk_fma_f32 v[56:57], v[66:67], v[198:199], v[58:59]
	v_pk_fma_f32 v[58:59], v[64:65], v[196:197], v[92:93]
	v_pk_mul_f32 v[54:55], v[54:55], v[202:203]
	v_pk_mul_f32 v[64:65], v[52:53], v[200:201]
	v_pk_fma_f32 v[88:89], v[52:53], v[192:193], v[88:89] neg_lo:[0,0,1] neg_hi:[0,0,1]
	v_pk_fma_f32 v[52:53], v[62:63], v[194:195], v[54:55]
	v_pk_fma_f32 v[54:55], v[60:61], v[192:193], v[64:65]
	s_cbranch_vccnz .LBB0_716
	v_pk_mul_f32 v[86:87], v[86:87], s[54:55] op_sel_hi:[1,0]
	v_pk_mul_f32 v[90:91], v[90:91], s[54:55] op_sel_hi:[1,0]
	v_pk_mul_f32 v[84:85], v[84:85], s[54:55] op_sel_hi:[1,0]
	v_pk_mul_f32 v[88:89], v[88:89], s[54:55] op_sel_hi:[1,0]
	v_pk_mul_f32 v[56:57], v[56:57], s[54:55] op_sel_hi:[1,0]
	v_pk_mul_f32 v[58:59], v[58:59], s[54:55] op_sel_hi:[1,0]
	v_pk_mul_f32 v[52:53], v[52:53], s[54:55] op_sel_hi:[1,0]
	v_pk_mul_f32 v[54:55], v[54:55], s[54:55] op_sel_hi:[1,0]
.LBB0_716:
	v_add_u32_e32 v0, 0x80000, v3
	v_and_b32_e32 v0, -2, v0
	v_cvt_pk_bf16_f32 v60, v90, v91
	v_cvt_pk_bf16_f32 v61, v86, v87
	v_lshl_add_u64 v[64:65], s[30:31], 0, v[0:1]
	v_add_u32_e32 v0, 0x80100, v3
	v_cvt_pk_bf16_f32 v62, v88, v89
	v_cvt_pk_bf16_f32 v63, v84, v85
	global_store_dwordx4 v[64:65], v[60:63], off sc1
	v_cvt_pk_bf16_f32 v58, v58, v59
	v_cvt_pk_bf16_f32 v59, v56, v57
	v_and_b32_e32 v0, -2, v0
	v_pk_mul_f32 v[56:57], v[46:47], v[202:203]
	v_cvt_pk_bf16_f32 v60, v54, v55
	v_cvt_pk_bf16_f32 v61, v52, v53
	v_pk_mul_f32 v[52:53], v[50:51], v[206:207]
	global_store_dwordx4 v0, v[58:61], s[30:31] sc1
	v_pk_mul_f32 v[54:55], v[48:49], v[204:205]
	v_pk_fma_f32 v[52:53], v[42:43], v[198:199], v[52:53] neg_lo:[0,0,1] neg_hi:[0,0,1]
	v_pk_mul_f32 v[42:43], v[42:43], v[206:207]
	v_pk_mul_f32 v[60:61], v[40:41], v[204:205]
	v_pk_fma_f32 v[54:55], v[40:41], v[196:197], v[54:55] neg_lo:[0,0,1] neg_hi:[0,0,1]
	v_pk_mul_f32 v[58:59], v[44:45], v[200:201]
	v_pk_fma_f32 v[56:57], v[38:39], v[194:195], v[56:57] neg_lo:[0,0,1] neg_hi:[0,0,1]
	v_pk_fma_f32 v[40:41], v[50:51], v[198:199], v[42:43]
	v_pk_fma_f32 v[42:43], v[48:49], v[196:197], v[60:61]
	v_pk_mul_f32 v[38:39], v[38:39], v[202:203]
	v_pk_mul_f32 v[48:49], v[36:37], v[200:201]
	v_pk_fma_f32 v[58:59], v[36:37], v[192:193], v[58:59] neg_lo:[0,0,1] neg_hi:[0,0,1]
	v_pk_fma_f32 v[36:37], v[46:47], v[194:195], v[38:39]
	s_and_b64 vcc, exec, s[6:7]
	v_pk_fma_f32 v[38:39], v[44:45], v[192:193], v[48:49]
	s_cbranch_vccnz .LBB0_718
	v_pk_mul_f32 v[52:53], v[52:53], s[54:55] op_sel_hi:[1,0]
	v_pk_mul_f32 v[54:55], v[54:55], s[54:55] op_sel_hi:[1,0]
	v_pk_mul_f32 v[56:57], v[56:57], s[54:55] op_sel_hi:[1,0]
	v_pk_mul_f32 v[58:59], v[58:59], s[54:55] op_sel_hi:[1,0]
	v_pk_mul_f32 v[40:41], v[40:41], s[54:55] op_sel_hi:[1,0]
	v_pk_mul_f32 v[42:43], v[42:43], s[54:55] op_sel_hi:[1,0]
	v_pk_mul_f32 v[36:37], v[36:37], s[54:55] op_sel_hi:[1,0]
	v_pk_mul_f32 v[38:39], v[38:39], s[54:55] op_sel_hi:[1,0]
; #define PG8_GAS __attribute__((address_space(1)))
; #define PG8_BAR __builtin_amdgcn_s_barrier()
;     __device__ __forceinline__ void operator()(const f32x4 (&acc)[2][2][4][2], const Unit& u, int wr, int wc, int fr_in, int fq_in) const {
;     ...
;         } else if (wc < 2) {
; #pragma unroll
;             for (int ai = 0; ai < 2; ++ai) {
;                 const int pos = (4 * u.pm + 2 * ai + wr) & 63;
;                 const f32x4 c0 = *(const PG8_GAS f32x4*)(cosT + pos * 64 + fidx), c1 = *(const PG8_GAS f32x4*)(cosT + pos * 64 + fidx + 4), s0 = *(const PG8_GAS f32x4*)(sinT + pos * 64 + fidx), s1 = *(const PG8_GAS f32x4*)(sinT + pos * 64 + fidx + 4);
; #pragma unroll
;                 for (int m = 0; m < 4; ++m) { const f32x4 a0 = acc[ai][0][m][0], a1 = acc[ai][0][m][1], b0 = acc[ai][1][m][0], b1 = acc[ai][1][m][1];
;                     store_rows(a0 * c0 - b0 * s0, a1 * c1 - b1 * s1, a0 * s0 + b0 * c0, a1 * s1 + b1 * c1, type, base, (size_t)(row0 + ai * HALF + m * 16) * 2048 + coff); }
;             }
; template <class Epi, class Sched, bool ALIGN_EPI = false, bool SP2 = false>
; __device__ __forceinline__ void gemm_phase(PG8_LAS unsigned char* lds, const Gemm g, const Sched& S, const Epi& E) {
;     ...
;         if (!kp_first) if constexpr (!Epi::AFTER_DRAIN) { E(acc, cur, wr, wc, fr, fq); if constexpr (REP_EPI > 1 && Epi::REP2) { asm volatile("" ::: "memory"); E(acc, cur, wr, wc, fr, fq); } S.done(cur); }
;         asm volatile("" ::: "memory");
;         if (!has_next) break;
;         if (!kp_first)
; #pragma unroll
;         for (int a = 0; a < 2; ++a)
; #pragma unroll
;             for (int b = 0; b < 2; ++b)
; #pragma unroll
;                 for (int m = 0; m < 4; ++m)
; #pragma unroll
;                     for (int n = 0; n < 2; ++n) acc[a][b][m][n] = (f32x4){0.f, 0.f, 0.f, 0.f};
;         cur = nxt; cA = nA; cB = nB; ++ui;
;         if constexpr (ALIGN_EPI) { if (wr == 1) PG8_BAR; }
.LBB0_718:
	v_add_u32_e32 v0, 0x90000, v3
	v_and_b32_e32 v0, -2, v0
	v_cvt_pk_bf16_f32 v44, v54, v55
	v_cvt_pk_bf16_f32 v45, v52, v53
	v_lshl_add_u64 v[48:49], s[30:31], 0, v[0:1]
	v_add_u32_e32 v0, 0x90100, v3
	v_cvt_pk_bf16_f32 v46, v58, v59
	v_cvt_pk_bf16_f32 v47, v56, v57
	global_store_dwordx4 v[48:49], v[44:47], off sc1
	v_cvt_pk_bf16_f32 v42, v42, v43
	v_cvt_pk_bf16_f32 v43, v40, v41
	v_and_b32_e32 v0, -2, v0
	v_pk_mul_f32 v[40:41], v[30:31], v[202:203]
	v_cvt_pk_bf16_f32 v44, v38, v39
	v_cvt_pk_bf16_f32 v45, v36, v37
	v_pk_mul_f32 v[36:37], v[34:35], v[206:207]
	global_store_dwordx4 v0, v[42:45], s[30:31] sc1
	v_pk_mul_f32 v[38:39], v[32:33], v[204:205]
	v_pk_fma_f32 v[36:37], v[26:27], v[198:199], v[36:37] neg_lo:[0,0,1] neg_hi:[0,0,1]
	v_pk_mul_f32 v[26:27], v[26:27], v[206:207]
	v_pk_mul_f32 v[44:45], v[24:25], v[204:205]
	v_pk_fma_f32 v[38:39], v[24:25], v[196:197], v[38:39] neg_lo:[0,0,1] neg_hi:[0,0,1]
	v_pk_mul_f32 v[42:43], v[28:29], v[200:201]
	v_pk_fma_f32 v[40:41], v[22:23], v[194:195], v[40:41] neg_lo:[0,0,1] neg_hi:[0,0,1]
	v_pk_fma_f32 v[24:25], v[34:35], v[198:199], v[26:27]
	v_pk_fma_f32 v[26:27], v[32:33], v[196:197], v[44:45]
	v_pk_mul_f32 v[22:23], v[22:23], v[202:203]
	v_pk_mul_f32 v[32:33], v[20:21], v[200:201]
	v_pk_fma_f32 v[42:43], v[20:21], v[192:193], v[42:43] neg_lo:[0,0,1] neg_hi:[0,0,1]
	v_pk_fma_f32 v[20:21], v[30:31], v[194:195], v[22:23]
	s_and_b64 vcc, exec, s[6:7]
	v_pk_fma_f32 v[22:23], v[28:29], v[192:193], v[32:33]
	s_cbranch_vccnz .LBB0_720
	v_pk_mul_f32 v[36:37], v[36:37], s[54:55] op_sel_hi:[1,0]
	v_pk_mul_f32 v[38:39], v[38:39], s[54:55] op_sel_hi:[1,0]
	v_pk_mul_f32 v[40:41], v[40:41], s[54:55] op_sel_hi:[1,0]
	v_pk_mul_f32 v[42:43], v[42:43], s[54:55] op_sel_hi:[1,0]
	v_pk_mul_f32 v[24:25], v[24:25], s[54:55] op_sel_hi:[1,0]
	v_pk_mul_f32 v[26:27], v[26:27], s[54:55] op_sel_hi:[1,0]
	v_pk_mul_f32 v[20:21], v[20:21], s[54:55] op_sel_hi:[1,0]
	v_pk_mul_f32 v[22:23], v[22:23], s[54:55] op_sel_hi:[1,0]
.LBB0_720:
	v_add_u32_e32 v0, 0xa0000, v3
	v_and_b32_e32 v0, -2, v0
	v_cvt_pk_bf16_f32 v28, v38, v39
	v_cvt_pk_bf16_f32 v29, v36, v37
	v_lshl_add_u64 v[32:33], s[30:31], 0, v[0:1]
	v_add_u32_e32 v0, 0xa0100, v3
	v_cvt_pk_bf16_f32 v30, v42, v43
	v_cvt_pk_bf16_f32 v31, v40, v41
	global_store_dwordx4 v[32:33], v[28:31], off sc1
	v_cvt_pk_bf16_f32 v26, v26, v27
	v_cvt_pk_bf16_f32 v27, v24, v25
	v_and_b32_e32 v0, -2, v0
	v_pk_mul_f32 v[24:25], v[14:15], v[202:203]
	v_cvt_pk_bf16_f32 v28, v22, v23
	v_cvt_pk_bf16_f32 v29, v20, v21
	v_pk_mul_f32 v[20:21], v[18:19], v[206:207]
	global_store_dwordx4 v0, v[26:29], s[30:31] sc1
	v_pk_mul_f32 v[22:23], v[16:17], v[204:205]
	v_pk_fma_f32 v[20:21], v[10:11], v[198:199], v[20:21] neg_lo:[0,0,1] neg_hi:[0,0,1]
	v_pk_mul_f32 v[10:11], v[10:11], v[206:207]
	v_pk_mul_f32 v[28:29], v[8:9], v[204:205]
	v_pk_fma_f32 v[22:23], v[8:9], v[196:197], v[22:23] neg_lo:[0,0,1] neg_hi:[0,0,1]
	v_pk_mul_f32 v[26:27], v[12:13], v[200:201]
	v_pk_fma_f32 v[24:25], v[6:7], v[194:195], v[24:25] neg_lo:[0,0,1] neg_hi:[0,0,1]
	v_pk_fma_f32 v[8:9], v[18:19], v[198:199], v[10:11]
	v_pk_fma_f32 v[10:11], v[16:17], v[196:197], v[28:29]
	v_pk_mul_f32 v[6:7], v[6:7], v[202:203]
	v_pk_mul_f32 v[16:17], v[4:5], v[200:201]
	v_pk_fma_f32 v[26:27], v[4:5], v[192:193], v[26:27] neg_lo:[0,0,1] neg_hi:[0,0,1]
	v_pk_fma_f32 v[4:5], v[14:15], v[194:195], v[6:7]
	s_and_b64 vcc, exec, s[6:7]
	v_pk_fma_f32 v[6:7], v[12:13], v[192:193], v[16:17]
	s_cbranch_vccnz .LBB0_722
	v_pk_mul_f32 v[20:21], v[20:21], s[54:55] op_sel_hi:[1,0]
	v_pk_mul_f32 v[22:23], v[22:23], s[54:55] op_sel_hi:[1,0]
	v_pk_mul_f32 v[24:25], v[24:25], s[54:55] op_sel_hi:[1,0]
	v_pk_mul_f32 v[26:27], v[26:27], s[54:55] op_sel_hi:[1,0]
	v_pk_mul_f32 v[8:9], v[8:9], s[54:55] op_sel_hi:[1,0]
	v_pk_mul_f32 v[10:11], v[10:11], s[54:55] op_sel_hi:[1,0]
	v_pk_mul_f32 v[4:5], v[4:5], s[54:55] op_sel_hi:[1,0]
	v_pk_mul_f32 v[6:7], v[6:7], s[54:55] op_sel_hi:[1,0]
.LBB0_722:
	v_ashrrev_i32_e32 v3, 31, v2
	v_lshlrev_b64 v[2:3], 12, v[2:3]
	v_lshl_add_u64 v[2:3], v[2:3], 0, v[148:149]
	s_mov_b64 s[6:7], 0xb0000
	v_lshl_add_u64 v[136:137], v[2:3], 0, s[6:7]
	v_and_b32_e32 v0, -2, v136
	v_lshl_add_u64 v[2:3], s[30:31], 0, v[0:1]
	v_cvt_pk_bf16_f32 v12, v22, v23
	v_cvt_pk_bf16_f32 v13, v20, v21
	v_cvt_pk_bf16_f32 v14, v26, v27
	v_cvt_pk_bf16_f32 v15, v24, v25
	global_store_dwordx4 v[2:3], v[12:15], off sc1
	v_cvt_pk_bf16_f32 v132, v10, v11
	v_cvt_pk_bf16_f32 v133, v8, v9
	v_cvt_pk_bf16_f32 v134, v6, v7
	v_cvt_pk_bf16_f32 v135, v4, v5
.LBB0_723:
	v_add_u32_e32 v0, 0x100, v136
	v_and_b32_e32 v0, -2, v0
	global_store_dwordx4 v0, v[132:135], s[30:31] sc1
	s_andn2_b64 vcc, exec, s[28:29]
	s_mov_b64 s[6:7], -1
	s_cbranch_vccnz .LBB0_640
	s_andn2_b64 vcc, exec, s[10:11]
	s_cbranch_vccnz .LBB0_639
	s_barrier
	s_branch .LBB0_639

;     __host__ __device__ bool next(int i, Unit& u) const { return StaticOrder::next(i >> 1, u); }
;     __device__ __forceinline__ bool next(int i, Unit& u) const { const int s = i * G + c; if (s >= 128) return false; const int t = s >> 2; u.pm = pm0 + (t & 3); u.pn = t >> 2; u.k0 = (s & 3) * ksub; return true; }
; #define PG8_WAIT_V(n) asm volatile("s_waitcnt vmcnt(" #n ")" ::: "memory")
; template <class Epi, class Sched, bool ALIGN_EPI = false, bool SP2 = false>
; __device__ __forceinline__ void gemm_phase(PG8_LAS unsigned char* lds, const Gemm g, const Sched& S, const Epi& E) {
;     ...
;     for (;;) {
;         const bool has_next = S.next(ui + 1, nxt);
;         const char* nA = has_next ? (const char*)g.A + (size_t)nxt.pm * tsA + (size_t)nxt.k0 * 2 : cA; const char* nB = has_next ? (const char*)g.Bt + (size_t)nxt.pn * tsB + (size_t)nxt.k0 * 2 : cB;
;         for (int t = (DRO && ui > 0) ? 2 : 0; t < nt; t += 2) {
;             const bool last = (t == nt - 2);
;             const char* a1 = cA + (size_t)(t + 1) * kstep;
;             const char* a2 = last ? nA : cA + (size_t)(t + 2) * kstep; const char* b2 = last ? nB : cB + (size_t)(t + 2) * kstep;
;             const char* a3 = a2 + kstep; const char* b3 = b2 + kstep;
;             if (last && has_next) S.a_ready(nxt);
;             if constexpr (SP2) {
;             PG8_TRIP(true, PG8_WAIT_V(8));
.LBB0_932:
	v_add_u32_e32 v0, 0x10000, v186
	v_add_u32_e32 v188, 0x14000, v186
	ds_read_b128 v[112:115], v0
	ds_read_b128 v[120:123], v0 offset:1024
	ds_read_b128 v[124:127], v0 offset:2048
	ds_read_b128 v[128:131], v0 offset:3072
	ds_read_b128 v[148:151], v188
	ds_read_b128 v[152:155], v188 offset:1024
	ds_read_b128 v[156:159], v188 offset:2048
	ds_read_b128 v[160:163], v188 offset:3072
	s_add_u32 s20, s18, 0xfff80080
	s_addc_u32 s21, s19, -1
	s_cmp_eq_u32 s78, 28
	s_cselect_b32 s24, s7, s20
	s_cselect_b32 s25, s6, s21
	s_cselect_b32 s22, s11, s79
	s_cselect_b32 s23, s9, s82
	s_add_u32 s20, s24, 0x80
	s_addc_u32 s21, s25, 0
	ds_read_b128 v[164:167], v187
	ds_read_b128 v[168:171], v187 offset:1024
	ds_read_b128 v[178:181], v187 offset:2048
	ds_read_b128 v[190:193], v187 offset:3072
	ds_read_b128 v[194:197], v187 offset:4096
	ds_read_b128 v[198:201], v187 offset:5120
	ds_read_b128 v[202:205], v187 offset:6144
	ds_read_b128 v[206:209], v187 offset:7168
	s_mov_b32 m0, s57
	s_nop 0
	global_load_lds_dwordx4 v174, s[18:19]
	s_nop 0
	s_mov_b32 m0, s63
	s_nop 0
	global_load_lds_dwordx4 v176, s[18:19]
	s_waitcnt vmcnt(8)
	s_waitcnt lgkmcnt(0)
	s_barrier
	s_setprio 1
	s_waitcnt lgkmcnt(0)
	v_mfma_f32_16x16x32_bf16 v[144:147], v[112:115], v[164:167], v[144:147]
	v_mfma_f32_16x16x32_bf16 v[140:143], v[124:127], v[164:167], v[140:143]
	s_waitcnt lgkmcnt(5)
	v_mfma_f32_16x16x32_bf16 v[116:119], v[112:115], v[178:181], v[116:119]
	v_mfma_f32_16x16x32_bf16 v[108:111], v[124:127], v[178:181], v[108:111]
	s_waitcnt lgkmcnt(3)
	v_mfma_f32_16x16x32_bf16 v[96:99], v[112:115], v[194:197], v[96:99]
	v_mfma_f32_16x16x32_bf16 v[92:95], v[124:127], v[194:197], v[92:95]
	s_waitcnt lgkmcnt(1)
	v_mfma_f32_16x16x32_bf16 v[80:83], v[112:115], v[202:205], v[80:83]
	v_mfma_f32_16x16x32_bf16 v[76:79], v[124:127], v[202:205], v[76:79]
	v_mfma_f32_16x16x32_bf16 v[144:147], v[120:123], v[168:171], v[144:147]
	v_mfma_f32_16x16x32_bf16 v[140:143], v[128:131], v[168:171], v[140:143]
	v_mfma_f32_16x16x32_bf16 v[116:119], v[120:123], v[190:193], v[116:119]
	v_mfma_f32_16x16x32_bf16 v[108:111], v[128:131], v[190:193], v[108:111]
	v_mfma_f32_16x16x32_bf16 v[96:99], v[120:123], v[198:201], v[96:99]
	v_mfma_f32_16x16x32_bf16 v[92:95], v[128:131], v[198:201], v[92:95]
	s_waitcnt lgkmcnt(0)
	v_mfma_f32_16x16x32_bf16 v[80:83], v[120:123], v[206:209], v[80:83]
	v_mfma_f32_16x16x32_bf16 v[76:79], v[128:131], v[206:209], v[76:79]
	s_setprio 0
	s_setprio 1
	v_mfma_f32_16x16x32_bf16 v[136:139], v[148:151], v[164:167], v[136:139]
	v_mfma_f32_16x16x32_bf16 v[132:135], v[156:159], v[164:167], v[132:135]
	v_mfma_f32_16x16x32_bf16 v[104:107], v[148:151], v[178:181], v[104:107]
	v_mfma_f32_16x16x32_bf16 v[100:103], v[156:159], v[178:181], v[100:103]
	v_mfma_f32_16x16x32_bf16 v[88:91], v[148:151], v[194:197], v[88:91]
	v_mfma_f32_16x16x32_bf16 v[84:87], v[156:159], v[194:197], v[84:87]
	v_mfma_f32_16x16x32_bf16 v[72:75], v[148:151], v[202:205], v[72:75]
	v_mfma_f32_16x16x32_bf16 v[68:71], v[156:159], v[202:205], v[68:71]
	v_mfma_f32_16x16x32_bf16 v[136:139], v[152:155], v[168:171], v[136:139]
	v_mfma_f32_16x16x32_bf16 v[132:135], v[160:163], v[168:171], v[132:135]
	v_mfma_f32_16x16x32_bf16 v[104:107], v[152:155], v[190:193], v[104:107]
	v_mfma_f32_16x16x32_bf16 v[100:103], v[160:163], v[190:193], v[100:103]
	v_mfma_f32_16x16x32_bf16 v[88:91], v[152:155], v[198:201], v[88:91]
	v_mfma_f32_16x16x32_bf16 v[84:87], v[160:163], v[198:201], v[84:87]
	v_mfma_f32_16x16x32_bf16 v[72:75], v[152:155], v[206:209], v[72:75]
	v_mfma_f32_16x16x32_bf16 v[68:71], v[160:163], v[206:209], v[68:71]
	s_setprio 0
	s_barrier
	ds_read_b128 v[164:167], v187 offset:16384
	ds_read_b128 v[168:171], v187 offset:17408
	ds_read_b128 v[178:181], v187 offset:18432
	ds_read_b128 v[190:193], v187 offset:19456
	ds_read_b128 v[194:197], v187 offset:20480
	ds_read_b128 v[198:201], v187 offset:21504
	ds_read_b128 v[202:205], v187 offset:22528
	ds_read_b128 v[206:209], v187 offset:23552
	s_mov_b32 m0, s28
	s_nop 0
	global_load_lds_dwordx4 v175, s[22:23]
	s_add_u32 s88, s22, 0x80000
	s_mov_b32 m0, s29
	s_nop 0
	global_load_lds_dwordx4 v177, s[22:23]
	s_addc_u32 s89, s23, 0
	s_mov_b32 m0, s30
	s_nop 0
	global_load_lds_dwordx4 v175, s[88:89]
	s_nop 0
	s_mov_b32 m0, s31
	s_nop 0
	global_load_lds_dwordx4 v177, s[88:89]
	s_nop 0
	s_mov_b32 m0, s27
	s_nop 0
	global_load_lds_dwordx4 v174, s[24:25]
	s_nop 0
	s_mov_b32 m0, s35
	s_nop 0
	global_load_lds_dwordx4 v176, s[24:25]
	s_waitcnt vmcnt(8)
	s_waitcnt lgkmcnt(0)
	s_barrier
	s_setprio 1
	s_waitcnt lgkmcnt(0)
	v_mfma_f32_16x16x32_bf16 v[64:67], v[112:115], v[164:167], v[64:67]
	v_mfma_f32_16x16x32_bf16 v[60:63], v[124:127], v[164:167], v[60:63]
	s_waitcnt lgkmcnt(5)
	v_mfma_f32_16x16x32_bf16 v[48:51], v[112:115], v[178:181], v[48:51]
	v_mfma_f32_16x16x32_bf16 v[44:47], v[124:127], v[178:181], v[44:47]
	s_waitcnt lgkmcnt(3)
	v_mfma_f32_16x16x32_bf16 v[32:35], v[112:115], v[194:197], v[32:35]
	v_mfma_f32_16x16x32_bf16 v[28:31], v[124:127], v[194:197], v[28:31]
	s_waitcnt lgkmcnt(1)
	v_mfma_f32_16x16x32_bf16 v[16:19], v[112:115], v[202:205], v[16:19]
	v_mfma_f32_16x16x32_bf16 v[12:15], v[124:127], v[202:205], v[12:15]
	v_mfma_f32_16x16x32_bf16 v[64:67], v[120:123], v[168:171], v[64:67]
	v_mfma_f32_16x16x32_bf16 v[60:63], v[128:131], v[168:171], v[60:63]
	v_mfma_f32_16x16x32_bf16 v[48:51], v[120:123], v[190:193], v[48:51]
	v_mfma_f32_16x16x32_bf16 v[44:47], v[128:131], v[190:193], v[44:47]
	v_mfma_f32_16x16x32_bf16 v[32:35], v[120:123], v[198:201], v[32:35]
	v_mfma_f32_16x16x32_bf16 v[28:31], v[128:131], v[198:201], v[28:31]
	s_waitcnt lgkmcnt(0)
	v_mfma_f32_16x16x32_bf16 v[16:19], v[120:123], v[206:209], v[16:19]
	v_mfma_f32_16x16x32_bf16 v[12:15], v[128:131], v[206:209], v[12:15]
	s_setprio 0
	s_setprio 1
	v_mfma_f32_16x16x32_bf16 v[56:59], v[148:151], v[164:167], v[56:59]
	v_mfma_f32_16x16x32_bf16 v[52:55], v[156:159], v[164:167], v[52:55]
	v_mfma_f32_16x16x32_bf16 v[40:43], v[148:151], v[178:181], v[40:43]
	v_mfma_f32_16x16x32_bf16 v[36:39], v[156:159], v[178:181], v[36:39]
	v_mfma_f32_16x16x32_bf16 v[24:27], v[148:151], v[194:197], v[24:27]
	v_mfma_f32_16x16x32_bf16 v[20:23], v[156:159], v[194:197], v[20:23]
	v_mfma_f32_16x16x32_bf16 v[8:11], v[148:151], v[202:205], v[8:11]
	v_mfma_f32_16x16x32_bf16 v[2:5], v[156:159], v[202:205], v[4:7]
	v_mfma_f32_16x16x32_bf16 v[56:59], v[152:155], v[168:171], v[56:59]
	v_mfma_f32_16x16x32_bf16 v[52:55], v[160:163], v[168:171], v[52:55]
	v_mfma_f32_16x16x32_bf16 v[40:43], v[152:155], v[190:193], v[40:43]
	v_mfma_f32_16x16x32_bf16 v[36:39], v[160:163], v[190:193], v[36:39]
	v_mfma_f32_16x16x32_bf16 v[24:27], v[152:155], v[198:201], v[24:27]
	v_mfma_f32_16x16x32_bf16 v[20:23], v[160:163], v[198:201], v[20:23]
	v_mfma_f32_16x16x32_bf16 v[8:11], v[152:155], v[206:209], v[8:11]
	v_mfma_f32_16x16x32_bf16 v[2:5], v[160:163], v[206:209], v[2:5]
	s_setprio 0
	s_barrier
	v_add_u32_e32 v189, 0x18000, v186
	v_add_u32_e32 v190, 0x1c000, v186
	ds_read_b128 v[112:115], v189
	ds_read_b128 v[120:123], v189 offset:1024
	ds_read_b128 v[124:127], v189 offset:2048
	ds_read_b128 v[128:131], v189 offset:3072
	ds_read_b128 v[148:151], v190
	ds_read_b128 v[152:155], v190 offset:1024
	ds_read_b128 v[156:159], v190 offset:2048
	ds_read_b128 v[160:163], v190 offset:3072
	ds_read_b128 v[164:167], v187 offset:32768
	ds_read_b128 v[168:171], v187 offset:33792
	ds_read_b128 v[178:181], v187 offset:34816
	ds_read_b128 v[192:195], v187 offset:35840
	ds_read_b128 v[196:199], v187 offset:36864
	ds_read_b128 v[200:203], v187 offset:37888
	ds_read_b128 v[204:207], v187 offset:38912
	ds_read_b128 v[208:211], v187 offset:39936
	s_add_u32 s24, s24, 0x80000
	s_addc_u32 s25, s25, 0
	s_mov_b32 m0, s36
	s_nop 0
	global_load_lds_dwordx4 v174, s[24:25]
	s_nop 0
	s_mov_b32 m0, s37
	s_nop 0
	global_load_lds_dwordx4 v176, s[24:25]
	s_waitcnt vmcnt(8)
	s_waitcnt lgkmcnt(0)
	s_barrier
	s_setprio 1
	s_waitcnt lgkmcnt(0)
	v_mfma_f32_16x16x32_bf16 v[144:147], v[112:115], v[164:167], v[144:147]
	v_mfma_f32_16x16x32_bf16 v[140:143], v[124:127], v[164:167], v[140:143]
	s_waitcnt lgkmcnt(5)
	v_mfma_f32_16x16x32_bf16 v[116:119], v[112:115], v[178:181], v[116:119]
	v_mfma_f32_16x16x32_bf16 v[108:111], v[124:127], v[178:181], v[108:111]
	s_waitcnt lgkmcnt(3)
	v_mfma_f32_16x16x32_bf16 v[96:99], v[112:115], v[196:199], v[96:99]
	v_mfma_f32_16x16x32_bf16 v[92:95], v[124:127], v[196:199], v[92:95]
	s_waitcnt lgkmcnt(1)
	v_mfma_f32_16x16x32_bf16 v[80:83], v[112:115], v[204:207], v[80:83]
	v_mfma_f32_16x16x32_bf16 v[76:79], v[124:127], v[204:207], v[76:79]
	v_mfma_f32_16x16x32_bf16 v[144:147], v[120:123], v[168:171], v[144:147]
	v_mfma_f32_16x16x32_bf16 v[140:143], v[128:131], v[168:171], v[140:143]
	v_mfma_f32_16x16x32_bf16 v[116:119], v[120:123], v[192:195], v[116:119]
	v_mfma_f32_16x16x32_bf16 v[108:111], v[128:131], v[192:195], v[108:111]
	v_mfma_f32_16x16x32_bf16 v[96:99], v[120:123], v[200:203], v[96:99]
	v_mfma_f32_16x16x32_bf16 v[92:95], v[128:131], v[200:203], v[92:95]
	s_waitcnt lgkmcnt(0)
	v_mfma_f32_16x16x32_bf16 v[80:83], v[120:123], v[208:211], v[80:83]
	v_mfma_f32_16x16x32_bf16 v[76:79], v[128:131], v[208:211], v[76:79]
	s_setprio 0
	s_setprio 1
	v_mfma_f32_16x16x32_bf16 v[136:139], v[148:151], v[164:167], v[136:139]
	v_mfma_f32_16x16x32_bf16 v[132:135], v[156:159], v[164:167], v[132:135]
	v_mfma_f32_16x16x32_bf16 v[104:107], v[148:151], v[178:181], v[104:107]
	v_mfma_f32_16x16x32_bf16 v[100:103], v[156:159], v[178:181], v[100:103]
	v_mfma_f32_16x16x32_bf16 v[88:91], v[148:151], v[196:199], v[88:91]
	v_mfma_f32_16x16x32_bf16 v[84:87], v[156:159], v[196:199], v[84:87]
	v_mfma_f32_16x16x32_bf16 v[72:75], v[148:151], v[204:207], v[72:75]
	v_mfma_f32_16x16x32_bf16 v[68:71], v[156:159], v[204:207], v[68:71]
	v_mfma_f32_16x16x32_bf16 v[136:139], v[152:155], v[168:171], v[136:139]
	v_mfma_f32_16x16x32_bf16 v[132:135], v[160:163], v[168:171], v[132:135]
	v_mfma_f32_16x16x32_bf16 v[104:107], v[152:155], v[192:195], v[104:107]
	v_mfma_f32_16x16x32_bf16 v[100:103], v[160:163], v[192:195], v[100:103]
	v_mfma_f32_16x16x32_bf16 v[88:91], v[152:155], v[200:203], v[88:91]
	v_mfma_f32_16x16x32_bf16 v[84:87], v[160:163], v[200:203], v[84:87]
	v_mfma_f32_16x16x32_bf16 v[72:75], v[152:155], v[208:211], v[72:75]
	v_mfma_f32_16x16x32_bf16 v[68:71], v[160:163], v[208:211], v[68:71]
	s_setprio 0
	s_barrier
; #define ER_LOAD(dst, ai, mp) do { _Pragma("unroll") for (int mm = 0; mm < 2; ++mm) _Pragma("unroll") for (int bj = 0; bj < 2; ++bj) \
;             dst[mm][bj] = *(const u32x4*)(xb + (size_t)((ai) * HALF + (2 * (mp) + mm) * 16) * 2048 + bj * HALF); } while (0)
;     __device__ __forceinline__ void operator()(const f32x4 (&acc)[2][2][4][2], const Unit& u, int wr, int wc, int fr, int fq) const {
;         const int row0 = u.pm * BM + wr * 64 + fr, col0 = u.pn * BM + wc * 32 + 8 * fq;
;         const int b = (u.pm < n_lat_panels) ? (u.pm >> 4) : 4;
;         const float* g = gate + (size_t)b * gstride + col0;
;         bf16_t* xb = X + (size_t)row0 * 2048 + col0;
;         f32x4 gv[2][2];
; #pragma unroll
;         for (int bj = 0; bj < 2; ++bj)
; #pragma unroll
;             for (int n = 0; n < 2; ++n) gv[bj][n] = *(const f32x4*)(g + bj * HALF + 4 * n);
;         u32x4 xa[2][2], xc[2][2];
;     ...
;         ER_LOAD(xa, 0, 0); ER_LOAD(xc, 0, 1);
	ds_read_b128 v[164:167], v187 offset:49152
	ds_read_b128 v[168:171], v187 offset:50176
	ds_read_b128 v[178:181], v187 offset:51200
	ds_read_b128 v[192:195], v187 offset:52224
	ds_read_b128 v[196:199], v187 offset:53248
	ds_read_b128 v[200:203], v187 offset:54272
	ds_read_b128 v[204:207], v187 offset:55296
	ds_read_b128 v[208:211], v187 offset:56320
	s_add_u32 s24, s22, 0x80
	s_addc_u32 s25, s23, 0
	s_mov_b32 m0, s44
	s_nop 0
	global_load_lds_dwordx4 v175, s[24:25]
	s_add_u32 s22, s22, 0x80080
	s_mov_b32 m0, s48
	s_nop 0
	global_load_lds_dwordx4 v177, s[24:25]
	s_addc_u32 s23, s23, 0
	s_mov_b32 m0, s52
	s_nop 0
	global_load_lds_dwordx4 v175, s[22:23]
	s_nop 0
	s_mov_b32 m0, s53
	s_nop 0
	global_load_lds_dwordx4 v177, s[22:23]
	s_nop 0
	s_mov_b32 m0, s49
	s_nop 0
	global_load_lds_dwordx4 v174, s[20:21]
	s_nop 0
	s_mov_b32 m0, s51
	s_nop 0
	global_load_lds_dwordx4 v176, s[20:21]
	s_waitcnt vmcnt(8)
	s_waitcnt lgkmcnt(0)
	s_barrier
	s_setprio 1
	s_waitcnt lgkmcnt(0)
	v_mfma_f32_16x16x32_bf16 v[64:67], v[112:115], v[164:167], v[64:67]
	v_mfma_f32_16x16x32_bf16 v[60:63], v[124:127], v[164:167], v[60:63]
	s_waitcnt lgkmcnt(5)
	v_mfma_f32_16x16x32_bf16 v[48:51], v[112:115], v[178:181], v[48:51]
	v_mfma_f32_16x16x32_bf16 v[44:47], v[124:127], v[178:181], v[44:47]
	s_waitcnt lgkmcnt(3)
	v_mfma_f32_16x16x32_bf16 v[32:35], v[112:115], v[196:199], v[32:35]
	v_mfma_f32_16x16x32_bf16 v[28:31], v[124:127], v[196:199], v[28:31]
	s_waitcnt lgkmcnt(1)
	v_mfma_f32_16x16x32_bf16 v[16:19], v[112:115], v[204:207], v[16:19]
	v_mfma_f32_16x16x32_bf16 v[12:15], v[124:127], v[204:207], v[12:15]
	v_mfma_f32_16x16x32_bf16 v[64:67], v[120:123], v[168:171], v[64:67]
	v_mfma_f32_16x16x32_bf16 v[60:63], v[128:131], v[168:171], v[60:63]
	v_mfma_f32_16x16x32_bf16 v[48:51], v[120:123], v[192:195], v[48:51]
	v_mfma_f32_16x16x32_bf16 v[44:47], v[128:131], v[192:195], v[44:47]
	v_mfma_f32_16x16x32_bf16 v[32:35], v[120:123], v[200:203], v[32:35]
	v_mfma_f32_16x16x32_bf16 v[28:31], v[128:131], v[200:203], v[28:31]
	s_waitcnt lgkmcnt(0)
	v_mfma_f32_16x16x32_bf16 v[16:19], v[120:123], v[208:211], v[16:19]
	v_mfma_f32_16x16x32_bf16 v[12:15], v[128:131], v[208:211], v[12:15]
	s_setprio 0
	s_setprio 1
	v_mfma_f32_16x16x32_bf16 v[56:59], v[148:151], v[164:167], v[56:59]
	v_mfma_f32_16x16x32_bf16 v[52:55], v[156:159], v[164:167], v[52:55]
	v_mfma_f32_16x16x32_bf16 v[40:43], v[148:151], v[178:181], v[40:43]
	v_mfma_f32_16x16x32_bf16 v[36:39], v[156:159], v[178:181], v[36:39]
	v_mfma_f32_16x16x32_bf16 v[24:27], v[148:151], v[196:199], v[24:27]
	v_mfma_f32_16x16x32_bf16 v[20:23], v[156:159], v[196:199], v[20:23]
	v_mfma_f32_16x16x32_bf16 v[6:9], v[148:151], v[204:207], v[8:11]
	v_mfma_f32_16x16x32_bf16 v[2:5], v[156:159], v[204:207], v[2:5]
	v_mfma_f32_16x16x32_bf16 v[56:59], v[152:155], v[168:171], v[56:59]
	v_mfma_f32_16x16x32_bf16 v[52:55], v[160:163], v[168:171], v[52:55]
	v_mfma_f32_16x16x32_bf16 v[40:43], v[152:155], v[192:195], v[40:43]
	v_mfma_f32_16x16x32_bf16 v[36:39], v[160:163], v[192:195], v[36:39]
	v_mfma_f32_16x16x32_bf16 v[24:27], v[152:155], v[200:203], v[24:27]
	v_mfma_f32_16x16x32_bf16 v[20:23], v[160:163], v[200:203], v[20:23]
	v_mfma_f32_16x16x32_bf16 v[8:11], v[152:155], v[208:211], v[6:9]
	v_mfma_f32_16x16x32_bf16 v[4:7], v[160:163], v[208:211], v[2:5]
	s_setprio 0
	s_barrier
	s_add_i32 s78, s78, 2
	s_add_u32 s79, s79, 0x100
	s_addc_u32 s82, s82, 0
	s_add_u32 s18, s18, 0x100
	s_addc_u32 s19, s19, 0
	s_cmp_gt_u32 s78, 29
	s_cbranch_scc0 .LBB0_932
	s_add_u32 s18, s7, 0x80080
	s_addc_u32 s19, s6, 0
	s_min_i32 s6, s69, 64
	v_lshl_add_u32 v2, s69, 8, v184
	s_ashr_i32 s6, s6, 4
	s_mul_hi_i32 s7, s6, 0xc000
	s_mul_i32 s6, s6, 0xc000
	v_ashrrev_i32_e32 v3, 31, v2
	s_mov_b32 m0, s57
	s_nop 0
	global_load_lds_dwordx4 v174, s[18:19]
	v_lshl_or_b32 v148, s67, 8, v185
	s_add_u32 s6, s40, s6
	v_lshlrev_b64 v[2:3], 12, v[2:3]
	s_mov_b32 m0, s63
	s_nop 0
	global_load_lds_dwordx4 v176, s[18:19]
	s_addc_u32 s7, s41, s7
	v_ashrrev_i32_e32 v149, 31, v148
	v_lshl_add_u64 v[2:3], s[80:81], 0, v[2:3]
	v_lshl_add_u64 v[112:113], v[148:149], 2, s[6:7]
	v_lshl_add_u64 v[2:3], v[148:149], 1, v[2:3]
	global_load_dwordx4 v[128:131], v[112:113], off
	global_load_dwordx4 v[124:127], v[112:113], off offset:16
	global_load_dwordx4 v[120:123], v[112:113], off offset:512
	global_load_dwordx4 v[112:115], v[112:113], off offset:528
	global_load_dwordx4 v[178:181], v[2:3], off
	global_load_dwordx4 v[192:195], v[2:3], off offset:256
	v_add_co_u32_e32 v172, vcc, 0x10000, v2
	s_nop 1
	v_addc_co_u32_e32 v173, vcc, 0, v3, vcc
	global_load_dwordx4 v[196:199], v[172:173], off
	global_load_dwordx4 v[164:167], v[172:173], off offset:256
	v_add_co_u32_e32 v170, vcc, 0x20000, v2
	s_nop 1
	v_addc_co_u32_e32 v171, vcc, 0, v3, vcc
	global_load_dwordx4 v[160:163], v[170:171], off
	global_load_dwordx4 v[156:159], v[170:171], off offset:256
	v_add_co_u32_e32 v168, vcc, 0x30000, v2
	s_nop 1
	v_addc_co_u32_e32 v169, vcc, 0, v3, vcc
	global_load_dwordx4 v[152:155], v[168:169], off
	global_load_dwordx4 v[148:151], v[168:169], off offset:256
	v_add_co_u32_e32 v244, vcc, 0x80000, v2
	s_nop 1
	v_addc_co_u32_e32 v245, vcc, 0, v3, vcc
	global_load_dwordx4 v[212:215], v[244:245], off
	global_load_dwordx4 v[216:219], v[244:245], off offset:256
	v_add_co_u32_e32 v246, vcc, 0x90000, v2
	s_nop 1
	v_addc_co_u32_e32 v247, vcc, 0, v3, vcc
	global_load_dwordx4 v[220:223], v[246:247], off
	global_load_dwordx4 v[224:227], v[246:247], off offset:256
	v_add_co_u32_e32 v248, vcc, 0xa0000, v2
	s_nop 1
	v_addc_co_u32_e32 v249, vcc, 0, v3, vcc
	global_load_dwordx4 v[228:231], v[248:249], off
	global_load_dwordx4 v[232:235], v[248:249], off offset:256
	v_add_co_u32_e32 v250, vcc, 0xb0000, v2
	s_nop 1
	v_addc_co_u32_e32 v251, vcc, 0, v3, vcc
	global_load_dwordx4 v[236:239], v[250:251], off
	global_load_dwordx4 v[240:243], v[250:251], off offset:256
	s_nop 0
	s_nop 0
	s_mov_b32 s6, 0x10000
	s_mov_b32 s6, 0x90000
	s_nop 0
	s_mov_b64 s[18:19], -1
	s_nop 0
	s_waitcnt vmcnt(15)
; #define ER_LOAD(dst, ai, mp) do { _Pragma("unroll") for (int mm = 0; mm < 2; ++mm) _Pragma("unroll") for (int bj = 0; bj < 2; ++bj) \
;             dst[mm][bj] = *(const u32x4*)(xb + (size_t)((ai) * HALF + (2 * (mp) + mm) * 16) * 2048 + bj * HALF); } while (0)
;     __device__ __forceinline__ void operator()(const f32x4 (&acc)[2][2][4][2], const Unit& u, int wr, int wc, int fr, int fq) const {
;     ...
;         ER_LOAD(xa, 0, 0); ER_LOAD(xc, 0, 1);
;         ER_STORE(xa, 0, 0); ER_LOAD(xa, 1, 0);
;         ER_STORE(xc, 0, 1); ER_LOAD(xc, 1, 1);
;         ER_STORE(xa, 1, 0); ER_STORE(xc, 1, 1);
	v_cvt_f32_f16_e32 v200, v178
	v_cvt_f32_f16_sdwa v201, v178 dst_sel:DWORD dst_unused:UNUSED_PAD src0_sel:WORD_1
	v_cvt_f32_f16_e32 v178, v179
	v_cvt_f32_f16_sdwa v179, v179 dst_sel:DWORD dst_unused:UNUSED_PAD src0_sel:WORD_1
	v_pk_fma_f32 v[144:145], v[144:145], v[128:129], v[200:201]
	v_pk_fma_f32 v[146:147], v[146:147], v[130:131], v[178:179]
	v_cvt_f32_f16_e32 v178, v180
	v_cvt_f32_f16_sdwa v179, v180 dst_sel:DWORD dst_unused:UNUSED_PAD src0_sel:WORD_1
	v_cvt_f32_f16_e32 v180, v181
	v_cvt_f32_f16_sdwa v181, v181 dst_sel:DWORD dst_unused:UNUSED_PAD src0_sel:WORD_1
	v_pk_fma_f32 v[180:181], v[142:143], v[126:127], v[180:181]
	v_pk_fma_f32 v[142:143], v[140:141], v[124:125], v[178:179]
	v_cvt_pk_f16_f32 v140, v144, v145
	v_cvt_pk_f16_f32 v141, v146, v147
	v_cvt_pk_f16_f32 v142, v142, v143
	v_cvt_pk_f16_f32 v143, v180, v181
	global_store_dwordx4 v[2:3], v[140:143], off sc1
	s_nop 1
	s_waitcnt vmcnt(15)
	v_cvt_f32_f16_e32 v140, v192
	v_cvt_f32_f16_sdwa v141, v192 dst_sel:DWORD dst_unused:UNUSED_PAD src0_sel:WORD_1
	v_cvt_f32_f16_e32 v142, v193
	v_cvt_f32_f16_sdwa v143, v193 dst_sel:DWORD dst_unused:UNUSED_PAD src0_sel:WORD_1
	v_pk_fma_f32 v[136:137], v[136:137], v[120:121], v[140:141]
	v_cvt_f32_f16_e32 v140, v194
	v_pk_fma_f32 v[138:139], v[138:139], v[122:123], v[142:143]
	v_cvt_f32_f16_sdwa v141, v194 dst_sel:DWORD dst_unused:UNUSED_PAD src0_sel:WORD_1
	v_cvt_f32_f16_e32 v142, v195
	v_cvt_f32_f16_sdwa v143, v195 dst_sel:DWORD dst_unused:UNUSED_PAD src0_sel:WORD_1
	v_pk_fma_f32 v[142:143], v[134:135], v[114:115], v[142:143]
	v_pk_fma_f32 v[134:135], v[132:133], v[112:113], v[140:141]
	v_cvt_pk_f16_f32 v132, v136, v137
	v_cvt_pk_f16_f32 v133, v138, v139
	v_cvt_pk_f16_f32 v134, v134, v135
	v_cvt_pk_f16_f32 v135, v142, v143
	global_store_dwordx4 v[2:3], v[132:135], off offset:256 sc1
	s_waitcnt vmcnt(13)
	v_cvt_f32_f16_e32 v136, v160
	v_cvt_f32_f16_sdwa v137, v160 dst_sel:DWORD dst_unused:UNUSED_PAD src0_sel:WORD_1
	v_cvt_f32_f16_e32 v132, v196
	v_cvt_f32_f16_sdwa v133, v196 dst_sel:DWORD dst_unused:UNUSED_PAD src0_sel:WORD_1
	v_cvt_f32_f16_e32 v134, v197
	v_cvt_f32_f16_sdwa v135, v197 dst_sel:DWORD dst_unused:UNUSED_PAD src0_sel:WORD_1
	v_cvt_f32_f16_e32 v138, v161
	v_pk_fma_f32 v[116:117], v[116:117], v[128:129], v[132:133]
	v_cvt_f32_f16_e32 v132, v198
	v_pk_fma_f32 v[118:119], v[118:119], v[130:131], v[134:135]
	v_cvt_f32_f16_sdwa v133, v198 dst_sel:DWORD dst_unused:UNUSED_PAD src0_sel:WORD_1
	v_cvt_f32_f16_e32 v134, v199
	v_cvt_f32_f16_sdwa v135, v199 dst_sel:DWORD dst_unused:UNUSED_PAD src0_sel:WORD_1
	v_cvt_f32_f16_sdwa v139, v161 dst_sel:DWORD dst_unused:UNUSED_PAD src0_sel:WORD_1
	v_pk_fma_f32 v[96:97], v[96:97], v[128:129], v[136:137]
	v_cvt_f32_f16_e32 v136, v162
	v_pk_fma_f32 v[134:135], v[110:111], v[126:127], v[134:135]
	v_pk_fma_f32 v[110:111], v[108:109], v[124:125], v[132:133]
	v_cvt_pk_f16_f32 v108, v116, v117
	v_cvt_pk_f16_f32 v109, v118, v119
	v_cvt_pk_f16_f32 v110, v110, v111
	v_cvt_pk_f16_f32 v111, v134, v135
	global_store_dwordx4 v[172:173], v[108:111], off sc1
	v_add_co_u32_e32 v134, vcc, s83, v2
	s_nop 0
	v_cvt_f32_f16_e32 v108, v164
	v_cvt_f32_f16_sdwa v109, v164 dst_sel:DWORD dst_unused:UNUSED_PAD src0_sel:WORD_1
	v_cvt_f32_f16_e32 v110, v165
	v_cvt_f32_f16_sdwa v111, v165 dst_sel:DWORD dst_unused:UNUSED_PAD src0_sel:WORD_1
	v_addc_co_u32_e32 v135, vcc, 0, v3, vcc
	v_pk_fma_f32 v[104:105], v[104:105], v[120:121], v[108:109]
	v_pk_fma_f32 v[106:107], v[106:107], v[122:123], v[110:111]
	v_cvt_f32_f16_e32 v108, v166
	v_cvt_f32_f16_sdwa v109, v166 dst_sel:DWORD dst_unused:UNUSED_PAD src0_sel:WORD_1
	v_cvt_f32_f16_e32 v110, v167
	v_cvt_f32_f16_sdwa v111, v167 dst_sel:DWORD dst_unused:UNUSED_PAD src0_sel:WORD_1
	v_pk_fma_f32 v[98:99], v[98:99], v[130:131], v[138:139]
	v_cvt_f32_f16_sdwa v137, v162 dst_sel:DWORD dst_unused:UNUSED_PAD src0_sel:WORD_1
	v_cvt_f32_f16_e32 v138, v163
	v_pk_fma_f32 v[110:111], v[102:103], v[114:115], v[110:111]
	v_pk_fma_f32 v[102:103], v[100:101], v[112:113], v[108:109]
	v_cvt_pk_f16_f32 v100, v104, v105
	v_cvt_pk_f16_f32 v101, v106, v107
	v_cvt_pk_f16_f32 v102, v102, v103
	v_cvt_pk_f16_f32 v103, v110, v111
	global_store_dwordx4 v[172:173], v[100:103], off offset:256 sc1
	v_cvt_f32_f16_sdwa v139, v163 dst_sel:DWORD dst_unused:UNUSED_PAD src0_sel:WORD_1
	v_add_co_u32_e32 v132, vcc, s6, v2
	s_mov_b32 s6, 0xa0000
	v_pk_fma_f32 v[138:139], v[94:95], v[126:127], v[138:139]
	v_pk_fma_f32 v[94:95], v[92:93], v[124:125], v[136:137]
	v_addc_co_u32_e32 v133, vcc, 0, v3, vcc
	v_cvt_pk_f16_f32 v92, v96, v97
	v_cvt_pk_f16_f32 v93, v98, v99
	v_cvt_pk_f16_f32 v94, v94, v95
	v_cvt_pk_f16_f32 v95, v138, v139
	s_nop 0
	global_store_dwordx4 v[170:171], v[92:95], off sc1
	s_nop 1
	s_waitcnt vmcnt(15)
	v_cvt_f32_f16_e32 v92, v156
	v_cvt_f32_f16_sdwa v93, v156 dst_sel:DWORD dst_unused:UNUSED_PAD src0_sel:WORD_1
	v_cvt_f32_f16_e32 v94, v157
	v_cvt_f32_f16_sdwa v95, v157 dst_sel:DWORD dst_unused:UNUSED_PAD src0_sel:WORD_1
	v_pk_fma_f32 v[88:89], v[88:89], v[120:121], v[92:93]
	v_cvt_f32_f16_e32 v92, v158
	v_pk_fma_f32 v[90:91], v[90:91], v[122:123], v[94:95]
	v_cvt_f32_f16_sdwa v93, v158 dst_sel:DWORD dst_unused:UNUSED_PAD src0_sel:WORD_1
	v_cvt_f32_f16_e32 v94, v159
	v_cvt_f32_f16_sdwa v95, v159 dst_sel:DWORD dst_unused:UNUSED_PAD src0_sel:WORD_1
	v_pk_fma_f32 v[94:95], v[86:87], v[114:115], v[94:95]
	v_pk_fma_f32 v[86:87], v[84:85], v[112:113], v[92:93]
	v_cvt_pk_f16_f32 v84, v88, v89
	v_cvt_pk_f16_f32 v85, v90, v91
	v_cvt_pk_f16_f32 v86, v86, v87
	v_cvt_pk_f16_f32 v87, v94, v95
	global_store_dwordx4 v[170:171], v[84:87], off offset:256 sc1
	s_waitcnt vmcnt(13)
; #define ER_LOAD(dst, ai, mp) do { _Pragma("unroll") for (int mm = 0; mm < 2; ++mm) _Pragma("unroll") for (int bj = 0; bj < 2; ++bj) \
;             dst[mm][bj] = *(const u32x4*)(xb + (size_t)((ai) * HALF + (2 * (mp) + mm) * 16) * 2048 + bj * HALF); } while (0)
;     __device__ __forceinline__ void operator()(const f32x4 (&acc)[2][2][4][2], const Unit& u, int wr, int wc, int fr, int fq) const {
;     ...
;         ER_LOAD(xa, 0, 0); ER_LOAD(xc, 0, 1);
;         ER_STORE(xa, 0, 0); ER_LOAD(xa, 1, 0);
;         ER_STORE(xc, 0, 1); ER_LOAD(xc, 1, 1);
;         ER_STORE(xa, 1, 0); ER_STORE(xc, 1, 1);
	v_cvt_f32_f16_e32 v88, v213
	v_cvt_f32_f16_e32 v84, v152
	v_cvt_f32_f16_sdwa v85, v152 dst_sel:DWORD dst_unused:UNUSED_PAD src0_sel:WORD_1
	v_cvt_f32_f16_e32 v86, v153
	v_cvt_f32_f16_sdwa v87, v153 dst_sel:DWORD dst_unused:UNUSED_PAD src0_sel:WORD_1
	v_cvt_f32_f16_sdwa v89, v213 dst_sel:DWORD dst_unused:UNUSED_PAD src0_sel:WORD_1
	v_pk_fma_f32 v[80:81], v[80:81], v[128:129], v[84:85]
	v_cvt_f32_f16_e32 v84, v154
	v_pk_fma_f32 v[82:83], v[82:83], v[130:131], v[86:87]
	v_cvt_f32_f16_sdwa v85, v154 dst_sel:DWORD dst_unused:UNUSED_PAD src0_sel:WORD_1
	v_cvt_f32_f16_e32 v86, v155
	v_cvt_f32_f16_sdwa v87, v155 dst_sel:DWORD dst_unused:UNUSED_PAD src0_sel:WORD_1
	v_pk_fma_f32 v[66:67], v[66:67], v[130:131], v[88:89]
	v_cvt_f32_f16_e32 v88, v215
	v_cvt_f32_f16_sdwa v89, v215 dst_sel:DWORD dst_unused:UNUSED_PAD src0_sel:WORD_1
	v_pk_fma_f32 v[86:87], v[78:79], v[126:127], v[86:87]
	v_pk_fma_f32 v[78:79], v[76:77], v[124:125], v[84:85]
	v_cvt_pk_f16_f32 v76, v80, v81
	v_cvt_pk_f16_f32 v77, v82, v83
	v_cvt_pk_f16_f32 v78, v78, v79
	v_cvt_pk_f16_f32 v79, v86, v87
	global_store_dwordx4 v[168:169], v[76:79], off sc1
	v_add_co_u32_e32 v84, vcc, s6, v2
	s_nop 0
	v_cvt_f32_f16_e32 v76, v148
	v_cvt_f32_f16_sdwa v77, v148 dst_sel:DWORD dst_unused:UNUSED_PAD src0_sel:WORD_1
	v_cvt_f32_f16_e32 v78, v149
	v_cvt_f32_f16_sdwa v79, v149 dst_sel:DWORD dst_unused:UNUSED_PAD src0_sel:WORD_1
	v_addc_co_u32_e32 v85, vcc, 0, v3, vcc
	v_pk_fma_f32 v[72:73], v[72:73], v[120:121], v[76:77]
	v_pk_fma_f32 v[74:75], v[74:75], v[122:123], v[78:79]
	v_cvt_f32_f16_e32 v76, v150
	v_cvt_f32_f16_sdwa v77, v150 dst_sel:DWORD dst_unused:UNUSED_PAD src0_sel:WORD_1
	v_cvt_f32_f16_e32 v78, v151
	v_cvt_f32_f16_sdwa v79, v151 dst_sel:DWORD dst_unused:UNUSED_PAD src0_sel:WORD_1
	s_mov_b32 s6, 0xb0000
	v_add_co_u32_e32 v2, vcc, s6, v2
	v_pk_fma_f32 v[78:79], v[70:71], v[114:115], v[78:79]
	v_pk_fma_f32 v[70:71], v[68:69], v[112:113], v[76:77]
	v_cvt_pk_f16_f32 v68, v72, v73
	v_cvt_pk_f16_f32 v69, v74, v75
	v_cvt_pk_f16_f32 v70, v70, v71
	v_cvt_pk_f16_f32 v71, v78, v79
	global_store_dwordx4 v[168:169], v[68:71], off offset:256 sc1
	v_addc_co_u32_e32 v3, vcc, 0, v3, vcc
	v_cvt_f32_f16_e32 v86, v212
	v_cvt_f32_f16_sdwa v87, v212 dst_sel:DWORD dst_unused:UNUSED_PAD src0_sel:WORD_1
	v_pk_fma_f32 v[88:89], v[62:63], v[126:127], v[88:89]
	s_and_b64 vcc, s[16:17], exec
	v_pk_fma_f32 v[64:65], v[64:65], v[128:129], v[86:87]
	v_cvt_f32_f16_e32 v86, v214
	v_cvt_f32_f16_sdwa v87, v214 dst_sel:DWORD dst_unused:UNUSED_PAD src0_sel:WORD_1
	v_pk_fma_f32 v[62:63], v[60:61], v[124:125], v[86:87]
	v_cvt_pk_f16_f32 v60, v64, v65
	v_cvt_pk_f16_f32 v61, v66, v67
	v_cvt_pk_f16_f32 v62, v62, v63
	v_cvt_pk_f16_f32 v63, v88, v89
	global_store_dwordx4 v[134:135], v[60:63], off sc1
	s_nop 1
	s_waitcnt vmcnt(15)
	v_cvt_f32_f16_e32 v60, v216
	v_cvt_f32_f16_sdwa v61, v216 dst_sel:DWORD dst_unused:UNUSED_PAD src0_sel:WORD_1
	v_cvt_f32_f16_e32 v62, v217
	v_cvt_f32_f16_sdwa v63, v217 dst_sel:DWORD dst_unused:UNUSED_PAD src0_sel:WORD_1
	v_pk_fma_f32 v[56:57], v[56:57], v[120:121], v[60:61]
	v_cvt_f32_f16_e32 v60, v218
	v_pk_fma_f32 v[58:59], v[58:59], v[122:123], v[62:63]
	v_cvt_f32_f16_sdwa v61, v218 dst_sel:DWORD dst_unused:UNUSED_PAD src0_sel:WORD_1
	v_cvt_f32_f16_e32 v62, v219
	v_cvt_f32_f16_sdwa v63, v219 dst_sel:DWORD dst_unused:UNUSED_PAD src0_sel:WORD_1
	v_pk_fma_f32 v[62:63], v[54:55], v[114:115], v[62:63]
	v_pk_fma_f32 v[54:55], v[52:53], v[112:113], v[60:61]
	v_cvt_pk_f16_f32 v52, v56, v57
	v_cvt_pk_f16_f32 v53, v58, v59
	v_cvt_pk_f16_f32 v54, v54, v55
	v_cvt_pk_f16_f32 v55, v62, v63
	global_store_dwordx4 v[134:135], v[52:55], off offset:256 sc1
	s_nop 1
	s_waitcnt vmcnt(15)
	v_cvt_f32_f16_e32 v52, v220
	v_cvt_f32_f16_sdwa v53, v220 dst_sel:DWORD dst_unused:UNUSED_PAD src0_sel:WORD_1
	v_cvt_f32_f16_e32 v54, v221
	v_cvt_f32_f16_sdwa v55, v221 dst_sel:DWORD dst_unused:UNUSED_PAD src0_sel:WORD_1
	v_pk_fma_f32 v[48:49], v[48:49], v[128:129], v[52:53]
	v_cvt_f32_f16_e32 v52, v222
	v_pk_fma_f32 v[50:51], v[50:51], v[130:131], v[54:55]
	v_cvt_f32_f16_sdwa v53, v222 dst_sel:DWORD dst_unused:UNUSED_PAD src0_sel:WORD_1
	v_cvt_f32_f16_e32 v54, v223
	v_cvt_f32_f16_sdwa v55, v223 dst_sel:DWORD dst_unused:UNUSED_PAD src0_sel:WORD_1
	v_pk_fma_f32 v[54:55], v[46:47], v[126:127], v[54:55]
	v_pk_fma_f32 v[46:47], v[44:45], v[124:125], v[52:53]
	v_cvt_pk_f16_f32 v44, v48, v49
	v_cvt_pk_f16_f32 v45, v50, v51
	v_cvt_pk_f16_f32 v46, v46, v47
	v_cvt_pk_f16_f32 v47, v54, v55
	global_store_dwordx4 v[132:133], v[44:47], off sc1
	s_nop 1
	s_waitcnt vmcnt(15)
	v_cvt_f32_f16_e32 v44, v224
	v_cvt_f32_f16_sdwa v45, v224 dst_sel:DWORD dst_unused:UNUSED_PAD src0_sel:WORD_1
	v_cvt_f32_f16_e32 v46, v225
	v_cvt_f32_f16_sdwa v47, v225 dst_sel:DWORD dst_unused:UNUSED_PAD src0_sel:WORD_1
	v_pk_fma_f32 v[40:41], v[40:41], v[120:121], v[44:45]
	v_cvt_f32_f16_e32 v44, v226
	v_pk_fma_f32 v[42:43], v[42:43], v[122:123], v[46:47]
	v_cvt_f32_f16_sdwa v45, v226 dst_sel:DWORD dst_unused:UNUSED_PAD src0_sel:WORD_1
	v_cvt_f32_f16_e32 v46, v227
	v_cvt_f32_f16_sdwa v47, v227 dst_sel:DWORD dst_unused:UNUSED_PAD src0_sel:WORD_1
	v_pk_fma_f32 v[46:47], v[38:39], v[114:115], v[46:47]
	v_pk_fma_f32 v[38:39], v[36:37], v[112:113], v[44:45]
	v_cvt_pk_f16_f32 v36, v40, v41
	v_cvt_pk_f16_f32 v37, v42, v43
	v_cvt_pk_f16_f32 v38, v38, v39
	v_cvt_pk_f16_f32 v39, v46, v47
	global_store_dwordx4 v[132:133], v[36:39], off offset:256 sc1
	s_nop 0
	s_waitcnt vmcnt(15)
; #define ER_LOAD(dst, ai, mp) do { _Pragma("unroll") for (int mm = 0; mm < 2; ++mm) _Pragma("unroll") for (int bj = 0; bj < 2; ++bj) \
;             dst[mm][bj] = *(const u32x4*)(xb + (size_t)((ai) * HALF + (2 * (mp) + mm) * 16) * 2048 + bj * HALF); } while (0)
;     __device__ __forceinline__ void operator()(const f32x4 (&acc)[2][2][4][2], const Unit& u, int wr, int wc, int fr, int fq) const {
;     ...
;         ER_LOAD(xa, 0, 0); ER_LOAD(xc, 0, 1);
;         ER_STORE(xa, 0, 0); ER_LOAD(xa, 1, 0);
;         ER_STORE(xc, 0, 1); ER_LOAD(xc, 1, 1);
;         ER_STORE(xa, 1, 0); ER_STORE(xc, 1, 1);
	v_cvt_f32_f16_e32 v36, v228
	v_cvt_f32_f16_sdwa v37, v228 dst_sel:DWORD dst_unused:UNUSED_PAD src0_sel:WORD_1
	v_cvt_f32_f16_e32 v38, v229
	v_cvt_f32_f16_sdwa v39, v229 dst_sel:DWORD dst_unused:UNUSED_PAD src0_sel:WORD_1
	v_pk_fma_f32 v[32:33], v[32:33], v[128:129], v[36:37]
	v_cvt_f32_f16_e32 v36, v230
	v_pk_fma_f32 v[34:35], v[34:35], v[130:131], v[38:39]
	v_cvt_f32_f16_sdwa v37, v230 dst_sel:DWORD dst_unused:UNUSED_PAD src0_sel:WORD_1
	v_cvt_f32_f16_e32 v38, v231
	v_cvt_f32_f16_sdwa v39, v231 dst_sel:DWORD dst_unused:UNUSED_PAD src0_sel:WORD_1
	v_pk_fma_f32 v[38:39], v[30:31], v[126:127], v[38:39]
	v_pk_fma_f32 v[30:31], v[28:29], v[124:125], v[36:37]
	v_cvt_pk_f16_f32 v28, v32, v33
	v_cvt_pk_f16_f32 v29, v34, v35
	v_cvt_pk_f16_f32 v30, v30, v31
	v_cvt_pk_f16_f32 v31, v38, v39
	global_store_dwordx4 v[84:85], v[28:31], off sc1
	s_nop 1
	s_waitcnt vmcnt(15)
	v_cvt_f32_f16_e32 v28, v232
	v_cvt_f32_f16_sdwa v29, v232 dst_sel:DWORD dst_unused:UNUSED_PAD src0_sel:WORD_1
	v_cvt_f32_f16_e32 v30, v233
	v_cvt_f32_f16_sdwa v31, v233 dst_sel:DWORD dst_unused:UNUSED_PAD src0_sel:WORD_1
	v_pk_fma_f32 v[24:25], v[24:25], v[120:121], v[28:29]
	v_cvt_f32_f16_e32 v28, v234
	v_pk_fma_f32 v[26:27], v[26:27], v[122:123], v[30:31]
	v_cvt_f32_f16_sdwa v29, v234 dst_sel:DWORD dst_unused:UNUSED_PAD src0_sel:WORD_1
	v_cvt_f32_f16_e32 v30, v235
	v_cvt_f32_f16_sdwa v31, v235 dst_sel:DWORD dst_unused:UNUSED_PAD src0_sel:WORD_1
	v_pk_fma_f32 v[30:31], v[22:23], v[114:115], v[30:31]
	v_pk_fma_f32 v[22:23], v[20:21], v[112:113], v[28:29]
	v_cvt_pk_f16_f32 v20, v24, v25
	v_cvt_pk_f16_f32 v21, v26, v27
	v_cvt_pk_f16_f32 v22, v22, v23
	v_cvt_pk_f16_f32 v23, v30, v31
	global_store_dwordx4 v[84:85], v[20:23], off offset:256 sc1
	s_nop 1
	s_waitcnt vmcnt(15)
	v_cvt_f32_f16_e32 v20, v236
	v_cvt_f32_f16_sdwa v21, v236 dst_sel:DWORD dst_unused:UNUSED_PAD src0_sel:WORD_1
	v_cvt_f32_f16_e32 v22, v237
	v_cvt_f32_f16_sdwa v23, v237 dst_sel:DWORD dst_unused:UNUSED_PAD src0_sel:WORD_1
	v_pk_fma_f32 v[16:17], v[16:17], v[128:129], v[20:21]
	v_cvt_f32_f16_e32 v20, v238
	v_pk_fma_f32 v[18:19], v[18:19], v[130:131], v[22:23]
	v_cvt_f32_f16_sdwa v21, v238 dst_sel:DWORD dst_unused:UNUSED_PAD src0_sel:WORD_1
	v_cvt_f32_f16_e32 v22, v239
	v_cvt_f32_f16_sdwa v23, v239 dst_sel:DWORD dst_unused:UNUSED_PAD src0_sel:WORD_1
	v_pk_fma_f32 v[22:23], v[14:15], v[126:127], v[22:23]
	v_pk_fma_f32 v[14:15], v[12:13], v[124:125], v[20:21]
	v_cvt_pk_f16_f32 v12, v16, v17
	v_cvt_pk_f16_f32 v13, v18, v19
	v_cvt_pk_f16_f32 v14, v14, v15
	v_cvt_pk_f16_f32 v15, v22, v23
	global_store_dwordx4 v[2:3], v[12:15], off sc1
	s_nop 1
	s_waitcnt vmcnt(15)
	v_cvt_f32_f16_e32 v12, v240
	v_cvt_f32_f16_sdwa v13, v240 dst_sel:DWORD dst_unused:UNUSED_PAD src0_sel:WORD_1
	v_cvt_f32_f16_e32 v14, v241
	v_cvt_f32_f16_sdwa v15, v241 dst_sel:DWORD dst_unused:UNUSED_PAD src0_sel:WORD_1
	v_pk_fma_f32 v[8:9], v[8:9], v[120:121], v[12:13]
	v_cvt_f32_f16_e32 v12, v242
	v_pk_fma_f32 v[10:11], v[10:11], v[122:123], v[14:15]
	v_cvt_f32_f16_sdwa v13, v242 dst_sel:DWORD dst_unused:UNUSED_PAD src0_sel:WORD_1
	v_cvt_f32_f16_e32 v14, v243
	v_cvt_f32_f16_sdwa v15, v243 dst_sel:DWORD dst_unused:UNUSED_PAD src0_sel:WORD_1
	v_pk_fma_f32 v[14:15], v[6:7], v[114:115], v[14:15]
	v_pk_fma_f32 v[6:7], v[4:5], v[112:113], v[12:13]
	v_cvt_pk_f16_f32 v4, v8, v9
	v_cvt_pk_f16_f32 v5, v10, v11
	v_cvt_pk_f16_f32 v6, v6, v7
	v_cvt_pk_f16_f32 v7, v14, v15
	global_store_dwordx4 v[2:3], v[4:7], off offset:256 sc1
	s_cbranch_vccz .LBB0_919
	ds_read_b128 v[2:5], v0
	ds_read_b128 v[6:9], v0 offset:1024
	ds_read_b128 v[10:13], v0 offset:2048
	ds_read_b128 v[14:17], v0 offset:3072
	ds_read_b128 v[18:21], v188
	ds_read_b128 v[22:25], v188 offset:1024
	ds_read_b128 v[26:29], v188 offset:2048
	ds_read_b128 v[30:33], v188 offset:3072
	s_add_u32 s18, s12, 0x100
	s_addc_u32 s19, s13, 0
	s_add_u32 s16, s12, 0x180
	s_addc_u32 s17, s13, 0
	s_add_u32 s6, s14, 0x100
	s_addc_u32 s7, s15, 0
	ds_read_b128 v[34:37], v187
	ds_read_b128 v[38:41], v187 offset:1024
	ds_read_b128 v[42:45], v187 offset:2048
	ds_read_b128 v[46:49], v187 offset:3072
	ds_read_b128 v[50:53], v187 offset:4096
	ds_read_b128 v[54:57], v187 offset:5120
	ds_read_b128 v[58:61], v187 offset:6144
	ds_read_b128 v[62:65], v187 offset:7168
	s_waitcnt vmcnt(44)
	s_waitcnt lgkmcnt(0)
	s_barrier
	s_setprio 1
	s_waitcnt lgkmcnt(0)
	v_mfma_f32_16x16x32_bf16 v[90:93], v[2:5], v[58:61], 0
	v_mfma_f32_16x16x32_bf16 v[66:69], v[2:5], v[34:37], 0
	v_mfma_f32_16x16x32_bf16 v[70:73], v[10:13], v[34:37], 0
	v_mfma_f32_16x16x32_bf16 v[74:77], v[2:5], v[42:45], 0
	v_mfma_f32_16x16x32_bf16 v[78:81], v[10:13], v[42:45], 0
	v_mfma_f32_16x16x32_bf16 v[82:85], v[2:5], v[50:53], 0
	v_mfma_f32_16x16x32_bf16 v[86:89], v[10:13], v[50:53], 0
	v_mfma_f32_16x16x32_bf16 v[100:103], v[6:9], v[62:65], v[90:93]
	v_mfma_f32_16x16x32_bf16 v[90:93], v[10:13], v[58:61], 0
	v_mfma_f32_16x16x32_bf16 v[66:69], v[6:9], v[38:41], v[66:69]
	v_mfma_f32_16x16x32_bf16 v[70:73], v[14:17], v[38:41], v[70:73]
	v_mfma_f32_16x16x32_bf16 v[74:77], v[6:9], v[46:49], v[74:77]
	v_mfma_f32_16x16x32_bf16 v[78:81], v[14:17], v[46:49], v[78:81]
	v_mfma_f32_16x16x32_bf16 v[82:85], v[6:9], v[54:57], v[82:85]
	v_mfma_f32_16x16x32_bf16 v[86:89], v[14:17], v[54:57], v[86:89]
	v_mfma_f32_16x16x32_bf16 v[104:107], v[14:17], v[62:65], v[90:93]
	s_setprio 0
	s_setprio 1
	v_mfma_f32_16x16x32_bf16 v[90:93], v[18:21], v[34:37], 0
	v_mfma_f32_16x16x32_bf16 v[34:37], v[26:29], v[34:37], 0
	v_mfma_f32_16x16x32_bf16 v[112:115], v[22:25], v[38:41], v[90:93]
	v_mfma_f32_16x16x32_bf16 v[34:37], v[30:33], v[38:41], v[34:37]
	v_mfma_f32_16x16x32_bf16 v[38:41], v[18:21], v[42:45], 0
	v_mfma_f32_16x16x32_bf16 v[42:45], v[26:29], v[42:45], 0
	v_mfma_f32_16x16x32_bf16 v[38:41], v[22:25], v[46:49], v[38:41]
	v_mfma_f32_16x16x32_bf16 v[42:45], v[30:33], v[46:49], v[42:45]
	v_mfma_f32_16x16x32_bf16 v[46:49], v[18:21], v[50:53], 0
	v_mfma_f32_16x16x32_bf16 v[50:53], v[26:29], v[50:53], 0
	v_mfma_f32_16x16x32_bf16 v[46:49], v[22:25], v[54:57], v[46:49]
	v_mfma_f32_16x16x32_bf16 v[50:53], v[30:33], v[54:57], v[50:53]
	v_mfma_f32_16x16x32_bf16 v[54:57], v[18:21], v[58:61], 0
	v_mfma_f32_16x16x32_bf16 v[58:61], v[26:29], v[58:61], 0
	v_mfma_f32_16x16x32_bf16 v[54:57], v[22:25], v[62:65], v[54:57]
	v_mfma_f32_16x16x32_bf16 v[58:61], v[30:33], v[62:65], v[58:61]
	s_setprio 0
	s_barrier
	ds_read_b128 v[62:65], v187 offset:16384
	ds_read_b128 v[90:93], v187 offset:17408
	ds_read_b128 v[94:97], v187 offset:18432
	ds_read_b128 v[108:111], v187 offset:19456
	ds_read_b128 v[116:119], v187 offset:20480
	ds_read_b128 v[120:123], v187 offset:21504
	ds_read_b128 v[124:127], v187 offset:22528
	ds_read_b128 v[128:131], v187 offset:23552
	s_mov_b32 m0, s28
	s_nop 0
	global_load_lds_dwordx4 v175, s[6:7]
	s_nop 0
	s_mov_b32 m0, s29
	s_nop 0
	global_load_lds_dwordx4 v177, s[6:7]
	s_add_u32 s6, s14, 0x80100
	s_addc_u32 s7, s15, 0
	s_mov_b32 m0, s30
	s_nop 0
	global_load_lds_dwordx4 v175, s[6:7]
	s_nop 0
	s_mov_b32 m0, s31
	s_nop 0
	global_load_lds_dwordx4 v177, s[6:7]
	s_nop 0
	s_mov_b32 m0, s27
	s_nop 0
	global_load_lds_dwordx4 v174, s[18:19]
	s_nop 0
	s_mov_b32 m0, s35
	s_nop 0
	global_load_lds_dwordx4 v176, s[18:19]
	s_waitcnt vmcnt(44)
	s_waitcnt lgkmcnt(0)
	s_barrier
	s_setprio 1
	s_waitcnt lgkmcnt(0)
	v_mfma_f32_16x16x32_bf16 v[132:135], v[2:5], v[62:65], 0
	v_mfma_f32_16x16x32_bf16 v[148:151], v[6:9], v[90:93], v[132:135]
	v_mfma_f32_16x16x32_bf16 v[132:135], v[10:13], v[62:65], 0
	v_mfma_f32_16x16x32_bf16 v[152:155], v[14:17], v[90:93], v[132:135]
	v_mfma_f32_16x16x32_bf16 v[132:135], v[2:5], v[94:97], 0
	v_mfma_f32_16x16x32_bf16 v[156:159], v[6:9], v[108:111], v[132:135]
	v_mfma_f32_16x16x32_bf16 v[132:135], v[10:13], v[94:97], 0
	v_mfma_f32_16x16x32_bf16 v[160:163], v[14:17], v[108:111], v[132:135]
	v_mfma_f32_16x16x32_bf16 v[132:135], v[2:5], v[116:119], 0
	v_mfma_f32_16x16x32_bf16 v[2:5], v[2:5], v[124:127], 0
	v_mfma_f32_16x16x32_bf16 v[164:167], v[6:9], v[120:123], v[132:135]
	v_mfma_f32_16x16x32_bf16 v[2:5], v[6:9], v[128:131], v[2:5]
	v_mfma_f32_16x16x32_bf16 v[6:9], v[10:13], v[124:127], 0
	v_mfma_f32_16x16x32_bf16 v[132:135], v[10:13], v[116:119], 0
	v_mfma_f32_16x16x32_bf16 v[6:9], v[14:17], v[128:131], v[6:9]
	v_mfma_f32_16x16x32_bf16 v[168:171], v[14:17], v[120:123], v[132:135]
	s_setprio 0
	s_setprio 1
	v_mfma_f32_16x16x32_bf16 v[10:13], v[18:21], v[62:65], 0
	v_mfma_f32_16x16x32_bf16 v[178:181], v[22:25], v[90:93], v[10:13]
	v_mfma_f32_16x16x32_bf16 v[10:13], v[26:29], v[62:65], 0
	v_mfma_f32_16x16x32_bf16 v[192:195], v[30:33], v[90:93], v[10:13]
	v_mfma_f32_16x16x32_bf16 v[10:13], v[18:21], v[94:97], 0
	v_mfma_f32_16x16x32_bf16 v[196:199], v[22:25], v[108:111], v[10:13]
	v_mfma_f32_16x16x32_bf16 v[10:13], v[26:29], v[94:97], 0
	v_mfma_f32_16x16x32_bf16 v[200:203], v[30:33], v[108:111], v[10:13]
	v_mfma_f32_16x16x32_bf16 v[10:13], v[18:21], v[116:119], 0
	v_mfma_f32_16x16x32_bf16 v[204:207], v[22:25], v[120:123], v[10:13]
	v_mfma_f32_16x16x32_bf16 v[10:13], v[26:29], v[116:119], 0
	v_mfma_f32_16x16x32_bf16 v[120:123], v[30:33], v[120:123], v[10:13]
	v_mfma_f32_16x16x32_bf16 v[10:13], v[18:21], v[124:127], 0
	v_mfma_f32_16x16x32_bf16 v[208:211], v[22:25], v[128:131], v[10:13]
	v_mfma_f32_16x16x32_bf16 v[10:13], v[26:29], v[124:127], 0
	v_mfma_f32_16x16x32_bf16 v[124:127], v[30:33], v[128:131], v[10:13]
	s_setprio 0
	s_barrier
	s_nop 4
	ds_read_b128 v[10:13], v189
	ds_read_b128 v[14:17], v189 offset:1024
	ds_read_b128 v[20:23], v189 offset:2048
	ds_read_b128 v[24:27], v189 offset:3072
	ds_read_b128 v[128:131], v190
	ds_read_b128 v[212:215], v190 offset:1024
	ds_read_b128 v[216:219], v190 offset:2048
	ds_read_b128 v[188:191], v190 offset:3072
	ds_read_b128 v[28:31], v187 offset:32768
	ds_read_b128 v[62:65], v187 offset:33792
	ds_read_b128 v[220:223], v187 offset:34816
	ds_read_b128 v[224:227], v187 offset:35840
	ds_read_b128 v[228:231], v187 offset:36864
	ds_read_b128 v[232:235], v187 offset:37888
	ds_read_b128 v[236:239], v187 offset:38912
	ds_read_b128 v[240:243], v187 offset:39936
	s_add_u32 s6, s12, 0x80100
	s_addc_u32 s7, s13, 0
	s_mov_b32 m0, s36
	s_nop 0
	global_load_lds_dwordx4 v174, s[6:7]
	s_nop 0
	s_mov_b32 m0, s37
	s_nop 0
	global_load_lds_dwordx4 v176, s[6:7]
	s_waitcnt vmcnt(44)
	s_waitcnt lgkmcnt(0)
	s_barrier
	s_setprio 1
	s_waitcnt lgkmcnt(0)
	v_mfma_f32_16x16x32_bf16 v[66:69], v[10:13], v[28:31], v[66:69]
	v_mfma_f32_16x16x32_bf16 v[144:147], v[14:17], v[62:65], v[66:69]
	v_mfma_f32_16x16x32_bf16 v[66:69], v[20:23], v[28:31], v[70:73]
	v_mfma_f32_16x16x32_bf16 v[140:143], v[24:27], v[62:65], v[66:69]
	v_mfma_f32_16x16x32_bf16 v[66:69], v[10:13], v[220:223], v[74:77]
	v_mfma_f32_16x16x32_bf16 v[116:119], v[14:17], v[224:227], v[66:69]
	v_mfma_f32_16x16x32_bf16 v[66:69], v[20:23], v[220:223], v[78:81]
	v_mfma_f32_16x16x32_bf16 v[108:111], v[24:27], v[224:227], v[66:69]
	v_mfma_f32_16x16x32_bf16 v[66:69], v[10:13], v[228:231], v[82:85]
	v_mfma_f32_16x16x32_bf16 v[96:99], v[14:17], v[232:235], v[66:69]
	v_mfma_f32_16x16x32_bf16 v[66:69], v[20:23], v[228:231], v[86:89]
	v_mfma_f32_16x16x32_bf16 v[92:95], v[24:27], v[232:235], v[66:69]
	v_mfma_f32_16x16x32_bf16 v[66:69], v[10:13], v[236:239], v[100:103]
	v_mfma_f32_16x16x32_bf16 v[80:83], v[14:17], v[240:243], v[66:69]
	v_mfma_f32_16x16x32_bf16 v[66:69], v[20:23], v[236:239], v[104:107]
	v_mfma_f32_16x16x32_bf16 v[76:79], v[24:27], v[240:243], v[66:69]
	s_setprio 0
	s_setprio 1
	v_mfma_f32_16x16x32_bf16 v[66:69], v[128:131], v[28:31], v[112:115]
	v_mfma_f32_16x16x32_bf16 v[28:31], v[216:219], v[28:31], v[34:37]
	v_mfma_f32_16x16x32_bf16 v[132:135], v[188:191], v[62:65], v[28:31]
	v_mfma_f32_16x16x32_bf16 v[28:31], v[128:131], v[220:223], v[38:41]
	v_mfma_f32_16x16x32_bf16 v[104:107], v[212:215], v[224:227], v[28:31]
	v_mfma_f32_16x16x32_bf16 v[28:31], v[216:219], v[220:223], v[42:45]
	v_mfma_f32_16x16x32_bf16 v[100:103], v[188:191], v[224:227], v[28:31]
	v_mfma_f32_16x16x32_bf16 v[28:31], v[128:131], v[228:231], v[46:49]
	v_mfma_f32_16x16x32_bf16 v[88:91], v[212:215], v[232:235], v[28:31]
	v_mfma_f32_16x16x32_bf16 v[28:31], v[216:219], v[228:231], v[50:53]
	v_mfma_f32_16x16x32_bf16 v[84:87], v[188:191], v[232:235], v[28:31]
	v_mfma_f32_16x16x32_bf16 v[28:31], v[128:131], v[236:239], v[54:57]
	v_mfma_f32_16x16x32_bf16 v[72:75], v[212:215], v[240:243], v[28:31]
	v_mfma_f32_16x16x32_bf16 v[28:31], v[216:219], v[236:239], v[58:61]
	v_mfma_f32_16x16x32_bf16 v[136:139], v[212:215], v[62:65], v[66:69]
	v_mfma_f32_16x16x32_bf16 v[68:71], v[188:191], v[240:243], v[28:31]
	s_setprio 0
	s_barrier
	ds_read_b128 v[36:39], v187 offset:49152
	ds_read_b128 v[40:43], v187 offset:50176
	ds_read_b128 v[112:115], v187 offset:51200
	ds_read_b128 v[220:223], v187 offset:52224
	ds_read_b128 v[224:227], v187 offset:53248
	ds_read_b128 v[228:231], v187 offset:54272
	ds_read_b128 v[232:235], v187 offset:55296
	ds_read_b128 v[236:239], v187 offset:56320
	s_add_u32 s6, s14, 0x180
	s_addc_u32 s7, s15, 0
	s_mov_b32 m0, s44
	s_nop 0
	global_load_lds_dwordx4 v175, s[6:7]
	s_nop 0
	s_mov_b32 m0, s48
	s_nop 0
	global_load_lds_dwordx4 v177, s[6:7]
	s_add_u32 s6, s14, 0x80180
	s_addc_u32 s7, s15, 0
	s_mov_b32 m0, s52
	s_nop 0
	global_load_lds_dwordx4 v175, s[6:7]
	s_nop 0
	s_mov_b32 m0, s53
	s_nop 0
	global_load_lds_dwordx4 v177, s[6:7]
	s_nop 0
	s_mov_b32 m0, s49
	s_nop 0
	global_load_lds_dwordx4 v174, s[16:17]
	s_nop 0
	s_mov_b32 m0, s51
	s_nop 0
	global_load_lds_dwordx4 v176, s[16:17]
	s_waitcnt vmcnt(8)
	s_waitcnt lgkmcnt(0)
	s_barrier
	s_setprio 1
	s_waitcnt lgkmcnt(0)
	v_mfma_f32_16x16x32_bf16 v[28:31], v[10:13], v[36:39], v[148:151]
	v_mfma_f32_16x16x32_bf16 v[64:67], v[14:17], v[40:43], v[28:31]
	v_mfma_f32_16x16x32_bf16 v[28:31], v[20:23], v[36:39], v[152:155]
	v_mfma_f32_16x16x32_bf16 v[60:63], v[24:27], v[40:43], v[28:31]
	v_mfma_f32_16x16x32_bf16 v[28:31], v[10:13], v[112:115], v[156:159]
	v_mfma_f32_16x16x32_bf16 v[48:51], v[14:17], v[220:223], v[28:31]
	v_mfma_f32_16x16x32_bf16 v[28:31], v[20:23], v[112:115], v[160:163]
	v_mfma_f32_16x16x32_bf16 v[44:47], v[24:27], v[220:223], v[28:31]
	v_mfma_f32_16x16x32_bf16 v[28:31], v[10:13], v[224:227], v[164:167]
	v_mfma_f32_16x16x32_bf16 v[2:5], v[10:13], v[232:235], v[2:5]
	v_mfma_f32_16x16x32_bf16 v[32:35], v[14:17], v[228:231], v[28:31]
	v_mfma_f32_16x16x32_bf16 v[28:31], v[20:23], v[224:227], v[168:171]
	v_mfma_f32_16x16x32_bf16 v[16:19], v[14:17], v[236:239], v[2:5]
	v_mfma_f32_16x16x32_bf16 v[2:5], v[20:23], v[232:235], v[6:9]
	v_mfma_f32_16x16x32_bf16 v[28:31], v[24:27], v[228:231], v[28:31]
	v_mfma_f32_16x16x32_bf16 v[12:15], v[24:27], v[236:239], v[2:5]
	s_setprio 0
	s_setprio 1
	v_mfma_f32_16x16x32_bf16 v[2:5], v[128:131], v[36:39], v[178:181]
	v_mfma_f32_16x16x32_bf16 v[56:59], v[212:215], v[40:43], v[2:5]
	v_mfma_f32_16x16x32_bf16 v[2:5], v[216:219], v[36:39], v[192:195]
	v_mfma_f32_16x16x32_bf16 v[52:55], v[188:191], v[40:43], v[2:5]
	v_mfma_f32_16x16x32_bf16 v[2:5], v[128:131], v[112:115], v[196:199]
	v_mfma_f32_16x16x32_bf16 v[40:43], v[212:215], v[220:223], v[2:5]
	v_mfma_f32_16x16x32_bf16 v[2:5], v[216:219], v[112:115], v[200:203]
	v_mfma_f32_16x16x32_bf16 v[36:39], v[188:191], v[220:223], v[2:5]
	v_mfma_f32_16x16x32_bf16 v[2:5], v[128:131], v[224:227], v[204:207]
	v_mfma_f32_16x16x32_bf16 v[24:27], v[212:215], v[228:231], v[2:5]
	v_mfma_f32_16x16x32_bf16 v[2:5], v[216:219], v[224:227], v[120:123]
	v_mfma_f32_16x16x32_bf16 v[20:23], v[188:191], v[228:231], v[2:5]
	v_mfma_f32_16x16x32_bf16 v[2:5], v[128:131], v[232:235], v[208:211]
	v_mfma_f32_16x16x32_bf16 v[8:11], v[212:215], v[236:239], v[2:5]
	v_mfma_f32_16x16x32_bf16 v[2:5], v[216:219], v[232:235], v[124:127]
	v_mfma_f32_16x16x32_bf16 v[4:7], v[188:191], v[236:239], v[2:5]
	s_setprio 0
	s_barrier
	s_mov_b64 s[18:19], 0
	s_branch .LBB0_919

; #define PG8_GAS __attribute__((address_space(1)))
;     __device__ __forceinline__ void operator()(const f32x4 (&acc)[2][2][4][2], const Unit& u, int wr, int wc, int fr, int fq) const {
;         float* base = slab + (size_t)(u.k0 / ksub) * kstride + (size_t)((u.pm - pm0) * BM + wr * 64 + fr) * 2048 + u.pn * BM + wc * 32 + 4 * fq;
; #pragma unroll
;         for (int ai = 0; ai < 2; ++ai)
; #pragma unroll
;             for (int m = 0; m < 4; ++m) { float* rowp = base + (size_t)(ai * HALF + m * 16) * 2048;
; #pragma unroll
;                 for (int bj = 0; bj < 2; ++bj)
; #pragma unroll
;                     for (int n = 0; n < 2; ++n) *(PG8_GAS f32x4*)(rowp + bj * HALF + n * 16) = acc[ai][bj][m][n]; }
;     }
.LBB0_955:
	s_ashr_i32 s7, s6, 31
	s_lshr_b32 s7, s7, 23
	s_add_i32 s6, s6, s7
	s_ashr_i32 s6, s6, 9
	s_ashr_i32 s7, s6, 31
	s_lshl_b64 s[6:7], s[6:7], 23
	v_lshl_add_u32 v140, s91, 8, v132
	s_add_u32 s6, s51, s6
	v_ashrrev_i32_e32 v141, 31, v140
	s_addc_u32 s7, s52, s7
	v_lshlrev_b64 v[140:141], 13, v[140:141]
	v_lshl_add_u64 v[140:141], s[6:7], 0, v[140:141]
	s_lshl_b32 s6, s83, 8
	s_ashr_i32 s7, s6, 31
	v_lshl_add_u64 v[140:141], s[6:7], 2, v[140:141]
	v_lshl_add_u64 v[140:141], v[140:141], 0, s[84:85]
	v_lshl_add_u64 v[140:141], v[140:141], 0, v[0:1]
	global_store_dwordx4 v[140:141], v[26:29], off sc1
	global_store_dwordx4 v[140:141], v[30:33], off offset:64 sc1
	global_store_dwordx4 v[140:141], v[58:61], off offset:512 sc1
	global_store_dwordx4 v[140:141], v[62:65], off offset:576 sc1
	v_add_co_u32_e32 v26, vcc, s50, v140
	s_mov_b32 s6, 0x40000
	s_nop 0
	v_addc_co_u32_e32 v27, vcc, 0, v141, vcc
	global_store_dwordx4 v[26:27], v[18:21], off sc1
	global_store_dwordx4 v[26:27], v[22:25], off offset:64 sc1
	global_store_dwordx4 v[26:27], v[50:53], off offset:512 sc1
	global_store_dwordx4 v[26:27], v[54:57], off offset:576 sc1
	v_add_co_u32_e32 v18, vcc, s6, v140
	s_mov_b32 s6, 0x60000
	s_nop 0
	v_addc_co_u32_e32 v19, vcc, 0, v141, vcc
	global_store_dwordx4 v[18:19], v[10:13], off sc1
	global_store_dwordx4 v[18:19], v[14:17], off offset:64 sc1
	global_store_dwordx4 v[18:19], v[42:45], off offset:512 sc1
	global_store_dwordx4 v[18:19], v[46:49], off offset:576 sc1
	v_add_co_u32_e32 v10, vcc, s6, v140
	s_mov_b32 s6, 0x100000
	s_nop 0
	v_addc_co_u32_e32 v11, vcc, 0, v141, vcc
	global_store_dwordx4 v[10:11], v[2:5], off sc1
	global_store_dwordx4 v[10:11], v[6:9], off offset:64 sc1
	global_store_dwordx4 v[10:11], v[34:37], off offset:512 sc1
	global_store_dwordx4 v[10:11], v[38:41], off offset:576 sc1
	v_add_co_u32_e32 v2, vcc, s6, v140
	s_mov_b32 s6, 0x120000
	s_nop 0
	v_addc_co_u32_e32 v3, vcc, 0, v141, vcc
	global_store_dwordx4 v[2:3], v[98:101], off sc1
	global_store_dwordx4 v[2:3], v[102:105], off offset:64 sc1
	global_store_dwordx4 v[2:3], v[122:125], off offset:512 sc1
	global_store_dwordx4 v[2:3], v[126:129], off offset:576 sc1
	v_add_co_u32_e32 v2, vcc, s6, v140
	s_mov_b32 s6, 0x140000
	s_nop 0
	v_addc_co_u32_e32 v3, vcc, 0, v141, vcc
	global_store_dwordx4 v[2:3], v[86:89], off sc1
	global_store_dwordx4 v[2:3], v[90:93], off offset:64 sc1
	global_store_dwordx4 v[2:3], v[114:117], off offset:512 sc1
	global_store_dwordx4 v[2:3], v[118:121], off offset:576 sc1
	v_add_co_u32_e32 v2, vcc, s6, v140
	s_nop 1
	v_addc_co_u32_e32 v3, vcc, 0, v141, vcc
	global_store_dwordx4 v[2:3], v[74:77], off sc1
	global_store_dwordx4 v[2:3], v[78:81], off offset:64 sc1
	global_store_dwordx4 v[2:3], v[106:109], off offset:512 sc1
	global_store_dwordx4 v[2:3], v[110:113], off offset:576 sc1
	v_add_co_u32_e32 v2, vcc, 0x160000, v140
	s_nop 1
	v_addc_co_u32_e32 v3, vcc, 0, v141, vcc
	global_store_dwordx4 v[2:3], v[66:69], off sc1
	global_store_dwordx4 v[2:3], v[70:73], off offset:64 sc1
	global_store_dwordx4 v[2:3], v[94:97], off offset:512 sc1
	global_store_dwordx4 v[2:3], v[82:85], off offset:576 sc1
	s_and_b64 vcc, exec, s[8:9]
	s_mov_b64 s[8:9], -1
	s_cbranch_vccnz .LBB0_944
	s_andn2_b64 vcc, exec, s[10:11]
	s_cbranch_vccnz .LBB0_943
	s_barrier
	s_branch .LBB0_943

; __device__ __forceinline__ u32x4 pack8(f32x4 v0, f32x4 v1) { u32x4 w; w.x = cvt_pk_bf16(v0[0], v0[1]); w.y = cvt_pk_bf16(v0[2], v0[3]); w.z = cvt_pk_bf16(v1[0], v1[1]); w.w = cvt_pk_bf16(v1[2], v1[3]); return w; }
; __device__ __forceinline__ f32x4 sigm4(f32x4 v) { const f32x4 t = v * -1.4426950408889634f; f32x4 e = {__builtin_amdgcn_exp2f(t[0]), __builtin_amdgcn_exp2f(t[1]), __builtin_amdgcn_exp2f(t[2]), __builtin_amdgcn_exp2f(t[3])};
;     e = e + 1.0f; return (f32x4){__builtin_amdgcn_rcpf(e[0]), __builtin_amdgcn_rcpf(e[1]), __builtin_amdgcn_rcpf(e[2]), __builtin_amdgcn_rcpf(e[3])}; }
; __device__ __forceinline__ f32x4 silu4(f32x4 v) { return v * sigm4(v); }
;     __device__ __forceinline__ void operator()(const f32x4 (&acc)[2][2][4][2], const Unit& u, int wr, int wc, int fr, int fq) const {
;         const int row0 = u.pm * BM + wr * 64 + fr, col0 = u.pn * HALF + wc * 32 + 8 * fq;
; #pragma unroll
;         for (int ai = 0; ai < 2; ++ai)
; #pragma unroll
;             for (int m = 0; m < 4; ++m) {
;                 const f32x4 h0 = silu4(acc[ai][0][m][0] * pre) * (acc[ai][1][m][0] * pre), h1 = silu4(acc[ai][0][m][1] * pre) * (acc[ai][1][m][1] * pre);
;                 st16(H, (size_t)(row0 + ai * HALF + m * 16) * ldh + col0, pack8(h0, h1));
;             }
;     }
.LBB0_1122:
	v_pk_mul_f32 v[142:143], v[126:127], s[96:97] op_sel_hi:[1,0]
	v_pk_mul_f32 v[144:145], v[124:125], s[96:97] op_sel_hi:[1,0]
	v_exp_f32_e32 v142, v142
	v_exp_f32_e32 v143, v143
	v_exp_f32_e32 v144, v144
	v_exp_f32_e32 v145, v145
	v_lshl_add_u32 v141, s24, 8, v136
	v_pk_add_f32 v[142:143], v[142:143], 1.0 op_sel_hi:[1,0]
	s_movk_i32 s6, 0x1600
	v_pk_add_f32 v[144:145], v[144:145], 1.0 op_sel_hi:[1,0]
	v_rcp_f32_e32 v142, v142
	v_rcp_f32_e32 v143, v143
	v_rcp_f32_e32 v144, v144
	v_rcp_f32_e32 v145, v145
	v_lshl_or_b32 v146, s22, 7, v137
	v_pk_mul_f32 v[126:127], v[126:127], v[142:143]
	s_mov_b64 s[22:23], -1
	v_pk_mul_f32 v[124:125], v[124:125], v[144:145]
	v_pk_mul_f32 v[126:127], v[126:127], v[130:131]
	v_pk_mul_f32 v[130:131], v[116:117], s[96:97] op_sel_hi:[1,0]
	v_pk_mul_f32 v[124:125], v[124:125], v[128:129]
	v_pk_mul_f32 v[128:129], v[118:119], s[96:97] op_sel_hi:[1,0]
	v_exp_f32_e32 v130, v130
	v_exp_f32_e32 v131, v131
	v_exp_f32_e32 v128, v128
	v_exp_f32_e32 v129, v129
	s_andn2_b64 vcc, exec, s[20:21]
	v_pk_add_f32 v[130:131], v[130:131], 1.0 op_sel_hi:[1,0]
	v_pk_add_f32 v[128:129], v[128:129], 1.0 op_sel_hi:[1,0]
	v_rcp_f32_e32 v130, v130
	v_rcp_f32_e32 v131, v131
	v_rcp_f32_e32 v128, v128
	v_rcp_f32_e32 v129, v129
	v_pk_mul_f32 v[116:117], v[116:117], v[130:131]
	s_nop 0
	v_pk_mul_f32 v[116:117], v[116:117], v[120:121]
	v_pk_mul_f32 v[118:119], v[118:119], v[128:129]
	v_mul_lo_u32 v128, v141, s6
	v_pk_mul_f32 v[122:123], v[118:119], v[122:123]
	v_cvt_pk_bf16_f32 v118, v124, v125
	v_cvt_pk_bf16_f32 v119, v126, v127
	v_cvt_pk_bf16_f32 v120, v116, v117
	v_add_lshl_u32 v116, v128, v146, 1
	v_cvt_pk_bf16_f32 v121, v122, v123
	global_store_dwordx4 v116, v[118:121], s[70:71] sc1
	s_nop 1
	v_pk_mul_f32 v[118:119], v[110:111], s[96:97] op_sel_hi:[1,0]
	v_pk_mul_f32 v[120:121], v[108:109], s[96:97] op_sel_hi:[1,0]
	v_exp_f32_e32 v118, v118
	v_exp_f32_e32 v120, v120
	v_exp_f32_e32 v121, v121
	v_exp_f32_e32 v119, v119
	v_pk_add_f32 v[120:121], v[120:121], 1.0 op_sel_hi:[1,0]
	v_pk_add_f32 v[118:119], v[118:119], 1.0 op_sel_hi:[1,0]
	v_rcp_f32_e32 v120, v120
	v_rcp_f32_e32 v121, v121
	v_rcp_f32_e32 v118, v118
	v_rcp_f32_e32 v119, v119
	v_pk_mul_f32 v[108:109], v[108:109], v[120:121]
	s_nop 0
	v_pk_mul_f32 v[108:109], v[108:109], v[112:113]
	v_pk_mul_f32 v[110:111], v[110:111], v[118:119]
	v_pk_mul_f32 v[112:113], v[102:103], s[96:97] op_sel_hi:[1,0]
	v_pk_mul_f32 v[110:111], v[110:111], v[114:115]
	v_pk_mul_f32 v[114:115], v[100:101], s[96:97] op_sel_hi:[1,0]
	v_exp_f32_e32 v112, v112
	v_exp_f32_e32 v114, v114
	v_exp_f32_e32 v115, v115
	v_exp_f32_e32 v113, v113
	v_pk_add_f32 v[114:115], v[114:115], 1.0 op_sel_hi:[1,0]
	v_pk_add_f32 v[112:113], v[112:113], 1.0 op_sel_hi:[1,0]
	v_rcp_f32_e32 v114, v114
	v_rcp_f32_e32 v115, v115
	v_rcp_f32_e32 v112, v112
	v_rcp_f32_e32 v113, v113
	v_pk_mul_f32 v[100:101], v[100:101], v[114:115]
	v_pk_mul_f32 v[102:103], v[102:103], v[112:113]
	s_nop 0
	v_pk_mul_f32 v[106:107], v[102:103], v[106:107]
	v_pk_mul_f32 v[102:103], v[100:101], v[104:105]
	v_cvt_pk_bf16_f32 v100, v108, v109
	v_cvt_pk_bf16_f32 v101, v110, v111
	v_add_u32_e32 v104, 0x2c000, v116
	v_cvt_pk_bf16_f32 v102, v102, v103
	v_cvt_pk_bf16_f32 v103, v106, v107
	global_store_dwordx4 v104, v[100:103], s[70:71] sc1
	s_nop 1
	v_pk_mul_f32 v[100:101], v[94:95], s[96:97] op_sel_hi:[1,0]
	v_pk_mul_f32 v[102:103], v[92:93], s[96:97] op_sel_hi:[1,0]
	v_exp_f32_e32 v100, v100
	v_exp_f32_e32 v102, v102
	v_exp_f32_e32 v103, v103
	v_exp_f32_e32 v101, v101
	v_pk_add_f32 v[102:103], v[102:103], 1.0 op_sel_hi:[1,0]
	v_pk_add_f32 v[100:101], v[100:101], 1.0 op_sel_hi:[1,0]
	v_rcp_f32_e32 v102, v102
	v_rcp_f32_e32 v103, v103
	v_rcp_f32_e32 v100, v100
	v_rcp_f32_e32 v101, v101
	v_pk_mul_f32 v[92:93], v[92:93], v[102:103]
	s_nop 0
	v_pk_mul_f32 v[92:93], v[92:93], v[96:97]
	v_pk_mul_f32 v[94:95], v[94:95], v[100:101]
	v_pk_mul_f32 v[96:97], v[86:87], s[96:97] op_sel_hi:[1,0]
	v_pk_mul_f32 v[94:95], v[94:95], v[98:99]
	v_pk_mul_f32 v[98:99], v[84:85], s[96:97] op_sel_hi:[1,0]
	v_exp_f32_e32 v96, v96
	v_exp_f32_e32 v98, v98
	v_exp_f32_e32 v99, v99
	v_exp_f32_e32 v97, v97
	v_pk_add_f32 v[98:99], v[98:99], 1.0 op_sel_hi:[1,0]
	v_pk_add_f32 v[96:97], v[96:97], 1.0 op_sel_hi:[1,0]
	v_rcp_f32_e32 v98, v98
	v_rcp_f32_e32 v99, v99
	v_rcp_f32_e32 v96, v96
	v_rcp_f32_e32 v97, v97
	v_pk_mul_f32 v[84:85], v[84:85], v[98:99]
	v_pk_mul_f32 v[86:87], v[86:87], v[96:97]
	s_nop 0
	v_pk_mul_f32 v[90:91], v[86:87], v[90:91]
	v_pk_mul_f32 v[86:87], v[84:85], v[88:89]
	v_cvt_pk_bf16_f32 v84, v92, v93
	v_cvt_pk_bf16_f32 v85, v94, v95
	v_add_u32_e32 v88, 0x58000, v116
	v_cvt_pk_bf16_f32 v86, v86, v87
	v_cvt_pk_bf16_f32 v87, v90, v91
	global_store_dwordx4 v88, v[84:87], s[70:71] sc1
	s_nop 1
	v_pk_mul_f32 v[84:85], v[78:79], s[96:97] op_sel_hi:[1,0]
	v_pk_mul_f32 v[86:87], v[76:77], s[96:97] op_sel_hi:[1,0]
	v_exp_f32_e32 v84, v84
	v_exp_f32_e32 v86, v86
	v_exp_f32_e32 v87, v87
	v_exp_f32_e32 v85, v85
	v_pk_add_f32 v[86:87], v[86:87], 1.0 op_sel_hi:[1,0]
	v_pk_add_f32 v[84:85], v[84:85], 1.0 op_sel_hi:[1,0]
	v_rcp_f32_e32 v86, v86
	v_rcp_f32_e32 v87, v87
	v_rcp_f32_e32 v84, v84
	v_rcp_f32_e32 v85, v85
	v_pk_mul_f32 v[76:77], v[76:77], v[86:87]
	s_nop 0
	v_pk_mul_f32 v[76:77], v[76:77], v[80:81]
	v_pk_mul_f32 v[78:79], v[78:79], v[84:85]
	v_pk_mul_f32 v[80:81], v[62:63], s[96:97] op_sel_hi:[1,0]
	v_pk_mul_f32 v[78:79], v[78:79], v[82:83]
	v_pk_mul_f32 v[82:83], v[60:61], s[96:97] op_sel_hi:[1,0]
	v_exp_f32_e32 v80, v80
	v_exp_f32_e32 v82, v82
	v_exp_f32_e32 v83, v83
	v_exp_f32_e32 v81, v81
	v_pk_add_f32 v[82:83], v[82:83], 1.0 op_sel_hi:[1,0]
	v_pk_add_f32 v[80:81], v[80:81], 1.0 op_sel_hi:[1,0]
; __device__ __forceinline__ u32x4 pack8(f32x4 v0, f32x4 v1) { u32x4 w; w.x = cvt_pk_bf16(v0[0], v0[1]); w.y = cvt_pk_bf16(v0[2], v0[3]); w.z = cvt_pk_bf16(v1[0], v1[1]); w.w = cvt_pk_bf16(v1[2], v1[3]); return w; }
; __device__ __forceinline__ f32x4 sigm4(f32x4 v) { const f32x4 t = v * -1.4426950408889634f; f32x4 e = {__builtin_amdgcn_exp2f(t[0]), __builtin_amdgcn_exp2f(t[1]), __builtin_amdgcn_exp2f(t[2]), __builtin_amdgcn_exp2f(t[3])};
;     e = e + 1.0f; return (f32x4){__builtin_amdgcn_rcpf(e[0]), __builtin_amdgcn_rcpf(e[1]), __builtin_amdgcn_rcpf(e[2]), __builtin_amdgcn_rcpf(e[3])}; }
; __device__ __forceinline__ f32x4 silu4(f32x4 v) { return v * sigm4(v); }
;     __device__ __forceinline__ void operator()(const f32x4 (&acc)[2][2][4][2], const Unit& u, int wr, int wc, int fr, int fq) const {
;         const int row0 = u.pm * BM + wr * 64 + fr, col0 = u.pn * HALF + wc * 32 + 8 * fq;
; #pragma unroll
;         for (int ai = 0; ai < 2; ++ai)
; #pragma unroll
;             for (int m = 0; m < 4; ++m) {
;                 const f32x4 h0 = silu4(acc[ai][0][m][0] * pre) * (acc[ai][1][m][0] * pre), h1 = silu4(acc[ai][0][m][1] * pre) * (acc[ai][1][m][1] * pre);
;                 st16(H, (size_t)(row0 + ai * HALF + m * 16) * ldh + col0, pack8(h0, h1));
;             }
;     }
	v_rcp_f32_e32 v82, v82
	v_rcp_f32_e32 v83, v83
	v_rcp_f32_e32 v80, v80
	v_rcp_f32_e32 v81, v81
	v_pk_mul_f32 v[60:61], v[60:61], v[82:83]
	v_pk_mul_f32 v[62:63], v[62:63], v[80:81]
	s_nop 0
	v_pk_mul_f32 v[70:71], v[62:63], v[70:71]
	v_pk_mul_f32 v[62:63], v[60:61], v[68:69]
	v_cvt_pk_bf16_f32 v60, v76, v77
	v_cvt_pk_bf16_f32 v61, v78, v79
	v_add_u32_e32 v68, 0x84000, v116
	v_cvt_pk_bf16_f32 v62, v62, v63
	v_cvt_pk_bf16_f32 v63, v70, v71
	global_store_dwordx4 v68, v[60:63], s[70:71] sc1
	s_nop 1
	v_pk_mul_f32 v[60:61], v[66:67], s[96:97] op_sel_hi:[1,0]
	v_pk_mul_f32 v[62:63], v[64:65], s[96:97] op_sel_hi:[1,0]
	v_exp_f32_e32 v60, v60
	v_exp_f32_e32 v62, v62
	v_exp_f32_e32 v63, v63
	v_exp_f32_e32 v61, v61
	v_pk_add_f32 v[62:63], v[62:63], 1.0 op_sel_hi:[1,0]
	v_pk_add_f32 v[60:61], v[60:61], 1.0 op_sel_hi:[1,0]
	v_rcp_f32_e32 v62, v62
	v_rcp_f32_e32 v63, v63
	v_rcp_f32_e32 v60, v60
	v_rcp_f32_e32 v61, v61
	v_pk_mul_f32 v[62:63], v[64:65], v[62:63]
	v_pk_mul_f32 v[64:65], v[54:55], s[96:97] op_sel_hi:[1,0]
	v_pk_mul_f32 v[60:61], v[66:67], v[60:61]
	v_pk_mul_f32 v[66:67], v[52:53], s[96:97] op_sel_hi:[1,0]
	v_exp_f32_e32 v64, v64
	v_exp_f32_e32 v66, v66
	v_exp_f32_e32 v67, v67
	v_exp_f32_e32 v65, v65
	v_pk_mul_f32 v[60:61], v[60:61], v[74:75]
	v_pk_mul_f32 v[62:63], v[62:63], v[72:73]
	v_pk_add_f32 v[66:67], v[66:67], 1.0 op_sel_hi:[1,0]
	v_pk_add_f32 v[64:65], v[64:65], 1.0 op_sel_hi:[1,0]
	v_rcp_f32_e32 v66, v66
	v_rcp_f32_e32 v67, v67
	v_rcp_f32_e32 v64, v64
	v_rcp_f32_e32 v65, v65
	v_pk_mul_f32 v[52:53], v[52:53], v[66:67]
	v_pk_mul_f32 v[54:55], v[54:55], v[64:65]
	s_nop 0
	v_pk_mul_f32 v[58:59], v[54:55], v[58:59]
	v_pk_mul_f32 v[54:55], v[52:53], v[56:57]
	v_cvt_pk_bf16_f32 v52, v62, v63
	v_cvt_pk_bf16_f32 v53, v60, v61
	v_add_u32_e32 v56, 0x160000, v116
	v_cvt_pk_bf16_f32 v54, v54, v55
	v_cvt_pk_bf16_f32 v55, v58, v59
	global_store_dwordx4 v56, v[52:55], s[70:71] sc1
	s_nop 1
	v_pk_mul_f32 v[52:53], v[46:47], s[96:97] op_sel_hi:[1,0]
	v_pk_mul_f32 v[54:55], v[44:45], s[96:97] op_sel_hi:[1,0]
	v_exp_f32_e32 v52, v52
	v_exp_f32_e32 v54, v54
	v_exp_f32_e32 v55, v55
	v_exp_f32_e32 v53, v53
	v_pk_add_f32 v[54:55], v[54:55], 1.0 op_sel_hi:[1,0]
	v_pk_add_f32 v[52:53], v[52:53], 1.0 op_sel_hi:[1,0]
	v_rcp_f32_e32 v54, v54
	v_rcp_f32_e32 v55, v55
	v_rcp_f32_e32 v52, v52
	v_rcp_f32_e32 v53, v53
	v_pk_mul_f32 v[44:45], v[44:45], v[54:55]
	s_nop 0
	v_pk_mul_f32 v[44:45], v[44:45], v[48:49]
	v_pk_mul_f32 v[46:47], v[46:47], v[52:53]
	v_pk_mul_f32 v[48:49], v[38:39], s[96:97] op_sel_hi:[1,0]
	v_pk_mul_f32 v[46:47], v[46:47], v[50:51]
	v_pk_mul_f32 v[50:51], v[36:37], s[96:97] op_sel_hi:[1,0]
	v_exp_f32_e32 v48, v48
	v_exp_f32_e32 v50, v50
	v_exp_f32_e32 v51, v51
	v_exp_f32_e32 v49, v49
	v_pk_add_f32 v[50:51], v[50:51], 1.0 op_sel_hi:[1,0]
	v_pk_add_f32 v[48:49], v[48:49], 1.0 op_sel_hi:[1,0]
	v_rcp_f32_e32 v50, v50
	v_rcp_f32_e32 v51, v51
	v_rcp_f32_e32 v48, v48
	v_rcp_f32_e32 v49, v49
	v_pk_mul_f32 v[36:37], v[36:37], v[50:51]
	v_pk_mul_f32 v[38:39], v[38:39], v[48:49]
	s_nop 0
	v_pk_mul_f32 v[42:43], v[38:39], v[42:43]
	v_pk_mul_f32 v[38:39], v[36:37], v[40:41]
	v_cvt_pk_bf16_f32 v36, v44, v45
	v_cvt_pk_bf16_f32 v37, v46, v47
	v_add_u32_e32 v40, 0x18c000, v116
	v_cvt_pk_bf16_f32 v38, v38, v39
	v_cvt_pk_bf16_f32 v39, v42, v43
	global_store_dwordx4 v40, v[36:39], s[70:71] sc1
	s_nop 1
	v_pk_mul_f32 v[36:37], v[30:31], s[96:97] op_sel_hi:[1,0]
	v_pk_mul_f32 v[38:39], v[28:29], s[96:97] op_sel_hi:[1,0]
	v_exp_f32_e32 v36, v36
	v_exp_f32_e32 v38, v38
	v_exp_f32_e32 v39, v39
	v_exp_f32_e32 v37, v37
	v_pk_add_f32 v[38:39], v[38:39], 1.0 op_sel_hi:[1,0]
	v_pk_add_f32 v[36:37], v[36:37], 1.0 op_sel_hi:[1,0]
	v_rcp_f32_e32 v38, v38
	v_rcp_f32_e32 v39, v39
	v_rcp_f32_e32 v36, v36
	v_rcp_f32_e32 v37, v37
	v_pk_mul_f32 v[28:29], v[28:29], v[38:39]
	s_nop 0
	v_pk_mul_f32 v[28:29], v[28:29], v[32:33]
	v_pk_mul_f32 v[30:31], v[30:31], v[36:37]
	v_pk_mul_f32 v[32:33], v[22:23], s[96:97] op_sel_hi:[1,0]
	v_pk_mul_f32 v[30:31], v[30:31], v[34:35]
	v_pk_mul_f32 v[34:35], v[20:21], s[96:97] op_sel_hi:[1,0]
	v_exp_f32_e32 v32, v32
	v_exp_f32_e32 v34, v34
	v_exp_f32_e32 v35, v35
	v_exp_f32_e32 v33, v33
	v_pk_add_f32 v[34:35], v[34:35], 1.0 op_sel_hi:[1,0]
	v_pk_add_f32 v[32:33], v[32:33], 1.0 op_sel_hi:[1,0]
	v_rcp_f32_e32 v34, v34
	v_rcp_f32_e32 v35, v35
	v_rcp_f32_e32 v32, v32
	v_rcp_f32_e32 v33, v33
	v_pk_mul_f32 v[20:21], v[20:21], v[34:35]
	v_pk_mul_f32 v[22:23], v[22:23], v[32:33]
	s_nop 0
	v_pk_mul_f32 v[26:27], v[22:23], v[26:27]
	v_pk_mul_f32 v[22:23], v[20:21], v[24:25]
	v_cvt_pk_bf16_f32 v20, v28, v29
	v_cvt_pk_bf16_f32 v21, v30, v31
	v_add_u32_e32 v24, 0x1b8000, v116
	v_cvt_pk_bf16_f32 v22, v22, v23
	v_cvt_pk_bf16_f32 v23, v26, v27
	global_store_dwordx4 v24, v[20:23], s[70:71] sc1
	s_nop 1
	v_pk_mul_f32 v[20:21], v[14:15], s[96:97] op_sel_hi:[1,0]
	v_pk_mul_f32 v[22:23], v[12:13], s[96:97] op_sel_hi:[1,0]
	v_exp_f32_e32 v20, v20
	v_exp_f32_e32 v22, v22
	v_exp_f32_e32 v23, v23
	v_exp_f32_e32 v21, v21
	v_pk_add_f32 v[22:23], v[22:23], 1.0 op_sel_hi:[1,0]
	v_pk_add_f32 v[20:21], v[20:21], 1.0 op_sel_hi:[1,0]
	v_rcp_f32_e32 v22, v22
	v_rcp_f32_e32 v23, v23
	v_rcp_f32_e32 v20, v20
	v_rcp_f32_e32 v21, v21
	v_pk_mul_f32 v[12:13], v[12:13], v[22:23]
	s_nop 0
	v_pk_mul_f32 v[12:13], v[12:13], v[16:17]
	v_pk_mul_f32 v[14:15], v[14:15], v[20:21]
	v_pk_mul_f32 v[16:17], v[6:7], s[96:97] op_sel_hi:[1,0]
	v_pk_mul_f32 v[14:15], v[14:15], v[18:19]
	v_pk_mul_f32 v[18:19], v[4:5], s[96:97] op_sel_hi:[1,0]
	v_exp_f32_e32 v16, v16
	v_exp_f32_e32 v18, v18
	v_exp_f32_e32 v19, v19
	v_exp_f32_e32 v17, v17
	v_pk_add_f32 v[18:19], v[18:19], 1.0 op_sel_hi:[1,0]
	v_pk_add_f32 v[16:17], v[16:17], 1.0 op_sel_hi:[1,0]
	v_rcp_f32_e32 v18, v18
	v_rcp_f32_e32 v19, v19
	v_rcp_f32_e32 v16, v16
	v_rcp_f32_e32 v17, v17
	v_pk_mul_f32 v[4:5], v[4:5], v[18:19]
	v_pk_mul_f32 v[6:7], v[6:7], v[16:17]
	s_nop 0
	v_pk_mul_f32 v[10:11], v[6:7], v[10:11]
	v_pk_mul_f32 v[6:7], v[4:5], v[8:9]
	v_add_u32_e32 v8, 0x1e4000, v116
	v_cvt_pk_bf16_f32 v4, v12, v13
	v_cvt_pk_bf16_f32 v5, v14, v15
	v_cvt_pk_bf16_f32 v6, v6, v7
	v_cvt_pk_bf16_f32 v7, v10, v11
	global_store_dwordx4 v8, v[4:7], s[70:71] sc1
	s_cbranch_vccnz .LBB0_1110
	s_andn2_b64 vcc, exec, s[8:9]
	s_cbranch_vccnz .LBB0_1109
	s_barrier
	s_branch .LBB0_1109

;     __host__ __device__ bool next(int i, Unit& u) const { return StaticOrder::next(i >> 1, u); }
;     __device__ __forceinline__ bool next(int i, Unit& u) const { const int s = i * G + c; if (s >= 128) return false; const int t = s >> 2; u.pm = pm0 + (t & 3); u.pn = t >> 2; u.k0 = (s & 3) * ksub; return true; }
; #define PG8_WAIT_V(n) asm volatile("s_waitcnt vmcnt(" #n ")" ::: "memory")
; template <class Epi, class Sched, bool ALIGN_EPI = false, bool SP2 = false>
; __device__ __forceinline__ void gemm_phase(PG8_LAS unsigned char* lds, const Gemm g, const Sched& S, const Epi& E) {
;     ...
;     for (;;) {
;         const bool has_next = S.next(ui + 1, nxt);
;         const char* nA = has_next ? (const char*)g.A + (size_t)nxt.pm * tsA + (size_t)nxt.k0 * 2 : cA; const char* nB = has_next ? (const char*)g.Bt + (size_t)nxt.pn * tsB + (size_t)nxt.k0 * 2 : cB;
;         for (int t = (DRO && ui > 0) ? 2 : 0; t < nt; t += 2) {
;             const bool last = (t == nt - 2);
;             const char* a1 = cA + (size_t)(t + 1) * kstep;
;             const char* a2 = last ? nA : cA + (size_t)(t + 2) * kstep; const char* b2 = last ? nB : cB + (size_t)(t + 2) * kstep;
;             const char* a3 = a2 + kstep; const char* b3 = b2 + kstep;
;             if (last && has_next) S.a_ready(nxt);
;             if constexpr (SP2) {
;             PG8_TRIP(true, PG8_WAIT_V(8));
.LBB0_1226:
	v_add_u32_e32 v0, 0x10000, v186
	v_add_u32_e32 v188, 0x14000, v186
	ds_read_b128 v[112:115], v0
	ds_read_b128 v[120:123], v0 offset:1024
	ds_read_b128 v[124:127], v0 offset:2048
	ds_read_b128 v[132:135], v0 offset:3072
	ds_read_b128 v[148:151], v188
	ds_read_b128 v[152:155], v188 offset:1024
	ds_read_b128 v[156:159], v188 offset:2048
	ds_read_b128 v[160:163], v188 offset:3072
	s_add_u32 s14, s12, 0xffea0080
	s_addc_u32 s15, s13, -1
	s_cmpk_eq_i32 s52, 0x54
	s_cselect_b32 s18, s8, s14
	s_cselect_b32 s19, s9, s15
	s_cselect_b32 s16, s6, s53
	s_cselect_b32 s17, s7, s57
	s_add_u32 s14, s18, 0x80
	s_addc_u32 s15, s19, 0
	ds_read_b128 v[164:167], v187
	ds_read_b128 v[168:171], v187 offset:1024
	ds_read_b128 v[178:181], v187 offset:2048
	ds_read_b128 v[190:193], v187 offset:3072
	ds_read_b128 v[194:197], v187 offset:4096
	ds_read_b128 v[198:201], v187 offset:5120
	ds_read_b128 v[202:205], v187 offset:6144
	ds_read_b128 v[206:209], v187 offset:7168
	s_mov_b32 m0, s44
	s_nop 0
	global_load_lds_dwordx4 v174, s[12:13]
	s_nop 0
	s_mov_b32 m0, s45
	s_nop 0
	global_load_lds_dwordx4 v176, s[12:13]
	s_waitcnt vmcnt(8)
	s_waitcnt lgkmcnt(0)
	s_barrier
	s_setprio 1
	s_waitcnt lgkmcnt(0)
	v_mfma_f32_16x16x32_bf16 v[144:147], v[112:115], v[164:167], v[144:147]
	v_mfma_f32_16x16x32_bf16 v[140:143], v[124:127], v[164:167], v[140:143]
	s_waitcnt lgkmcnt(5)
	v_mfma_f32_16x16x32_bf16 v[116:119], v[112:115], v[178:181], v[116:119]
	v_mfma_f32_16x16x32_bf16 v[108:111], v[124:127], v[178:181], v[108:111]
	s_waitcnt lgkmcnt(3)
	v_mfma_f32_16x16x32_bf16 v[96:99], v[112:115], v[194:197], v[96:99]
	v_mfma_f32_16x16x32_bf16 v[92:95], v[124:127], v[194:197], v[92:95]
	s_waitcnt lgkmcnt(1)
	v_mfma_f32_16x16x32_bf16 v[80:83], v[112:115], v[202:205], v[80:83]
	v_mfma_f32_16x16x32_bf16 v[76:79], v[124:127], v[202:205], v[76:79]
	v_mfma_f32_16x16x32_bf16 v[144:147], v[120:123], v[168:171], v[144:147]
	v_mfma_f32_16x16x32_bf16 v[140:143], v[132:135], v[168:171], v[140:143]
	v_mfma_f32_16x16x32_bf16 v[116:119], v[120:123], v[190:193], v[116:119]
	v_mfma_f32_16x16x32_bf16 v[108:111], v[132:135], v[190:193], v[108:111]
	v_mfma_f32_16x16x32_bf16 v[96:99], v[120:123], v[198:201], v[96:99]
	v_mfma_f32_16x16x32_bf16 v[92:95], v[132:135], v[198:201], v[92:95]
	s_waitcnt lgkmcnt(0)
	v_mfma_f32_16x16x32_bf16 v[80:83], v[120:123], v[206:209], v[80:83]
	v_mfma_f32_16x16x32_bf16 v[76:79], v[132:135], v[206:209], v[76:79]
	s_setprio 0
	s_setprio 1
	v_mfma_f32_16x16x32_bf16 v[136:139], v[148:151], v[164:167], v[136:139]
	v_mfma_f32_16x16x32_bf16 v[128:131], v[156:159], v[164:167], v[128:131]
	v_mfma_f32_16x16x32_bf16 v[104:107], v[148:151], v[178:181], v[104:107]
	v_mfma_f32_16x16x32_bf16 v[100:103], v[156:159], v[178:181], v[100:103]
	v_mfma_f32_16x16x32_bf16 v[88:91], v[148:151], v[194:197], v[88:91]
	v_mfma_f32_16x16x32_bf16 v[84:87], v[156:159], v[194:197], v[84:87]
	v_mfma_f32_16x16x32_bf16 v[72:75], v[148:151], v[202:205], v[72:75]
	v_mfma_f32_16x16x32_bf16 v[68:71], v[156:159], v[202:205], v[68:71]
	v_mfma_f32_16x16x32_bf16 v[136:139], v[152:155], v[168:171], v[136:139]
	v_mfma_f32_16x16x32_bf16 v[128:131], v[160:163], v[168:171], v[128:131]
	v_mfma_f32_16x16x32_bf16 v[104:107], v[152:155], v[190:193], v[104:107]
	v_mfma_f32_16x16x32_bf16 v[100:103], v[160:163], v[190:193], v[100:103]
	v_mfma_f32_16x16x32_bf16 v[88:91], v[152:155], v[198:201], v[88:91]
	v_mfma_f32_16x16x32_bf16 v[84:87], v[160:163], v[198:201], v[84:87]
	v_mfma_f32_16x16x32_bf16 v[72:75], v[152:155], v[206:209], v[72:75]
	v_mfma_f32_16x16x32_bf16 v[68:71], v[160:163], v[206:209], v[68:71]
	s_setprio 0
	s_barrier
	ds_read_b128 v[164:167], v187 offset:16384
	ds_read_b128 v[168:171], v187 offset:17408
	ds_read_b128 v[178:181], v187 offset:18432
	ds_read_b128 v[190:193], v187 offset:19456
	ds_read_b128 v[194:197], v187 offset:20480
	ds_read_b128 v[198:201], v187 offset:21504
	ds_read_b128 v[202:205], v187 offset:22528
	ds_read_b128 v[206:209], v187 offset:23552
	s_mov_b32 m0, s22
	s_nop 0
	global_load_lds_dwordx4 v175, s[16:17]
	s_add_u32 s78, s16, 0x160000
	s_mov_b32 m0, s23
	s_nop 0
	global_load_lds_dwordx4 v177, s[16:17]
	s_addc_u32 s79, s17, 0
	s_mov_b32 m0, s26
	s_nop 0
	global_load_lds_dwordx4 v175, s[78:79]
	s_nop 0
	s_mov_b32 m0, s27
	s_nop 0
	global_load_lds_dwordx4 v177, s[78:79]
	s_nop 0
	s_mov_b32 m0, s21
	s_nop 0
	global_load_lds_dwordx4 v174, s[18:19]
	s_nop 0
	s_mov_b32 m0, s28
	s_nop 0
	global_load_lds_dwordx4 v176, s[18:19]
	s_waitcnt vmcnt(8)
	s_waitcnt lgkmcnt(0)
	s_barrier
	s_setprio 1
	s_waitcnt lgkmcnt(0)
	v_mfma_f32_16x16x32_bf16 v[64:67], v[112:115], v[164:167], v[64:67]
	v_mfma_f32_16x16x32_bf16 v[60:63], v[124:127], v[164:167], v[60:63]
	s_waitcnt lgkmcnt(5)
	v_mfma_f32_16x16x32_bf16 v[48:51], v[112:115], v[178:181], v[48:51]
	v_mfma_f32_16x16x32_bf16 v[44:47], v[124:127], v[178:181], v[44:47]
	s_waitcnt lgkmcnt(3)
	v_mfma_f32_16x16x32_bf16 v[32:35], v[112:115], v[194:197], v[32:35]
	v_mfma_f32_16x16x32_bf16 v[28:31], v[124:127], v[194:197], v[28:31]
	s_waitcnt lgkmcnt(1)
	v_mfma_f32_16x16x32_bf16 v[16:19], v[112:115], v[202:205], v[16:19]
	v_mfma_f32_16x16x32_bf16 v[12:15], v[124:127], v[202:205], v[12:15]
	v_mfma_f32_16x16x32_bf16 v[64:67], v[120:123], v[168:171], v[64:67]
	v_mfma_f32_16x16x32_bf16 v[60:63], v[132:135], v[168:171], v[60:63]
	v_mfma_f32_16x16x32_bf16 v[48:51], v[120:123], v[190:193], v[48:51]
	v_mfma_f32_16x16x32_bf16 v[44:47], v[132:135], v[190:193], v[44:47]
	v_mfma_f32_16x16x32_bf16 v[32:35], v[120:123], v[198:201], v[32:35]
	v_mfma_f32_16x16x32_bf16 v[28:31], v[132:135], v[198:201], v[28:31]
	s_waitcnt lgkmcnt(0)
	v_mfma_f32_16x16x32_bf16 v[16:19], v[120:123], v[206:209], v[16:19]
	v_mfma_f32_16x16x32_bf16 v[12:15], v[132:135], v[206:209], v[12:15]
	s_setprio 0
	s_setprio 1
	v_mfma_f32_16x16x32_bf16 v[56:59], v[148:151], v[164:167], v[56:59]
	v_mfma_f32_16x16x32_bf16 v[52:55], v[156:159], v[164:167], v[52:55]
	v_mfma_f32_16x16x32_bf16 v[40:43], v[148:151], v[178:181], v[40:43]
	v_mfma_f32_16x16x32_bf16 v[36:39], v[156:159], v[178:181], v[36:39]
	v_mfma_f32_16x16x32_bf16 v[24:27], v[148:151], v[194:197], v[24:27]
	v_mfma_f32_16x16x32_bf16 v[20:23], v[156:159], v[194:197], v[20:23]
	v_mfma_f32_16x16x32_bf16 v[8:11], v[148:151], v[202:205], v[8:11]
	v_mfma_f32_16x16x32_bf16 v[2:5], v[156:159], v[202:205], v[4:7]
	v_mfma_f32_16x16x32_bf16 v[56:59], v[152:155], v[168:171], v[56:59]
	v_mfma_f32_16x16x32_bf16 v[52:55], v[160:163], v[168:171], v[52:55]
	v_mfma_f32_16x16x32_bf16 v[40:43], v[152:155], v[190:193], v[40:43]
	v_mfma_f32_16x16x32_bf16 v[36:39], v[160:163], v[190:193], v[36:39]
	v_mfma_f32_16x16x32_bf16 v[24:27], v[152:155], v[198:201], v[24:27]
	v_mfma_f32_16x16x32_bf16 v[20:23], v[160:163], v[198:201], v[20:23]
	v_mfma_f32_16x16x32_bf16 v[8:11], v[152:155], v[206:209], v[8:11]
	v_mfma_f32_16x16x32_bf16 v[2:5], v[160:163], v[206:209], v[2:5]
	s_setprio 0
	s_barrier
	v_add_u32_e32 v189, 0x18000, v186
	v_add_u32_e32 v190, 0x1c000, v186
	ds_read_b128 v[112:115], v189
	ds_read_b128 v[120:123], v189 offset:1024
	ds_read_b128 v[124:127], v189 offset:2048
	ds_read_b128 v[132:135], v189 offset:3072
	ds_read_b128 v[148:151], v190
	ds_read_b128 v[152:155], v190 offset:1024
	ds_read_b128 v[156:159], v190 offset:2048
	ds_read_b128 v[160:163], v190 offset:3072
	ds_read_b128 v[164:167], v187 offset:32768
	ds_read_b128 v[168:171], v187 offset:33792
	ds_read_b128 v[178:181], v187 offset:34816
	ds_read_b128 v[192:195], v187 offset:35840
	ds_read_b128 v[196:199], v187 offset:36864
	ds_read_b128 v[200:203], v187 offset:37888
	ds_read_b128 v[204:207], v187 offset:38912
	ds_read_b128 v[208:211], v187 offset:39936
	s_add_u32 s18, s18, 0x160000
	s_addc_u32 s19, s19, 0
	s_mov_b32 m0, s29
	s_nop 0
	global_load_lds_dwordx4 v174, s[18:19]
	s_nop 0
	s_mov_b32 m0, s30
	s_nop 0
	global_load_lds_dwordx4 v176, s[18:19]
	s_waitcnt vmcnt(8)
	s_waitcnt lgkmcnt(0)
	s_barrier
	s_setprio 1
	s_waitcnt lgkmcnt(0)
	v_mfma_f32_16x16x32_bf16 v[144:147], v[112:115], v[164:167], v[144:147]
	v_mfma_f32_16x16x32_bf16 v[140:143], v[124:127], v[164:167], v[140:143]
	s_waitcnt lgkmcnt(5)
	v_mfma_f32_16x16x32_bf16 v[116:119], v[112:115], v[178:181], v[116:119]
	v_mfma_f32_16x16x32_bf16 v[108:111], v[124:127], v[178:181], v[108:111]
	s_waitcnt lgkmcnt(3)
	v_mfma_f32_16x16x32_bf16 v[96:99], v[112:115], v[196:199], v[96:99]
	v_mfma_f32_16x16x32_bf16 v[92:95], v[124:127], v[196:199], v[92:95]
	s_waitcnt lgkmcnt(1)
	v_mfma_f32_16x16x32_bf16 v[80:83], v[112:115], v[204:207], v[80:83]
	v_mfma_f32_16x16x32_bf16 v[76:79], v[124:127], v[204:207], v[76:79]
	v_mfma_f32_16x16x32_bf16 v[144:147], v[120:123], v[168:171], v[144:147]
	v_mfma_f32_16x16x32_bf16 v[140:143], v[132:135], v[168:171], v[140:143]
	v_mfma_f32_16x16x32_bf16 v[116:119], v[120:123], v[192:195], v[116:119]
	v_mfma_f32_16x16x32_bf16 v[108:111], v[132:135], v[192:195], v[108:111]
	v_mfma_f32_16x16x32_bf16 v[96:99], v[120:123], v[200:203], v[96:99]
	v_mfma_f32_16x16x32_bf16 v[92:95], v[132:135], v[200:203], v[92:95]
	s_waitcnt lgkmcnt(0)
	v_mfma_f32_16x16x32_bf16 v[80:83], v[120:123], v[208:211], v[80:83]
	v_mfma_f32_16x16x32_bf16 v[76:79], v[132:135], v[208:211], v[76:79]
	s_setprio 0
	s_setprio 1
	v_mfma_f32_16x16x32_bf16 v[136:139], v[148:151], v[164:167], v[136:139]
	v_mfma_f32_16x16x32_bf16 v[128:131], v[156:159], v[164:167], v[128:131]
	v_mfma_f32_16x16x32_bf16 v[104:107], v[148:151], v[178:181], v[104:107]
	v_mfma_f32_16x16x32_bf16 v[100:103], v[156:159], v[178:181], v[100:103]
	v_mfma_f32_16x16x32_bf16 v[88:91], v[148:151], v[196:199], v[88:91]
	v_mfma_f32_16x16x32_bf16 v[84:87], v[156:159], v[196:199], v[84:87]
	v_mfma_f32_16x16x32_bf16 v[72:75], v[148:151], v[204:207], v[72:75]
	v_mfma_f32_16x16x32_bf16 v[68:71], v[156:159], v[204:207], v[68:71]
	v_mfma_f32_16x16x32_bf16 v[136:139], v[152:155], v[168:171], v[136:139]
	v_mfma_f32_16x16x32_bf16 v[128:131], v[160:163], v[168:171], v[128:131]
	v_mfma_f32_16x16x32_bf16 v[104:107], v[152:155], v[192:195], v[104:107]
	v_mfma_f32_16x16x32_bf16 v[100:103], v[160:163], v[192:195], v[100:103]
	v_mfma_f32_16x16x32_bf16 v[88:91], v[152:155], v[200:203], v[88:91]
	v_mfma_f32_16x16x32_bf16 v[84:87], v[160:163], v[200:203], v[84:87]
	v_mfma_f32_16x16x32_bf16 v[72:75], v[152:155], v[208:211], v[72:75]
	v_mfma_f32_16x16x32_bf16 v[68:71], v[160:163], v[208:211], v[68:71]
	s_setprio 0
	s_barrier
; #define ER_LOAD(dst, ai, mp) do { _Pragma("unroll") for (int mm = 0; mm < 2; ++mm) _Pragma("unroll") for (int bj = 0; bj < 2; ++bj) \
;             dst[mm][bj] = *(const u32x4*)(xb + (size_t)((ai) * HALF + (2 * (mp) + mm) * 16) * 2048 + bj * HALF); } while (0)
;     __device__ __forceinline__ void operator()(const f32x4 (&acc)[2][2][4][2], const Unit& u, int wr, int wc, int fr, int fq) const {
;         const int row0 = u.pm * BM + wr * 64 + fr, col0 = u.pn * BM + wc * 32 + 8 * fq;
;         const int b = (u.pm < n_lat_panels) ? (u.pm >> 4) : 4;
;         const float* g = gate + (size_t)b * gstride + col0;
;         bf16_t* xb = X + (size_t)row0 * 2048 + col0;
;         f32x4 gv[2][2];
; #pragma unroll
;         for (int bj = 0; bj < 2; ++bj)
; #pragma unroll
;             for (int n = 0; n < 2; ++n) gv[bj][n] = *(const f32x4*)(g + bj * HALF + 4 * n);
;         u32x4 xa[2][2], xc[2][2];
;     ...
;         ER_LOAD(xa, 0, 0); ER_LOAD(xc, 0, 1);
	ds_read_b128 v[164:167], v187 offset:49152
	ds_read_b128 v[168:171], v187 offset:50176
	ds_read_b128 v[178:181], v187 offset:51200
	ds_read_b128 v[192:195], v187 offset:52224
	ds_read_b128 v[196:199], v187 offset:53248
	ds_read_b128 v[200:203], v187 offset:54272
	ds_read_b128 v[204:207], v187 offset:55296
	ds_read_b128 v[208:211], v187 offset:56320
	s_add_u32 s18, s16, 0x80
	s_addc_u32 s19, s17, 0
	s_mov_b32 m0, s34
	s_nop 0
	global_load_lds_dwordx4 v175, s[18:19]
	s_add_u32 s16, s16, 0x160080
	s_mov_b32 m0, s35
	s_nop 0
	global_load_lds_dwordx4 v177, s[18:19]
	s_addc_u32 s17, s17, 0
	s_mov_b32 m0, s40
	s_nop 0
	global_load_lds_dwordx4 v175, s[16:17]
	s_nop 0
	s_mov_b32 m0, s41
	s_nop 0
	global_load_lds_dwordx4 v177, s[16:17]
	s_nop 0
	s_mov_b32 m0, s36
	s_nop 0
	global_load_lds_dwordx4 v174, s[14:15]
	s_nop 0
	s_mov_b32 m0, s37
	s_nop 0
	global_load_lds_dwordx4 v176, s[14:15]
	s_waitcnt vmcnt(8)
	s_waitcnt lgkmcnt(0)
	s_barrier
	s_setprio 1
	s_waitcnt lgkmcnt(0)
	v_mfma_f32_16x16x32_bf16 v[64:67], v[112:115], v[164:167], v[64:67]
	v_mfma_f32_16x16x32_bf16 v[60:63], v[124:127], v[164:167], v[60:63]
	s_waitcnt lgkmcnt(5)
	v_mfma_f32_16x16x32_bf16 v[48:51], v[112:115], v[178:181], v[48:51]
	v_mfma_f32_16x16x32_bf16 v[44:47], v[124:127], v[178:181], v[44:47]
	s_waitcnt lgkmcnt(3)
	v_mfma_f32_16x16x32_bf16 v[32:35], v[112:115], v[196:199], v[32:35]
	v_mfma_f32_16x16x32_bf16 v[28:31], v[124:127], v[196:199], v[28:31]
	s_waitcnt lgkmcnt(1)
	v_mfma_f32_16x16x32_bf16 v[16:19], v[112:115], v[204:207], v[16:19]
	v_mfma_f32_16x16x32_bf16 v[12:15], v[124:127], v[204:207], v[12:15]
	v_mfma_f32_16x16x32_bf16 v[64:67], v[120:123], v[168:171], v[64:67]
	v_mfma_f32_16x16x32_bf16 v[60:63], v[132:135], v[168:171], v[60:63]
	v_mfma_f32_16x16x32_bf16 v[48:51], v[120:123], v[192:195], v[48:51]
	v_mfma_f32_16x16x32_bf16 v[44:47], v[132:135], v[192:195], v[44:47]
	v_mfma_f32_16x16x32_bf16 v[32:35], v[120:123], v[200:203], v[32:35]
	v_mfma_f32_16x16x32_bf16 v[28:31], v[132:135], v[200:203], v[28:31]
	s_waitcnt lgkmcnt(0)
	v_mfma_f32_16x16x32_bf16 v[16:19], v[120:123], v[208:211], v[16:19]
	v_mfma_f32_16x16x32_bf16 v[12:15], v[132:135], v[208:211], v[12:15]
	s_setprio 0
	s_setprio 1
	v_mfma_f32_16x16x32_bf16 v[56:59], v[148:151], v[164:167], v[56:59]
	v_mfma_f32_16x16x32_bf16 v[52:55], v[156:159], v[164:167], v[52:55]
	v_mfma_f32_16x16x32_bf16 v[40:43], v[148:151], v[178:181], v[40:43]
	v_mfma_f32_16x16x32_bf16 v[36:39], v[156:159], v[178:181], v[36:39]
	v_mfma_f32_16x16x32_bf16 v[24:27], v[148:151], v[196:199], v[24:27]
	v_mfma_f32_16x16x32_bf16 v[20:23], v[156:159], v[196:199], v[20:23]
	v_mfma_f32_16x16x32_bf16 v[6:9], v[148:151], v[204:207], v[8:11]
	v_mfma_f32_16x16x32_bf16 v[2:5], v[156:159], v[204:207], v[2:5]
	v_mfma_f32_16x16x32_bf16 v[56:59], v[152:155], v[168:171], v[56:59]
	v_mfma_f32_16x16x32_bf16 v[52:55], v[160:163], v[168:171], v[52:55]
	v_mfma_f32_16x16x32_bf16 v[40:43], v[152:155], v[192:195], v[40:43]
	v_mfma_f32_16x16x32_bf16 v[36:39], v[160:163], v[192:195], v[36:39]
	v_mfma_f32_16x16x32_bf16 v[24:27], v[152:155], v[200:203], v[24:27]
	v_mfma_f32_16x16x32_bf16 v[20:23], v[160:163], v[200:203], v[20:23]
	v_mfma_f32_16x16x32_bf16 v[8:11], v[152:155], v[208:211], v[6:9]
	v_mfma_f32_16x16x32_bf16 v[4:7], v[160:163], v[208:211], v[2:5]
	s_setprio 0
	s_barrier
	s_add_i32 s52, s52, 2
	s_add_u32 s53, s53, 0x100
	s_addc_u32 s57, s57, 0
	s_add_u32 s12, s12, 0x100
	s_addc_u32 s13, s13, 0
	s_cmpk_gt_u32 s52, 0x55
	s_cbranch_scc0 .LBB0_1226
	s_add_u32 s12, s8, 0x160080
	s_addc_u32 s13, s9, 0
	s_mov_b32 m0, s44
	s_nop 0
	global_load_lds_dwordx4 v174, s[12:13]
	v_lshl_add_u32 v2, s51, 8, v184
	s_mov_b32 m0, s45
	s_nop 0
	global_load_lds_dwordx4 v176, s[12:13]
	s_min_i32 s12, s51, 64
	s_ashr_i32 s12, s12, 4
	s_mul_hi_i32 s13, s12, 0xc000
	s_mul_i32 s12, s12, 0xc000
	v_ashrrev_i32_e32 v3, 31, v2
	v_lshl_or_b32 v148, s49, 8, v185
	s_add_u32 s12, s31, s12
	v_lshlrev_b64 v[2:3], 12, v[2:3]
	s_addc_u32 s13, s33, s13
	v_ashrrev_i32_e32 v149, 31, v148
	v_lshl_add_u64 v[2:3], s[80:81], 0, v[2:3]
	v_lshl_add_u64 v[112:113], v[148:149], 2, s[12:13]
	v_lshl_add_u64 v[2:3], v[148:149], 1, v[2:3]
	global_load_dwordx4 v[132:135], v[112:113], off
	global_load_dwordx4 v[124:127], v[112:113], off offset:16
	global_load_dwordx4 v[120:123], v[112:113], off offset:512
	global_load_dwordx4 v[112:115], v[112:113], off offset:528
	global_load_dwordx4 v[178:181], v[2:3], off
	global_load_dwordx4 v[192:195], v[2:3], off offset:256
	v_add_co_u32_e32 v172, vcc, 0x10000, v2
	s_nop 1
	v_addc_co_u32_e32 v173, vcc, 0, v3, vcc
	global_load_dwordx4 v[196:199], v[172:173], off
	global_load_dwordx4 v[164:167], v[172:173], off offset:256
	v_add_co_u32_e32 v170, vcc, 0x20000, v2
	s_nop 1
	v_addc_co_u32_e32 v171, vcc, 0, v3, vcc
	global_load_dwordx4 v[160:163], v[170:171], off
	global_load_dwordx4 v[156:159], v[170:171], off offset:256
	v_add_co_u32_e32 v168, vcc, 0x30000, v2
	s_nop 1
	v_addc_co_u32_e32 v169, vcc, 0, v3, vcc
	global_load_dwordx4 v[152:155], v[168:169], off
	global_load_dwordx4 v[148:151], v[168:169], off offset:256
	v_add_co_u32_e32 v244, vcc, 0x80000, v2
	s_nop 1
	v_addc_co_u32_e32 v245, vcc, 0, v3, vcc
	global_load_dwordx4 v[212:215], v[244:245], off
	global_load_dwordx4 v[216:219], v[244:245], off offset:256
	v_add_co_u32_e32 v246, vcc, 0x90000, v2
	s_nop 1
	v_addc_co_u32_e32 v247, vcc, 0, v3, vcc
	global_load_dwordx4 v[220:223], v[246:247], off
	global_load_dwordx4 v[224:227], v[246:247], off offset:256
	v_add_co_u32_e32 v248, vcc, 0xa0000, v2
	s_nop 1
	v_addc_co_u32_e32 v249, vcc, 0, v3, vcc
	global_load_dwordx4 v[228:231], v[248:249], off
	global_load_dwordx4 v[232:235], v[248:249], off offset:256
	v_add_co_u32_e32 v250, vcc, 0xb0000, v2
	s_nop 1
	v_addc_co_u32_e32 v251, vcc, 0, v3, vcc
	global_load_dwordx4 v[236:239], v[250:251], off
	global_load_dwordx4 v[240:243], v[250:251], off offset:256
	s_nop 0
	s_nop 0
	s_mov_b32 s12, 0x10000
	s_mov_b32 s12, 0x90000
	s_nop 0
	s_waitcnt vmcnt(15)
; #define ER_LOAD(dst, ai, mp) do { _Pragma("unroll") for (int mm = 0; mm < 2; ++mm) _Pragma("unroll") for (int bj = 0; bj < 2; ++bj) \
;             dst[mm][bj] = *(const u32x4*)(xb + (size_t)((ai) * HALF + (2 * (mp) + mm) * 16) * 2048 + bj * HALF); } while (0)
;     __device__ __forceinline__ void operator()(const f32x4 (&acc)[2][2][4][2], const Unit& u, int wr, int wc, int fr, int fq) const {
;     ...
;         ER_LOAD(xa, 0, 0); ER_LOAD(xc, 0, 1);
;         ER_STORE(xa, 0, 0); ER_LOAD(xa, 1, 0);
;         ER_STORE(xc, 0, 1); ER_LOAD(xc, 1, 1);
;         ER_STORE(xa, 1, 0); ER_STORE(xc, 1, 1);
	v_cvt_f32_f16_e32 v200, v178
	v_cvt_f32_f16_sdwa v201, v178 dst_sel:DWORD dst_unused:UNUSED_PAD src0_sel:WORD_1
	s_nop 0
	v_cvt_f32_f16_e32 v178, v179
	v_cvt_f32_f16_sdwa v179, v179 dst_sel:DWORD dst_unused:UNUSED_PAD src0_sel:WORD_1
	v_pk_fma_f32 v[144:145], v[144:145], v[132:133], v[200:201]
	v_pk_fma_f32 v[146:147], v[146:147], v[134:135], v[178:179]
	v_cvt_f32_f16_e32 v178, v180
	v_cvt_f32_f16_sdwa v179, v180 dst_sel:DWORD dst_unused:UNUSED_PAD src0_sel:WORD_1
	v_cvt_f32_f16_e32 v180, v181
	v_cvt_f32_f16_sdwa v181, v181 dst_sel:DWORD dst_unused:UNUSED_PAD src0_sel:WORD_1
	v_pk_fma_f32 v[180:181], v[142:143], v[126:127], v[180:181]
	v_pk_fma_f32 v[142:143], v[140:141], v[124:125], v[178:179]
	v_cvt_pk_f16_f32 v140, v144, v145
	v_cvt_pk_f16_f32 v141, v146, v147
	v_cvt_pk_f16_f32 v142, v142, v143
	v_cvt_pk_f16_f32 v143, v180, v181
	global_store_dwordx4 v[2:3], v[140:143], off sc1
	s_nop 1
	s_waitcnt vmcnt(15)
	v_cvt_f32_f16_e32 v140, v192
	v_cvt_f32_f16_sdwa v141, v192 dst_sel:DWORD dst_unused:UNUSED_PAD src0_sel:WORD_1
	v_cvt_f32_f16_e32 v142, v193
	v_cvt_f32_f16_sdwa v143, v193 dst_sel:DWORD dst_unused:UNUSED_PAD src0_sel:WORD_1
	v_pk_fma_f32 v[136:137], v[136:137], v[120:121], v[140:141]
	v_cvt_f32_f16_e32 v140, v194
	v_pk_fma_f32 v[138:139], v[138:139], v[122:123], v[142:143]
	v_cvt_f32_f16_sdwa v141, v194 dst_sel:DWORD dst_unused:UNUSED_PAD src0_sel:WORD_1
	v_cvt_f32_f16_e32 v142, v195
	v_cvt_f32_f16_sdwa v143, v195 dst_sel:DWORD dst_unused:UNUSED_PAD src0_sel:WORD_1
	v_pk_fma_f32 v[142:143], v[130:131], v[114:115], v[142:143]
	v_pk_fma_f32 v[130:131], v[128:129], v[112:113], v[140:141]
	v_cvt_pk_f16_f32 v128, v136, v137
	v_cvt_pk_f16_f32 v129, v138, v139
	v_cvt_pk_f16_f32 v130, v130, v131
	v_cvt_pk_f16_f32 v131, v142, v143
	global_store_dwordx4 v[2:3], v[128:131], off offset:256 sc1
	s_waitcnt vmcnt(13)
	v_cvt_f32_f16_e32 v136, v160
	v_cvt_f32_f16_e32 v128, v196
	v_cvt_f32_f16_sdwa v129, v196 dst_sel:DWORD dst_unused:UNUSED_PAD src0_sel:WORD_1
	v_cvt_f32_f16_e32 v130, v197
	v_cvt_f32_f16_sdwa v131, v197 dst_sel:DWORD dst_unused:UNUSED_PAD src0_sel:WORD_1
	v_cvt_f32_f16_sdwa v137, v160 dst_sel:DWORD dst_unused:UNUSED_PAD src0_sel:WORD_1
	v_pk_fma_f32 v[116:117], v[116:117], v[132:133], v[128:129]
	v_cvt_f32_f16_e32 v128, v198
	v_pk_fma_f32 v[118:119], v[118:119], v[134:135], v[130:131]
	v_cvt_f32_f16_sdwa v129, v198 dst_sel:DWORD dst_unused:UNUSED_PAD src0_sel:WORD_1
	v_cvt_f32_f16_e32 v130, v199
	v_cvt_f32_f16_sdwa v131, v199 dst_sel:DWORD dst_unused:UNUSED_PAD src0_sel:WORD_1
	v_cvt_f32_f16_e32 v138, v161
	v_cvt_f32_f16_sdwa v139, v161 dst_sel:DWORD dst_unused:UNUSED_PAD src0_sel:WORD_1
	v_pk_fma_f32 v[96:97], v[96:97], v[132:133], v[136:137]
	v_pk_fma_f32 v[130:131], v[110:111], v[126:127], v[130:131]
	v_pk_fma_f32 v[110:111], v[108:109], v[124:125], v[128:129]
	v_cvt_pk_f16_f32 v108, v116, v117
	v_cvt_pk_f16_f32 v109, v118, v119
	v_cvt_pk_f16_f32 v110, v110, v111
	v_cvt_pk_f16_f32 v111, v130, v131
	global_store_dwordx4 v[172:173], v[108:111], off sc1
	v_add_co_u32_e32 v130, vcc, s83, v2
	s_nop 0
	v_cvt_f32_f16_e32 v108, v164
	v_cvt_f32_f16_sdwa v109, v164 dst_sel:DWORD dst_unused:UNUSED_PAD src0_sel:WORD_1
	v_cvt_f32_f16_e32 v110, v165
	v_cvt_f32_f16_sdwa v111, v165 dst_sel:DWORD dst_unused:UNUSED_PAD src0_sel:WORD_1
	v_addc_co_u32_e32 v131, vcc, 0, v3, vcc
	v_pk_fma_f32 v[104:105], v[104:105], v[120:121], v[108:109]
	v_pk_fma_f32 v[106:107], v[106:107], v[122:123], v[110:111]
	v_cvt_f32_f16_e32 v108, v166
	v_cvt_f32_f16_sdwa v109, v166 dst_sel:DWORD dst_unused:UNUSED_PAD src0_sel:WORD_1
	v_cvt_f32_f16_e32 v110, v167
	v_cvt_f32_f16_sdwa v111, v167 dst_sel:DWORD dst_unused:UNUSED_PAD src0_sel:WORD_1
	v_pk_fma_f32 v[98:99], v[98:99], v[134:135], v[138:139]
	v_cvt_f32_f16_e32 v136, v162
	v_cvt_f32_f16_sdwa v137, v162 dst_sel:DWORD dst_unused:UNUSED_PAD src0_sel:WORD_1
	v_pk_fma_f32 v[110:111], v[102:103], v[114:115], v[110:111]
	v_pk_fma_f32 v[102:103], v[100:101], v[112:113], v[108:109]
	v_cvt_pk_f16_f32 v100, v104, v105
	v_cvt_pk_f16_f32 v101, v106, v107
	v_cvt_pk_f16_f32 v102, v102, v103
	v_cvt_pk_f16_f32 v103, v110, v111
	global_store_dwordx4 v[172:173], v[100:103], off offset:256 sc1
	v_cvt_f32_f16_e32 v138, v163
	v_cvt_f32_f16_sdwa v139, v163 dst_sel:DWORD dst_unused:UNUSED_PAD src0_sel:WORD_1
	v_add_co_u32_e32 v128, vcc, s12, v2
	s_mov_b32 s12, 0xa0000
	v_pk_fma_f32 v[138:139], v[94:95], v[126:127], v[138:139]
	v_pk_fma_f32 v[94:95], v[92:93], v[124:125], v[136:137]
	v_addc_co_u32_e32 v129, vcc, 0, v3, vcc
	v_cvt_pk_f16_f32 v92, v96, v97
	v_cvt_pk_f16_f32 v93, v98, v99
	v_cvt_pk_f16_f32 v94, v94, v95
	v_cvt_pk_f16_f32 v95, v138, v139
	s_nop 0
	global_store_dwordx4 v[170:171], v[92:95], off sc1
	s_nop 1
	s_waitcnt vmcnt(15)
	v_cvt_f32_f16_e32 v92, v156
	v_cvt_f32_f16_sdwa v93, v156 dst_sel:DWORD dst_unused:UNUSED_PAD src0_sel:WORD_1
	v_cvt_f32_f16_e32 v94, v157
	v_cvt_f32_f16_sdwa v95, v157 dst_sel:DWORD dst_unused:UNUSED_PAD src0_sel:WORD_1
	v_pk_fma_f32 v[88:89], v[88:89], v[120:121], v[92:93]
	v_cvt_f32_f16_e32 v92, v158
	v_pk_fma_f32 v[90:91], v[90:91], v[122:123], v[94:95]
	v_cvt_f32_f16_sdwa v93, v158 dst_sel:DWORD dst_unused:UNUSED_PAD src0_sel:WORD_1
	v_cvt_f32_f16_e32 v94, v159
	v_cvt_f32_f16_sdwa v95, v159 dst_sel:DWORD dst_unused:UNUSED_PAD src0_sel:WORD_1
	v_pk_fma_f32 v[94:95], v[86:87], v[114:115], v[94:95]
	v_pk_fma_f32 v[86:87], v[84:85], v[112:113], v[92:93]
	v_cvt_pk_f16_f32 v84, v88, v89
	v_cvt_pk_f16_f32 v85, v90, v91
	v_cvt_pk_f16_f32 v86, v86, v87
	v_cvt_pk_f16_f32 v87, v94, v95
	global_store_dwordx4 v[170:171], v[84:87], off offset:256 sc1
	s_waitcnt vmcnt(13)
; #define ER_LOAD(dst, ai, mp) do { _Pragma("unroll") for (int mm = 0; mm < 2; ++mm) _Pragma("unroll") for (int bj = 0; bj < 2; ++bj) \
;             dst[mm][bj] = *(const u32x4*)(xb + (size_t)((ai) * HALF + (2 * (mp) + mm) * 16) * 2048 + bj * HALF); } while (0)
;     __device__ __forceinline__ void operator()(const f32x4 (&acc)[2][2][4][2], const Unit& u, int wr, int wc, int fr, int fq) const {
;     ...
;         ER_LOAD(xa, 0, 0); ER_LOAD(xc, 0, 1);
;         ER_STORE(xa, 0, 0); ER_LOAD(xa, 1, 0);
;         ER_STORE(xc, 0, 1); ER_LOAD(xc, 1, 1);
;         ER_STORE(xa, 1, 0); ER_STORE(xc, 1, 1);
	v_cvt_f32_f16_e32 v88, v213
	v_cvt_f32_f16_e32 v84, v152
	v_cvt_f32_f16_sdwa v85, v152 dst_sel:DWORD dst_unused:UNUSED_PAD src0_sel:WORD_1
	v_cvt_f32_f16_e32 v86, v153
	v_cvt_f32_f16_sdwa v87, v153 dst_sel:DWORD dst_unused:UNUSED_PAD src0_sel:WORD_1
	v_cvt_f32_f16_sdwa v89, v213 dst_sel:DWORD dst_unused:UNUSED_PAD src0_sel:WORD_1
	v_pk_fma_f32 v[80:81], v[80:81], v[132:133], v[84:85]
	v_cvt_f32_f16_e32 v84, v154
	v_pk_fma_f32 v[82:83], v[82:83], v[134:135], v[86:87]
	v_cvt_f32_f16_sdwa v85, v154 dst_sel:DWORD dst_unused:UNUSED_PAD src0_sel:WORD_1
	v_cvt_f32_f16_e32 v86, v155
	v_cvt_f32_f16_sdwa v87, v155 dst_sel:DWORD dst_unused:UNUSED_PAD src0_sel:WORD_1
	v_pk_fma_f32 v[66:67], v[66:67], v[134:135], v[88:89]
	v_cvt_f32_f16_e32 v88, v215
	v_cvt_f32_f16_sdwa v89, v215 dst_sel:DWORD dst_unused:UNUSED_PAD src0_sel:WORD_1
	v_pk_fma_f32 v[86:87], v[78:79], v[126:127], v[86:87]
	v_pk_fma_f32 v[78:79], v[76:77], v[124:125], v[84:85]
	v_cvt_pk_f16_f32 v76, v80, v81
	v_cvt_pk_f16_f32 v77, v82, v83
	v_cvt_pk_f16_f32 v78, v78, v79
	v_cvt_pk_f16_f32 v79, v86, v87
	global_store_dwordx4 v[168:169], v[76:79], off sc1
	v_add_co_u32_e32 v84, vcc, s12, v2
	s_nop 0
	v_cvt_f32_f16_e32 v76, v148
	v_cvt_f32_f16_sdwa v77, v148 dst_sel:DWORD dst_unused:UNUSED_PAD src0_sel:WORD_1
	v_cvt_f32_f16_e32 v78, v149
	v_cvt_f32_f16_sdwa v79, v149 dst_sel:DWORD dst_unused:UNUSED_PAD src0_sel:WORD_1
	v_addc_co_u32_e32 v85, vcc, 0, v3, vcc
	v_pk_fma_f32 v[72:73], v[72:73], v[120:121], v[76:77]
	v_pk_fma_f32 v[74:75], v[74:75], v[122:123], v[78:79]
	v_cvt_f32_f16_e32 v76, v150
	v_cvt_f32_f16_sdwa v77, v150 dst_sel:DWORD dst_unused:UNUSED_PAD src0_sel:WORD_1
	v_cvt_f32_f16_e32 v78, v151
	v_cvt_f32_f16_sdwa v79, v151 dst_sel:DWORD dst_unused:UNUSED_PAD src0_sel:WORD_1
	s_mov_b32 s12, 0xb0000
	v_add_co_u32_e32 v2, vcc, s12, v2
	v_pk_fma_f32 v[78:79], v[70:71], v[114:115], v[78:79]
	v_pk_fma_f32 v[70:71], v[68:69], v[112:113], v[76:77]
	v_cvt_pk_f16_f32 v68, v72, v73
	v_cvt_pk_f16_f32 v69, v74, v75
	v_cvt_pk_f16_f32 v70, v70, v71
	v_cvt_pk_f16_f32 v71, v78, v79
	global_store_dwordx4 v[168:169], v[68:71], off offset:256 sc1
	v_addc_co_u32_e32 v3, vcc, 0, v3, vcc
	v_cvt_f32_f16_e32 v86, v212
	v_cvt_f32_f16_sdwa v87, v212 dst_sel:DWORD dst_unused:UNUSED_PAD src0_sel:WORD_1
	v_pk_fma_f32 v[88:89], v[62:63], v[126:127], v[88:89]
	s_mov_b64 s[12:13], -1
	s_and_b64 vcc, exec, s[10:11]
	v_pk_fma_f32 v[64:65], v[64:65], v[132:133], v[86:87]
	v_cvt_f32_f16_e32 v86, v214
	v_cvt_f32_f16_sdwa v87, v214 dst_sel:DWORD dst_unused:UNUSED_PAD src0_sel:WORD_1
	v_pk_fma_f32 v[62:63], v[60:61], v[124:125], v[86:87]
	v_cvt_pk_f16_f32 v60, v64, v65
	v_cvt_pk_f16_f32 v61, v66, v67
	v_cvt_pk_f16_f32 v62, v62, v63
	v_cvt_pk_f16_f32 v63, v88, v89
	global_store_dwordx4 v[130:131], v[60:63], off sc1
	s_nop 1
	s_waitcnt vmcnt(15)
	v_cvt_f32_f16_e32 v60, v216
	v_cvt_f32_f16_sdwa v61, v216 dst_sel:DWORD dst_unused:UNUSED_PAD src0_sel:WORD_1
	v_cvt_f32_f16_e32 v62, v217
	v_cvt_f32_f16_sdwa v63, v217 dst_sel:DWORD dst_unused:UNUSED_PAD src0_sel:WORD_1
	v_pk_fma_f32 v[56:57], v[56:57], v[120:121], v[60:61]
	v_cvt_f32_f16_e32 v60, v218
	v_pk_fma_f32 v[58:59], v[58:59], v[122:123], v[62:63]
	v_cvt_f32_f16_sdwa v61, v218 dst_sel:DWORD dst_unused:UNUSED_PAD src0_sel:WORD_1
	v_cvt_f32_f16_e32 v62, v219
	v_cvt_f32_f16_sdwa v63, v219 dst_sel:DWORD dst_unused:UNUSED_PAD src0_sel:WORD_1
	v_pk_fma_f32 v[62:63], v[54:55], v[114:115], v[62:63]
	v_pk_fma_f32 v[54:55], v[52:53], v[112:113], v[60:61]
	v_cvt_pk_f16_f32 v52, v56, v57
	v_cvt_pk_f16_f32 v53, v58, v59
	v_cvt_pk_f16_f32 v54, v54, v55
	v_cvt_pk_f16_f32 v55, v62, v63
	global_store_dwordx4 v[130:131], v[52:55], off offset:256 sc1
	s_nop 1
	s_waitcnt vmcnt(15)
	v_cvt_f32_f16_e32 v52, v220
	v_cvt_f32_f16_sdwa v53, v220 dst_sel:DWORD dst_unused:UNUSED_PAD src0_sel:WORD_1
	v_cvt_f32_f16_e32 v54, v221
	v_cvt_f32_f16_sdwa v55, v221 dst_sel:DWORD dst_unused:UNUSED_PAD src0_sel:WORD_1
	v_pk_fma_f32 v[48:49], v[48:49], v[132:133], v[52:53]
	v_cvt_f32_f16_e32 v52, v222
	v_pk_fma_f32 v[50:51], v[50:51], v[134:135], v[54:55]
	v_cvt_f32_f16_sdwa v53, v222 dst_sel:DWORD dst_unused:UNUSED_PAD src0_sel:WORD_1
	v_cvt_f32_f16_e32 v54, v223
	v_cvt_f32_f16_sdwa v55, v223 dst_sel:DWORD dst_unused:UNUSED_PAD src0_sel:WORD_1
	v_pk_fma_f32 v[54:55], v[46:47], v[126:127], v[54:55]
	v_pk_fma_f32 v[46:47], v[44:45], v[124:125], v[52:53]
	v_cvt_pk_f16_f32 v44, v48, v49
	v_cvt_pk_f16_f32 v45, v50, v51
	v_cvt_pk_f16_f32 v46, v46, v47
	v_cvt_pk_f16_f32 v47, v54, v55
	global_store_dwordx4 v[128:129], v[44:47], off sc1
	s_nop 1
	s_waitcnt vmcnt(15)
	v_cvt_f32_f16_e32 v44, v224
	v_cvt_f32_f16_sdwa v45, v224 dst_sel:DWORD dst_unused:UNUSED_PAD src0_sel:WORD_1
	v_cvt_f32_f16_e32 v46, v225
	v_cvt_f32_f16_sdwa v47, v225 dst_sel:DWORD dst_unused:UNUSED_PAD src0_sel:WORD_1
	v_pk_fma_f32 v[40:41], v[40:41], v[120:121], v[44:45]
	v_cvt_f32_f16_e32 v44, v226
	v_pk_fma_f32 v[42:43], v[42:43], v[122:123], v[46:47]
	v_cvt_f32_f16_sdwa v45, v226 dst_sel:DWORD dst_unused:UNUSED_PAD src0_sel:WORD_1
	v_cvt_f32_f16_e32 v46, v227
	v_cvt_f32_f16_sdwa v47, v227 dst_sel:DWORD dst_unused:UNUSED_PAD src0_sel:WORD_1
	v_pk_fma_f32 v[46:47], v[38:39], v[114:115], v[46:47]
	v_pk_fma_f32 v[38:39], v[36:37], v[112:113], v[44:45]
	v_cvt_pk_f16_f32 v36, v40, v41
	v_cvt_pk_f16_f32 v37, v42, v43
	v_cvt_pk_f16_f32 v38, v38, v39
	v_cvt_pk_f16_f32 v39, v46, v47
	global_store_dwordx4 v[128:129], v[36:39], off offset:256 sc1
	s_nop 0
	s_waitcnt vmcnt(15)
; #define ER_LOAD(dst, ai, mp) do { _Pragma("unroll") for (int mm = 0; mm < 2; ++mm) _Pragma("unroll") for (int bj = 0; bj < 2; ++bj) \
;             dst[mm][bj] = *(const u32x4*)(xb + (size_t)((ai) * HALF + (2 * (mp) + mm) * 16) * 2048 + bj * HALF); } while (0)
;     __device__ __forceinline__ void operator()(const f32x4 (&acc)[2][2][4][2], const Unit& u, int wr, int wc, int fr, int fq) const {
;     ...
;         ER_LOAD(xa, 0, 0); ER_LOAD(xc, 0, 1);
;         ER_STORE(xa, 0, 0); ER_LOAD(xa, 1, 0);
;         ER_STORE(xc, 0, 1); ER_LOAD(xc, 1, 1);
;         ER_STORE(xa, 1, 0); ER_STORE(xc, 1, 1);
	v_cvt_f32_f16_e32 v36, v228
	v_cvt_f32_f16_sdwa v37, v228 dst_sel:DWORD dst_unused:UNUSED_PAD src0_sel:WORD_1
	v_cvt_f32_f16_e32 v38, v229
	v_cvt_f32_f16_sdwa v39, v229 dst_sel:DWORD dst_unused:UNUSED_PAD src0_sel:WORD_1
	v_pk_fma_f32 v[32:33], v[32:33], v[132:133], v[36:37]
	v_cvt_f32_f16_e32 v36, v230
	v_pk_fma_f32 v[34:35], v[34:35], v[134:135], v[38:39]
	v_cvt_f32_f16_sdwa v37, v230 dst_sel:DWORD dst_unused:UNUSED_PAD src0_sel:WORD_1
	v_cvt_f32_f16_e32 v38, v231
	v_cvt_f32_f16_sdwa v39, v231 dst_sel:DWORD dst_unused:UNUSED_PAD src0_sel:WORD_1
	v_pk_fma_f32 v[38:39], v[30:31], v[126:127], v[38:39]
	v_pk_fma_f32 v[30:31], v[28:29], v[124:125], v[36:37]
	v_cvt_pk_f16_f32 v28, v32, v33
	v_cvt_pk_f16_f32 v29, v34, v35
	v_cvt_pk_f16_f32 v30, v30, v31
	v_cvt_pk_f16_f32 v31, v38, v39
	global_store_dwordx4 v[84:85], v[28:31], off sc1
	s_nop 1
	s_waitcnt vmcnt(15)
	v_cvt_f32_f16_e32 v28, v232
	v_cvt_f32_f16_sdwa v29, v232 dst_sel:DWORD dst_unused:UNUSED_PAD src0_sel:WORD_1
	v_cvt_f32_f16_e32 v30, v233
	v_cvt_f32_f16_sdwa v31, v233 dst_sel:DWORD dst_unused:UNUSED_PAD src0_sel:WORD_1
	v_pk_fma_f32 v[24:25], v[24:25], v[120:121], v[28:29]
	v_cvt_f32_f16_e32 v28, v234
	v_pk_fma_f32 v[26:27], v[26:27], v[122:123], v[30:31]
	v_cvt_f32_f16_sdwa v29, v234 dst_sel:DWORD dst_unused:UNUSED_PAD src0_sel:WORD_1
	v_cvt_f32_f16_e32 v30, v235
	v_cvt_f32_f16_sdwa v31, v235 dst_sel:DWORD dst_unused:UNUSED_PAD src0_sel:WORD_1
	v_pk_fma_f32 v[30:31], v[22:23], v[114:115], v[30:31]
	v_pk_fma_f32 v[22:23], v[20:21], v[112:113], v[28:29]
	v_cvt_pk_f16_f32 v20, v24, v25
	v_cvt_pk_f16_f32 v21, v26, v27
	v_cvt_pk_f16_f32 v22, v22, v23
	v_cvt_pk_f16_f32 v23, v30, v31
	global_store_dwordx4 v[84:85], v[20:23], off offset:256 sc1
	s_nop 1
	s_waitcnt vmcnt(15)
	v_cvt_f32_f16_e32 v20, v236
	v_cvt_f32_f16_sdwa v21, v236 dst_sel:DWORD dst_unused:UNUSED_PAD src0_sel:WORD_1
	v_cvt_f32_f16_e32 v22, v237
	v_cvt_f32_f16_sdwa v23, v237 dst_sel:DWORD dst_unused:UNUSED_PAD src0_sel:WORD_1
	v_pk_fma_f32 v[16:17], v[16:17], v[132:133], v[20:21]
	v_cvt_f32_f16_e32 v20, v238
	v_pk_fma_f32 v[18:19], v[18:19], v[134:135], v[22:23]
	v_cvt_f32_f16_sdwa v21, v238 dst_sel:DWORD dst_unused:UNUSED_PAD src0_sel:WORD_1
	v_cvt_f32_f16_e32 v22, v239
	v_cvt_f32_f16_sdwa v23, v239 dst_sel:DWORD dst_unused:UNUSED_PAD src0_sel:WORD_1
	v_pk_fma_f32 v[22:23], v[14:15], v[126:127], v[22:23]
	v_pk_fma_f32 v[14:15], v[12:13], v[124:125], v[20:21]
	v_cvt_pk_f16_f32 v12, v16, v17
	v_cvt_pk_f16_f32 v13, v18, v19
	v_cvt_pk_f16_f32 v14, v14, v15
	v_cvt_pk_f16_f32 v15, v22, v23
	global_store_dwordx4 v[2:3], v[12:15], off sc1
	s_nop 1
	s_waitcnt vmcnt(15)
	v_cvt_f32_f16_e32 v12, v240
	v_cvt_f32_f16_sdwa v13, v240 dst_sel:DWORD dst_unused:UNUSED_PAD src0_sel:WORD_1
	v_cvt_f32_f16_e32 v14, v241
	v_cvt_f32_f16_sdwa v15, v241 dst_sel:DWORD dst_unused:UNUSED_PAD src0_sel:WORD_1
	v_pk_fma_f32 v[8:9], v[8:9], v[120:121], v[12:13]
	v_cvt_f32_f16_e32 v12, v242
	v_pk_fma_f32 v[10:11], v[10:11], v[122:123], v[14:15]
	v_cvt_f32_f16_sdwa v13, v242 dst_sel:DWORD dst_unused:UNUSED_PAD src0_sel:WORD_1
	v_cvt_f32_f16_e32 v14, v243
	v_cvt_f32_f16_sdwa v15, v243 dst_sel:DWORD dst_unused:UNUSED_PAD src0_sel:WORD_1
	v_pk_fma_f32 v[14:15], v[6:7], v[114:115], v[14:15]
	v_pk_fma_f32 v[6:7], v[4:5], v[112:113], v[12:13]
	v_cvt_pk_f16_f32 v4, v8, v9
	v_cvt_pk_f16_f32 v5, v10, v11
	v_cvt_pk_f16_f32 v6, v6, v7
	v_cvt_pk_f16_f32 v7, v14, v15
	global_store_dwordx4 v[2:3], v[4:7], off offset:256 sc1
	s_cbranch_vccz .LBB0_1209
	ds_read_b128 v[2:5], v0
	ds_read_b128 v[6:9], v0 offset:1024
	ds_read_b128 v[10:13], v0 offset:2048
	ds_read_b128 v[14:17], v0 offset:3072
	ds_read_b128 v[18:21], v188
	ds_read_b128 v[22:25], v188 offset:1024
	ds_read_b128 v[26:29], v188 offset:2048
	ds_read_b128 v[30:33], v188 offset:3072
	s_add_u32 s12, s8, 0x100
	s_addc_u32 s13, s9, 0
	s_add_u32 s10, s8, 0x180
	s_addc_u32 s11, s9, 0
	s_add_u32 s14, s6, 0x100
	s_addc_u32 s15, s7, 0
	ds_read_b128 v[34:37], v187
	ds_read_b128 v[38:41], v187 offset:1024
	ds_read_b128 v[42:45], v187 offset:2048
	ds_read_b128 v[46:49], v187 offset:3072
	ds_read_b128 v[50:53], v187 offset:4096
	ds_read_b128 v[54:57], v187 offset:5120
	ds_read_b128 v[58:61], v187 offset:6144
	ds_read_b128 v[62:65], v187 offset:7168
	s_waitcnt vmcnt(44)
	s_waitcnt lgkmcnt(0)
	s_barrier
	s_setprio 1
	s_waitcnt lgkmcnt(0)
	v_mfma_f32_16x16x32_bf16 v[90:93], v[2:5], v[58:61], 0
	v_mfma_f32_16x16x32_bf16 v[66:69], v[2:5], v[34:37], 0
	v_mfma_f32_16x16x32_bf16 v[70:73], v[10:13], v[34:37], 0
	v_mfma_f32_16x16x32_bf16 v[74:77], v[2:5], v[42:45], 0
	v_mfma_f32_16x16x32_bf16 v[78:81], v[10:13], v[42:45], 0
	v_mfma_f32_16x16x32_bf16 v[82:85], v[2:5], v[50:53], 0
	v_mfma_f32_16x16x32_bf16 v[86:89], v[10:13], v[50:53], 0
	v_mfma_f32_16x16x32_bf16 v[100:103], v[6:9], v[62:65], v[90:93]
	v_mfma_f32_16x16x32_bf16 v[90:93], v[10:13], v[58:61], 0
	v_mfma_f32_16x16x32_bf16 v[66:69], v[6:9], v[38:41], v[66:69]
	v_mfma_f32_16x16x32_bf16 v[70:73], v[14:17], v[38:41], v[70:73]
	v_mfma_f32_16x16x32_bf16 v[74:77], v[6:9], v[46:49], v[74:77]
	v_mfma_f32_16x16x32_bf16 v[78:81], v[14:17], v[46:49], v[78:81]
	v_mfma_f32_16x16x32_bf16 v[82:85], v[6:9], v[54:57], v[82:85]
	v_mfma_f32_16x16x32_bf16 v[86:89], v[14:17], v[54:57], v[86:89]
	v_mfma_f32_16x16x32_bf16 v[104:107], v[14:17], v[62:65], v[90:93]
	s_setprio 0
	s_setprio 1
	v_mfma_f32_16x16x32_bf16 v[90:93], v[18:21], v[34:37], 0
	v_mfma_f32_16x16x32_bf16 v[34:37], v[26:29], v[34:37], 0
	v_mfma_f32_16x16x32_bf16 v[112:115], v[22:25], v[38:41], v[90:93]
	v_mfma_f32_16x16x32_bf16 v[34:37], v[30:33], v[38:41], v[34:37]
	v_mfma_f32_16x16x32_bf16 v[38:41], v[18:21], v[42:45], 0
	v_mfma_f32_16x16x32_bf16 v[42:45], v[26:29], v[42:45], 0
	v_mfma_f32_16x16x32_bf16 v[38:41], v[22:25], v[46:49], v[38:41]
	v_mfma_f32_16x16x32_bf16 v[42:45], v[30:33], v[46:49], v[42:45]
	v_mfma_f32_16x16x32_bf16 v[46:49], v[18:21], v[50:53], 0
	v_mfma_f32_16x16x32_bf16 v[50:53], v[26:29], v[50:53], 0
	v_mfma_f32_16x16x32_bf16 v[46:49], v[22:25], v[54:57], v[46:49]
	v_mfma_f32_16x16x32_bf16 v[50:53], v[30:33], v[54:57], v[50:53]
	v_mfma_f32_16x16x32_bf16 v[54:57], v[18:21], v[58:61], 0
	v_mfma_f32_16x16x32_bf16 v[58:61], v[26:29], v[58:61], 0
	v_mfma_f32_16x16x32_bf16 v[54:57], v[22:25], v[62:65], v[54:57]
	v_mfma_f32_16x16x32_bf16 v[58:61], v[30:33], v[62:65], v[58:61]
	s_setprio 0
	s_barrier
	ds_read_b128 v[62:65], v187 offset:16384
	ds_read_b128 v[90:93], v187 offset:17408
	ds_read_b128 v[94:97], v187 offset:18432
	ds_read_b128 v[108:111], v187 offset:19456
	ds_read_b128 v[116:119], v187 offset:20480
	ds_read_b128 v[120:123], v187 offset:21504
	ds_read_b128 v[124:127], v187 offset:22528
	ds_read_b128 v[128:131], v187 offset:23552
	s_mov_b32 m0, s22
	s_nop 0
	global_load_lds_dwordx4 v175, s[14:15]
	s_nop 0
	s_mov_b32 m0, s23
	s_nop 0
	global_load_lds_dwordx4 v177, s[14:15]
	s_add_u32 s14, s6, 0x160100
	s_addc_u32 s15, s7, 0
	s_mov_b32 m0, s26
	s_nop 0
	global_load_lds_dwordx4 v175, s[14:15]
	s_nop 0
	s_mov_b32 m0, s27
	s_nop 0
	global_load_lds_dwordx4 v177, s[14:15]
	s_nop 0
	s_mov_b32 m0, s21
	s_nop 0
	global_load_lds_dwordx4 v174, s[12:13]
	s_nop 0
	s_mov_b32 m0, s28
	s_nop 0
	global_load_lds_dwordx4 v176, s[12:13]
	s_waitcnt vmcnt(44)
	s_waitcnt lgkmcnt(0)
	s_barrier
	s_setprio 1
	s_waitcnt lgkmcnt(0)
	v_mfma_f32_16x16x32_bf16 v[136:139], v[10:13], v[62:65], 0
	v_mfma_f32_16x16x32_bf16 v[148:151], v[14:17], v[90:93], v[136:139]
	v_mfma_f32_16x16x32_bf16 v[136:139], v[2:5], v[94:97], 0
	v_mfma_f32_16x16x32_bf16 v[152:155], v[6:9], v[108:111], v[136:139]
	v_mfma_f32_16x16x32_bf16 v[136:139], v[10:13], v[94:97], 0
	v_mfma_f32_16x16x32_bf16 v[132:135], v[2:5], v[62:65], 0
	v_mfma_f32_16x16x32_bf16 v[156:159], v[14:17], v[108:111], v[136:139]
	v_mfma_f32_16x16x32_bf16 v[136:139], v[2:5], v[116:119], 0
	v_mfma_f32_16x16x32_bf16 v[2:5], v[2:5], v[124:127], 0
	v_mfma_f32_16x16x32_bf16 v[132:135], v[6:9], v[90:93], v[132:135]
	v_mfma_f32_16x16x32_bf16 v[160:163], v[6:9], v[120:123], v[136:139]
	v_mfma_f32_16x16x32_bf16 v[2:5], v[6:9], v[128:131], v[2:5]
	v_mfma_f32_16x16x32_bf16 v[6:9], v[10:13], v[124:127], 0
	v_mfma_f32_16x16x32_bf16 v[136:139], v[10:13], v[116:119], 0
	v_mfma_f32_16x16x32_bf16 v[6:9], v[14:17], v[128:131], v[6:9]
	v_mfma_f32_16x16x32_bf16 v[164:167], v[14:17], v[120:123], v[136:139]
	s_setprio 0
	s_setprio 1
	v_mfma_f32_16x16x32_bf16 v[10:13], v[18:21], v[62:65], 0
	v_mfma_f32_16x16x32_bf16 v[168:171], v[22:25], v[90:93], v[10:13]
	v_mfma_f32_16x16x32_bf16 v[10:13], v[26:29], v[62:65], 0
	v_mfma_f32_16x16x32_bf16 v[178:181], v[30:33], v[90:93], v[10:13]
	v_mfma_f32_16x16x32_bf16 v[10:13], v[18:21], v[94:97], 0
	v_mfma_f32_16x16x32_bf16 v[192:195], v[22:25], v[108:111], v[10:13]
	v_mfma_f32_16x16x32_bf16 v[10:13], v[26:29], v[94:97], 0
	v_mfma_f32_16x16x32_bf16 v[196:199], v[30:33], v[108:111], v[10:13]
	v_mfma_f32_16x16x32_bf16 v[10:13], v[18:21], v[116:119], 0
	v_mfma_f32_16x16x32_bf16 v[200:203], v[22:25], v[120:123], v[10:13]
	v_mfma_f32_16x16x32_bf16 v[10:13], v[26:29], v[116:119], 0
	v_mfma_f32_16x16x32_bf16 v[120:123], v[30:33], v[120:123], v[10:13]
	v_mfma_f32_16x16x32_bf16 v[10:13], v[18:21], v[124:127], 0
	v_mfma_f32_16x16x32_bf16 v[204:207], v[22:25], v[128:131], v[10:13]
	v_mfma_f32_16x16x32_bf16 v[10:13], v[26:29], v[124:127], 0
	v_mfma_f32_16x16x32_bf16 v[124:127], v[30:33], v[128:131], v[10:13]
	s_setprio 0
	s_barrier
	s_nop 4
	ds_read_b128 v[10:13], v189
	ds_read_b128 v[14:17], v189 offset:1024
	ds_read_b128 v[20:23], v189 offset:2048
	ds_read_b128 v[24:27], v189 offset:3072
	ds_read_b128 v[208:211], v190
	ds_read_b128 v[212:215], v190 offset:1024
	ds_read_b128 v[216:219], v190 offset:2048
	ds_read_b128 v[188:191], v190 offset:3072
	ds_read_b128 v[28:31], v187 offset:32768
	ds_read_b128 v[62:65], v187 offset:33792
	ds_read_b128 v[220:223], v187 offset:34816
	ds_read_b128 v[224:227], v187 offset:35840
	ds_read_b128 v[228:231], v187 offset:36864
	ds_read_b128 v[232:235], v187 offset:37888
	ds_read_b128 v[236:239], v187 offset:38912
	ds_read_b128 v[240:243], v187 offset:39936
	s_add_u32 s12, s8, 0x160100
	s_addc_u32 s13, s9, 0
	s_mov_b32 m0, s29
	s_nop 0
	global_load_lds_dwordx4 v174, s[12:13]
	s_nop 0
	s_mov_b32 m0, s30
	s_nop 0
	global_load_lds_dwordx4 v176, s[12:13]
	s_waitcnt vmcnt(44)
	s_waitcnt lgkmcnt(0)
	s_barrier
	s_setprio 1
	s_waitcnt lgkmcnt(0)
	v_mfma_f32_16x16x32_bf16 v[66:69], v[10:13], v[28:31], v[66:69]
	v_mfma_f32_16x16x32_bf16 v[144:147], v[14:17], v[62:65], v[66:69]
	v_mfma_f32_16x16x32_bf16 v[66:69], v[20:23], v[28:31], v[70:73]
	v_mfma_f32_16x16x32_bf16 v[140:143], v[24:27], v[62:65], v[66:69]
	v_mfma_f32_16x16x32_bf16 v[66:69], v[10:13], v[220:223], v[74:77]
	v_mfma_f32_16x16x32_bf16 v[116:119], v[14:17], v[224:227], v[66:69]
	v_mfma_f32_16x16x32_bf16 v[66:69], v[20:23], v[220:223], v[78:81]
	v_mfma_f32_16x16x32_bf16 v[108:111], v[24:27], v[224:227], v[66:69]
	v_mfma_f32_16x16x32_bf16 v[66:69], v[10:13], v[228:231], v[82:85]
	v_mfma_f32_16x16x32_bf16 v[96:99], v[14:17], v[232:235], v[66:69]
	v_mfma_f32_16x16x32_bf16 v[66:69], v[20:23], v[228:231], v[86:89]
	v_mfma_f32_16x16x32_bf16 v[92:95], v[24:27], v[232:235], v[66:69]
	v_mfma_f32_16x16x32_bf16 v[66:69], v[10:13], v[236:239], v[100:103]
	v_mfma_f32_16x16x32_bf16 v[80:83], v[14:17], v[240:243], v[66:69]
	v_mfma_f32_16x16x32_bf16 v[66:69], v[20:23], v[236:239], v[104:107]
	v_mfma_f32_16x16x32_bf16 v[76:79], v[24:27], v[240:243], v[66:69]
	s_setprio 0
	s_setprio 1
	v_mfma_f32_16x16x32_bf16 v[66:69], v[208:211], v[28:31], v[112:115]
	v_mfma_f32_16x16x32_bf16 v[28:31], v[216:219], v[28:31], v[34:37]
	v_mfma_f32_16x16x32_bf16 v[128:131], v[188:191], v[62:65], v[28:31]
	v_mfma_f32_16x16x32_bf16 v[28:31], v[208:211], v[220:223], v[38:41]
	v_mfma_f32_16x16x32_bf16 v[104:107], v[212:215], v[224:227], v[28:31]
	v_mfma_f32_16x16x32_bf16 v[28:31], v[216:219], v[220:223], v[42:45]
	v_mfma_f32_16x16x32_bf16 v[100:103], v[188:191], v[224:227], v[28:31]
	v_mfma_f32_16x16x32_bf16 v[28:31], v[208:211], v[228:231], v[46:49]
	v_mfma_f32_16x16x32_bf16 v[88:91], v[212:215], v[232:235], v[28:31]
	v_mfma_f32_16x16x32_bf16 v[28:31], v[216:219], v[228:231], v[50:53]
	v_mfma_f32_16x16x32_bf16 v[84:87], v[188:191], v[232:235], v[28:31]
	v_mfma_f32_16x16x32_bf16 v[28:31], v[208:211], v[236:239], v[54:57]
	v_mfma_f32_16x16x32_bf16 v[72:75], v[212:215], v[240:243], v[28:31]
	v_mfma_f32_16x16x32_bf16 v[28:31], v[216:219], v[236:239], v[58:61]
	v_mfma_f32_16x16x32_bf16 v[136:139], v[212:215], v[62:65], v[66:69]
	v_mfma_f32_16x16x32_bf16 v[68:71], v[188:191], v[240:243], v[28:31]
	s_setprio 0
	s_barrier
	ds_read_b128 v[36:39], v187 offset:49152
	ds_read_b128 v[40:43], v187 offset:50176
	ds_read_b128 v[112:115], v187 offset:51200
	ds_read_b128 v[220:223], v187 offset:52224
	ds_read_b128 v[224:227], v187 offset:53248
	ds_read_b128 v[228:231], v187 offset:54272
	ds_read_b128 v[232:235], v187 offset:55296
	ds_read_b128 v[236:239], v187 offset:56320
	s_add_u32 s12, s6, 0x180
	s_addc_u32 s13, s7, 0
	s_mov_b32 m0, s34
	s_nop 0
	global_load_lds_dwordx4 v175, s[12:13]
	s_nop 0
	s_mov_b32 m0, s35
	s_nop 0
	global_load_lds_dwordx4 v177, s[12:13]
	s_add_u32 s12, s6, 0x160180
	s_addc_u32 s13, s7, 0
	s_mov_b32 m0, s40
	s_nop 0
	global_load_lds_dwordx4 v175, s[12:13]
	s_nop 0
	s_mov_b32 m0, s41
	s_nop 0
	global_load_lds_dwordx4 v177, s[12:13]
	s_nop 0
	s_mov_b32 m0, s36
	s_nop 0
	global_load_lds_dwordx4 v174, s[10:11]
	s_nop 0
	s_mov_b32 m0, s37
	s_nop 0
	global_load_lds_dwordx4 v176, s[10:11]
	s_waitcnt vmcnt(8)
	s_waitcnt lgkmcnt(0)
	s_barrier
	s_setprio 1
	s_waitcnt lgkmcnt(0)
	v_mfma_f32_16x16x32_bf16 v[28:31], v[10:13], v[36:39], v[132:135]
	v_mfma_f32_16x16x32_bf16 v[64:67], v[14:17], v[40:43], v[28:31]
	v_mfma_f32_16x16x32_bf16 v[28:31], v[20:23], v[36:39], v[148:151]
	v_mfma_f32_16x16x32_bf16 v[60:63], v[24:27], v[40:43], v[28:31]
	v_mfma_f32_16x16x32_bf16 v[28:31], v[10:13], v[112:115], v[152:155]
	v_mfma_f32_16x16x32_bf16 v[48:51], v[14:17], v[220:223], v[28:31]
	v_mfma_f32_16x16x32_bf16 v[28:31], v[20:23], v[112:115], v[156:159]
	v_mfma_f32_16x16x32_bf16 v[44:47], v[24:27], v[220:223], v[28:31]
	v_mfma_f32_16x16x32_bf16 v[28:31], v[10:13], v[224:227], v[160:163]
	v_mfma_f32_16x16x32_bf16 v[2:5], v[10:13], v[232:235], v[2:5]
	v_mfma_f32_16x16x32_bf16 v[32:35], v[14:17], v[228:231], v[28:31]
	v_mfma_f32_16x16x32_bf16 v[28:31], v[20:23], v[224:227], v[164:167]
	v_mfma_f32_16x16x32_bf16 v[16:19], v[14:17], v[236:239], v[2:5]
	v_mfma_f32_16x16x32_bf16 v[2:5], v[20:23], v[232:235], v[6:9]
	v_mfma_f32_16x16x32_bf16 v[28:31], v[24:27], v[228:231], v[28:31]
	v_mfma_f32_16x16x32_bf16 v[12:15], v[24:27], v[236:239], v[2:5]
	s_setprio 0
	s_setprio 1
	v_mfma_f32_16x16x32_bf16 v[2:5], v[208:211], v[36:39], v[168:171]
	v_mfma_f32_16x16x32_bf16 v[56:59], v[212:215], v[40:43], v[2:5]
	v_mfma_f32_16x16x32_bf16 v[2:5], v[216:219], v[36:39], v[178:181]
	v_mfma_f32_16x16x32_bf16 v[52:55], v[188:191], v[40:43], v[2:5]
	v_mfma_f32_16x16x32_bf16 v[2:5], v[208:211], v[112:115], v[192:195]
	v_mfma_f32_16x16x32_bf16 v[40:43], v[212:215], v[220:223], v[2:5]
	v_mfma_f32_16x16x32_bf16 v[2:5], v[216:219], v[112:115], v[196:199]
	v_mfma_f32_16x16x32_bf16 v[36:39], v[188:191], v[220:223], v[2:5]
	v_mfma_f32_16x16x32_bf16 v[2:5], v[208:211], v[224:227], v[200:203]
	v_mfma_f32_16x16x32_bf16 v[24:27], v[212:215], v[228:231], v[2:5]
	v_mfma_f32_16x16x32_bf16 v[2:5], v[216:219], v[224:227], v[120:123]
	v_mfma_f32_16x16x32_bf16 v[20:23], v[188:191], v[228:231], v[2:5]
	v_mfma_f32_16x16x32_bf16 v[2:5], v[208:211], v[232:235], v[204:207]
	v_mfma_f32_16x16x32_bf16 v[8:11], v[212:215], v[236:239], v[2:5]
	v_mfma_f32_16x16x32_bf16 v[2:5], v[216:219], v[232:235], v[124:127]
	v_mfma_f32_16x16x32_bf16 v[4:7], v[188:191], v[236:239], v[2:5]
	s_setprio 0
	s_barrier
	s_mov_b64 s[12:13], 0
	s_branch .LBB0_1209

; #define PG8_GAS __attribute__((address_space(1)))
;     __device__ __forceinline__ void operator()(const f32x4 (&acc)[2][2][4][2], const Unit& u, int wr, int wc, int fr, int fq) const {
;         float* base = slab + (size_t)(u.k0 / ksub) * kstride + (size_t)((u.pm - pm0) * BM + wr * 64 + fr) * 2048 + u.pn * BM + wc * 32 + 4 * fq;
; #pragma unroll
;         for (int ai = 0; ai < 2; ++ai)
; #pragma unroll
;             for (int m = 0; m < 4; ++m) { float* rowp = base + (size_t)(ai * HALF + m * 16) * 2048;
; #pragma unroll
;                 for (int bj = 0; bj < 2; ++bj)
; #pragma unroll
;                     for (int n = 0; n < 2; ++n) *(PG8_GAS f32x4*)(rowp + bj * HALF + n * 16) = acc[ai][bj][m][n]; }
;     }
.LBB0_1249:
	s_mul_hi_i32 s11, s63, 0x2e8ba2e9
	s_lshr_b32 s16, s11, 31
	s_ashr_i32 s11, s11, 8
	s_add_i32 s16, s11, s16
	s_ashr_i32 s17, s16, 31
	s_lshl_b64 s[16:17], s[16:17], 23
	v_lshl_add_u32 v140, s57, 8, v132
	s_add_u32 s16, s35, s16
	v_ashrrev_i32_e32 v141, 31, v140
	s_addc_u32 s17, s36, s17
	v_lshlrev_b64 v[140:141], 13, v[140:141]
	v_lshl_add_u64 v[140:141], s[16:17], 0, v[140:141]
	s_lshl_b32 s16, s53, 8
	s_ashr_i32 s17, s16, 31
	v_lshl_add_u64 v[140:141], s[16:17], 2, v[140:141]
	v_lshl_add_u64 v[140:141], v[140:141], 0, s[84:85]
	v_lshl_add_u64 v[140:141], v[140:141], 0, v[0:1]
	global_store_dwordx4 v[140:141], v[26:29], off sc1
	global_store_dwordx4 v[140:141], v[30:33], off offset:64 sc1
	global_store_dwordx4 v[140:141], v[58:61], off offset:512 sc1
	global_store_dwordx4 v[140:141], v[62:65], off offset:576 sc1
	v_add_co_u32_e32 v26, vcc, s50, v140
	s_mov_b32 s11, 0x40000
	s_nop 0
	v_addc_co_u32_e32 v27, vcc, 0, v141, vcc
	global_store_dwordx4 v[26:27], v[18:21], off sc1
	global_store_dwordx4 v[26:27], v[22:25], off offset:64 sc1
	global_store_dwordx4 v[26:27], v[50:53], off offset:512 sc1
	global_store_dwordx4 v[26:27], v[54:57], off offset:576 sc1
	v_add_co_u32_e32 v18, vcc, s11, v140
	s_mov_b32 s11, 0x60000
	s_nop 0
	v_addc_co_u32_e32 v19, vcc, 0, v141, vcc
	global_store_dwordx4 v[18:19], v[10:13], off sc1
	global_store_dwordx4 v[18:19], v[14:17], off offset:64 sc1
	global_store_dwordx4 v[18:19], v[42:45], off offset:512 sc1
	global_store_dwordx4 v[18:19], v[46:49], off offset:576 sc1
	v_add_co_u32_e32 v10, vcc, s11, v140
	s_mov_b32 s11, 0x100000
	s_nop 0
	v_addc_co_u32_e32 v11, vcc, 0, v141, vcc
	global_store_dwordx4 v[10:11], v[2:5], off sc1
	global_store_dwordx4 v[10:11], v[6:9], off offset:64 sc1
	global_store_dwordx4 v[10:11], v[34:37], off offset:512 sc1
	global_store_dwordx4 v[10:11], v[38:41], off offset:576 sc1
	v_add_co_u32_e32 v2, vcc, s11, v140
	s_mov_b32 s11, 0x120000
	s_nop 0
	v_addc_co_u32_e32 v3, vcc, 0, v141, vcc
	global_store_dwordx4 v[2:3], v[98:101], off sc1
	global_store_dwordx4 v[2:3], v[102:105], off offset:64 sc1
	global_store_dwordx4 v[2:3], v[122:125], off offset:512 sc1
	global_store_dwordx4 v[2:3], v[126:129], off offset:576 sc1
	v_add_co_u32_e32 v2, vcc, s11, v140
	s_mov_b32 s11, 0x140000
	s_nop 0
	v_addc_co_u32_e32 v3, vcc, 0, v141, vcc
	global_store_dwordx4 v[2:3], v[86:89], off sc1
	global_store_dwordx4 v[2:3], v[90:93], off offset:64 sc1
	global_store_dwordx4 v[2:3], v[114:117], off offset:512 sc1
	global_store_dwordx4 v[2:3], v[118:121], off offset:576 sc1
	v_add_co_u32_e32 v2, vcc, s11, v140
	s_mov_b32 s64, 0x50000
	s_nop 0
	v_addc_co_u32_e32 v3, vcc, 0, v141, vcc
	global_store_dwordx4 v[2:3], v[74:77], off sc1
	global_store_dwordx4 v[2:3], v[78:81], off offset:64 sc1
	global_store_dwordx4 v[2:3], v[106:109], off offset:512 sc1
	global_store_dwordx4 v[2:3], v[110:113], off offset:576 sc1
	v_add_co_u32_e32 v2, vcc, 0x160000, v140
	s_mov_b32 s67, 0xd5800000
	s_nop 0
	v_addc_co_u32_e32 v3, vcc, 0, v141, vcc
	global_store_dwordx4 v[2:3], v[66:69], off sc1
	global_store_dwordx4 v[2:3], v[70:73], off offset:64 sc1
	global_store_dwordx4 v[2:3], v[94:97], off offset:512 sc1
	global_store_dwordx4 v[2:3], v[82:85], off offset:576 sc1
	s_and_b64 vcc, exec, s[6:7]
	s_mov_b64 s[6:7], -1
	s_cbranch_vccnz .LBB0_1238
	s_andn2_b64 vcc, exec, s[4:5]
	s_cbranch_vccnz .LBB0_1237
	s_barrier
	s_branch .LBB0_1237
